# nt (non-temporal) hint on all GEMM epilogue dwordx4 stores
# baseline (speedup 1.0000x reference)
; #define LAS __attribute__((address_space(3)))
; __device__ __forceinline__ unsigned cvt_pk_bf16(float lo, float hi) { unsigned r; asm("v_cvt_pk_bf16_f32 %0, %1, %2" : "=v"(r) : "v"(lo), "v"(hi)); return r; }
; #define LDS_WAIT() asm volatile("s_waitcnt lgkmcnt(0)" ::: "memory")
; __device__ __forceinline__ void tstore_sub(const f32x4 (&v)[4][2], bf16_t* dst  , LAS unsigned char* x, int fr, int fq, int lane) {
; #pragma unroll
;     for (int m = 0; m < 4; ++m)
; #pragma unroll
;         for (int n = 0; n < 2; ++n)
; #pragma unroll
;             for (int j = 0; j < 4; ++j) {
;                 const int ch = 8 * fq + 4 * n + j, tok = 16 * m + fr;
;                 const unsigned b = cvt_pk_bf16(v[m][n][j], 0.f);
;                 *(LAS unsigned short*)(x + ch * 128 + ((((tok >> 3) ^ fq) << 4) | ((tok & 7) << 1))) = (unsigned short)b;
;             }
;     LDS_WAIT();
; #pragma unroll
;     for (int i = 0; i < 4; ++i) {
;         const int q = lane + 64 * i, ch = q >> 3, tc = q & 7;
;         const u32x4 o = *(const LAS u32x4*)(x + ch * 128 + ((tc ^ ((ch >> 3) & 3)) << 4));
;         *(u32x4*)(dst + (size_t)ch * T + tc * 8) = o;
;     }
;     LDS_WAIT();
; }
;     __device__ __forceinline__ void operator()(const f32x4 (&acc)[2][2][4][2], const Unit& u, int wr, int wc, int fr, int fq, LAS unsigned char* xs, int wid, int lane) const {
;     ...
; #pragma unroll
;             for (int ai = 0; ai < 2; ++ai)
; #pragma unroll
;                 for (int bj = 0; bj < 2; ++bj) {
;                     f32x4 v[4][2];
; #pragma unroll
;                     for (int m = 0; m < 4; ++m) { v[m][0] = acc[ai][bj][m][0] * rs[ai][m]; v[m][1] = acc[ai][bj][m][1] * rs[ai][m]; }
.LBB0_230:
	s_waitcnt lgkmcnt(7)
	v_pk_mul_f32 v[176:177], v[124:125], v[172:173] op_sel_hi:[1,0]
	v_pk_mul_f32 v[174:175], v[126:127], v[172:173] op_sel_hi:[1,0]
	v_cvt_pk_bf16_f32 v143, v176, v137
	ds_write_b16 v167, v143
	v_cvt_pk_bf16_f32 v143, v177, v137
	ds_write_b16 v167, v143 offset:128
	v_cvt_pk_bf16_f32 v143, v174, v137
	ds_write_b16 v167, v143 offset:256
	v_cvt_pk_bf16_f32 v143, v175, v137
	v_pk_mul_f32 v[180:181], v[120:121], v[172:173] op_sel_hi:[1,0]
	ds_write_b16 v167, v143 offset:384
	v_cvt_pk_bf16_f32 v143, v180, v137
	ds_write_b16 v167, v143 offset:512
	v_cvt_pk_bf16_f32 v143, v181, v137
	v_pk_mul_f32 v[178:179], v[122:123], v[172:173] op_sel_hi:[1,0]
	ds_write_b16 v167, v143 offset:640
	v_cvt_pk_bf16_f32 v143, v178, v137
	ds_write_b16 v167, v143 offset:768
	v_cvt_pk_bf16_f32 v143, v179, v137
	s_waitcnt lgkmcnt(13)
	v_pk_mul_f32 v[192:193], v[108:109], v[170:171] op_sel_hi:[1,0]
	ds_write_b16 v167, v143 offset:896
	v_cvt_pk_bf16_f32 v143, v192, v137
	ds_write_b16 v169, v143
	v_cvt_pk_bf16_f32 v143, v193, v137
	v_pk_mul_f32 v[190:191], v[110:111], v[170:171] op_sel_hi:[1,0]
	ds_write_b16 v169, v143 offset:128
	v_cvt_pk_bf16_f32 v143, v190, v137
	ds_write_b16 v169, v143 offset:256
	v_cvt_pk_bf16_f32 v143, v191, v137
	v_pk_mul_f32 v[196:197], v[104:105], v[170:171] op_sel_hi:[1,0]
	ds_write_b16 v169, v143 offset:384
	v_cvt_pk_bf16_f32 v143, v196, v137
	ds_write_b16 v169, v143 offset:512
	v_cvt_pk_bf16_f32 v143, v197, v137
	v_pk_mul_f32 v[194:195], v[106:107], v[170:171] op_sel_hi:[1,0]
	ds_write_b16 v169, v143 offset:640
	v_cvt_pk_bf16_f32 v143, v194, v137
	ds_write_b16 v169, v143 offset:768
	v_cvt_pk_bf16_f32 v143, v195, v137
	s_waitcnt lgkmcnt(14)
	v_pk_mul_f32 v[200:201], v[92:93], v[168:169] op_sel_hi:[1,0]
	ds_write_b16 v169, v143 offset:896
	v_cvt_pk_bf16_f32 v143, v200, v137
	ds_write_b16 v171, v143
	v_cvt_pk_bf16_f32 v143, v201, v137
	v_pk_mul_f32 v[198:199], v[94:95], v[168:169] op_sel_hi:[1,0]
	ds_write_b16 v171, v143 offset:128
	v_cvt_pk_bf16_f32 v143, v198, v137
	ds_write_b16 v171, v143 offset:256
	v_cvt_pk_bf16_f32 v143, v199, v137
	v_pk_mul_f32 v[204:205], v[88:89], v[168:169] op_sel_hi:[1,0]
	ds_write_b16 v171, v143 offset:384
	v_cvt_pk_bf16_f32 v143, v204, v137
	ds_write_b16 v171, v143 offset:512
	v_cvt_pk_bf16_f32 v143, v205, v137
	v_pk_mul_f32 v[202:203], v[90:91], v[168:169] op_sel_hi:[1,0]
	ds_write_b16 v171, v143 offset:640
	v_cvt_pk_bf16_f32 v143, v202, v137
	ds_write_b16 v171, v143 offset:768
	v_cvt_pk_bf16_f32 v143, v203, v137
	v_pk_mul_f32 v[208:209], v[76:77], v[166:167] op_sel_hi:[1,0]
	ds_write_b16 v171, v143 offset:896
	v_cvt_pk_bf16_f32 v143, v208, v137
	ds_write_b16 v173, v143
	v_cvt_pk_bf16_f32 v143, v209, v137
	v_pk_mul_f32 v[206:207], v[78:79], v[166:167] op_sel_hi:[1,0]
	ds_write_b16 v173, v143 offset:128
	v_cvt_pk_bf16_f32 v143, v206, v137
	ds_write_b16 v173, v143 offset:256
	v_cvt_pk_bf16_f32 v143, v207, v137
	v_pk_mul_f32 v[212:213], v[72:73], v[166:167] op_sel_hi:[1,0]
	ds_write_b16 v173, v143 offset:384
	v_cvt_pk_bf16_f32 v143, v212, v137
	ds_write_b16 v173, v143 offset:512
	v_cvt_pk_bf16_f32 v143, v213, v137
	v_pk_mul_f32 v[210:211], v[74:75], v[166:167] op_sel_hi:[1,0]
	ds_write_b16 v173, v143 offset:640
	v_cvt_pk_bf16_f32 v143, v210, v137
	s_ashr_i32 s55, s54, 31
	ds_write_b16 v173, v143 offset:768
	v_cvt_pk_bf16_f32 v143, v211, v137
	ds_write_b16 v173, v143 offset:896
	s_lshl_b64 s[18:19], s[54:55], 1
	s_waitcnt lgkmcnt(0)
	s_add_u32 s18, s56, s18
	ds_read_b128 v[176:179], v184
	ds_read_b128 v[190:193], v185
	s_addc_u32 s19, s57, s19
	v_lshl_add_u64 v[182:183], s[18:19], 0, v[136:137]
	s_mov_b32 s43, s21
	v_lshl_add_u64 v[180:181], v[182:183], 0, s[42:43]
	v_mov_b32_e32 v143, v137
	v_lshl_add_u64 v[174:175], v[180:181], 0, v[142:143]
	v_mov_b32_e32 v145, v137
	s_waitcnt lgkmcnt(1)
	global_store_dwordx4 v[174:175], v[176:179], off nt
	ds_read_b128 v[194:197], v186
	v_mov_b32_e32 v147, v137
	v_lshl_add_u64 v[176:177], v[180:181], 0, v[144:145]
	s_waitcnt lgkmcnt(1)
	global_store_dwordx4 v[176:177], v[190:193], off nt
	ds_read_b128 v[190:193], v187
	v_mov_b32_e32 v149, v137
	v_lshl_add_u64 v[178:179], v[180:181], 0, v[146:147]
	v_lshl_add_u64 v[180:181], v[180:181], 0, v[148:149]
	s_waitcnt lgkmcnt(1)
	global_store_dwordx4 v[178:179], v[194:197], off nt
	s_waitcnt lgkmcnt(0)
	global_store_dwordx4 v[180:181], v[190:193], off nt
	s_waitcnt lgkmcnt(0)
; #define LAS __attribute__((address_space(3)))
; __device__ __forceinline__ unsigned cvt_pk_bf16(float lo, float hi) { unsigned r; asm("v_cvt_pk_bf16_f32 %0, %1, %2" : "=v"(r) : "v"(lo), "v"(hi)); return r; }
; #define LDS_WAIT() asm volatile("s_waitcnt lgkmcnt(0)" ::: "memory")
; __device__ __forceinline__ void tstore_sub(const f32x4 (&v)[4][2], bf16_t* dst  , LAS unsigned char* x, int fr, int fq, int lane) {
; #pragma unroll
;     for (int m = 0; m < 4; ++m)
; #pragma unroll
;         for (int n = 0; n < 2; ++n)
; #pragma unroll
;             for (int j = 0; j < 4; ++j) {
;                 const int ch = 8 * fq + 4 * n + j, tok = 16 * m + fr;
;                 const unsigned b = cvt_pk_bf16(v[m][n][j], 0.f);
;                 *(LAS unsigned short*)(x + ch * 128 + ((((tok >> 3) ^ fq) << 4) | ((tok & 7) << 1))) = (unsigned short)b;
;             }
;     LDS_WAIT();
; #pragma unroll
;     for (int i = 0; i < 4; ++i) {
;         const int q = lane + 64 * i, ch = q >> 3, tc = q & 7;
;         const u32x4 o = *(const LAS u32x4*)(x + ch * 128 + ((tc ^ ((ch >> 3) & 3)) << 4));
;         *(u32x4*)(dst + (size_t)ch * T + tc * 8) = o;
;     }
;     LDS_WAIT();
; }
;     __device__ __forceinline__ void operator()(const f32x4 (&acc)[2][2][4][2], const Unit& u, int wr, int wc, int fr, int fq, LAS unsigned char* xs, int wid, int lane) const {
;     ...
; #pragma unroll
;             for (int ai = 0; ai < 2; ++ai)
; #pragma unroll
;                 for (int bj = 0; bj < 2; ++bj) {
;                     f32x4 v[4][2];
; #pragma unroll
;                     for (int m = 0; m < 4; ++m) { v[m][0] = acc[ai][bj][m][0] * rs[ai][m]; v[m][1] = acc[ai][bj][m][1] * rs[ai][m]; }
	v_pk_mul_f32 v[200:201], v[100:101], v[170:171] op_sel_hi:[1,0]
	v_pk_mul_f32 v[196:197], v[112:113], v[172:173] op_sel_hi:[1,0]
	v_pk_mul_f32 v[192:193], v[116:117], v[172:173] op_sel_hi:[1,0]
	v_pk_mul_f32 v[190:191], v[118:119], v[172:173] op_sel_hi:[1,0]
	v_cvt_pk_bf16_f32 v151, v192, v137
	ds_write_b16 v167, v151
	v_cvt_pk_bf16_f32 v151, v193, v137
	ds_write_b16 v167, v151 offset:128
	v_cvt_pk_bf16_f32 v151, v190, v137
	ds_write_b16 v167, v151 offset:256
	v_cvt_pk_bf16_f32 v151, v191, v137
	ds_write_b16 v167, v151 offset:384
	v_cvt_pk_bf16_f32 v151, v196, v137
	ds_write_b16 v167, v151 offset:512
	v_cvt_pk_bf16_f32 v151, v197, v137
	v_pk_mul_f32 v[194:195], v[114:115], v[172:173] op_sel_hi:[1,0]
	ds_write_b16 v167, v151 offset:640
	v_cvt_pk_bf16_f32 v151, v194, v137
	ds_write_b16 v167, v151 offset:768
	v_cvt_pk_bf16_f32 v151, v195, v137
	ds_write_b16 v167, v151 offset:896
	v_cvt_pk_bf16_f32 v151, v200, v137
	ds_write_b16 v169, v151
	v_cvt_pk_bf16_f32 v151, v201, v137
	v_pk_mul_f32 v[198:199], v[102:103], v[170:171] op_sel_hi:[1,0]
	ds_write_b16 v169, v151 offset:128
	v_cvt_pk_bf16_f32 v151, v198, v137
	ds_write_b16 v169, v151 offset:256
	v_cvt_pk_bf16_f32 v151, v199, v137
	v_pk_mul_f32 v[204:205], v[96:97], v[170:171] op_sel_hi:[1,0]
	ds_write_b16 v169, v151 offset:384
	v_cvt_pk_bf16_f32 v151, v204, v137
	ds_write_b16 v169, v151 offset:512
	v_cvt_pk_bf16_f32 v151, v205, v137
	v_pk_mul_f32 v[202:203], v[98:99], v[170:171] op_sel_hi:[1,0]
	ds_write_b16 v169, v151 offset:640
	v_cvt_pk_bf16_f32 v151, v202, v137
	ds_write_b16 v169, v151 offset:768
	v_cvt_pk_bf16_f32 v151, v203, v137
	v_pk_mul_f32 v[208:209], v[84:85], v[168:169] op_sel_hi:[1,0]
	ds_write_b16 v169, v151 offset:896
	v_cvt_pk_bf16_f32 v151, v208, v137
	ds_write_b16 v171, v151
	v_cvt_pk_bf16_f32 v151, v209, v137
	v_pk_mul_f32 v[206:207], v[86:87], v[168:169] op_sel_hi:[1,0]
	ds_write_b16 v171, v151 offset:128
	v_cvt_pk_bf16_f32 v151, v206, v137
	ds_write_b16 v171, v151 offset:256
	v_cvt_pk_bf16_f32 v151, v207, v137
	v_pk_mul_f32 v[212:213], v[80:81], v[168:169] op_sel_hi:[1,0]
	ds_write_b16 v171, v151 offset:384
	v_cvt_pk_bf16_f32 v151, v212, v137
	ds_write_b16 v171, v151 offset:512
	v_cvt_pk_bf16_f32 v151, v213, v137
	v_pk_mul_f32 v[210:211], v[82:83], v[168:169] op_sel_hi:[1,0]
	ds_write_b16 v171, v151 offset:640
	v_cvt_pk_bf16_f32 v151, v210, v137
	ds_write_b16 v171, v151 offset:768
	v_cvt_pk_bf16_f32 v151, v211, v137
	v_pk_mul_f32 v[216:217], v[68:69], v[166:167] op_sel_hi:[1,0]
	ds_write_b16 v171, v151 offset:896
	v_cvt_pk_bf16_f32 v151, v216, v137
	ds_write_b16 v173, v151
	v_cvt_pk_bf16_f32 v151, v217, v137
	v_pk_mul_f32 v[214:215], v[70:71], v[166:167] op_sel_hi:[1,0]
	ds_write_b16 v173, v151 offset:128
	v_cvt_pk_bf16_f32 v151, v214, v137
	ds_write_b16 v173, v151 offset:256
	v_cvt_pk_bf16_f32 v151, v215, v137
	v_pk_mul_f32 v[220:221], v[64:65], v[166:167] op_sel_hi:[1,0]
	ds_write_b16 v173, v151 offset:384
	v_cvt_pk_bf16_f32 v151, v220, v137
	ds_write_b16 v173, v151 offset:512
	v_cvt_pk_bf16_f32 v151, v221, v137
	v_pk_mul_f32 v[218:219], v[66:67], v[166:167] op_sel_hi:[1,0]
	ds_write_b16 v173, v151 offset:640
	v_cvt_pk_bf16_f32 v151, v218, v137
	ds_write_b16 v173, v151 offset:768
	v_cvt_pk_bf16_f32 v151, v219, v137
	ds_write_b16 v173, v151 offset:896
	s_waitcnt lgkmcnt(0)
	ds_read_b128 v[190:193], v184
	ds_read_b128 v[194:197], v185
	s_mov_b32 s45, s21
	v_lshl_add_u64 v[182:183], v[182:183], 0, s[44:45]
	v_lshl_add_u64 v[198:199], v[182:183], 0, v[142:143]
	s_waitcnt lgkmcnt(1)
	global_store_dwordx4 v[198:199], v[190:193], off nt
	ds_read_b128 v[190:193], v186
	ds_read_b128 v[198:201], v187
	v_lshl_add_u64 v[202:203], v[182:183], 0, v[144:145]
	s_waitcnt lgkmcnt(2)
	global_store_dwordx4 v[202:203], v[194:197], off nt
	v_pk_mul_f32 v[204:205], v[40:41], v[162:163] op_sel_hi:[1,0]
	v_pk_mul_f32 v[202:203], v[42:43], v[162:163] op_sel_hi:[1,0]
	v_lshl_add_u64 v[194:195], v[182:183], 0, v[146:147]
	s_waitcnt lgkmcnt(1)
	global_store_dwordx4 v[194:195], v[190:193], off nt
	v_pk_mul_f32 v[196:197], v[56:57], v[164:165] op_sel_hi:[1,0]
	v_pk_mul_f32 v[194:195], v[58:59], v[164:165] op_sel_hi:[1,0]
	v_lshl_add_u64 v[190:191], v[182:183], 0, v[148:149]
	s_waitcnt lgkmcnt(0)
	global_store_dwordx4 v[190:191], v[198:201], off nt
	v_pk_mul_f32 v[192:193], v[60:61], v[164:165] op_sel_hi:[1,0]
	s_waitcnt lgkmcnt(0)
; #define LAS __attribute__((address_space(3)))
; __device__ __forceinline__ unsigned cvt_pk_bf16(float lo, float hi) { unsigned r; asm("v_cvt_pk_bf16_f32 %0, %1, %2" : "=v"(r) : "v"(lo), "v"(hi)); return r; }
; __device__ __forceinline__ void tstore_sub(const f32x4 (&v)[4][2], bf16_t* dst  , LAS unsigned char* x, int fr, int fq, int lane) {
; #pragma unroll
;     for (int m = 0; m < 4; ++m)
; #pragma unroll
;         for (int n = 0; n < 2; ++n)
; #pragma unroll
;             for (int j = 0; j < 4; ++j) {
;                 const int ch = 8 * fq + 4 * n + j, tok = 16 * m + fr;
;                 const unsigned b = cvt_pk_bf16(v[m][n][j], 0.f);
;                 *(LAS unsigned short*)(x + ch * 128 + ((((tok >> 3) ^ fq) << 4) | ((tok & 7) << 1))) = (unsigned short)b;
;             }
;     LDS_WAIT();
; #pragma unroll
;     for (int i = 0; i < 4; ++i) {
;         const int q = lane + 64 * i, ch = q >> 3, tc = q & 7;
;         const u32x4 o = *(const LAS u32x4*)(x + ch * 128 + ((tc ^ ((ch >> 3) & 3)) << 4));
;         *(u32x4*)(dst + (size_t)ch * T + tc * 8) = o;
;     }
;     LDS_WAIT();
; }
;     __device__ __forceinline__ void operator()(const f32x4 (&acc)[2][2][4][2], const Unit& u, int wr, int wc, int fr, int fq, LAS unsigned char* xs, int wid, int lane) const {
;     ...
; #pragma unroll
;             for (int ai = 0; ai < 2; ++ai)
; #pragma unroll
;                 for (int bj = 0; bj < 2; ++bj) {
;                     f32x4 v[4][2];
; #pragma unroll
;                     for (int m = 0; m < 4; ++m) { v[m][0] = acc[ai][bj][m][0] * rs[ai][m]; v[m][1] = acc[ai][bj][m][1] * rs[ai][m]; }
;                     if (ODD) {
;                         float* vss = (float*)(ws + OFF_VSS);
; #pragma unroll
;                         for (int m = 0; m < 4; ++m) {
;                             float s = 0.f;
; #pragma unroll
;                             for (int n = 0; n < 2; ++n) s += (v[m][n][0] * v[m][n][0] + v[m][n][1] * v[m][n][1]) + (v[m][n][2] * v[m][n][2] + v[m][n][3] * v[m][n][3]);
;                             s += __shfl_xor(s, 16); s += __shfl_xor(s, 32);
;                             if (fq == 0) vss[(size_t)(row0 + ai * 128 + m * 16 + fr) * 32 + (2 * (pn - 24) + bj) * 4 + wc] = s;
;                         }
;                     }
;                     tstore_sub(v, base + (size_t)(bj * 128 + wc * 32) * T + row0 + ai * 128, x, fr, fq, lane);
	v_pk_mul_f32 v[190:191], v[62:63], v[164:165] op_sel_hi:[1,0]
	v_cvt_pk_bf16_f32 v151, v192, v137
	ds_write_b16 v167, v151
	v_cvt_pk_bf16_f32 v151, v193, v137
	ds_write_b16 v167, v151 offset:128
	v_cvt_pk_bf16_f32 v151, v190, v137
	ds_write_b16 v167, v151 offset:256
	v_cvt_pk_bf16_f32 v151, v191, v137
	ds_write_b16 v167, v151 offset:384
	v_cvt_pk_bf16_f32 v151, v196, v137
	ds_write_b16 v167, v151 offset:512
	v_cvt_pk_bf16_f32 v151, v197, v137
	ds_write_b16 v167, v151 offset:640
	v_cvt_pk_bf16_f32 v151, v194, v137
	ds_write_b16 v167, v151 offset:768
	v_cvt_pk_bf16_f32 v151, v195, v137
	v_pk_mul_f32 v[200:201], v[44:45], v[162:163] op_sel_hi:[1,0]
	ds_write_b16 v167, v151 offset:896
	v_cvt_pk_bf16_f32 v151, v200, v137
	ds_write_b16 v169, v151
	v_cvt_pk_bf16_f32 v151, v201, v137
	v_pk_mul_f32 v[198:199], v[46:47], v[162:163] op_sel_hi:[1,0]
	ds_write_b16 v169, v151 offset:128
	v_cvt_pk_bf16_f32 v151, v198, v137
	ds_write_b16 v169, v151 offset:256
	v_cvt_pk_bf16_f32 v151, v199, v137
	ds_write_b16 v169, v151 offset:384
	v_cvt_pk_bf16_f32 v151, v204, v137
	ds_write_b16 v169, v151 offset:512
	v_cvt_pk_bf16_f32 v151, v205, v137
	ds_write_b16 v169, v151 offset:640
	v_cvt_pk_bf16_f32 v151, v202, v137
	ds_write_b16 v169, v151 offset:768
	v_cvt_pk_bf16_f32 v151, v203, v137
	v_pk_mul_f32 v[208:209], v[28:29], v[160:161] op_sel_hi:[1,0]
	ds_write_b16 v169, v151 offset:896
	v_cvt_pk_bf16_f32 v151, v208, v137
	ds_write_b16 v171, v151
	v_cvt_pk_bf16_f32 v151, v209, v137
	v_pk_mul_f32 v[206:207], v[30:31], v[160:161] op_sel_hi:[1,0]
	ds_write_b16 v171, v151 offset:128
	v_cvt_pk_bf16_f32 v151, v206, v137
	ds_write_b16 v171, v151 offset:256
	v_cvt_pk_bf16_f32 v151, v207, v137
	v_pk_mul_f32 v[212:213], v[24:25], v[160:161] op_sel_hi:[1,0]
	ds_write_b16 v171, v151 offset:384
	v_cvt_pk_bf16_f32 v151, v212, v137
	ds_write_b16 v171, v151 offset:512
	v_cvt_pk_bf16_f32 v151, v213, v137
	v_pk_mul_f32 v[210:211], v[26:27], v[160:161] op_sel_hi:[1,0]
	ds_write_b16 v171, v151 offset:640
	v_cvt_pk_bf16_f32 v151, v210, v137
	ds_write_b16 v171, v151 offset:768
	v_cvt_pk_bf16_f32 v151, v211, v137
	v_pk_mul_f32 v[216:217], v[12:13], v[158:159] op_sel_hi:[1,0]
	ds_write_b16 v171, v151 offset:896
	v_cvt_pk_bf16_f32 v151, v216, v137
	ds_write_b16 v173, v151
	v_cvt_pk_bf16_f32 v151, v217, v137
	v_pk_mul_f32 v[214:215], v[14:15], v[158:159] op_sel_hi:[1,0]
	ds_write_b16 v173, v151 offset:128
	v_cvt_pk_bf16_f32 v151, v214, v137
	ds_write_b16 v173, v151 offset:256
	v_cvt_pk_bf16_f32 v151, v215, v137
	v_pk_mul_f32 v[220:221], v[8:9], v[158:159] op_sel_hi:[1,0]
	ds_write_b16 v173, v151 offset:384
	v_cvt_pk_bf16_f32 v151, v220, v137
	ds_write_b16 v173, v151 offset:512
	v_cvt_pk_bf16_f32 v151, v221, v137
	v_pk_mul_f32 v[218:219], v[10:11], v[158:159] op_sel_hi:[1,0]
	ds_write_b16 v173, v151 offset:640
	v_cvt_pk_bf16_f32 v151, v218, v137
	ds_write_b16 v173, v151 offset:768
	v_cvt_pk_bf16_f32 v151, v219, v137
	ds_write_b16 v173, v151 offset:896
	s_waitcnt lgkmcnt(0)
	ds_read_b128 v[190:193], v184
	ds_read_b128 v[194:197], v185
	ds_read_b128 v[198:201], v186
	ds_read_b128 v[202:205], v187
	s_waitcnt lgkmcnt(3)
	global_store_dwordx4 v[174:175], v[190:193], off offset:256 nt
	s_waitcnt lgkmcnt(2)
	global_store_dwordx4 v[176:177], v[194:197], off offset:256 nt
	s_waitcnt lgkmcnt(1)
	global_store_dwordx4 v[178:179], v[198:201], off offset:256 nt
	s_waitcnt lgkmcnt(0)
	global_store_dwordx4 v[180:181], v[202:205], off offset:256 nt
	v_pk_mul_f32 v[176:177], v[52:53], v[164:165] op_sel_hi:[1,0]
	s_waitcnt lgkmcnt(0)
	v_pk_mul_f32 v[174:175], v[54:55], v[164:165] op_sel_hi:[1,0]
	v_cvt_pk_bf16_f32 v151, v176, v137
	ds_write_b16 v167, v151
	v_cvt_pk_bf16_f32 v151, v177, v137
	ds_write_b16 v167, v151 offset:128
	v_cvt_pk_bf16_f32 v151, v174, v137
	ds_write_b16 v167, v151 offset:256
	v_cvt_pk_bf16_f32 v151, v175, v137
	v_pk_mul_f32 v[180:181], v[48:49], v[164:165] op_sel_hi:[1,0]
	ds_write_b16 v167, v151 offset:384
	v_cvt_pk_bf16_f32 v151, v180, v137
	ds_write_b16 v167, v151 offset:512
	v_cvt_pk_bf16_f32 v151, v181, v137
	v_pk_mul_f32 v[178:179], v[50:51], v[164:165] op_sel_hi:[1,0]
	ds_write_b16 v167, v151 offset:640
	v_cvt_pk_bf16_f32 v151, v178, v137
	ds_write_b16 v167, v151 offset:768
	v_cvt_pk_bf16_f32 v151, v179, v137
	v_pk_mul_f32 v[192:193], v[36:37], v[162:163] op_sel_hi:[1,0]
	ds_write_b16 v167, v151 offset:896
	v_cvt_pk_bf16_f32 v151, v192, v137
	ds_write_b16 v169, v151
	v_cvt_pk_bf16_f32 v151, v193, v137
	v_pk_mul_f32 v[190:191], v[38:39], v[162:163] op_sel_hi:[1,0]
	ds_write_b16 v169, v151 offset:128
	v_cvt_pk_bf16_f32 v151, v190, v137
	ds_write_b16 v169, v151 offset:256
	v_cvt_pk_bf16_f32 v151, v191, v137
	v_pk_mul_f32 v[196:197], v[32:33], v[162:163] op_sel_hi:[1,0]
	ds_write_b16 v169, v151 offset:384
	v_cvt_pk_bf16_f32 v151, v196, v137
	ds_write_b16 v169, v151 offset:512
	v_cvt_pk_bf16_f32 v151, v197, v137
	v_pk_mul_f32 v[194:195], v[34:35], v[162:163] op_sel_hi:[1,0]
	ds_write_b16 v169, v151 offset:640
	v_cvt_pk_bf16_f32 v151, v194, v137
	ds_write_b16 v169, v151 offset:768
	v_cvt_pk_bf16_f32 v151, v195, v137
	v_pk_mul_f32 v[200:201], v[20:21], v[160:161] op_sel_hi:[1,0]
	ds_write_b16 v169, v151 offset:896
	v_cvt_pk_bf16_f32 v151, v200, v137
	ds_write_b16 v171, v151
	v_cvt_pk_bf16_f32 v151, v201, v137
	v_pk_mul_f32 v[198:199], v[22:23], v[160:161] op_sel_hi:[1,0]
	ds_write_b16 v171, v151 offset:128
	v_cvt_pk_bf16_f32 v151, v198, v137
	ds_write_b16 v171, v151 offset:256
	v_cvt_pk_bf16_f32 v151, v199, v137
	v_pk_mul_f32 v[204:205], v[16:17], v[160:161] op_sel_hi:[1,0]
	ds_write_b16 v171, v151 offset:384
	v_cvt_pk_bf16_f32 v151, v204, v137
	ds_write_b16 v171, v151 offset:512
	v_cvt_pk_bf16_f32 v151, v205, v137
	v_pk_mul_f32 v[202:203], v[18:19], v[160:161] op_sel_hi:[1,0]
	ds_write_b16 v171, v151 offset:640
	v_cvt_pk_bf16_f32 v151, v202, v137
	ds_write_b16 v171, v151 offset:768
	v_cvt_pk_bf16_f32 v151, v203, v137
	v_pk_mul_f32 v[208:209], v[4:5], v[158:159] op_sel_hi:[1,0]
	ds_write_b16 v171, v151 offset:896
	v_cvt_pk_bf16_f32 v151, v208, v137
	ds_write_b16 v173, v151
	v_cvt_pk_bf16_f32 v151, v209, v137
	v_pk_mul_f32 v[206:207], v[6:7], v[158:159] op_sel_hi:[1,0]
	ds_write_b16 v173, v151 offset:128
	v_cvt_pk_bf16_f32 v151, v206, v137
	ds_write_b16 v173, v151 offset:256
	v_cvt_pk_bf16_f32 v151, v207, v137
	v_pk_mul_f32 v[212:213], v[0:1], v[158:159] op_sel_hi:[1,0]
	ds_write_b16 v173, v151 offset:384
	v_cvt_pk_bf16_f32 v151, v212, v137
	ds_write_b16 v173, v151 offset:512
	v_cvt_pk_bf16_f32 v151, v213, v137
	v_pk_mul_f32 v[210:211], v[2:3], v[158:159] op_sel_hi:[1,0]
	ds_write_b16 v173, v151 offset:640
	v_cvt_pk_bf16_f32 v151, v210, v137
	ds_write_b16 v173, v151 offset:768
	v_cvt_pk_bf16_f32 v151, v211, v137
	ds_write_b16 v173, v151 offset:896
	s_waitcnt lgkmcnt(0)
; #define LAS __attribute__((address_space(3)))
; __device__ __forceinline__ unsigned cvt_pk_bf16(float lo, float hi) { unsigned r; asm("v_cvt_pk_bf16_f32 %0, %1, %2" : "=v"(r) : "v"(lo), "v"(hi)); return r; }
; #define LDS_WAIT() asm volatile("s_waitcnt lgkmcnt(0)" ::: "memory")
; __device__ __forceinline__ void tstore_sub(const f32x4 (&v)[4][2], bf16_t* dst  , LAS unsigned char* x, int fr, int fq, int lane) {
; #pragma unroll
;     for (int m = 0; m < 4; ++m)
; #pragma unroll
;         for (int n = 0; n < 2; ++n)
; #pragma unroll
;             for (int j = 0; j < 4; ++j) {
;                 const int ch = 8 * fq + 4 * n + j, tok = 16 * m + fr;
;                 const unsigned b = cvt_pk_bf16(v[m][n][j], 0.f);
;                 *(LAS unsigned short*)(x + ch * 128 + ((((tok >> 3) ^ fq) << 4) | ((tok & 7) << 1))) = (unsigned short)b;
;             }
;     LDS_WAIT();
; #pragma unroll
;     for (int i = 0; i < 4; ++i) {
;         const int q = lane + 64 * i, ch = q >> 3, tc = q & 7;
;         const u32x4 o = *(const LAS u32x4*)(x + ch * 128 + ((tc ^ ((ch >> 3) & 3)) << 4));
;         *(u32x4*)(dst + (size_t)ch * T + tc * 8) = o;
;     }
;     LDS_WAIT();
; }
;     __device__ __forceinline__ void operator()(const f32x4 (&acc)[2][2][4][2], const Unit& u, int wr, int wc, int fr, int fq, LAS unsigned char* xs, int wid, int lane) const {
;     ...
;         if (mode == 0) {
; #pragma unroll
;             for (int ai = 0; ai < 2; ++ai)
; #pragma unroll
;                 for (int m = 0; m < 4; ++m) {
;                     const float r = rs[ai][m];
;                     bf16_t* rowp = base + (size_t)(row0 + ai * 128 + m * 16 + fr) * ldc + wc * 32 + 8 * fq;
; #pragma unroll
;                     for (int bj = 0; bj < 2; ++bj) { const f32x4 v0 = acc[ai][bj][m][0] * r, v1 = acc[ai][bj][m][1] * r;
;                         u32x4 w; w.x = cvt_pk_bf16(v0[0], v0[1]); w.y = cvt_pk_bf16(v0[2], v0[3]); w.z = cvt_pk_bf16(v1[0], v1[1]); w.w = cvt_pk_bf16(v1[2], v1[3]);
;                         *(u32x4*)(rowp + bj * 128) = w; }
;                     __builtin_amdgcn_sched_barrier(0);
;                 }
	ds_read_b128 v[174:177], v184
	ds_read_b128 v[178:181], v185
	v_lshl_add_u64 v[182:183], v[182:183], 0, s[26:27]
	v_lshl_add_u64 v[190:191], v[182:183], 0, v[142:143]
	v_lshl_add_u64 v[194:195], v[182:183], 0, v[144:145]
	s_waitcnt lgkmcnt(1)
	global_store_dwordx4 v[190:191], v[174:177], off nt
	ds_read_b128 v[174:177], v186
	ds_read_b128 v[190:193], v187
	s_waitcnt lgkmcnt(2)
	global_store_dwordx4 v[194:195], v[178:181], off nt
	s_nop 1
	v_lshl_add_u64 v[178:179], v[182:183], 0, v[146:147]
	s_waitcnt lgkmcnt(1)
	global_store_dwordx4 v[178:179], v[174:177], off nt
	s_nop 1
	v_lshl_add_u64 v[174:175], v[182:183], 0, v[148:149]
	s_waitcnt lgkmcnt(0)
	global_store_dwordx4 v[174:175], v[190:193], off nt
	s_waitcnt lgkmcnt(0)
	s_cbranch_execnz .LBB0_216
.LBB0_231:
	s_add_u32 s18, s56, s71
	v_or_b32_e32 v143, s54, v157
	s_addc_u32 s19, s57, 0
	v_mov_b32_e32 v151, v137
	s_ashr_i32 s0, s54, 31
	v_lshl_add_u64 v[174:175], s[18:19], 0, v[150:151]
	v_mul_lo_u32 v145, s7, v143
	s_mul_i32 s0, s6, s0
	v_mad_u64_u32 v[176:177], s[18:19], s6, v143, 0
	v_add3_u32 v177, v177, s0, v145
	v_lshl_add_u64 v[176:177], v[176:177], 1, v[174:175]
	s_waitcnt lgkmcnt(7)
	v_pk_mul_f32 v[126:127], v[126:127], v[172:173] op_sel_hi:[1,0]
	v_pk_mul_f32 v[124:125], v[124:125], v[172:173] op_sel_hi:[1,0]
	v_pk_mul_f32 v[178:179], v[122:123], v[172:173] op_sel_hi:[1,0]
	v_pk_mul_f32 v[122:123], v[120:121], v[172:173] op_sel_hi:[1,0]
	v_cvt_pk_bf16_f32 v120, v124, v125
	v_cvt_pk_bf16_f32 v121, v126, v127
	v_pk_mul_f32 v[118:119], v[118:119], v[172:173] op_sel_hi:[1,0]
	v_cvt_pk_bf16_f32 v122, v122, v123
	v_cvt_pk_bf16_f32 v123, v178, v179
	global_store_dwordx4 v[176:177], v[120:123], off nt
	v_pk_mul_f32 v[116:117], v[116:117], v[172:173] op_sel_hi:[1,0]
	s_nop 0
	v_pk_mul_f32 v[120:121], v[114:115], v[172:173] op_sel_hi:[1,0]
	v_pk_mul_f32 v[114:115], v[112:113], v[172:173] op_sel_hi:[1,0]
	v_cvt_pk_bf16_f32 v112, v116, v117
	v_cvt_pk_bf16_f32 v113, v118, v119
	s_nop 0
	v_cvt_pk_bf16_f32 v114, v114, v115
	v_cvt_pk_bf16_f32 v115, v120, v121
	global_store_dwordx4 v[176:177], v[112:115], off offset:256 nt
	s_nop 1
	v_or_b32_e32 v112, 16, v143
	v_mul_lo_u32 v114, s7, v112
	v_mad_u64_u32 v[112:113], s[18:19], s6, v112, 0
	v_add3_u32 v113, v113, s0, v114
	v_lshl_add_u64 v[112:113], v[112:113], 1, v[174:175]
	s_waitcnt lgkmcnt(6)
	v_pk_mul_f32 v[110:111], v[110:111], v[170:171] op_sel_hi:[1,0]
	v_pk_mul_f32 v[108:109], v[108:109], v[170:171] op_sel_hi:[1,0]
	v_pk_mul_f32 v[114:115], v[106:107], v[170:171] op_sel_hi:[1,0]
	v_pk_mul_f32 v[106:107], v[104:105], v[170:171] op_sel_hi:[1,0]
	v_cvt_pk_bf16_f32 v104, v108, v109
	v_cvt_pk_bf16_f32 v105, v110, v111
	v_pk_mul_f32 v[102:103], v[102:103], v[170:171] op_sel_hi:[1,0]
	v_cvt_pk_bf16_f32 v106, v106, v107
	v_cvt_pk_bf16_f32 v107, v114, v115
	global_store_dwordx4 v[112:113], v[104:107], off nt
	v_pk_mul_f32 v[100:101], v[100:101], v[170:171] op_sel_hi:[1,0]
	s_nop 0
	v_pk_mul_f32 v[104:105], v[98:99], v[170:171] op_sel_hi:[1,0]
	v_pk_mul_f32 v[98:99], v[96:97], v[170:171] op_sel_hi:[1,0]
	v_cvt_pk_bf16_f32 v96, v100, v101
	v_cvt_pk_bf16_f32 v97, v102, v103
	s_nop 0
	v_cvt_pk_bf16_f32 v98, v98, v99
	v_cvt_pk_bf16_f32 v99, v104, v105
	global_store_dwordx4 v[112:113], v[96:99], off offset:256 nt
	s_nop 1
	v_or_b32_e32 v96, 32, v143
	v_mul_lo_u32 v98, s7, v96
	v_mad_u64_u32 v[96:97], s[18:19], s6, v96, 0
	v_add3_u32 v97, v97, s0, v98
	v_lshl_add_u64 v[96:97], v[96:97], 1, v[174:175]
	s_waitcnt lgkmcnt(5)
	v_pk_mul_f32 v[94:95], v[94:95], v[168:169] op_sel_hi:[1,0]
	v_pk_mul_f32 v[92:93], v[92:93], v[168:169] op_sel_hi:[1,0]
	v_pk_mul_f32 v[98:99], v[90:91], v[168:169] op_sel_hi:[1,0]
	v_pk_mul_f32 v[90:91], v[88:89], v[168:169] op_sel_hi:[1,0]
	v_cvt_pk_bf16_f32 v88, v92, v93
	v_cvt_pk_bf16_f32 v89, v94, v95
	v_pk_mul_f32 v[86:87], v[86:87], v[168:169] op_sel_hi:[1,0]
	v_cvt_pk_bf16_f32 v90, v90, v91
	v_cvt_pk_bf16_f32 v91, v98, v99
	global_store_dwordx4 v[96:97], v[88:91], off nt
	v_pk_mul_f32 v[84:85], v[84:85], v[168:169] op_sel_hi:[1,0]
	s_nop 0
	v_pk_mul_f32 v[88:89], v[82:83], v[168:169] op_sel_hi:[1,0]
	v_pk_mul_f32 v[82:83], v[80:81], v[168:169] op_sel_hi:[1,0]
	v_cvt_pk_bf16_f32 v80, v84, v85
	v_cvt_pk_bf16_f32 v81, v86, v87
	s_nop 0
	v_cvt_pk_bf16_f32 v82, v82, v83
	v_cvt_pk_bf16_f32 v83, v88, v89
	global_store_dwordx4 v[96:97], v[80:83], off offset:256 nt
	s_nop 1
	v_or_b32_e32 v80, 48, v143
	v_mul_lo_u32 v82, s7, v80
	v_mad_u64_u32 v[80:81], s[18:19], s6, v80, 0
	v_add3_u32 v81, v81, s0, v82
	v_lshl_add_u64 v[80:81], v[80:81], 1, v[174:175]
	s_waitcnt lgkmcnt(4)
; __device__ __forceinline__ unsigned cvt_pk_bf16(float lo, float hi) { unsigned r; asm("v_cvt_pk_bf16_f32 %0, %1, %2" : "=v"(r) : "v"(lo), "v"(hi)); return r; }
;     __device__ __forceinline__ void operator()(const f32x4 (&acc)[2][2][4][2], const Unit& u, int wr, int wc, int fr, int fq, LAS unsigned char* xs, int wid, int lane) const {
;     ...
;         if (mode == 0) {
; #pragma unroll
;             for (int ai = 0; ai < 2; ++ai)
; #pragma unroll
;                 for (int m = 0; m < 4; ++m) {
;                     const float r = rs[ai][m];
;                     bf16_t* rowp = base + (size_t)(row0 + ai * 128 + m * 16 + fr) * ldc + wc * 32 + 8 * fq;
; #pragma unroll
;                     for (int bj = 0; bj < 2; ++bj) { const f32x4 v0 = acc[ai][bj][m][0] * r, v1 = acc[ai][bj][m][1] * r;
;                         u32x4 w; w.x = cvt_pk_bf16(v0[0], v0[1]); w.y = cvt_pk_bf16(v0[2], v0[3]); w.z = cvt_pk_bf16(v1[0], v1[1]); w.w = cvt_pk_bf16(v1[2], v1[3]);
;                         *(u32x4*)(rowp + bj * 128) = w; }
;                     __builtin_amdgcn_sched_barrier(0);
;                 }
	v_pk_mul_f32 v[78:79], v[78:79], v[166:167] op_sel_hi:[1,0]
	v_pk_mul_f32 v[76:77], v[76:77], v[166:167] op_sel_hi:[1,0]
	v_pk_mul_f32 v[82:83], v[74:75], v[166:167] op_sel_hi:[1,0]
	v_pk_mul_f32 v[74:75], v[72:73], v[166:167] op_sel_hi:[1,0]
	v_cvt_pk_bf16_f32 v72, v76, v77
	v_cvt_pk_bf16_f32 v73, v78, v79
	v_pk_mul_f32 v[70:71], v[70:71], v[166:167] op_sel_hi:[1,0]
	v_cvt_pk_bf16_f32 v74, v74, v75
	v_cvt_pk_bf16_f32 v75, v82, v83
	global_store_dwordx4 v[80:81], v[72:75], off nt
	v_pk_mul_f32 v[68:69], v[68:69], v[166:167] op_sel_hi:[1,0]
	s_nop 0
	v_pk_mul_f32 v[72:73], v[66:67], v[166:167] op_sel_hi:[1,0]
	v_pk_mul_f32 v[66:67], v[64:65], v[166:167] op_sel_hi:[1,0]
	v_cvt_pk_bf16_f32 v64, v68, v69
	v_cvt_pk_bf16_f32 v65, v70, v71
	s_nop 0
	v_cvt_pk_bf16_f32 v66, v66, v67
	v_cvt_pk_bf16_f32 v67, v72, v73
	global_store_dwordx4 v[80:81], v[64:67], off offset:256 nt
	s_nop 1
	v_add_u32_e32 v64, 0x80, v143
	v_ashrrev_i32_e32 v65, 31, v64
	v_mul_lo_u32 v66, s6, v65
	v_mul_lo_u32 v67, s7, v64
	v_mad_u64_u32 v[64:65], s[18:19], s6, v64, 0
	v_add3_u32 v65, v65, v66, v67
	v_lshl_add_u64 v[64:65], v[64:65], 1, v[174:175]
	s_waitcnt lgkmcnt(3)
	v_pk_mul_f32 v[62:63], v[62:63], v[164:165] op_sel_hi:[1,0]
	v_pk_mul_f32 v[60:61], v[60:61], v[164:165] op_sel_hi:[1,0]
	v_pk_mul_f32 v[66:67], v[58:59], v[164:165] op_sel_hi:[1,0]
	v_pk_mul_f32 v[58:59], v[56:57], v[164:165] op_sel_hi:[1,0]
	v_cvt_pk_bf16_f32 v56, v60, v61
	v_cvt_pk_bf16_f32 v57, v62, v63
	v_pk_mul_f32 v[54:55], v[54:55], v[164:165] op_sel_hi:[1,0]
	v_cvt_pk_bf16_f32 v58, v58, v59
	v_cvt_pk_bf16_f32 v59, v66, v67
	global_store_dwordx4 v[64:65], v[56:59], off nt
	v_pk_mul_f32 v[52:53], v[52:53], v[164:165] op_sel_hi:[1,0]
	s_nop 0
	v_pk_mul_f32 v[56:57], v[50:51], v[164:165] op_sel_hi:[1,0]
	v_pk_mul_f32 v[50:51], v[48:49], v[164:165] op_sel_hi:[1,0]
	v_cvt_pk_bf16_f32 v48, v52, v53
	v_cvt_pk_bf16_f32 v49, v54, v55
	s_nop 0
	v_cvt_pk_bf16_f32 v50, v50, v51
	v_cvt_pk_bf16_f32 v51, v56, v57
	global_store_dwordx4 v[64:65], v[48:51], off offset:256 nt
	s_nop 1
	v_add_u32_e32 v48, 0x90, v143
	v_ashrrev_i32_e32 v49, 31, v48
	v_mul_lo_u32 v50, s6, v49
	v_mul_lo_u32 v51, s7, v48
	v_mad_u64_u32 v[48:49], s[18:19], s6, v48, 0
	v_add3_u32 v49, v49, v50, v51
	v_lshl_add_u64 v[48:49], v[48:49], 1, v[174:175]
	s_waitcnt lgkmcnt(2)
	v_pk_mul_f32 v[46:47], v[46:47], v[162:163] op_sel_hi:[1,0]
	v_pk_mul_f32 v[44:45], v[44:45], v[162:163] op_sel_hi:[1,0]
	v_pk_mul_f32 v[50:51], v[42:43], v[162:163] op_sel_hi:[1,0]
	v_pk_mul_f32 v[42:43], v[40:41], v[162:163] op_sel_hi:[1,0]
	v_cvt_pk_bf16_f32 v40, v44, v45
	v_cvt_pk_bf16_f32 v41, v46, v47
	v_pk_mul_f32 v[38:39], v[38:39], v[162:163] op_sel_hi:[1,0]
	v_cvt_pk_bf16_f32 v42, v42, v43
	v_cvt_pk_bf16_f32 v43, v50, v51
	global_store_dwordx4 v[48:49], v[40:43], off nt
	v_pk_mul_f32 v[36:37], v[36:37], v[162:163] op_sel_hi:[1,0]
	s_nop 0
	v_pk_mul_f32 v[40:41], v[34:35], v[162:163] op_sel_hi:[1,0]
	v_pk_mul_f32 v[34:35], v[32:33], v[162:163] op_sel_hi:[1,0]
	v_cvt_pk_bf16_f32 v32, v36, v37
	v_cvt_pk_bf16_f32 v33, v38, v39
	s_nop 0
	v_cvt_pk_bf16_f32 v34, v34, v35
	v_cvt_pk_bf16_f32 v35, v40, v41
	global_store_dwordx4 v[48:49], v[32:35], off offset:256 nt
	s_nop 1
	v_add_u32_e32 v32, 0xa0, v143
	v_ashrrev_i32_e32 v33, 31, v32
	v_mul_lo_u32 v34, s6, v33
	v_mul_lo_u32 v35, s7, v32
	v_mad_u64_u32 v[32:33], s[18:19], s6, v32, 0
	v_add3_u32 v33, v33, v34, v35
	v_lshl_add_u64 v[32:33], v[32:33], 1, v[174:175]
	s_waitcnt lgkmcnt(1)
	v_pk_mul_f32 v[30:31], v[30:31], v[160:161] op_sel_hi:[1,0]
	v_pk_mul_f32 v[28:29], v[28:29], v[160:161] op_sel_hi:[1,0]
	v_pk_mul_f32 v[34:35], v[26:27], v[160:161] op_sel_hi:[1,0]
	v_pk_mul_f32 v[26:27], v[24:25], v[160:161] op_sel_hi:[1,0]
	v_cvt_pk_bf16_f32 v24, v28, v29
	v_cvt_pk_bf16_f32 v25, v30, v31
	v_pk_mul_f32 v[22:23], v[22:23], v[160:161] op_sel_hi:[1,0]
	v_cvt_pk_bf16_f32 v26, v26, v27
	v_cvt_pk_bf16_f32 v27, v34, v35
	global_store_dwordx4 v[32:33], v[24:27], off nt
	v_pk_mul_f32 v[20:21], v[20:21], v[160:161] op_sel_hi:[1,0]
	s_nop 0
	v_pk_mul_f32 v[24:25], v[18:19], v[160:161] op_sel_hi:[1,0]
	v_pk_mul_f32 v[18:19], v[16:17], v[160:161] op_sel_hi:[1,0]
	v_cvt_pk_bf16_f32 v16, v20, v21
	v_cvt_pk_bf16_f32 v17, v22, v23
	s_nop 0
	v_cvt_pk_bf16_f32 v18, v18, v19
	v_cvt_pk_bf16_f32 v19, v24, v25
	global_store_dwordx4 v[32:33], v[16:19], off offset:256 nt
	s_nop 1
	v_add_u32_e32 v16, 0xb0, v143
	v_ashrrev_i32_e32 v17, 31, v16
	v_mul_lo_u32 v18, s6, v17
	v_mul_lo_u32 v19, s7, v16
	v_mad_u64_u32 v[16:17], s[6:7], s6, v16, 0
	v_add3_u32 v17, v17, v18, v19
	v_lshl_add_u64 v[16:17], v[16:17], 1, v[174:175]
	s_waitcnt lgkmcnt(0)
	v_pk_mul_f32 v[14:15], v[14:15], v[158:159] op_sel_hi:[1,0]
	v_pk_mul_f32 v[12:13], v[12:13], v[158:159] op_sel_hi:[1,0]
	v_pk_mul_f32 v[18:19], v[10:11], v[158:159] op_sel_hi:[1,0]
	v_pk_mul_f32 v[10:11], v[8:9], v[158:159] op_sel_hi:[1,0]
	v_cvt_pk_bf16_f32 v8, v12, v13
	v_cvt_pk_bf16_f32 v9, v14, v15
	v_pk_mul_f32 v[6:7], v[6:7], v[158:159] op_sel_hi:[1,0]
	v_cvt_pk_bf16_f32 v10, v10, v11
	v_cvt_pk_bf16_f32 v11, v18, v19
	global_store_dwordx4 v[16:17], v[8:11], off nt
	v_pk_mul_f32 v[4:5], v[4:5], v[158:159] op_sel_hi:[1,0]
	s_nop 0
	v_pk_mul_f32 v[8:9], v[2:3], v[158:159] op_sel_hi:[1,0]
	v_pk_mul_f32 v[2:3], v[0:1], v[158:159] op_sel_hi:[1,0]
	v_cvt_pk_bf16_f32 v0, v4, v5
	v_cvt_pk_bf16_f32 v1, v6, v7
	s_nop 0
	v_cvt_pk_bf16_f32 v2, v2, v3
	v_cvt_pk_bf16_f32 v3, v8, v9
	global_store_dwordx4 v[16:17], v[0:3], off offset:256 nt
	s_andn2_b64 vcc, exec, s[4:5]
	s_mov_b64 s[4:5], -1
	s_cbranch_vccnz .LBB0_205

; __device__ __forceinline__ unsigned cvt_pk_bf16(float lo, float hi) { unsigned r; asm("v_cvt_pk_bf16_f32 %0, %1, %2" : "=v"(r) : "v"(lo), "v"(hi)); return r; }
;     __device__ __forceinline__ void operator()(const f32x4 (&acc)[2][2][4][2], const Unit& u, int wr, int wc, int fr, int fq, LAS unsigned char* xs, int wid, int lane) const {
;         const int S = lng ? 4096 : 2048, hp = lng ? 8 : 4;
;         const int cs = u.pm >= hp, k0 = (u.pm - hp * cs) * 256 + wr * 64;
;         const size_t tok0 = lng ? (size_t)TP + (size_t)u.aux * 4096 : (size_t)u.aux * 2048;
;         const float sc = lng ? 0.015625f : 0.02209708691207961f;
;         const float scm = cs ? -sc : sc;
;         float hv[2][8];
;         const float csm = cs ? 0.f : 1.f;
; #pragma unroll
;         for (int bj = 0; bj < 2; ++bj)
; #pragma unroll
;             for (int e = 0; e < 8; ++e) {
;                 const unsigned short h = ft[(size_t)(u.pn * 256 + bj * 128 + wc * 32 + 8 * fq + e) * T + tok0 + S / 2];
;                 const float v = __builtin_bit_cast(float, (unsigned)h << 16) * csm;
;                 hv[bj][e] = (fr & 1) ? -v : v;
;             }
; #pragma unroll
;         for (int ai = 0; ai < 2; ++ai)
; #pragma unroll
;             for (int m = 0; m < 4; ++m) {
;                 const int k = k0 + ai * 128 + m * 16 + fr;
; #pragma unroll
;                 for (int bj = 0; bj < 2; ++bj) {
;                     const int col = (2 * u.pn + bj) * 256 + cs * 128 + wc * 32 + 8 * fq;
;                     f32x4 a = acc[ai][bj][m][0], b = acc[ai][bj][m][1];
; #pragma unroll
;                     for (int j = 0; j < 4; ++j) { a[j] += hv[bj][j]; b[j] += hv[bj][4 + j]; }
;                     u32x4 w; w.x = cvt_pk_bf16(a[0] * sc, a[1] * sc); w.y = cvt_pk_bf16(a[2] * sc, a[3] * sc); w.z = cvt_pk_bf16(b[0] * sc, b[1] * sc); w.w = cvt_pk_bf16(b[2] * sc, b[3] * sc);
;                     *(u32x4*)(pq + (tok0 + k) * 1024 + col) = w;
;                     if (k > 0) {
;                         u32x4 w2; w2.x = cvt_pk_bf16(a[0] * scm, a[1] * scm); w2.y = cvt_pk_bf16(a[2] * scm, a[3] * scm); w2.z = cvt_pk_bf16(b[0] * scm, b[1] * scm); w2.w = cvt_pk_bf16(b[2] * scm, b[3] * scm);
;                         *(u32x4*)(pq + (tok0 + S - k) * 1024 + col) = w2;
.LBB0_430:
	s_lshl_b32 s8, s19, 8
	s_and_b32 s62, s8, 0x700
	s_ashr_i32 s59, s58, 31
	s_add_i32 s62, s62, s34
	s_lshl_b64 s[8:9], s[58:59], 12
	s_add_u32 s58, s8, 0x4000
	s_addc_u32 s59, s9, 0
	s_lshl_b64 s[60:61], s[58:59], 1
	s_add_u32 s60, s44, s60
	v_lshlrev_b32_e32 v136, 16, v150
	s_addc_u32 s61, s45, s61
	v_lshl_or_b32 v136, s18, 24, v136
	v_lshl_add_u64 v[146:147], s[60:61], 0, v[136:137]
	s_movk_i32 s55, 0x1000
	v_add_co_u32_e32 v156, vcc, s55, v146
	s_mov_b32 s55, 0x11000
	s_nop 0
	v_addc_co_u32_e32 v157, vcc, 0, v147, vcc
	global_load_ushort v136, v[156:157], off
	v_add_co_u32_e32 v156, vcc, s55, v146
	s_mov_b32 s55, 0x21000
	s_nop 0
	v_addc_co_u32_e32 v157, vcc, 0, v147, vcc
	global_load_ushort v158, v[156:157], off
	v_add_co_u32_e32 v156, vcc, s55, v146
	s_mov_b32 s55, 0x31000
	s_nop 0
	v_addc_co_u32_e32 v157, vcc, 0, v147, vcc
	global_load_ushort v159, v[156:157], off
	v_add_co_u32_e32 v156, vcc, s55, v146
	s_mov_b32 s55, 0x41000
	s_nop 0
	v_addc_co_u32_e32 v157, vcc, 0, v147, vcc
	global_load_ushort v160, v[156:157], off
	v_add_co_u32_e32 v156, vcc, s55, v146
	s_mov_b32 s55, 0x51000
	s_nop 0
	v_addc_co_u32_e32 v157, vcc, 0, v147, vcc
	global_load_ushort v161, v[156:157], off
	v_add_co_u32_e32 v156, vcc, s55, v146
	s_mov_b32 s55, 0x61000
	s_nop 0
	v_addc_co_u32_e32 v157, vcc, 0, v147, vcc
	global_load_ushort v162, v[156:157], off
	v_add_co_u32_e32 v156, vcc, s55, v146
	s_mov_b32 s55, 0x71000
	s_nop 0
	v_addc_co_u32_e32 v157, vcc, 0, v147, vcc
	global_load_ushort v163, v[156:157], off
	v_add_co_u32_e32 v156, vcc, s55, v146
	s_mov_b32 s55, 0x801000
	s_nop 0
	v_addc_co_u32_e32 v157, vcc, 0, v147, vcc
	global_load_ushort v164, v[156:157], off
	v_add_co_u32_e32 v156, vcc, s55, v146
	s_cmp_lt_u32 s19, 8
	s_nop 0
	v_addc_co_u32_e32 v157, vcc, 0, v147, vcc
	global_load_ushort v165, v[156:157], off
	v_add_co_u32_e32 v156, vcc, s65, v146
	s_waitcnt vmcnt(0)
	v_lshlrev_b32_e32 v136, 16, v136
	v_addc_co_u32_e32 v157, vcc, 0, v147, vcc
	global_load_ushort v166, v[156:157], off
	v_add_co_u32_e32 v156, vcc, s66, v146
	s_nop 1
	v_addc_co_u32_e32 v157, vcc, 0, v147, vcc
	global_load_ushort v167, v[156:157], off
	v_add_co_u32_e32 v156, vcc, s67, v146
	s_nop 1
	v_addc_co_u32_e32 v157, vcc, 0, v147, vcc
	global_load_ushort v168, v[156:157], off
	v_add_co_u32_e32 v156, vcc, s68, v146
	s_nop 1
	v_addc_co_u32_e32 v157, vcc, 0, v147, vcc
	global_load_ushort v169, v[156:157], off
	v_add_co_u32_e32 v156, vcc, s69, v146
	s_nop 1
	v_addc_co_u32_e32 v157, vcc, 0, v147, vcc
	global_load_ushort v170, v[156:157], off
	v_add_co_u32_e32 v156, vcc, s70, v146
	s_nop 1
	v_addc_co_u32_e32 v157, vcc, 0, v147, vcc
	v_add_co_u32_e32 v146, vcc, s71, v146
	global_load_ushort v171, v[156:157], off
	s_nop 0
	v_addc_co_u32_e32 v147, vcc, 0, v147, vcc
	global_load_ushort v172, v[146:147], off
	s_cselect_b64 vcc, -1, 0
	v_cndmask_b32_e64 v173, 0, 1.0, vcc
	v_mul_f32_e32 v136, v173, v136
	v_cndmask_b32_e64 v157, -v136, v136, s[4:5]
	v_lshlrev_b32_e32 v136, 16, v158
	v_mul_f32_e32 v136, v173, v136
	v_cndmask_b32_e64 v158, -v136, v136, s[4:5]
	v_lshlrev_b32_e32 v136, 16, v159
	v_mul_f32_e32 v136, v173, v136
	v_cndmask_b32_e64 v159, -v136, v136, s[4:5]
	v_lshlrev_b32_e32 v136, 16, v160
	v_mul_f32_e32 v136, v173, v136
	v_cndmask_b32_e64 v160, -v136, v136, s[4:5]
	v_lshlrev_b32_e32 v136, 16, v161
	v_mul_f32_e32 v136, v173, v136
	v_cndmask_b32_e64 v161, -v136, v136, s[4:5]
	v_lshlrev_b32_e32 v136, 16, v162
	v_mul_f32_e32 v136, v173, v136
	v_cndmask_b32_e64 v162, -v136, v136, s[4:5]
	v_lshlrev_b32_e32 v136, 16, v163
	v_mul_f32_e32 v136, v173, v136
	v_or_b32_e32 v146, s62, v148
	s_and_b64 s[60:61], vcc, exec
	v_cndmask_b32_e64 v163, -v136, v136, s[4:5]
	v_lshlrev_b32_e32 v136, 16, v164
	s_cselect_b32 s60, 0, 0x80
	s_add_u32 s19, s8, 0x5000
	v_ashrrev_i32_e32 v147, 31, v146
	v_mul_f32_e32 v136, v173, v136
	s_addc_u32 s55, s9, 0
	v_lshl_add_u64 v[174:175], s[58:59], 0, v[146:147]
	v_cndmask_b32_e64 v164, -v136, v136, s[4:5]
	v_lshlrev_b64 v[182:183], 11, v[174:175]
	v_sub_co_u32_e64 v174, s[8:9], s19, v146
	v_mov_b32_e32 v136, s55
	s_nop 0
	v_subb_co_u32_e64 v175, s[8:9], v136, v147, s[8:9]
	v_lshlrev_b64 v[184:185], 11, v[174:175]
	v_add_f32_e32 v147, v124, v157
	v_add_f32_e32 v174, v125, v158
	v_add_f32_e32 v124, v120, v161
	v_add_f32_e32 v125, v121, v162
	v_add_f32_e32 v175, v126, v159
	v_add_f32_e32 v176, v127, v160
	v_mul_f32_e32 v120, 0x3c800000, v147
	v_mul_f32_e32 v121, 0x3c800000, v174
	s_lshl_b32 s8, s18, 9
	v_cvt_pk_bf16_f32 v178, v120, v121
	v_mul_f32_e32 v120, 0x3c800000, v175
	v_mul_f32_e32 v121, 0x3c800000, v176
	v_add_f32_e32 v126, v122, v163
	v_add_f32_e32 v127, v123, v164
	s_or_b32 s8, s60, s8
	v_cvt_pk_bf16_f32 v179, v120, v121
	v_mul_f32_e32 v120, 0x3c800000, v124
	v_mul_f32_e32 v121, 0x3c800000, v125
	v_or_b32_e32 v122, s8, v150
	v_cvt_pk_bf16_f32 v180, v120, v121
	v_mul_f32_e32 v120, 0x3c800000, v126
	v_mul_f32_e32 v121, 0x3c800000, v127
	v_cvt_pk_bf16_f32 v181, v120, v121
	v_lshl_add_u64 v[120:121], s[10:11], 0, v[182:183]
	v_lshlrev_b32_e32 v136, 1, v122
	v_cndmask_b32_e32 v156, v154, v155, vcc
	v_cmp_lt_i32_e32 vcc, 0, v146
	v_lshl_add_u64 v[122:123], v[120:121], 0, v[136:137]
	v_lshl_add_u64 v[120:121], s[10:11], 0, v[184:185]
	global_store_dwordx4 v[122:123], v[178:181], off nt
	s_and_saveexec_b64 s[8:9], vcc
	s_cbranch_execz .LBB0_432
	v_mul_f32_e32 v147, v156, v147
	v_mul_f32_e32 v174, v156, v174
	v_mul_f32_e32 v124, v156, v124
	v_mul_f32_e32 v125, v156, v125
	v_cvt_pk_bf16_f32 v174, v147, v174
	v_mul_f32_e32 v147, v156, v175
	v_mul_f32_e32 v175, v156, v176
	v_cvt_pk_bf16_f32 v176, v124, v125
	v_mul_f32_e32 v124, v156, v126
	v_mul_f32_e32 v125, v156, v127
	v_cvt_pk_bf16_f32 v177, v124, v125
	v_lshl_add_u64 v[124:125], v[120:121], 0, v[136:137]
	v_cvt_pk_bf16_f32 v175, v147, v175
	global_store_dwordx4 v[124:125], v[174:177], off nt
; __device__ __forceinline__ unsigned cvt_pk_bf16(float lo, float hi) { unsigned r; asm("v_cvt_pk_bf16_f32 %0, %1, %2" : "=v"(r) : "v"(lo), "v"(hi)); return r; }
;     __device__ __forceinline__ void operator()(const f32x4 (&acc)[2][2][4][2], const Unit& u, int wr, int wc, int fr, int fq, LAS unsigned char* xs, int wid, int lane) const {
;     ...
; #pragma unroll
;         for (int ai = 0; ai < 2; ++ai)
; #pragma unroll
;             for (int m = 0; m < 4; ++m) {
;                 const int k = k0 + ai * 128 + m * 16 + fr;
; #pragma unroll
;                 for (int bj = 0; bj < 2; ++bj) {
;                     const int col = (2 * u.pn + bj) * 256 + cs * 128 + wc * 32 + 8 * fq;
;                     f32x4 a = acc[ai][bj][m][0], b = acc[ai][bj][m][1];
; #pragma unroll
;                     for (int j = 0; j < 4; ++j) { a[j] += hv[bj][j]; b[j] += hv[bj][4 + j]; }
;                     u32x4 w; w.x = cvt_pk_bf16(a[0] * sc, a[1] * sc); w.y = cvt_pk_bf16(a[2] * sc, a[3] * sc); w.z = cvt_pk_bf16(b[0] * sc, b[1] * sc); w.w = cvt_pk_bf16(b[2] * sc, b[3] * sc);
;                     *(u32x4*)(pq + (tok0 + k) * 1024 + col) = w;
;                     if (k > 0) {
;                         u32x4 w2; w2.x = cvt_pk_bf16(a[0] * scm, a[1] * scm); w2.y = cvt_pk_bf16(a[2] * scm, a[3] * scm); w2.z = cvt_pk_bf16(b[0] * scm, b[1] * scm); w2.w = cvt_pk_bf16(b[2] * scm, b[3] * scm);
;                         *(u32x4*)(pq + (tok0 + S - k) * 1024 + col) = w2;
;                     }
;                 }
;                 __builtin_amdgcn_sched_barrier(0);
.LBB0_432:
	s_or_b64 exec, exec, s[8:9]
	v_lshlrev_b32_e32 v124, 16, v165
	s_waitcnt vmcnt(7)
	v_lshlrev_b32_e32 v125, 16, v166
	v_mul_f32_e32 v124, v173, v124
	v_mul_f32_e32 v125, v173, v125
	s_waitcnt vmcnt(6)
	v_lshlrev_b32_e32 v126, 16, v167
	s_waitcnt vmcnt(5)
	v_lshlrev_b32_e32 v127, 16, v168
	v_cndmask_b32_e64 v124, -v124, v124, s[4:5]
	v_cndmask_b32_e64 v125, -v125, v125, s[4:5]
	v_mul_f32_e32 v126, v173, v126
	v_mul_f32_e32 v127, v173, v127
	s_waitcnt vmcnt(4)
	v_lshlrev_b32_e32 v147, 16, v169
	s_waitcnt vmcnt(3)
	v_lshlrev_b32_e32 v165, 16, v170
	v_cndmask_b32_e64 v126, -v126, v126, s[4:5]
	v_cndmask_b32_e64 v127, -v127, v127, s[4:5]
	v_mul_f32_e32 v147, v173, v147
	v_mul_f32_e32 v165, v173, v165
	s_waitcnt vmcnt(2)
	v_lshlrev_b32_e32 v166, 16, v171
	v_add_f32_e32 v116, v116, v124
	v_add_f32_e32 v117, v117, v125
	v_cndmask_b32_e64 v147, -v147, v147, s[4:5]
	v_cndmask_b32_e64 v165, -v165, v165, s[4:5]
	v_mul_f32_e32 v166, v173, v166
	s_waitcnt vmcnt(1)
	v_lshlrev_b32_e32 v167, 16, v172
	v_add_f32_e32 v118, v118, v126
	v_add_f32_e32 v119, v119, v127
	v_mul_f32_e32 v168, 0x3c800000, v116
	v_mul_f32_e32 v169, 0x3c800000, v117
	v_cndmask_b32_e64 v166, -v166, v166, s[4:5]
	v_mul_f32_e32 v167, v173, v167
	v_add_f32_e32 v112, v112, v147
	v_add_f32_e32 v113, v113, v165
	v_cvt_pk_bf16_f32 v168, v168, v169
	v_mul_f32_e32 v169, 0x3c800000, v118
	v_mul_f32_e32 v170, 0x3c800000, v119
	v_cndmask_b32_e64 v167, -v167, v167, s[4:5]
	v_add_f32_e32 v114, v114, v166
	v_cvt_pk_bf16_f32 v169, v169, v170
	v_mul_f32_e32 v170, 0x3c800000, v112
	v_mul_f32_e32 v171, 0x3c800000, v113
	v_add_f32_e32 v115, v115, v167
	v_cvt_pk_bf16_f32 v170, v170, v171
	v_mul_f32_e32 v171, 0x3c800000, v114
	v_mul_f32_e32 v172, 0x3c800000, v115
	v_cvt_pk_bf16_f32 v171, v171, v172
	global_store_dwordx4 v[122:123], v[168:171], off offset:512 nt
	s_and_saveexec_b64 s[8:9], vcc
	s_cbranch_execz .LBB0_434
	v_mul_f32_e32 v116, v156, v116
	v_mul_f32_e32 v117, v156, v117
	v_cvt_pk_bf16_f32 v116, v116, v117
	v_mul_f32_e32 v117, v156, v118
	v_mul_f32_e32 v118, v156, v119
	v_mul_f32_e32 v112, v156, v112
	v_mul_f32_e32 v113, v156, v113
	v_cvt_pk_bf16_f32 v117, v117, v118
	v_cvt_pk_bf16_f32 v118, v112, v113
	v_mul_f32_e32 v112, v156, v114
	v_mul_f32_e32 v113, v156, v115
	v_cvt_pk_bf16_f32 v119, v112, v113
	v_lshl_add_u64 v[112:113], v[120:121], 0, v[136:137]
	global_store_dwordx4 v[112:113], v[116:119], off offset:512 nt
.LBB0_434:
	s_or_b64 exec, exec, s[8:9]
	v_or_b32_e32 v112, 16, v146
	v_ashrrev_i32_e32 v113, 31, v112
	v_lshl_add_u64 v[114:115], s[58:59], 0, v[112:113]
	v_lshlrev_b64 v[120:121], 11, v[114:115]
	v_mov_b32_e32 v114, s55
	v_sub_co_u32_e32 v112, vcc, s19, v112
	v_add_f32_e32 v115, v111, v160
	s_nop 0
	v_subb_co_u32_e32 v113, vcc, v114, v113, vcc
	v_lshlrev_b64 v[122:123], 11, v[112:113]
	v_add_f32_e32 v112, v108, v157
	v_add_f32_e32 v113, v109, v158
	v_add_f32_e32 v108, v104, v161
	v_add_f32_e32 v109, v105, v162
	v_add_f32_e32 v114, v110, v159
	v_mul_f32_e32 v104, 0x3c800000, v112
	v_mul_f32_e32 v105, 0x3c800000, v113
	v_cvt_pk_bf16_f32 v116, v104, v105
	v_mul_f32_e32 v104, 0x3c800000, v114
	v_mul_f32_e32 v105, 0x3c800000, v115
	v_add_f32_e32 v110, v106, v163
	v_add_f32_e32 v111, v107, v164
	v_cvt_pk_bf16_f32 v117, v104, v105
	v_mul_f32_e32 v104, 0x3c800000, v108
	v_mul_f32_e32 v105, 0x3c800000, v109
	v_cvt_pk_bf16_f32 v118, v104, v105
	v_mul_f32_e32 v104, 0x3c800000, v110
	v_mul_f32_e32 v105, 0x3c800000, v111
	s_cmp_gt_i32 s62, -1
	v_cvt_pk_bf16_f32 v119, v104, v105
	v_lshl_add_u64 v[104:105], s[10:11], 0, v[120:121]
	s_cselect_b64 s[60:61], -1, 0
	s_cmp_lt_i32 s62, 0
	v_lshl_add_u64 v[106:107], v[104:105], 0, v[136:137]
	v_lshl_add_u64 v[104:105], s[10:11], 0, v[122:123]
	global_store_dwordx4 v[106:107], v[116:119], off nt
	s_cbranch_scc1 .LBB0_436
	v_mul_f32_e32 v112, v156, v112
	v_mul_f32_e32 v113, v156, v113
	v_cvt_pk_bf16_f32 v112, v112, v113
	v_mul_f32_e32 v113, v156, v114
	v_mul_f32_e32 v114, v156, v115
	v_mul_f32_e32 v108, v156, v108
	v_mul_f32_e32 v109, v156, v109
	v_cvt_pk_bf16_f32 v113, v113, v114
	v_cvt_pk_bf16_f32 v114, v108, v109
	v_mul_f32_e32 v108, v156, v110
	v_mul_f32_e32 v109, v156, v111
	v_cvt_pk_bf16_f32 v115, v108, v109
	v_lshl_add_u64 v[108:109], v[104:105], 0, v[136:137]
	global_store_dwordx4 v[108:109], v[112:115], off nt
.LBB0_436:
	v_add_f32_e32 v100, v100, v124
	v_add_f32_e32 v101, v101, v125
	v_add_f32_e32 v102, v102, v126
	v_add_f32_e32 v103, v103, v127
	v_mul_f32_e32 v108, 0x3c800000, v100
	v_mul_f32_e32 v109, 0x3c800000, v101
	v_add_f32_e32 v96, v96, v147
	v_add_f32_e32 v97, v97, v165
	v_cvt_pk_bf16_f32 v108, v108, v109
	v_mul_f32_e32 v109, 0x3c800000, v102
	v_mul_f32_e32 v110, 0x3c800000, v103
	v_add_f32_e32 v98, v98, v166
	v_add_f32_e32 v99, v99, v167
	v_cvt_pk_bf16_f32 v109, v109, v110
	v_mul_f32_e32 v110, 0x3c800000, v96
	v_mul_f32_e32 v111, 0x3c800000, v97
	v_cvt_pk_bf16_f32 v110, v110, v111
	v_mul_f32_e32 v111, 0x3c800000, v98
	v_mul_f32_e32 v112, 0x3c800000, v99
	v_cvt_pk_bf16_f32 v111, v111, v112
	v_cndmask_b32_e64 v112, 0, 1, s[60:61]
	v_cmp_ne_u32_e64 s[8:9], 1, v112
	s_andn2_b64 vcc, exec, s[60:61]
	global_store_dwordx4 v[106:107], v[108:111], off offset:512 nt
	s_cbranch_vccnz .LBB0_438
	v_mul_f32_e32 v100, v156, v100
	v_mul_f32_e32 v101, v156, v101
	v_cvt_pk_bf16_f32 v100, v100, v101
	v_mul_f32_e32 v101, v156, v102
	v_mul_f32_e32 v102, v156, v103
	v_mul_f32_e32 v96, v156, v96
	v_mul_f32_e32 v97, v156, v97
	v_cvt_pk_bf16_f32 v101, v101, v102
	v_cvt_pk_bf16_f32 v102, v96, v97
	v_mul_f32_e32 v96, v156, v98
	v_mul_f32_e32 v97, v156, v99
	v_cvt_pk_bf16_f32 v103, v96, v97
	v_lshl_add_u64 v[96:97], v[104:105], 0, v[136:137]
	global_store_dwordx4 v[96:97], v[100:103], off offset:512 nt
; __device__ __forceinline__ unsigned cvt_pk_bf16(float lo, float hi) { unsigned r; asm("v_cvt_pk_bf16_f32 %0, %1, %2" : "=v"(r) : "v"(lo), "v"(hi)); return r; }
;     __device__ __forceinline__ void operator()(const f32x4 (&acc)[2][2][4][2], const Unit& u, int wr, int wc, int fr, int fq, LAS unsigned char* xs, int wid, int lane) const {
;     ...
; #pragma unroll
;         for (int ai = 0; ai < 2; ++ai)
; #pragma unroll
;             for (int m = 0; m < 4; ++m) {
;                 const int k = k0 + ai * 128 + m * 16 + fr;
; #pragma unroll
;                 for (int bj = 0; bj < 2; ++bj) {
;                     const int col = (2 * u.pn + bj) * 256 + cs * 128 + wc * 32 + 8 * fq;
;                     f32x4 a = acc[ai][bj][m][0], b = acc[ai][bj][m][1];
; #pragma unroll
;                     for (int j = 0; j < 4; ++j) { a[j] += hv[bj][j]; b[j] += hv[bj][4 + j]; }
;                     u32x4 w; w.x = cvt_pk_bf16(a[0] * sc, a[1] * sc); w.y = cvt_pk_bf16(a[2] * sc, a[3] * sc); w.z = cvt_pk_bf16(b[0] * sc, b[1] * sc); w.w = cvt_pk_bf16(b[2] * sc, b[3] * sc);
;                     *(u32x4*)(pq + (tok0 + k) * 1024 + col) = w;
;                     if (k > 0) {
;                         u32x4 w2; w2.x = cvt_pk_bf16(a[0] * scm, a[1] * scm); w2.y = cvt_pk_bf16(a[2] * scm, a[3] * scm); w2.z = cvt_pk_bf16(b[0] * scm, b[1] * scm); w2.w = cvt_pk_bf16(b[2] * scm, b[3] * scm);
;                         *(u32x4*)(pq + (tok0 + S - k) * 1024 + col) = w2;
;                     }
;                 }
;                 __builtin_amdgcn_sched_barrier(0);
.LBB0_438:
	v_or_b32_e32 v96, 32, v146
	v_ashrrev_i32_e32 v97, 31, v96
	v_lshl_add_u64 v[98:99], s[58:59], 0, v[96:97]
	v_lshlrev_b64 v[104:105], 11, v[98:99]
	v_mov_b32_e32 v98, s55
	v_sub_co_u32_e32 v96, vcc, s19, v96
	v_add_f32_e32 v99, v95, v160
	s_nop 0
	v_subb_co_u32_e32 v97, vcc, v98, v97, vcc
	v_lshlrev_b64 v[106:107], 11, v[96:97]
	v_add_f32_e32 v96, v92, v157
	v_add_f32_e32 v97, v93, v158
	v_add_f32_e32 v92, v88, v161
	v_add_f32_e32 v93, v89, v162
	v_add_f32_e32 v98, v94, v159
	v_mul_f32_e32 v88, 0x3c800000, v96
	v_mul_f32_e32 v89, 0x3c800000, v97
	v_cvt_pk_bf16_f32 v100, v88, v89
	v_mul_f32_e32 v88, 0x3c800000, v98
	v_mul_f32_e32 v89, 0x3c800000, v99
	v_add_f32_e32 v94, v90, v163
	v_add_f32_e32 v95, v91, v164
	v_cvt_pk_bf16_f32 v101, v88, v89
	v_mul_f32_e32 v88, 0x3c800000, v92
	v_mul_f32_e32 v89, 0x3c800000, v93
	v_cvt_pk_bf16_f32 v102, v88, v89
	v_mul_f32_e32 v88, 0x3c800000, v94
	v_mul_f32_e32 v89, 0x3c800000, v95
	v_cvt_pk_bf16_f32 v103, v88, v89
	v_lshl_add_u64 v[88:89], s[10:11], 0, v[104:105]
	v_lshl_add_u64 v[90:91], v[88:89], 0, v[136:137]
	s_and_b64 vcc, exec, s[8:9]
	v_lshl_add_u64 v[88:89], s[10:11], 0, v[106:107]
	global_store_dwordx4 v[90:91], v[100:103], off nt
	s_cbranch_vccnz .LBB0_440
	v_mul_f32_e32 v96, v156, v96
	v_mul_f32_e32 v97, v156, v97
	v_cvt_pk_bf16_f32 v96, v96, v97
	v_mul_f32_e32 v97, v156, v98
	v_mul_f32_e32 v98, v156, v99
	v_mul_f32_e32 v92, v156, v92
	v_mul_f32_e32 v93, v156, v93
	v_cvt_pk_bf16_f32 v97, v97, v98
	v_cvt_pk_bf16_f32 v98, v92, v93
	v_mul_f32_e32 v92, v156, v94
	v_mul_f32_e32 v93, v156, v95
	v_cvt_pk_bf16_f32 v99, v92, v93
	v_lshl_add_u64 v[92:93], v[88:89], 0, v[136:137]
	global_store_dwordx4 v[92:93], v[96:99], off nt
.LBB0_440:
	v_add_f32_e32 v84, v84, v124
	v_add_f32_e32 v85, v85, v125
	v_add_f32_e32 v86, v86, v126
	v_add_f32_e32 v87, v87, v127
	v_mul_f32_e32 v92, 0x3c800000, v84
	v_mul_f32_e32 v93, 0x3c800000, v85
	v_add_f32_e32 v80, v80, v147
	v_add_f32_e32 v81, v81, v165
	v_cvt_pk_bf16_f32 v92, v92, v93
	v_mul_f32_e32 v93, 0x3c800000, v86
	v_mul_f32_e32 v94, 0x3c800000, v87
	v_add_f32_e32 v82, v82, v166
	v_cvt_pk_bf16_f32 v93, v93, v94
	v_mul_f32_e32 v94, 0x3c800000, v80
	v_mul_f32_e32 v95, 0x3c800000, v81
	v_add_f32_e32 v83, v83, v167
	v_cvt_pk_bf16_f32 v94, v94, v95
	v_mul_f32_e32 v95, 0x3c800000, v82
	s_and_b64 vcc, exec, s[8:9]
	v_mul_f32_e32 v96, 0x3c800000, v83
	v_cvt_pk_bf16_f32 v95, v95, v96
	global_store_dwordx4 v[90:91], v[92:95], off offset:512 nt
	s_cbranch_vccnz .LBB0_442
	v_mul_f32_e32 v84, v156, v84
	v_mul_f32_e32 v85, v156, v85
	v_cvt_pk_bf16_f32 v84, v84, v85
	v_mul_f32_e32 v85, v156, v86
	v_mul_f32_e32 v86, v156, v87
	v_mul_f32_e32 v80, v156, v80
	v_mul_f32_e32 v81, v156, v81
	v_cvt_pk_bf16_f32 v85, v85, v86
	v_cvt_pk_bf16_f32 v86, v80, v81
	v_mul_f32_e32 v80, v156, v82
	v_mul_f32_e32 v81, v156, v83
	v_cvt_pk_bf16_f32 v87, v80, v81
	v_lshl_add_u64 v[80:81], v[88:89], 0, v[136:137]
	global_store_dwordx4 v[80:81], v[84:87], off offset:512 nt
.LBB0_442:
	v_or_b32_e32 v80, 48, v146
	v_ashrrev_i32_e32 v81, 31, v80
	v_lshl_add_u64 v[82:83], s[58:59], 0, v[80:81]
	v_lshlrev_b64 v[88:89], 11, v[82:83]
	v_mov_b32_e32 v82, s55
	v_sub_co_u32_e32 v80, vcc, s19, v80
	v_add_f32_e32 v83, v79, v160
	s_nop 0
	v_subb_co_u32_e32 v81, vcc, v82, v81, vcc
	v_lshlrev_b64 v[90:91], 11, v[80:81]
	v_add_f32_e32 v80, v76, v157
	v_add_f32_e32 v81, v77, v158
	v_add_f32_e32 v76, v72, v161
	v_add_f32_e32 v77, v73, v162
	v_add_f32_e32 v82, v78, v159
	v_mul_f32_e32 v72, 0x3c800000, v80
	v_mul_f32_e32 v73, 0x3c800000, v81
	v_cvt_pk_bf16_f32 v84, v72, v73
	v_mul_f32_e32 v72, 0x3c800000, v82
	v_mul_f32_e32 v73, 0x3c800000, v83
	v_add_f32_e32 v78, v74, v163
	v_add_f32_e32 v79, v75, v164
	v_cvt_pk_bf16_f32 v85, v72, v73
	v_mul_f32_e32 v72, 0x3c800000, v76
	v_mul_f32_e32 v73, 0x3c800000, v77
	v_cvt_pk_bf16_f32 v86, v72, v73
	v_mul_f32_e32 v72, 0x3c800000, v78
	v_mul_f32_e32 v73, 0x3c800000, v79
	v_cvt_pk_bf16_f32 v87, v72, v73
	v_lshl_add_u64 v[72:73], s[10:11], 0, v[88:89]
	v_lshl_add_u64 v[74:75], v[72:73], 0, v[136:137]
	s_and_b64 vcc, exec, s[8:9]
	v_lshl_add_u64 v[72:73], s[10:11], 0, v[90:91]
	global_store_dwordx4 v[74:75], v[84:87], off nt
	s_cbranch_vccnz .LBB0_444
	v_mul_f32_e32 v80, v156, v80
	v_mul_f32_e32 v81, v156, v81
	v_cvt_pk_bf16_f32 v80, v80, v81
	v_mul_f32_e32 v81, v156, v82
	v_mul_f32_e32 v82, v156, v83
	v_mul_f32_e32 v76, v156, v76
	v_mul_f32_e32 v77, v156, v77
	v_cvt_pk_bf16_f32 v81, v81, v82
	v_cvt_pk_bf16_f32 v82, v76, v77
	v_mul_f32_e32 v76, v156, v78
	v_mul_f32_e32 v77, v156, v79
	v_cvt_pk_bf16_f32 v83, v76, v77
	v_lshl_add_u64 v[76:77], v[72:73], 0, v[136:137]
	global_store_dwordx4 v[76:77], v[80:83], off nt
.LBB0_444:
	v_add_f32_e32 v68, v68, v124
	v_add_f32_e32 v69, v69, v125
	v_add_f32_e32 v70, v70, v126
	v_add_f32_e32 v71, v71, v127
	v_mul_f32_e32 v76, 0x3c800000, v68
	v_mul_f32_e32 v77, 0x3c800000, v69
	v_add_f32_e32 v64, v64, v147
	v_add_f32_e32 v65, v65, v165
	v_cvt_pk_bf16_f32 v76, v76, v77
	v_mul_f32_e32 v77, 0x3c800000, v70
	v_mul_f32_e32 v78, 0x3c800000, v71
	v_add_f32_e32 v66, v66, v166
	v_cvt_pk_bf16_f32 v77, v77, v78
	v_mul_f32_e32 v78, 0x3c800000, v64
	v_mul_f32_e32 v79, 0x3c800000, v65
	v_add_f32_e32 v67, v67, v167
	v_cvt_pk_bf16_f32 v78, v78, v79
	v_mul_f32_e32 v79, 0x3c800000, v66
	s_and_b64 vcc, exec, s[8:9]
	v_mul_f32_e32 v80, 0x3c800000, v67
	v_cvt_pk_bf16_f32 v79, v79, v80
	global_store_dwordx4 v[74:75], v[76:79], off offset:512 nt
	s_cbranch_vccnz .LBB0_446
	v_mul_f32_e32 v68, v156, v68
	v_mul_f32_e32 v69, v156, v69
	v_cvt_pk_bf16_f32 v68, v68, v69
	v_mul_f32_e32 v69, v156, v70
	v_mul_f32_e32 v70, v156, v71
	v_mul_f32_e32 v64, v156, v64
	v_mul_f32_e32 v65, v156, v65
	v_cvt_pk_bf16_f32 v69, v69, v70
	v_cvt_pk_bf16_f32 v70, v64, v65
	v_mul_f32_e32 v64, v156, v66
	v_mul_f32_e32 v65, v156, v67
	v_cvt_pk_bf16_f32 v71, v64, v65
	v_lshl_add_u64 v[64:65], v[72:73], 0, v[136:137]
	global_store_dwordx4 v[64:65], v[68:71], off offset:512 nt
; __device__ __forceinline__ unsigned cvt_pk_bf16(float lo, float hi) { unsigned r; asm("v_cvt_pk_bf16_f32 %0, %1, %2" : "=v"(r) : "v"(lo), "v"(hi)); return r; }
;     __device__ __forceinline__ void operator()(const f32x4 (&acc)[2][2][4][2], const Unit& u, int wr, int wc, int fr, int fq, LAS unsigned char* xs, int wid, int lane) const {
;     ...
; #pragma unroll
;         for (int ai = 0; ai < 2; ++ai)
; #pragma unroll
;             for (int m = 0; m < 4; ++m) {
;                 const int k = k0 + ai * 128 + m * 16 + fr;
; #pragma unroll
;                 for (int bj = 0; bj < 2; ++bj) {
;                     const int col = (2 * u.pn + bj) * 256 + cs * 128 + wc * 32 + 8 * fq;
;                     f32x4 a = acc[ai][bj][m][0], b = acc[ai][bj][m][1];
; #pragma unroll
;                     for (int j = 0; j < 4; ++j) { a[j] += hv[bj][j]; b[j] += hv[bj][4 + j]; }
;                     u32x4 w; w.x = cvt_pk_bf16(a[0] * sc, a[1] * sc); w.y = cvt_pk_bf16(a[2] * sc, a[3] * sc); w.z = cvt_pk_bf16(b[0] * sc, b[1] * sc); w.w = cvt_pk_bf16(b[2] * sc, b[3] * sc);
;                     *(u32x4*)(pq + (tok0 + k) * 1024 + col) = w;
;                     if (k > 0) {
;                         u32x4 w2; w2.x = cvt_pk_bf16(a[0] * scm, a[1] * scm); w2.y = cvt_pk_bf16(a[2] * scm, a[3] * scm); w2.z = cvt_pk_bf16(b[0] * scm, b[1] * scm); w2.w = cvt_pk_bf16(b[2] * scm, b[3] * scm);
;                         *(u32x4*)(pq + (tok0 + S - k) * 1024 + col) = w2;
;                     }
;                 }
;                 __builtin_amdgcn_sched_barrier(0);
.LBB0_446:
	v_add_u32_e32 v64, 0x80, v146
	v_ashrrev_i32_e32 v65, 31, v64
	v_lshl_add_u64 v[66:67], s[58:59], 0, v[64:65]
	v_lshlrev_b64 v[72:73], 11, v[66:67]
	v_mov_b32_e32 v66, s55
	v_sub_co_u32_e64 v64, s[8:9], s19, v64
	v_add_f32_e32 v67, v63, v160
	s_nop 0
	v_subb_co_u32_e64 v65, s[8:9], v66, v65, s[8:9]
	v_lshlrev_b64 v[74:75], 11, v[64:65]
	v_add_f32_e32 v64, v60, v157
	v_add_f32_e32 v65, v61, v158
	v_add_f32_e32 v60, v56, v161
	v_add_f32_e32 v61, v57, v162
	v_add_f32_e32 v66, v62, v159
	v_mul_f32_e32 v56, 0x3c800000, v64
	v_mul_f32_e32 v57, 0x3c800000, v65
	v_cvt_pk_bf16_f32 v68, v56, v57
	v_mul_f32_e32 v56, 0x3c800000, v66
	v_mul_f32_e32 v57, 0x3c800000, v67
	v_add_f32_e32 v62, v58, v163
	v_add_f32_e32 v63, v59, v164
	v_cvt_pk_bf16_f32 v69, v56, v57
	v_mul_f32_e32 v56, 0x3c800000, v60
	v_mul_f32_e32 v57, 0x3c800000, v61
	v_cvt_pk_bf16_f32 v70, v56, v57
	v_mul_f32_e32 v56, 0x3c800000, v62
	v_mul_f32_e32 v57, 0x3c800000, v63
	v_cvt_pk_bf16_f32 v71, v56, v57
	v_lshl_add_u64 v[56:57], s[10:11], 0, v[72:73]
	v_cmp_lt_i32_e32 vcc, s72, v146
	v_lshl_add_u64 v[58:59], v[56:57], 0, v[136:137]
	v_lshl_add_u64 v[56:57], s[10:11], 0, v[74:75]
	global_store_dwordx4 v[58:59], v[68:71], off nt
	s_and_saveexec_b64 s[8:9], vcc
	s_cbranch_execz .LBB0_448
	v_mul_f32_e32 v64, v156, v64
	v_mul_f32_e32 v65, v156, v65
	v_cvt_pk_bf16_f32 v64, v64, v65
	v_mul_f32_e32 v65, v156, v66
	v_mul_f32_e32 v66, v156, v67
	v_mul_f32_e32 v60, v156, v60
	v_mul_f32_e32 v61, v156, v61
	v_cvt_pk_bf16_f32 v65, v65, v66
	v_cvt_pk_bf16_f32 v66, v60, v61
	v_mul_f32_e32 v60, v156, v62
	v_mul_f32_e32 v61, v156, v63
	v_cvt_pk_bf16_f32 v67, v60, v61
	v_lshl_add_u64 v[60:61], v[56:57], 0, v[136:137]
	global_store_dwordx4 v[60:61], v[64:67], off nt
.LBB0_448:
	s_or_b64 exec, exec, s[8:9]
	v_add_f32_e32 v52, v52, v124
	v_add_f32_e32 v53, v53, v125
	v_add_f32_e32 v54, v54, v126
	v_add_f32_e32 v55, v55, v127
	v_mul_f32_e32 v60, 0x3c800000, v52
	v_mul_f32_e32 v61, 0x3c800000, v53
	v_add_f32_e32 v48, v48, v147
	v_add_f32_e32 v49, v49, v165
	v_cvt_pk_bf16_f32 v60, v60, v61
	v_mul_f32_e32 v61, 0x3c800000, v54
	v_mul_f32_e32 v62, 0x3c800000, v55
	v_add_f32_e32 v50, v50, v166
	v_cvt_pk_bf16_f32 v61, v61, v62
	v_mul_f32_e32 v62, 0x3c800000, v48
	v_mul_f32_e32 v63, 0x3c800000, v49
	v_add_f32_e32 v51, v51, v167
	v_cvt_pk_bf16_f32 v62, v62, v63
	v_mul_f32_e32 v63, 0x3c800000, v50
	v_mul_f32_e32 v64, 0x3c800000, v51
	v_cvt_pk_bf16_f32 v63, v63, v64
	global_store_dwordx4 v[58:59], v[60:63], off offset:512 nt
	s_and_saveexec_b64 s[8:9], vcc
	s_cbranch_execz .LBB0_450
	v_mul_f32_e32 v52, v156, v52
	v_mul_f32_e32 v53, v156, v53
	v_cvt_pk_bf16_f32 v52, v52, v53
	v_mul_f32_e32 v53, v156, v54
	v_mul_f32_e32 v54, v156, v55
	v_mul_f32_e32 v48, v156, v48
	v_mul_f32_e32 v49, v156, v49
	v_cvt_pk_bf16_f32 v53, v53, v54
	v_cvt_pk_bf16_f32 v54, v48, v49
	v_mul_f32_e32 v48, v156, v50
	v_mul_f32_e32 v49, v156, v51
	v_cvt_pk_bf16_f32 v55, v48, v49
	v_lshl_add_u64 v[48:49], v[56:57], 0, v[136:137]
	global_store_dwordx4 v[48:49], v[52:55], off offset:512 nt
.LBB0_450:
	s_or_b64 exec, exec, s[8:9]
	v_add_u32_e32 v48, 0x90, v146
	v_ashrrev_i32_e32 v49, 31, v48
	v_lshl_add_u64 v[50:51], s[58:59], 0, v[48:49]
	v_lshlrev_b64 v[56:57], 11, v[50:51]
	v_mov_b32_e32 v50, s55
	v_sub_co_u32_e64 v48, s[8:9], s19, v48
	v_add_f32_e32 v51, v47, v160
	s_nop 0
	v_subb_co_u32_e64 v49, s[8:9], v50, v49, s[8:9]
	v_lshlrev_b64 v[58:59], 11, v[48:49]
	v_add_f32_e32 v48, v44, v157
	v_add_f32_e32 v49, v45, v158
	v_add_f32_e32 v44, v40, v161
	v_add_f32_e32 v45, v41, v162
	v_add_f32_e32 v50, v46, v159
	v_mul_f32_e32 v40, 0x3c800000, v48
	v_mul_f32_e32 v41, 0x3c800000, v49
	v_cvt_pk_bf16_f32 v52, v40, v41
	v_mul_f32_e32 v40, 0x3c800000, v50
	v_mul_f32_e32 v41, 0x3c800000, v51
	v_add_f32_e32 v46, v42, v163
	v_add_f32_e32 v47, v43, v164
	v_cvt_pk_bf16_f32 v53, v40, v41
	v_mul_f32_e32 v40, 0x3c800000, v44
	v_mul_f32_e32 v41, 0x3c800000, v45
	v_cvt_pk_bf16_f32 v54, v40, v41
	v_mul_f32_e32 v40, 0x3c800000, v46
	v_mul_f32_e32 v41, 0x3c800000, v47
	v_cvt_pk_bf16_f32 v55, v40, v41
	v_lshl_add_u64 v[40:41], s[10:11], 0, v[56:57]
	v_cmp_lt_i32_e32 vcc, s73, v146
	v_lshl_add_u64 v[42:43], v[40:41], 0, v[136:137]
	v_lshl_add_u64 v[40:41], s[10:11], 0, v[58:59]
	global_store_dwordx4 v[42:43], v[52:55], off nt
	s_and_saveexec_b64 s[8:9], vcc
	s_cbranch_execz .LBB0_452
	v_mul_f32_e32 v48, v156, v48
	v_mul_f32_e32 v49, v156, v49
	v_cvt_pk_bf16_f32 v48, v48, v49
	v_mul_f32_e32 v49, v156, v50
	v_mul_f32_e32 v50, v156, v51
	v_mul_f32_e32 v44, v156, v44
	v_mul_f32_e32 v45, v156, v45
	v_cvt_pk_bf16_f32 v49, v49, v50
	v_cvt_pk_bf16_f32 v50, v44, v45
	v_mul_f32_e32 v44, v156, v46
	v_mul_f32_e32 v45, v156, v47
	v_cvt_pk_bf16_f32 v51, v44, v45
	v_lshl_add_u64 v[44:45], v[40:41], 0, v[136:137]
	global_store_dwordx4 v[44:45], v[48:51], off nt
.LBB0_452:
	s_or_b64 exec, exec, s[8:9]
	v_add_f32_e32 v36, v36, v124
	v_add_f32_e32 v37, v37, v125
	v_add_f32_e32 v38, v38, v126
	v_add_f32_e32 v39, v39, v127
	v_mul_f32_e32 v44, 0x3c800000, v36
	v_mul_f32_e32 v45, 0x3c800000, v37
	v_add_f32_e32 v32, v32, v147
	v_add_f32_e32 v33, v33, v165
	v_cvt_pk_bf16_f32 v44, v44, v45
	v_mul_f32_e32 v45, 0x3c800000, v38
	v_mul_f32_e32 v46, 0x3c800000, v39
	v_add_f32_e32 v34, v34, v166
	v_cvt_pk_bf16_f32 v45, v45, v46
	v_mul_f32_e32 v46, 0x3c800000, v32
	v_mul_f32_e32 v47, 0x3c800000, v33
	v_add_f32_e32 v35, v35, v167
	v_cvt_pk_bf16_f32 v46, v46, v47
	v_mul_f32_e32 v47, 0x3c800000, v34
	v_mul_f32_e32 v48, 0x3c800000, v35
	v_cvt_pk_bf16_f32 v47, v47, v48
	global_store_dwordx4 v[42:43], v[44:47], off offset:512 nt
	s_and_saveexec_b64 s[8:9], vcc
	s_cbranch_execz .LBB0_454
	v_mul_f32_e32 v36, v156, v36
	v_mul_f32_e32 v37, v156, v37
	v_cvt_pk_bf16_f32 v36, v36, v37
	v_mul_f32_e32 v37, v156, v38
	v_mul_f32_e32 v38, v156, v39
	v_mul_f32_e32 v32, v156, v32
	v_mul_f32_e32 v33, v156, v33
	v_cvt_pk_bf16_f32 v37, v37, v38
	v_cvt_pk_bf16_f32 v38, v32, v33
	v_mul_f32_e32 v32, v156, v34
	v_mul_f32_e32 v33, v156, v35
	v_cvt_pk_bf16_f32 v39, v32, v33
	v_lshl_add_u64 v[32:33], v[40:41], 0, v[136:137]
	global_store_dwordx4 v[32:33], v[36:39], off offset:512 nt
; __device__ __forceinline__ unsigned cvt_pk_bf16(float lo, float hi) { unsigned r; asm("v_cvt_pk_bf16_f32 %0, %1, %2" : "=v"(r) : "v"(lo), "v"(hi)); return r; }
;     __device__ __forceinline__ void operator()(const f32x4 (&acc)[2][2][4][2], const Unit& u, int wr, int wc, int fr, int fq, LAS unsigned char* xs, int wid, int lane) const {
;     ...
; #pragma unroll
;         for (int ai = 0; ai < 2; ++ai)
; #pragma unroll
;             for (int m = 0; m < 4; ++m) {
;                 const int k = k0 + ai * 128 + m * 16 + fr;
; #pragma unroll
;                 for (int bj = 0; bj < 2; ++bj) {
;                     const int col = (2 * u.pn + bj) * 256 + cs * 128 + wc * 32 + 8 * fq;
;                     f32x4 a = acc[ai][bj][m][0], b = acc[ai][bj][m][1];
; #pragma unroll
;                     for (int j = 0; j < 4; ++j) { a[j] += hv[bj][j]; b[j] += hv[bj][4 + j]; }
;                     u32x4 w; w.x = cvt_pk_bf16(a[0] * sc, a[1] * sc); w.y = cvt_pk_bf16(a[2] * sc, a[3] * sc); w.z = cvt_pk_bf16(b[0] * sc, b[1] * sc); w.w = cvt_pk_bf16(b[2] * sc, b[3] * sc);
;                     *(u32x4*)(pq + (tok0 + k) * 1024 + col) = w;
;                     if (k > 0) {
;                         u32x4 w2; w2.x = cvt_pk_bf16(a[0] * scm, a[1] * scm); w2.y = cvt_pk_bf16(a[2] * scm, a[3] * scm); w2.z = cvt_pk_bf16(b[0] * scm, b[1] * scm); w2.w = cvt_pk_bf16(b[2] * scm, b[3] * scm);
;                         *(u32x4*)(pq + (tok0 + S - k) * 1024 + col) = w2;
;                     }
;                 }
;                 __builtin_amdgcn_sched_barrier(0);
.LBB0_454:
	s_or_b64 exec, exec, s[8:9]
	v_add_u32_e32 v32, 0xa0, v146
	v_ashrrev_i32_e32 v33, 31, v32
	v_lshl_add_u64 v[34:35], s[58:59], 0, v[32:33]
	v_lshlrev_b64 v[40:41], 11, v[34:35]
	v_mov_b32_e32 v34, s55
	v_sub_co_u32_e64 v32, s[8:9], s19, v32
	v_add_f32_e32 v35, v31, v160
	s_nop 0
	v_subb_co_u32_e64 v33, s[8:9], v34, v33, s[8:9]
	v_lshlrev_b64 v[42:43], 11, v[32:33]
	v_add_f32_e32 v32, v28, v157
	v_add_f32_e32 v33, v29, v158
	v_add_f32_e32 v28, v24, v161
	v_add_f32_e32 v29, v25, v162
	v_add_f32_e32 v34, v30, v159
	v_mul_f32_e32 v24, 0x3c800000, v32
	v_mul_f32_e32 v25, 0x3c800000, v33
	v_cvt_pk_bf16_f32 v36, v24, v25
	v_mul_f32_e32 v24, 0x3c800000, v34
	v_mul_f32_e32 v25, 0x3c800000, v35
	v_add_f32_e32 v30, v26, v163
	v_add_f32_e32 v31, v27, v164
	v_cvt_pk_bf16_f32 v37, v24, v25
	v_mul_f32_e32 v24, 0x3c800000, v28
	v_mul_f32_e32 v25, 0x3c800000, v29
	v_cvt_pk_bf16_f32 v38, v24, v25
	v_mul_f32_e32 v24, 0x3c800000, v30
	v_mul_f32_e32 v25, 0x3c800000, v31
	v_cvt_pk_bf16_f32 v39, v24, v25
	v_lshl_add_u64 v[24:25], s[10:11], 0, v[40:41]
	v_cmp_lt_i32_e32 vcc, s74, v146
	v_lshl_add_u64 v[26:27], v[24:25], 0, v[136:137]
	v_lshl_add_u64 v[24:25], s[10:11], 0, v[42:43]
	global_store_dwordx4 v[26:27], v[36:39], off nt
	s_and_saveexec_b64 s[8:9], vcc
	s_cbranch_execz .LBB0_456
	v_mul_f32_e32 v32, v156, v32
	v_mul_f32_e32 v33, v156, v33
	v_cvt_pk_bf16_f32 v32, v32, v33
	v_mul_f32_e32 v33, v156, v34
	v_mul_f32_e32 v34, v156, v35
	v_mul_f32_e32 v28, v156, v28
	v_mul_f32_e32 v29, v156, v29
	v_cvt_pk_bf16_f32 v33, v33, v34
	v_cvt_pk_bf16_f32 v34, v28, v29
	v_mul_f32_e32 v28, v156, v30
	v_mul_f32_e32 v29, v156, v31
	v_cvt_pk_bf16_f32 v35, v28, v29
	v_lshl_add_u64 v[28:29], v[24:25], 0, v[136:137]
	global_store_dwordx4 v[28:29], v[32:35], off nt
.LBB0_456:
	s_or_b64 exec, exec, s[8:9]
	v_add_f32_e32 v20, v20, v124
	v_add_f32_e32 v21, v21, v125
	v_add_f32_e32 v22, v22, v126
	v_add_f32_e32 v23, v23, v127
	v_mul_f32_e32 v28, 0x3c800000, v20
	v_mul_f32_e32 v29, 0x3c800000, v21
	v_add_f32_e32 v16, v16, v147
	v_add_f32_e32 v17, v17, v165
	v_cvt_pk_bf16_f32 v28, v28, v29
	v_mul_f32_e32 v29, 0x3c800000, v22
	v_mul_f32_e32 v30, 0x3c800000, v23
	v_add_f32_e32 v18, v18, v166
	v_cvt_pk_bf16_f32 v29, v29, v30
	v_mul_f32_e32 v30, 0x3c800000, v16
	v_mul_f32_e32 v31, 0x3c800000, v17
	v_add_f32_e32 v19, v19, v167
	v_cvt_pk_bf16_f32 v30, v30, v31
	v_mul_f32_e32 v31, 0x3c800000, v18
	v_mul_f32_e32 v32, 0x3c800000, v19
	v_cvt_pk_bf16_f32 v31, v31, v32
	global_store_dwordx4 v[26:27], v[28:31], off offset:512 nt
	s_and_saveexec_b64 s[8:9], vcc
	s_cbranch_execz .LBB0_458
	v_mul_f32_e32 v20, v156, v20
	v_mul_f32_e32 v21, v156, v21
	v_cvt_pk_bf16_f32 v20, v20, v21
	v_mul_f32_e32 v21, v156, v22
	v_mul_f32_e32 v22, v156, v23
	v_mul_f32_e32 v16, v156, v16
	v_mul_f32_e32 v17, v156, v17
	v_cvt_pk_bf16_f32 v21, v21, v22
	v_cvt_pk_bf16_f32 v22, v16, v17
	v_mul_f32_e32 v16, v156, v18
	v_mul_f32_e32 v17, v156, v19
	v_cvt_pk_bf16_f32 v23, v16, v17
	v_lshl_add_u64 v[16:17], v[24:25], 0, v[136:137]
	global_store_dwordx4 v[16:17], v[20:23], off offset:512 nt
.LBB0_458:
	s_or_b64 exec, exec, s[8:9]
	v_add_u32_e32 v16, 0xb0, v146
	v_ashrrev_i32_e32 v17, 31, v16
	v_lshl_add_u64 v[18:19], s[58:59], 0, v[16:17]
	v_lshlrev_b64 v[24:25], 11, v[18:19]
	v_mov_b32_e32 v18, s55
	v_sub_co_u32_e64 v16, s[8:9], s19, v16
	v_add_f32_e32 v19, v15, v160
	s_nop 0
	v_subb_co_u32_e64 v17, s[8:9], v18, v17, s[8:9]
	v_lshlrev_b64 v[26:27], 11, v[16:17]
	v_add_f32_e32 v16, v12, v157
	v_add_f32_e32 v17, v13, v158
	v_add_f32_e32 v12, v8, v161
	v_add_f32_e32 v13, v9, v162
	v_add_f32_e32 v18, v14, v159
	v_mul_f32_e32 v8, 0x3c800000, v16
	v_mul_f32_e32 v9, 0x3c800000, v17
	v_cvt_pk_bf16_f32 v20, v8, v9
	v_mul_f32_e32 v8, 0x3c800000, v18
	v_mul_f32_e32 v9, 0x3c800000, v19
	v_add_f32_e32 v14, v10, v163
	v_add_f32_e32 v15, v11, v164
	v_cvt_pk_bf16_f32 v21, v8, v9
	v_mul_f32_e32 v8, 0x3c800000, v12
	v_mul_f32_e32 v9, 0x3c800000, v13
	v_cvt_pk_bf16_f32 v22, v8, v9
	v_mul_f32_e32 v8, 0x3c800000, v14
	v_mul_f32_e32 v9, 0x3c800000, v15
	v_cvt_pk_bf16_f32 v23, v8, v9
	v_lshl_add_u64 v[8:9], s[10:11], 0, v[24:25]
	v_cmp_lt_i32_e32 vcc, s75, v146
	v_lshl_add_u64 v[10:11], v[8:9], 0, v[136:137]
	v_lshl_add_u64 v[8:9], s[10:11], 0, v[26:27]
	global_store_dwordx4 v[10:11], v[20:23], off nt
	s_and_saveexec_b64 s[8:9], vcc
	s_cbranch_execz .LBB0_460
	v_mul_f32_e32 v16, v156, v16
	v_mul_f32_e32 v17, v156, v17
	v_cvt_pk_bf16_f32 v16, v16, v17
	v_mul_f32_e32 v17, v156, v18
	v_mul_f32_e32 v18, v156, v19
	v_mul_f32_e32 v12, v156, v12
	v_mul_f32_e32 v13, v156, v13
	v_cvt_pk_bf16_f32 v17, v17, v18
	v_cvt_pk_bf16_f32 v18, v12, v13
	v_mul_f32_e32 v12, v156, v14
	v_mul_f32_e32 v13, v156, v15
	v_cvt_pk_bf16_f32 v19, v12, v13
	v_lshl_add_u64 v[12:13], v[8:9], 0, v[136:137]
	global_store_dwordx4 v[12:13], v[16:19], off nt
.LBB0_460:
	s_or_b64 exec, exec, s[8:9]
	v_add_f32_e32 v4, v4, v124
	v_add_f32_e32 v5, v5, v125
	v_add_f32_e32 v6, v6, v126
	v_add_f32_e32 v7, v7, v127
	v_mul_f32_e32 v12, 0x3c800000, v4
	v_mul_f32_e32 v13, 0x3c800000, v5
	v_add_f32_e32 v0, v0, v147
	v_add_f32_e32 v1, v1, v165
	v_cvt_pk_bf16_f32 v12, v12, v13
	v_mul_f32_e32 v13, 0x3c800000, v6
	v_mul_f32_e32 v14, 0x3c800000, v7
	v_add_f32_e32 v2, v2, v166
	v_cvt_pk_bf16_f32 v13, v13, v14
	v_mul_f32_e32 v14, 0x3c800000, v0
	v_mul_f32_e32 v15, 0x3c800000, v1
	v_add_f32_e32 v3, v3, v167
	v_cvt_pk_bf16_f32 v14, v14, v15
	v_mul_f32_e32 v15, 0x3c800000, v2
	v_mul_f32_e32 v16, 0x3c800000, v3
	v_cvt_pk_bf16_f32 v15, v15, v16
	global_store_dwordx4 v[10:11], v[12:15], off offset:512 nt
	s_and_saveexec_b64 s[8:9], vcc
	s_cbranch_execz .LBB0_462
	v_mul_f32_e32 v4, v156, v4
	v_mul_f32_e32 v5, v156, v5
	v_cvt_pk_bf16_f32 v4, v4, v5
	v_mul_f32_e32 v5, v156, v6
	v_mul_f32_e32 v6, v156, v7
	v_mul_f32_e32 v0, v156, v0
	v_mul_f32_e32 v1, v156, v1
	v_cvt_pk_bf16_f32 v5, v5, v6
	v_cvt_pk_bf16_f32 v6, v0, v1
	v_mul_f32_e32 v0, v156, v2
	v_mul_f32_e32 v1, v156, v3
	v_cvt_pk_bf16_f32 v7, v0, v1
	v_lshl_add_u64 v[0:1], v[8:9], 0, v[136:137]
	global_store_dwordx4 v[0:1], v[4:7], off offset:512 nt

; __device__ __forceinline__ unsigned cvt_pk_bf16(float lo, float hi) { unsigned r; asm("v_cvt_pk_bf16_f32 %0, %1, %2" : "=v"(r) : "v"(lo), "v"(hi)); return r; }
;     __device__ __forceinline__ void operator()(const f32x4 (&acc)[2][2][4][2], const Unit& u, int wr, int wc, int fr, int fq, LAS unsigned char* xs, int wid, int lane) const {
;         const int S = lng ? 4096 : 2048, hp = lng ? 8 : 4;
;         const int cs = u.pm >= hp, k0 = (u.pm - hp * cs) * 256 + wr * 64;
;         const size_t tok0 = lng ? (size_t)TP + (size_t)u.aux * 4096 : (size_t)u.aux * 2048;
;         const float sc = lng ? 0.015625f : 0.02209708691207961f;
;         const float scm = cs ? -sc : sc;
;         float hv[2][8];
;         const float csm = cs ? 0.f : 1.f;
; #pragma unroll
;         for (int bj = 0; bj < 2; ++bj)
; #pragma unroll
;             for (int e = 0; e < 8; ++e) {
;                 const unsigned short h = ft[(size_t)(u.pn * 256 + bj * 128 + wc * 32 + 8 * fq + e) * T + tok0 + S / 2];
;                 const float v = __builtin_bit_cast(float, (unsigned)h << 16) * csm;
;                 hv[bj][e] = (fr & 1) ? -v : v;
;             }
; #pragma unroll
;         for (int ai = 0; ai < 2; ++ai)
; #pragma unroll
;             for (int m = 0; m < 4; ++m) {
;                 const int k = k0 + ai * 128 + m * 16 + fr;
; #pragma unroll
;                 for (int bj = 0; bj < 2; ++bj) {
;                     const int col = (2 * u.pn + bj) * 256 + cs * 128 + wc * 32 + 8 * fq;
;                     f32x4 a = acc[ai][bj][m][0], b = acc[ai][bj][m][1];
; #pragma unroll
;                     for (int j = 0; j < 4; ++j) { a[j] += hv[bj][j]; b[j] += hv[bj][4 + j]; }
;                     u32x4 w; w.x = cvt_pk_bf16(a[0] * sc, a[1] * sc); w.y = cvt_pk_bf16(a[2] * sc, a[3] * sc); w.z = cvt_pk_bf16(b[0] * sc, b[1] * sc); w.w = cvt_pk_bf16(b[2] * sc, b[3] * sc);
;                     *(u32x4*)(pq + (tok0 + k) * 1024 + col) = w;
;                     if (k > 0) {
;                         u32x4 w2; w2.x = cvt_pk_bf16(a[0] * scm, a[1] * scm); w2.y = cvt_pk_bf16(a[2] * scm, a[3] * scm); w2.z = cvt_pk_bf16(b[0] * scm, b[1] * scm); w2.w = cvt_pk_bf16(b[2] * scm, b[3] * scm);
;                         *(u32x4*)(pq + (tok0 + S - k) * 1024 + col) = w2;
.LBB0_480:
	s_lshl_b32 s8, s18, 8
	s_and_b32 s57, s8, 0x300
	s_ashr_i32 s63, s62, 31
	s_add_i32 s57, s57, s29
	s_lshl_b64 s[60:61], s[62:63], 11
	s_lshl_b64 s[8:9], s[62:63], 12
	s_add_u32 s8, s44, s8
	v_lshlrev_b32_e32 v136, 16, v150
	s_addc_u32 s9, s45, s9
	v_lshl_or_b32 v136, s0, 24, v136
	v_lshl_add_u64 v[146:147], s[8:9], 0, v[136:137]
	global_load_ushort v136, v136, s[8:9] offset:2048
	s_cmp_lt_u32 s18, 4
	s_cselect_b64 vcc, -1, 0
	s_mov_b32 s8, 0x10000
	v_cndmask_b32_e64 v167, 0, 1.0, vcc
	v_add_co_u32_e64 v158, s[8:9], s8, v146
	s_waitcnt vmcnt(0)
	v_lshlrev_b32_e32 v136, 16, v136
	v_mul_f32_e32 v136, v167, v136
	v_addc_co_u32_e64 v159, s[8:9], 0, v147, s[8:9]
	v_cndmask_b32_e64 v156, -v136, v136, s[4:5]
	global_load_ushort v136, v[158:159], off offset:2048
	s_mov_b32 s8, 0x20000
	v_add_co_u32_e64 v158, s[8:9], s8, v146
	s_waitcnt vmcnt(0)
	v_lshlrev_b32_e32 v136, 16, v136
	v_mul_f32_e32 v136, v167, v136
	v_addc_co_u32_e64 v159, s[8:9], 0, v147, s[8:9]
	v_cndmask_b32_e64 v157, -v136, v136, s[4:5]
	global_load_ushort v136, v[158:159], off offset:2048
	s_mov_b32 s8, 0x30000
	v_add_co_u32_e64 v160, s[8:9], s8, v146
	s_waitcnt vmcnt(0)
	v_lshlrev_b32_e32 v136, 16, v136
	v_mul_f32_e32 v136, v167, v136
	v_addc_co_u32_e64 v161, s[8:9], 0, v147, s[8:9]
	v_cndmask_b32_e64 v158, -v136, v136, s[4:5]
	global_load_ushort v136, v[160:161], off offset:2048
	s_mov_b32 s8, 0x40000
	v_add_co_u32_e64 v160, s[8:9], s8, v146
	s_waitcnt vmcnt(0)
	v_lshlrev_b32_e32 v136, 16, v136
	v_mul_f32_e32 v136, v167, v136
	v_addc_co_u32_e64 v161, s[8:9], 0, v147, s[8:9]
	v_cndmask_b32_e64 v159, -v136, v136, s[4:5]
	global_load_ushort v136, v[160:161], off offset:2048
	s_mov_b32 s8, 0x50000
	v_add_co_u32_e64 v162, s[8:9], s8, v146
	v_add_f32_e32 v176, v127, v159
	s_nop 0
	v_addc_co_u32_e64 v163, s[8:9], 0, v147, s[8:9]
	s_mov_b32 s8, 0x60000
	s_waitcnt vmcnt(0)
	v_lshlrev_b32_e32 v136, 16, v136
	v_mul_f32_e32 v136, v167, v136
	v_cndmask_b32_e64 v160, -v136, v136, s[4:5]
	global_load_ushort v136, v[162:163], off offset:2048
	v_add_co_u32_e64 v162, s[8:9], s8, v146
	s_waitcnt vmcnt(0)
	v_lshlrev_b32_e32 v136, 16, v136
	v_mul_f32_e32 v136, v167, v136
	v_addc_co_u32_e64 v163, s[8:9], 0, v147, s[8:9]
	v_cndmask_b32_e64 v161, -v136, v136, s[4:5]
	global_load_ushort v136, v[162:163], off offset:2048
	s_mov_b32 s8, 0x70000
	v_add_co_u32_e64 v164, s[8:9], s8, v146
	s_waitcnt vmcnt(0)
	v_lshlrev_b32_e32 v136, 16, v136
	v_addc_co_u32_e64 v165, s[8:9], 0, v147, s[8:9]
	v_mul_f32_e32 v136, v167, v136
	s_mov_b32 s8, 0x800000
	v_cndmask_b32_e64 v162, -v136, v136, s[4:5]
	global_load_ushort v136, v[164:165], off offset:2048
	v_add_co_u32_e64 v164, s[8:9], s8, v146
	s_waitcnt vmcnt(0)
	v_lshlrev_b32_e32 v136, 16, v136
	v_addc_co_u32_e64 v165, s[8:9], 0, v147, s[8:9]
	s_mov_b32 s8, 0x810000
	s_nop 0
	v_add_co_u32_e64 v168, s[8:9], s8, v146
	global_load_ushort v165, v[164:165], off offset:2048
	s_nop 0
	v_addc_co_u32_e64 v169, s[8:9], 0, v147, s[8:9]
	s_mov_b32 s8, 0x820000
	global_load_ushort v166, v[168:169], off offset:2048
	v_add_co_u32_e64 v168, s[8:9], s8, v146
	v_mul_f32_e32 v136, v167, v136
	s_nop 0
	v_addc_co_u32_e64 v169, s[8:9], 0, v147, s[8:9]
	s_mov_b32 s8, 0x830000
	s_nop 0
	v_add_co_u32_e64 v170, s[8:9], s8, v146
	global_load_ushort v168, v[168:169], off offset:2048
	s_nop 0
	v_addc_co_u32_e64 v171, s[8:9], 0, v147, s[8:9]
	s_mov_b32 s8, 0x840000
	global_load_ushort v169, v[170:171], off offset:2048
	v_add_co_u32_e64 v170, s[8:9], s8, v146
	v_cndmask_b32_e64 v163, -v136, v136, s[4:5]
	s_nop 0
	v_addc_co_u32_e64 v171, s[8:9], 0, v147, s[8:9]
	s_mov_b32 s8, 0x850000
	s_nop 0
	v_add_co_u32_e64 v172, s[8:9], s8, v146
	global_load_ushort v170, v[170:171], off offset:2048
	s_nop 0
	v_addc_co_u32_e64 v173, s[8:9], 0, v147, s[8:9]
	s_mov_b32 s8, 0x860000
	global_load_ushort v171, v[172:173], off offset:2048
	v_add_co_u32_e64 v172, s[8:9], s8, v146
	v_add_f32_e32 v127, v123, v163
	s_nop 0
	v_addc_co_u32_e64 v173, s[8:9], 0, v147, s[8:9]
	v_add_co_u32_e64 v146, s[8:9], s67, v146
	global_load_ushort v172, v[172:173], off offset:2048
	s_nop 0
	v_addc_co_u32_e64 v147, s[8:9], 0, v147, s[8:9]
	global_load_ushort v173, v[146:147], off offset:2048
	v_or_b32_e32 v146, s57, v148
	s_and_b64 s[8:9], vcc, exec
	s_cselect_b32 s62, 0, 0x80
	s_add_u32 s18, s60, 0x800
	v_ashrrev_i32_e32 v147, 31, v146
	s_addc_u32 s19, s61, 0
	v_lshl_add_u64 v[174:175], s[60:61], 0, v[146:147]
	v_lshlrev_b64 v[182:183], 11, v[174:175]
	v_sub_co_u32_e64 v174, s[8:9], s18, v146
	v_mov_b32_e32 v136, s19
	s_nop 0
	v_subb_co_u32_e64 v175, s[8:9], v136, v147, s[8:9]
	v_lshlrev_b64 v[184:185], 11, v[174:175]
	v_add_f32_e32 v147, v124, v156
	v_add_f32_e32 v174, v125, v157
	v_add_f32_e32 v124, v120, v160
	v_add_f32_e32 v125, v121, v161
	v_add_f32_e32 v175, v126, v158
	v_mul_f32_e32 v120, 0x3cb504f3, v147
	v_mul_f32_e32 v121, 0x3cb504f3, v174
	s_lshl_b32 s0, s0, 9
	v_cvt_pk_bf16_f32 v178, v120, v121
	v_mul_f32_e32 v120, 0x3cb504f3, v175
	v_mul_f32_e32 v121, 0x3cb504f3, v176
	v_add_f32_e32 v126, v122, v162
	s_or_b32 s0, s62, s0
	v_cvt_pk_bf16_f32 v179, v120, v121
	v_mul_f32_e32 v120, 0x3cb504f3, v124
	v_mul_f32_e32 v121, 0x3cb504f3, v125
	v_or_b32_e32 v122, s0, v150
	v_cvt_pk_bf16_f32 v180, v120, v121
	v_mul_f32_e32 v120, 0x3cb504f3, v126
	v_mul_f32_e32 v121, 0x3cb504f3, v127
	v_cvt_pk_bf16_f32 v181, v120, v121
	v_lshl_add_u64 v[120:121], s[10:11], 0, v[182:183]
	v_lshlrev_b32_e32 v136, 1, v122
	v_cndmask_b32_e32 v164, v154, v155, vcc
	v_cmp_lt_i32_e32 vcc, 0, v146
	v_lshl_add_u64 v[122:123], v[120:121], 0, v[136:137]
	v_lshl_add_u64 v[120:121], s[10:11], 0, v[184:185]
	global_store_dwordx4 v[122:123], v[178:181], off nt
	s_and_saveexec_b64 s[8:9], vcc
	s_cbranch_execz .LBB0_482
	v_mul_f32_e32 v147, v164, v147
	v_mul_f32_e32 v174, v164, v174
	v_mul_f32_e32 v124, v164, v124
	v_mul_f32_e32 v125, v164, v125
	v_cvt_pk_bf16_f32 v174, v147, v174
	v_mul_f32_e32 v147, v164, v175
	v_mul_f32_e32 v175, v164, v176
	v_cvt_pk_bf16_f32 v176, v124, v125
	v_mul_f32_e32 v124, v164, v126
	v_mul_f32_e32 v125, v164, v127
	v_cvt_pk_bf16_f32 v177, v124, v125
	v_lshl_add_u64 v[124:125], v[120:121], 0, v[136:137]
	v_cvt_pk_bf16_f32 v175, v147, v175
	global_store_dwordx4 v[124:125], v[174:177], off nt
; __device__ __forceinline__ unsigned cvt_pk_bf16(float lo, float hi) { unsigned r; asm("v_cvt_pk_bf16_f32 %0, %1, %2" : "=v"(r) : "v"(lo), "v"(hi)); return r; }
;     __device__ __forceinline__ void operator()(const f32x4 (&acc)[2][2][4][2], const Unit& u, int wr, int wc, int fr, int fq, LAS unsigned char* xs, int wid, int lane) const {
;     ...
; #pragma unroll
;         for (int ai = 0; ai < 2; ++ai)
; #pragma unroll
;             for (int m = 0; m < 4; ++m) {
;                 const int k = k0 + ai * 128 + m * 16 + fr;
; #pragma unroll
;                 for (int bj = 0; bj < 2; ++bj) {
;                     const int col = (2 * u.pn + bj) * 256 + cs * 128 + wc * 32 + 8 * fq;
;                     f32x4 a = acc[ai][bj][m][0], b = acc[ai][bj][m][1];
; #pragma unroll
;                     for (int j = 0; j < 4; ++j) { a[j] += hv[bj][j]; b[j] += hv[bj][4 + j]; }
;                     u32x4 w; w.x = cvt_pk_bf16(a[0] * sc, a[1] * sc); w.y = cvt_pk_bf16(a[2] * sc, a[3] * sc); w.z = cvt_pk_bf16(b[0] * sc, b[1] * sc); w.w = cvt_pk_bf16(b[2] * sc, b[3] * sc);
;                     *(u32x4*)(pq + (tok0 + k) * 1024 + col) = w;
;                     if (k > 0) {
;                         u32x4 w2; w2.x = cvt_pk_bf16(a[0] * scm, a[1] * scm); w2.y = cvt_pk_bf16(a[2] * scm, a[3] * scm); w2.z = cvt_pk_bf16(b[0] * scm, b[1] * scm); w2.w = cvt_pk_bf16(b[2] * scm, b[3] * scm);
;                         *(u32x4*)(pq + (tok0 + S - k) * 1024 + col) = w2;
;                     }
;                 }
;                 __builtin_amdgcn_sched_barrier(0);
.LBB0_482:
	s_or_b64 exec, exec, s[8:9]
	s_waitcnt vmcnt(8)
	v_lshlrev_b32_e32 v124, 16, v165
	s_waitcnt vmcnt(7)
	v_lshlrev_b32_e32 v125, 16, v166
	v_mul_f32_e32 v124, v167, v124
	v_mul_f32_e32 v125, v167, v125
	s_waitcnt vmcnt(6)
	v_lshlrev_b32_e32 v126, 16, v168
	s_waitcnt vmcnt(5)
	v_lshlrev_b32_e32 v127, 16, v169
	v_cndmask_b32_e64 v124, -v124, v124, s[4:5]
	v_cndmask_b32_e64 v125, -v125, v125, s[4:5]
	v_mul_f32_e32 v126, v167, v126
	v_mul_f32_e32 v127, v167, v127
	s_waitcnt vmcnt(4)
	v_lshlrev_b32_e32 v147, 16, v170
	s_waitcnt vmcnt(3)
	v_lshlrev_b32_e32 v165, 16, v171
	v_cndmask_b32_e64 v126, -v126, v126, s[4:5]
	v_cndmask_b32_e64 v127, -v127, v127, s[4:5]
	v_mul_f32_e32 v147, v167, v147
	v_mul_f32_e32 v165, v167, v165
	s_waitcnt vmcnt(2)
	v_lshlrev_b32_e32 v166, 16, v172
	s_waitcnt vmcnt(1)
	v_lshlrev_b32_e32 v168, 16, v173
	v_add_f32_e32 v116, v116, v124
	v_add_f32_e32 v117, v117, v125
	v_cndmask_b32_e64 v147, -v147, v147, s[4:5]
	v_cndmask_b32_e64 v165, -v165, v165, s[4:5]
	v_mul_f32_e32 v166, v167, v166
	v_mul_f32_e32 v167, v167, v168
	v_add_f32_e32 v118, v118, v126
	v_add_f32_e32 v119, v119, v127
	v_mul_f32_e32 v168, 0x3cb504f3, v116
	v_mul_f32_e32 v169, 0x3cb504f3, v117
	v_cndmask_b32_e64 v166, -v166, v166, s[4:5]
	v_add_f32_e32 v112, v112, v147
	v_add_f32_e32 v113, v113, v165
	v_cvt_pk_bf16_f32 v168, v168, v169
	v_mul_f32_e32 v169, 0x3cb504f3, v118
	v_mul_f32_e32 v170, 0x3cb504f3, v119
	v_cndmask_b32_e64 v167, -v167, v167, s[4:5]
	v_add_f32_e32 v114, v114, v166
	v_cvt_pk_bf16_f32 v169, v169, v170
	v_mul_f32_e32 v170, 0x3cb504f3, v112
	v_mul_f32_e32 v171, 0x3cb504f3, v113
	v_add_f32_e32 v115, v115, v167
	v_cvt_pk_bf16_f32 v170, v170, v171
	v_mul_f32_e32 v171, 0x3cb504f3, v114
	v_mul_f32_e32 v172, 0x3cb504f3, v115
	v_cvt_pk_bf16_f32 v171, v171, v172
	global_store_dwordx4 v[122:123], v[168:171], off offset:512 nt
	s_and_saveexec_b64 s[8:9], vcc
	s_cbranch_execz .LBB0_484
	v_mul_f32_e32 v116, v164, v116
	v_mul_f32_e32 v117, v164, v117
	v_cvt_pk_bf16_f32 v116, v116, v117
	v_mul_f32_e32 v117, v164, v118
	v_mul_f32_e32 v118, v164, v119
	v_mul_f32_e32 v112, v164, v112
	v_mul_f32_e32 v113, v164, v113
	v_cvt_pk_bf16_f32 v117, v117, v118
	v_cvt_pk_bf16_f32 v118, v112, v113
	v_mul_f32_e32 v112, v164, v114
	v_mul_f32_e32 v113, v164, v115
	v_cvt_pk_bf16_f32 v119, v112, v113
	v_lshl_add_u64 v[112:113], v[120:121], 0, v[136:137]
	global_store_dwordx4 v[112:113], v[116:119], off offset:512 nt
.LBB0_484:
	s_or_b64 exec, exec, s[8:9]
	v_or_b32_e32 v112, 16, v146
	v_ashrrev_i32_e32 v113, 31, v112
	v_lshl_add_u64 v[114:115], s[60:61], 0, v[112:113]
	v_lshlrev_b64 v[120:121], 11, v[114:115]
	v_mov_b32_e32 v114, s19
	v_sub_co_u32_e32 v112, vcc, s18, v112
	v_add_f32_e32 v115, v111, v159
	s_nop 0
	v_subb_co_u32_e32 v113, vcc, v114, v113, vcc
	v_lshlrev_b64 v[122:123], 11, v[112:113]
	v_add_f32_e32 v112, v108, v156
	v_add_f32_e32 v113, v109, v157
	v_add_f32_e32 v108, v104, v160
	v_add_f32_e32 v109, v105, v161
	v_add_f32_e32 v114, v110, v158
	v_mul_f32_e32 v104, 0x3cb504f3, v112
	v_mul_f32_e32 v105, 0x3cb504f3, v113
	v_cvt_pk_bf16_f32 v116, v104, v105
	v_mul_f32_e32 v104, 0x3cb504f3, v114
	v_mul_f32_e32 v105, 0x3cb504f3, v115
	v_add_f32_e32 v110, v106, v162
	v_add_f32_e32 v111, v107, v163
	v_cvt_pk_bf16_f32 v117, v104, v105
	v_mul_f32_e32 v104, 0x3cb504f3, v108
	v_mul_f32_e32 v105, 0x3cb504f3, v109
	v_cvt_pk_bf16_f32 v118, v104, v105
	v_mul_f32_e32 v104, 0x3cb504f3, v110
	v_mul_f32_e32 v105, 0x3cb504f3, v111
	s_cmp_gt_i32 s57, -1
	v_cvt_pk_bf16_f32 v119, v104, v105
	v_lshl_add_u64 v[104:105], s[10:11], 0, v[120:121]
	s_cselect_b64 s[62:63], -1, 0
	s_cmp_lt_i32 s57, 0
	v_lshl_add_u64 v[106:107], v[104:105], 0, v[136:137]
	v_lshl_add_u64 v[104:105], s[10:11], 0, v[122:123]
	global_store_dwordx4 v[106:107], v[116:119], off nt
	s_cbranch_scc1 .LBB0_486
	v_mul_f32_e32 v112, v164, v112
	v_mul_f32_e32 v113, v164, v113
	v_cvt_pk_bf16_f32 v112, v112, v113
	v_mul_f32_e32 v113, v164, v114
	v_mul_f32_e32 v114, v164, v115
	v_mul_f32_e32 v108, v164, v108
	v_mul_f32_e32 v109, v164, v109
	v_cvt_pk_bf16_f32 v113, v113, v114
	v_cvt_pk_bf16_f32 v114, v108, v109
	v_mul_f32_e32 v108, v164, v110
	v_mul_f32_e32 v109, v164, v111
	v_cvt_pk_bf16_f32 v115, v108, v109
	v_lshl_add_u64 v[108:109], v[104:105], 0, v[136:137]
	global_store_dwordx4 v[108:109], v[112:115], off nt
.LBB0_486:
	v_add_f32_e32 v100, v100, v124
	v_add_f32_e32 v101, v101, v125
	v_add_f32_e32 v102, v102, v126
	v_add_f32_e32 v103, v103, v127
	v_mul_f32_e32 v108, 0x3cb504f3, v100
	v_mul_f32_e32 v109, 0x3cb504f3, v101
	v_add_f32_e32 v96, v96, v147
	v_add_f32_e32 v97, v97, v165
	v_cvt_pk_bf16_f32 v108, v108, v109
	v_mul_f32_e32 v109, 0x3cb504f3, v102
	v_mul_f32_e32 v110, 0x3cb504f3, v103
	v_add_f32_e32 v98, v98, v166
	v_add_f32_e32 v99, v99, v167
	v_cvt_pk_bf16_f32 v109, v109, v110
	v_mul_f32_e32 v110, 0x3cb504f3, v96
	v_mul_f32_e32 v111, 0x3cb504f3, v97
	v_cvt_pk_bf16_f32 v110, v110, v111
	v_mul_f32_e32 v111, 0x3cb504f3, v98
	v_mul_f32_e32 v112, 0x3cb504f3, v99
	v_cvt_pk_bf16_f32 v111, v111, v112
	v_cndmask_b32_e64 v112, 0, 1, s[62:63]
	v_cmp_ne_u32_e64 s[8:9], 1, v112
	s_andn2_b64 vcc, exec, s[62:63]
	global_store_dwordx4 v[106:107], v[108:111], off offset:512 nt
	s_cbranch_vccnz .LBB0_488
	v_mul_f32_e32 v100, v164, v100
	v_mul_f32_e32 v101, v164, v101
	v_cvt_pk_bf16_f32 v100, v100, v101
	v_mul_f32_e32 v101, v164, v102
	v_mul_f32_e32 v102, v164, v103
	v_mul_f32_e32 v96, v164, v96
	v_mul_f32_e32 v97, v164, v97
	v_cvt_pk_bf16_f32 v101, v101, v102
	v_cvt_pk_bf16_f32 v102, v96, v97
	v_mul_f32_e32 v96, v164, v98
	v_mul_f32_e32 v97, v164, v99
	v_cvt_pk_bf16_f32 v103, v96, v97
	v_lshl_add_u64 v[96:97], v[104:105], 0, v[136:137]
	global_store_dwordx4 v[96:97], v[100:103], off offset:512 nt
; __device__ __forceinline__ unsigned cvt_pk_bf16(float lo, float hi) { unsigned r; asm("v_cvt_pk_bf16_f32 %0, %1, %2" : "=v"(r) : "v"(lo), "v"(hi)); return r; }
;     __device__ __forceinline__ void operator()(const f32x4 (&acc)[2][2][4][2], const Unit& u, int wr, int wc, int fr, int fq, LAS unsigned char* xs, int wid, int lane) const {
;     ...
; #pragma unroll
;         for (int ai = 0; ai < 2; ++ai)
; #pragma unroll
;             for (int m = 0; m < 4; ++m) {
;                 const int k = k0 + ai * 128 + m * 16 + fr;
; #pragma unroll
;                 for (int bj = 0; bj < 2; ++bj) {
;                     const int col = (2 * u.pn + bj) * 256 + cs * 128 + wc * 32 + 8 * fq;
;                     f32x4 a = acc[ai][bj][m][0], b = acc[ai][bj][m][1];
; #pragma unroll
;                     for (int j = 0; j < 4; ++j) { a[j] += hv[bj][j]; b[j] += hv[bj][4 + j]; }
;                     u32x4 w; w.x = cvt_pk_bf16(a[0] * sc, a[1] * sc); w.y = cvt_pk_bf16(a[2] * sc, a[3] * sc); w.z = cvt_pk_bf16(b[0] * sc, b[1] * sc); w.w = cvt_pk_bf16(b[2] * sc, b[3] * sc);
;                     *(u32x4*)(pq + (tok0 + k) * 1024 + col) = w;
;                     if (k > 0) {
;                         u32x4 w2; w2.x = cvt_pk_bf16(a[0] * scm, a[1] * scm); w2.y = cvt_pk_bf16(a[2] * scm, a[3] * scm); w2.z = cvt_pk_bf16(b[0] * scm, b[1] * scm); w2.w = cvt_pk_bf16(b[2] * scm, b[3] * scm);
;                         *(u32x4*)(pq + (tok0 + S - k) * 1024 + col) = w2;
;                     }
;                 }
;                 __builtin_amdgcn_sched_barrier(0);
.LBB0_488:
	v_or_b32_e32 v96, 32, v146
	v_ashrrev_i32_e32 v97, 31, v96
	v_lshl_add_u64 v[98:99], s[60:61], 0, v[96:97]
	v_lshlrev_b64 v[104:105], 11, v[98:99]
	v_mov_b32_e32 v98, s19
	v_sub_co_u32_e32 v96, vcc, s18, v96
	v_add_f32_e32 v99, v95, v159
	s_nop 0
	v_subb_co_u32_e32 v97, vcc, v98, v97, vcc
	v_lshlrev_b64 v[106:107], 11, v[96:97]
	v_add_f32_e32 v96, v92, v156
	v_add_f32_e32 v97, v93, v157
	v_add_f32_e32 v92, v88, v160
	v_add_f32_e32 v93, v89, v161
	v_add_f32_e32 v98, v94, v158
	v_mul_f32_e32 v88, 0x3cb504f3, v96
	v_mul_f32_e32 v89, 0x3cb504f3, v97
	v_cvt_pk_bf16_f32 v100, v88, v89
	v_mul_f32_e32 v88, 0x3cb504f3, v98
	v_mul_f32_e32 v89, 0x3cb504f3, v99
	v_add_f32_e32 v94, v90, v162
	v_add_f32_e32 v95, v91, v163
	v_cvt_pk_bf16_f32 v101, v88, v89
	v_mul_f32_e32 v88, 0x3cb504f3, v92
	v_mul_f32_e32 v89, 0x3cb504f3, v93
	v_cvt_pk_bf16_f32 v102, v88, v89
	v_mul_f32_e32 v88, 0x3cb504f3, v94
	v_mul_f32_e32 v89, 0x3cb504f3, v95
	v_cvt_pk_bf16_f32 v103, v88, v89
	v_lshl_add_u64 v[88:89], s[10:11], 0, v[104:105]
	v_lshl_add_u64 v[90:91], v[88:89], 0, v[136:137]
	s_and_b64 vcc, exec, s[8:9]
	v_lshl_add_u64 v[88:89], s[10:11], 0, v[106:107]
	global_store_dwordx4 v[90:91], v[100:103], off nt
	s_cbranch_vccnz .LBB0_490
	v_mul_f32_e32 v96, v164, v96
	v_mul_f32_e32 v97, v164, v97
	v_cvt_pk_bf16_f32 v96, v96, v97
	v_mul_f32_e32 v97, v164, v98
	v_mul_f32_e32 v98, v164, v99
	v_mul_f32_e32 v92, v164, v92
	v_mul_f32_e32 v93, v164, v93
	v_cvt_pk_bf16_f32 v97, v97, v98
	v_cvt_pk_bf16_f32 v98, v92, v93
	v_mul_f32_e32 v92, v164, v94
	v_mul_f32_e32 v93, v164, v95
	v_cvt_pk_bf16_f32 v99, v92, v93
	v_lshl_add_u64 v[92:93], v[88:89], 0, v[136:137]
	global_store_dwordx4 v[92:93], v[96:99], off nt
.LBB0_490:
	v_add_f32_e32 v84, v84, v124
	v_add_f32_e32 v85, v85, v125
	v_add_f32_e32 v86, v86, v126
	v_add_f32_e32 v87, v87, v127
	v_mul_f32_e32 v92, 0x3cb504f3, v84
	v_mul_f32_e32 v93, 0x3cb504f3, v85
	v_add_f32_e32 v80, v80, v147
	v_add_f32_e32 v81, v81, v165
	v_cvt_pk_bf16_f32 v92, v92, v93
	v_mul_f32_e32 v93, 0x3cb504f3, v86
	v_mul_f32_e32 v94, 0x3cb504f3, v87
	v_add_f32_e32 v82, v82, v166
	v_cvt_pk_bf16_f32 v93, v93, v94
	v_mul_f32_e32 v94, 0x3cb504f3, v80
	v_mul_f32_e32 v95, 0x3cb504f3, v81
	v_add_f32_e32 v83, v83, v167
	v_cvt_pk_bf16_f32 v94, v94, v95
	v_mul_f32_e32 v95, 0x3cb504f3, v82
	s_and_b64 vcc, exec, s[8:9]
	v_mul_f32_e32 v96, 0x3cb504f3, v83
	v_cvt_pk_bf16_f32 v95, v95, v96
	global_store_dwordx4 v[90:91], v[92:95], off offset:512 nt
	s_cbranch_vccnz .LBB0_492
	v_mul_f32_e32 v84, v164, v84
	v_mul_f32_e32 v85, v164, v85
	v_cvt_pk_bf16_f32 v84, v84, v85
	v_mul_f32_e32 v85, v164, v86
	v_mul_f32_e32 v86, v164, v87
	v_mul_f32_e32 v80, v164, v80
	v_mul_f32_e32 v81, v164, v81
	v_cvt_pk_bf16_f32 v85, v85, v86
	v_cvt_pk_bf16_f32 v86, v80, v81
	v_mul_f32_e32 v80, v164, v82
	v_mul_f32_e32 v81, v164, v83
	v_cvt_pk_bf16_f32 v87, v80, v81
	v_lshl_add_u64 v[80:81], v[88:89], 0, v[136:137]
	global_store_dwordx4 v[80:81], v[84:87], off offset:512 nt
.LBB0_492:
	v_or_b32_e32 v80, 48, v146
	v_ashrrev_i32_e32 v81, 31, v80
	v_lshl_add_u64 v[82:83], s[60:61], 0, v[80:81]
	v_lshlrev_b64 v[88:89], 11, v[82:83]
	v_mov_b32_e32 v82, s19
	v_sub_co_u32_e32 v80, vcc, s18, v80
	v_add_f32_e32 v83, v79, v159
	s_nop 0
	v_subb_co_u32_e32 v81, vcc, v82, v81, vcc
	v_lshlrev_b64 v[90:91], 11, v[80:81]
	v_add_f32_e32 v80, v76, v156
	v_add_f32_e32 v81, v77, v157
	v_add_f32_e32 v76, v72, v160
	v_add_f32_e32 v77, v73, v161
	v_add_f32_e32 v82, v78, v158
	v_mul_f32_e32 v72, 0x3cb504f3, v80
	v_mul_f32_e32 v73, 0x3cb504f3, v81
	v_cvt_pk_bf16_f32 v84, v72, v73
	v_mul_f32_e32 v72, 0x3cb504f3, v82
	v_mul_f32_e32 v73, 0x3cb504f3, v83
	v_add_f32_e32 v78, v74, v162
	v_add_f32_e32 v79, v75, v163
	v_cvt_pk_bf16_f32 v85, v72, v73
	v_mul_f32_e32 v72, 0x3cb504f3, v76
	v_mul_f32_e32 v73, 0x3cb504f3, v77
	v_cvt_pk_bf16_f32 v86, v72, v73
	v_mul_f32_e32 v72, 0x3cb504f3, v78
	v_mul_f32_e32 v73, 0x3cb504f3, v79
	v_cvt_pk_bf16_f32 v87, v72, v73
	v_lshl_add_u64 v[72:73], s[10:11], 0, v[88:89]
	v_lshl_add_u64 v[74:75], v[72:73], 0, v[136:137]
	s_and_b64 vcc, exec, s[8:9]
	v_lshl_add_u64 v[72:73], s[10:11], 0, v[90:91]
	global_store_dwordx4 v[74:75], v[84:87], off nt
	s_cbranch_vccnz .LBB0_494
	v_mul_f32_e32 v80, v164, v80
	v_mul_f32_e32 v81, v164, v81
	v_cvt_pk_bf16_f32 v80, v80, v81
	v_mul_f32_e32 v81, v164, v82
	v_mul_f32_e32 v82, v164, v83
	v_mul_f32_e32 v76, v164, v76
	v_mul_f32_e32 v77, v164, v77
	v_cvt_pk_bf16_f32 v81, v81, v82
	v_cvt_pk_bf16_f32 v82, v76, v77
	v_mul_f32_e32 v76, v164, v78
	v_mul_f32_e32 v77, v164, v79
	v_cvt_pk_bf16_f32 v83, v76, v77
	v_lshl_add_u64 v[76:77], v[72:73], 0, v[136:137]
	global_store_dwordx4 v[76:77], v[80:83], off nt
.LBB0_494:
	v_add_f32_e32 v68, v68, v124
	v_add_f32_e32 v69, v69, v125
	v_add_f32_e32 v70, v70, v126
	v_add_f32_e32 v71, v71, v127
	v_mul_f32_e32 v76, 0x3cb504f3, v68
	v_mul_f32_e32 v77, 0x3cb504f3, v69
	v_add_f32_e32 v64, v64, v147
	v_add_f32_e32 v65, v65, v165
	v_cvt_pk_bf16_f32 v76, v76, v77
	v_mul_f32_e32 v77, 0x3cb504f3, v70
	v_mul_f32_e32 v78, 0x3cb504f3, v71
	v_add_f32_e32 v66, v66, v166
	v_cvt_pk_bf16_f32 v77, v77, v78
	v_mul_f32_e32 v78, 0x3cb504f3, v64
	v_mul_f32_e32 v79, 0x3cb504f3, v65
	v_add_f32_e32 v67, v67, v167
	v_cvt_pk_bf16_f32 v78, v78, v79
	v_mul_f32_e32 v79, 0x3cb504f3, v66
	s_and_b64 vcc, exec, s[8:9]
	v_mul_f32_e32 v80, 0x3cb504f3, v67
	v_cvt_pk_bf16_f32 v79, v79, v80
	global_store_dwordx4 v[74:75], v[76:79], off offset:512 nt
	s_cbranch_vccnz .LBB0_496
	v_mul_f32_e32 v68, v164, v68
	v_mul_f32_e32 v69, v164, v69
	v_cvt_pk_bf16_f32 v68, v68, v69
	v_mul_f32_e32 v69, v164, v70
	v_mul_f32_e32 v70, v164, v71
	v_mul_f32_e32 v64, v164, v64
	v_mul_f32_e32 v65, v164, v65
	v_cvt_pk_bf16_f32 v69, v69, v70
	v_cvt_pk_bf16_f32 v70, v64, v65
	v_mul_f32_e32 v64, v164, v66
	v_mul_f32_e32 v65, v164, v67
	v_cvt_pk_bf16_f32 v71, v64, v65
	v_lshl_add_u64 v[64:65], v[72:73], 0, v[136:137]
	global_store_dwordx4 v[64:65], v[68:71], off offset:512 nt
; __device__ __forceinline__ unsigned cvt_pk_bf16(float lo, float hi) { unsigned r; asm("v_cvt_pk_bf16_f32 %0, %1, %2" : "=v"(r) : "v"(lo), "v"(hi)); return r; }
;     __device__ __forceinline__ void operator()(const f32x4 (&acc)[2][2][4][2], const Unit& u, int wr, int wc, int fr, int fq, LAS unsigned char* xs, int wid, int lane) const {
;     ...
; #pragma unroll
;         for (int ai = 0; ai < 2; ++ai)
; #pragma unroll
;             for (int m = 0; m < 4; ++m) {
;                 const int k = k0 + ai * 128 + m * 16 + fr;
; #pragma unroll
;                 for (int bj = 0; bj < 2; ++bj) {
;                     const int col = (2 * u.pn + bj) * 256 + cs * 128 + wc * 32 + 8 * fq;
;                     f32x4 a = acc[ai][bj][m][0], b = acc[ai][bj][m][1];
; #pragma unroll
;                     for (int j = 0; j < 4; ++j) { a[j] += hv[bj][j]; b[j] += hv[bj][4 + j]; }
;                     u32x4 w; w.x = cvt_pk_bf16(a[0] * sc, a[1] * sc); w.y = cvt_pk_bf16(a[2] * sc, a[3] * sc); w.z = cvt_pk_bf16(b[0] * sc, b[1] * sc); w.w = cvt_pk_bf16(b[2] * sc, b[3] * sc);
;                     *(u32x4*)(pq + (tok0 + k) * 1024 + col) = w;
;                     if (k > 0) {
;                         u32x4 w2; w2.x = cvt_pk_bf16(a[0] * scm, a[1] * scm); w2.y = cvt_pk_bf16(a[2] * scm, a[3] * scm); w2.z = cvt_pk_bf16(b[0] * scm, b[1] * scm); w2.w = cvt_pk_bf16(b[2] * scm, b[3] * scm);
;                         *(u32x4*)(pq + (tok0 + S - k) * 1024 + col) = w2;
;                     }
;                 }
;                 __builtin_amdgcn_sched_barrier(0);
.LBB0_496:
	v_add_u32_e32 v64, 0x80, v146
	v_ashrrev_i32_e32 v65, 31, v64
	v_lshl_add_u64 v[66:67], s[60:61], 0, v[64:65]
	v_lshlrev_b64 v[72:73], 11, v[66:67]
	v_mov_b32_e32 v66, s19
	v_sub_co_u32_e64 v64, s[8:9], s18, v64
	v_add_f32_e32 v67, v63, v159
	s_nop 0
	v_subb_co_u32_e64 v65, s[8:9], v66, v65, s[8:9]
	v_lshlrev_b64 v[74:75], 11, v[64:65]
	v_add_f32_e32 v64, v60, v156
	v_add_f32_e32 v65, v61, v157
	v_add_f32_e32 v60, v56, v160
	v_add_f32_e32 v61, v57, v161
	v_add_f32_e32 v66, v62, v158
	v_mul_f32_e32 v56, 0x3cb504f3, v64
	v_mul_f32_e32 v57, 0x3cb504f3, v65
	v_cvt_pk_bf16_f32 v68, v56, v57
	v_mul_f32_e32 v56, 0x3cb504f3, v66
	v_mul_f32_e32 v57, 0x3cb504f3, v67
	v_add_f32_e32 v62, v58, v162
	v_add_f32_e32 v63, v59, v163
	v_cvt_pk_bf16_f32 v69, v56, v57
	v_mul_f32_e32 v56, 0x3cb504f3, v60
	v_mul_f32_e32 v57, 0x3cb504f3, v61
	v_cvt_pk_bf16_f32 v70, v56, v57
	v_mul_f32_e32 v56, 0x3cb504f3, v62
	v_mul_f32_e32 v57, 0x3cb504f3, v63
	v_cvt_pk_bf16_f32 v71, v56, v57
	v_lshl_add_u64 v[56:57], s[10:11], 0, v[72:73]
	v_cmp_lt_i32_e32 vcc, s68, v146
	v_lshl_add_u64 v[58:59], v[56:57], 0, v[136:137]
	v_lshl_add_u64 v[56:57], s[10:11], 0, v[74:75]
	global_store_dwordx4 v[58:59], v[68:71], off nt
	s_and_saveexec_b64 s[8:9], vcc
	s_cbranch_execz .LBB0_498
	v_mul_f32_e32 v64, v164, v64
	v_mul_f32_e32 v65, v164, v65
	v_cvt_pk_bf16_f32 v64, v64, v65
	v_mul_f32_e32 v65, v164, v66
	v_mul_f32_e32 v66, v164, v67
	v_mul_f32_e32 v60, v164, v60
	v_mul_f32_e32 v61, v164, v61
	v_cvt_pk_bf16_f32 v65, v65, v66
	v_cvt_pk_bf16_f32 v66, v60, v61
	v_mul_f32_e32 v60, v164, v62
	v_mul_f32_e32 v61, v164, v63
	v_cvt_pk_bf16_f32 v67, v60, v61
	v_lshl_add_u64 v[60:61], v[56:57], 0, v[136:137]
	global_store_dwordx4 v[60:61], v[64:67], off nt
.LBB0_498:
	s_or_b64 exec, exec, s[8:9]
	v_add_f32_e32 v52, v52, v124
	v_add_f32_e32 v53, v53, v125
	v_add_f32_e32 v54, v54, v126
	v_add_f32_e32 v55, v55, v127
	v_mul_f32_e32 v60, 0x3cb504f3, v52
	v_mul_f32_e32 v61, 0x3cb504f3, v53
	v_add_f32_e32 v48, v48, v147
	v_add_f32_e32 v49, v49, v165
	v_cvt_pk_bf16_f32 v60, v60, v61
	v_mul_f32_e32 v61, 0x3cb504f3, v54
	v_mul_f32_e32 v62, 0x3cb504f3, v55
	v_add_f32_e32 v50, v50, v166
	v_cvt_pk_bf16_f32 v61, v61, v62
	v_mul_f32_e32 v62, 0x3cb504f3, v48
	v_mul_f32_e32 v63, 0x3cb504f3, v49
	v_add_f32_e32 v51, v51, v167
	v_cvt_pk_bf16_f32 v62, v62, v63
	v_mul_f32_e32 v63, 0x3cb504f3, v50
	v_mul_f32_e32 v64, 0x3cb504f3, v51
	v_cvt_pk_bf16_f32 v63, v63, v64
	global_store_dwordx4 v[58:59], v[60:63], off offset:512 nt
	s_and_saveexec_b64 s[8:9], vcc
	s_cbranch_execz .LBB0_500
	v_mul_f32_e32 v52, v164, v52
	v_mul_f32_e32 v53, v164, v53
	v_cvt_pk_bf16_f32 v52, v52, v53
	v_mul_f32_e32 v53, v164, v54
	v_mul_f32_e32 v54, v164, v55
	v_mul_f32_e32 v48, v164, v48
	v_mul_f32_e32 v49, v164, v49
	v_cvt_pk_bf16_f32 v53, v53, v54
	v_cvt_pk_bf16_f32 v54, v48, v49
	v_mul_f32_e32 v48, v164, v50
	v_mul_f32_e32 v49, v164, v51
	v_cvt_pk_bf16_f32 v55, v48, v49
	v_lshl_add_u64 v[48:49], v[56:57], 0, v[136:137]
	global_store_dwordx4 v[48:49], v[52:55], off offset:512 nt
.LBB0_500:
	s_or_b64 exec, exec, s[8:9]
	v_add_u32_e32 v48, 0x90, v146
	v_ashrrev_i32_e32 v49, 31, v48
	v_lshl_add_u64 v[50:51], s[60:61], 0, v[48:49]
	v_lshlrev_b64 v[56:57], 11, v[50:51]
	v_mov_b32_e32 v50, s19
	v_sub_co_u32_e64 v48, s[8:9], s18, v48
	v_add_f32_e32 v51, v47, v159
	s_nop 0
	v_subb_co_u32_e64 v49, s[8:9], v50, v49, s[8:9]
	v_lshlrev_b64 v[58:59], 11, v[48:49]
	v_add_f32_e32 v48, v44, v156
	v_add_f32_e32 v49, v45, v157
	v_add_f32_e32 v44, v40, v160
	v_add_f32_e32 v45, v41, v161
	v_add_f32_e32 v50, v46, v158
	v_mul_f32_e32 v40, 0x3cb504f3, v48
	v_mul_f32_e32 v41, 0x3cb504f3, v49
	v_cvt_pk_bf16_f32 v52, v40, v41
	v_mul_f32_e32 v40, 0x3cb504f3, v50
	v_mul_f32_e32 v41, 0x3cb504f3, v51
	v_add_f32_e32 v46, v42, v162
	v_add_f32_e32 v47, v43, v163
	v_cvt_pk_bf16_f32 v53, v40, v41
	v_mul_f32_e32 v40, 0x3cb504f3, v44
	v_mul_f32_e32 v41, 0x3cb504f3, v45
	v_cvt_pk_bf16_f32 v54, v40, v41
	v_mul_f32_e32 v40, 0x3cb504f3, v46
	v_mul_f32_e32 v41, 0x3cb504f3, v47
	v_cvt_pk_bf16_f32 v55, v40, v41
	v_lshl_add_u64 v[40:41], s[10:11], 0, v[56:57]
	v_cmp_lt_i32_e32 vcc, s69, v146
	v_lshl_add_u64 v[42:43], v[40:41], 0, v[136:137]
	v_lshl_add_u64 v[40:41], s[10:11], 0, v[58:59]
	global_store_dwordx4 v[42:43], v[52:55], off nt
	s_and_saveexec_b64 s[8:9], vcc
	s_cbranch_execz .LBB0_502
	v_mul_f32_e32 v48, v164, v48
	v_mul_f32_e32 v49, v164, v49
	v_cvt_pk_bf16_f32 v48, v48, v49
	v_mul_f32_e32 v49, v164, v50
	v_mul_f32_e32 v50, v164, v51
	v_mul_f32_e32 v44, v164, v44
	v_mul_f32_e32 v45, v164, v45
	v_cvt_pk_bf16_f32 v49, v49, v50
	v_cvt_pk_bf16_f32 v50, v44, v45
	v_mul_f32_e32 v44, v164, v46
	v_mul_f32_e32 v45, v164, v47
	v_cvt_pk_bf16_f32 v51, v44, v45
	v_lshl_add_u64 v[44:45], v[40:41], 0, v[136:137]
	global_store_dwordx4 v[44:45], v[48:51], off nt
.LBB0_502:
	s_or_b64 exec, exec, s[8:9]
	v_add_f32_e32 v36, v36, v124
	v_add_f32_e32 v37, v37, v125
	v_add_f32_e32 v38, v38, v126
	v_add_f32_e32 v39, v39, v127
	v_mul_f32_e32 v44, 0x3cb504f3, v36
	v_mul_f32_e32 v45, 0x3cb504f3, v37
	v_add_f32_e32 v32, v32, v147
	v_add_f32_e32 v33, v33, v165
	v_cvt_pk_bf16_f32 v44, v44, v45
	v_mul_f32_e32 v45, 0x3cb504f3, v38
	v_mul_f32_e32 v46, 0x3cb504f3, v39
	v_add_f32_e32 v34, v34, v166
	v_cvt_pk_bf16_f32 v45, v45, v46
	v_mul_f32_e32 v46, 0x3cb504f3, v32
	v_mul_f32_e32 v47, 0x3cb504f3, v33
	v_add_f32_e32 v35, v35, v167
	v_cvt_pk_bf16_f32 v46, v46, v47
	v_mul_f32_e32 v47, 0x3cb504f3, v34
	v_mul_f32_e32 v48, 0x3cb504f3, v35
	v_cvt_pk_bf16_f32 v47, v47, v48
	global_store_dwordx4 v[42:43], v[44:47], off offset:512 nt
	s_and_saveexec_b64 s[8:9], vcc
	s_cbranch_execz .LBB0_504
	v_mul_f32_e32 v36, v164, v36
	v_mul_f32_e32 v37, v164, v37
	v_cvt_pk_bf16_f32 v36, v36, v37
	v_mul_f32_e32 v37, v164, v38
	v_mul_f32_e32 v38, v164, v39
	v_mul_f32_e32 v32, v164, v32
	v_mul_f32_e32 v33, v164, v33
	v_cvt_pk_bf16_f32 v37, v37, v38
	v_cvt_pk_bf16_f32 v38, v32, v33
	v_mul_f32_e32 v32, v164, v34
	v_mul_f32_e32 v33, v164, v35
	v_cvt_pk_bf16_f32 v39, v32, v33
	v_lshl_add_u64 v[32:33], v[40:41], 0, v[136:137]
	global_store_dwordx4 v[32:33], v[36:39], off offset:512 nt
; __device__ __forceinline__ unsigned cvt_pk_bf16(float lo, float hi) { unsigned r; asm("v_cvt_pk_bf16_f32 %0, %1, %2" : "=v"(r) : "v"(lo), "v"(hi)); return r; }
;     __device__ __forceinline__ void operator()(const f32x4 (&acc)[2][2][4][2], const Unit& u, int wr, int wc, int fr, int fq, LAS unsigned char* xs, int wid, int lane) const {
;     ...
; #pragma unroll
;         for (int ai = 0; ai < 2; ++ai)
; #pragma unroll
;             for (int m = 0; m < 4; ++m) {
;                 const int k = k0 + ai * 128 + m * 16 + fr;
; #pragma unroll
;                 for (int bj = 0; bj < 2; ++bj) {
;                     const int col = (2 * u.pn + bj) * 256 + cs * 128 + wc * 32 + 8 * fq;
;                     f32x4 a = acc[ai][bj][m][0], b = acc[ai][bj][m][1];
; #pragma unroll
;                     for (int j = 0; j < 4; ++j) { a[j] += hv[bj][j]; b[j] += hv[bj][4 + j]; }
;                     u32x4 w; w.x = cvt_pk_bf16(a[0] * sc, a[1] * sc); w.y = cvt_pk_bf16(a[2] * sc, a[3] * sc); w.z = cvt_pk_bf16(b[0] * sc, b[1] * sc); w.w = cvt_pk_bf16(b[2] * sc, b[3] * sc);
;                     *(u32x4*)(pq + (tok0 + k) * 1024 + col) = w;
;                     if (k > 0) {
;                         u32x4 w2; w2.x = cvt_pk_bf16(a[0] * scm, a[1] * scm); w2.y = cvt_pk_bf16(a[2] * scm, a[3] * scm); w2.z = cvt_pk_bf16(b[0] * scm, b[1] * scm); w2.w = cvt_pk_bf16(b[2] * scm, b[3] * scm);
;                         *(u32x4*)(pq + (tok0 + S - k) * 1024 + col) = w2;
;                     }
;                 }
;                 __builtin_amdgcn_sched_barrier(0);
.LBB0_504:
	s_or_b64 exec, exec, s[8:9]
	v_add_u32_e32 v32, 0xa0, v146
	v_ashrrev_i32_e32 v33, 31, v32
	v_lshl_add_u64 v[34:35], s[60:61], 0, v[32:33]
	v_lshlrev_b64 v[40:41], 11, v[34:35]
	v_mov_b32_e32 v34, s19
	v_sub_co_u32_e64 v32, s[8:9], s18, v32
	v_add_f32_e32 v35, v31, v159
	s_nop 0
	v_subb_co_u32_e64 v33, s[8:9], v34, v33, s[8:9]
	v_lshlrev_b64 v[42:43], 11, v[32:33]
	v_add_f32_e32 v32, v28, v156
	v_add_f32_e32 v33, v29, v157
	v_add_f32_e32 v28, v24, v160
	v_add_f32_e32 v29, v25, v161
	v_add_f32_e32 v34, v30, v158
	v_mul_f32_e32 v24, 0x3cb504f3, v32
	v_mul_f32_e32 v25, 0x3cb504f3, v33
	v_cvt_pk_bf16_f32 v36, v24, v25
	v_mul_f32_e32 v24, 0x3cb504f3, v34
	v_mul_f32_e32 v25, 0x3cb504f3, v35
	v_add_f32_e32 v30, v26, v162
	v_add_f32_e32 v31, v27, v163
	v_cvt_pk_bf16_f32 v37, v24, v25
	v_mul_f32_e32 v24, 0x3cb504f3, v28
	v_mul_f32_e32 v25, 0x3cb504f3, v29
	v_cvt_pk_bf16_f32 v38, v24, v25
	v_mul_f32_e32 v24, 0x3cb504f3, v30
	v_mul_f32_e32 v25, 0x3cb504f3, v31
	v_cvt_pk_bf16_f32 v39, v24, v25
	v_lshl_add_u64 v[24:25], s[10:11], 0, v[40:41]
	v_cmp_lt_i32_e32 vcc, s70, v146
	v_lshl_add_u64 v[26:27], v[24:25], 0, v[136:137]
	v_lshl_add_u64 v[24:25], s[10:11], 0, v[42:43]
	global_store_dwordx4 v[26:27], v[36:39], off nt
	s_and_saveexec_b64 s[8:9], vcc
	s_cbranch_execz .LBB0_506
	v_mul_f32_e32 v32, v164, v32
	v_mul_f32_e32 v33, v164, v33
	v_cvt_pk_bf16_f32 v32, v32, v33
	v_mul_f32_e32 v33, v164, v34
	v_mul_f32_e32 v34, v164, v35
	v_mul_f32_e32 v28, v164, v28
	v_mul_f32_e32 v29, v164, v29
	v_cvt_pk_bf16_f32 v33, v33, v34
	v_cvt_pk_bf16_f32 v34, v28, v29
	v_mul_f32_e32 v28, v164, v30
	v_mul_f32_e32 v29, v164, v31
	v_cvt_pk_bf16_f32 v35, v28, v29
	v_lshl_add_u64 v[28:29], v[24:25], 0, v[136:137]
	global_store_dwordx4 v[28:29], v[32:35], off nt
.LBB0_506:
	s_or_b64 exec, exec, s[8:9]
	v_add_f32_e32 v20, v20, v124
	v_add_f32_e32 v21, v21, v125
	v_add_f32_e32 v22, v22, v126
	v_add_f32_e32 v23, v23, v127
	v_mul_f32_e32 v28, 0x3cb504f3, v20
	v_mul_f32_e32 v29, 0x3cb504f3, v21
	v_add_f32_e32 v16, v16, v147
	v_add_f32_e32 v17, v17, v165
	v_cvt_pk_bf16_f32 v28, v28, v29
	v_mul_f32_e32 v29, 0x3cb504f3, v22
	v_mul_f32_e32 v30, 0x3cb504f3, v23
	v_add_f32_e32 v18, v18, v166
	v_cvt_pk_bf16_f32 v29, v29, v30
	v_mul_f32_e32 v30, 0x3cb504f3, v16
	v_mul_f32_e32 v31, 0x3cb504f3, v17
	v_add_f32_e32 v19, v19, v167
	v_cvt_pk_bf16_f32 v30, v30, v31
	v_mul_f32_e32 v31, 0x3cb504f3, v18
	v_mul_f32_e32 v32, 0x3cb504f3, v19
	v_cvt_pk_bf16_f32 v31, v31, v32
	global_store_dwordx4 v[26:27], v[28:31], off offset:512 nt
	s_and_saveexec_b64 s[8:9], vcc
	s_cbranch_execz .LBB0_508
	v_mul_f32_e32 v20, v164, v20
	v_mul_f32_e32 v21, v164, v21
	v_cvt_pk_bf16_f32 v20, v20, v21
	v_mul_f32_e32 v21, v164, v22
	v_mul_f32_e32 v22, v164, v23
	v_mul_f32_e32 v16, v164, v16
	v_mul_f32_e32 v17, v164, v17
	v_cvt_pk_bf16_f32 v21, v21, v22
	v_cvt_pk_bf16_f32 v22, v16, v17
	v_mul_f32_e32 v16, v164, v18
	v_mul_f32_e32 v17, v164, v19
	v_cvt_pk_bf16_f32 v23, v16, v17
	v_lshl_add_u64 v[16:17], v[24:25], 0, v[136:137]
	global_store_dwordx4 v[16:17], v[20:23], off offset:512 nt
.LBB0_508:
	s_or_b64 exec, exec, s[8:9]
	v_add_u32_e32 v16, 0xb0, v146
	v_ashrrev_i32_e32 v17, 31, v16
	v_lshl_add_u64 v[18:19], s[60:61], 0, v[16:17]
	v_lshlrev_b64 v[24:25], 11, v[18:19]
	v_mov_b32_e32 v18, s19
	v_sub_co_u32_e64 v16, s[8:9], s18, v16
	v_add_f32_e32 v19, v15, v159
	s_nop 0
	v_subb_co_u32_e64 v17, s[8:9], v18, v17, s[8:9]
	v_lshlrev_b64 v[26:27], 11, v[16:17]
	v_add_f32_e32 v16, v12, v156
	v_add_f32_e32 v17, v13, v157
	v_add_f32_e32 v12, v8, v160
	v_add_f32_e32 v13, v9, v161
	v_add_f32_e32 v18, v14, v158
	v_mul_f32_e32 v8, 0x3cb504f3, v16
	v_mul_f32_e32 v9, 0x3cb504f3, v17
	v_cvt_pk_bf16_f32 v20, v8, v9
	v_mul_f32_e32 v8, 0x3cb504f3, v18
	v_mul_f32_e32 v9, 0x3cb504f3, v19
	v_add_f32_e32 v14, v10, v162
	v_add_f32_e32 v15, v11, v163
	v_cvt_pk_bf16_f32 v21, v8, v9
	v_mul_f32_e32 v8, 0x3cb504f3, v12
	v_mul_f32_e32 v9, 0x3cb504f3, v13
	v_cvt_pk_bf16_f32 v22, v8, v9
	v_mul_f32_e32 v8, 0x3cb504f3, v14
	v_mul_f32_e32 v9, 0x3cb504f3, v15
	v_cvt_pk_bf16_f32 v23, v8, v9
	v_lshl_add_u64 v[8:9], s[10:11], 0, v[24:25]
	v_cmp_lt_i32_e32 vcc, s71, v146
	v_lshl_add_u64 v[10:11], v[8:9], 0, v[136:137]
	v_lshl_add_u64 v[8:9], s[10:11], 0, v[26:27]
	global_store_dwordx4 v[10:11], v[20:23], off nt
	s_and_saveexec_b64 s[8:9], vcc
	s_cbranch_execz .LBB0_510
	v_mul_f32_e32 v16, v164, v16
	v_mul_f32_e32 v17, v164, v17
	v_cvt_pk_bf16_f32 v16, v16, v17
	v_mul_f32_e32 v17, v164, v18
	v_mul_f32_e32 v18, v164, v19
	v_mul_f32_e32 v12, v164, v12
	v_mul_f32_e32 v13, v164, v13
	v_cvt_pk_bf16_f32 v17, v17, v18
	v_cvt_pk_bf16_f32 v18, v12, v13
	v_mul_f32_e32 v12, v164, v14
	v_mul_f32_e32 v13, v164, v15
	v_cvt_pk_bf16_f32 v19, v12, v13
	v_lshl_add_u64 v[12:13], v[8:9], 0, v[136:137]
	global_store_dwordx4 v[12:13], v[16:19], off nt
.LBB0_510:
	s_or_b64 exec, exec, s[8:9]
	v_add_f32_e32 v4, v4, v124
	v_add_f32_e32 v5, v5, v125
	v_add_f32_e32 v6, v6, v126
	v_add_f32_e32 v7, v7, v127
	v_mul_f32_e32 v12, 0x3cb504f3, v4
	v_mul_f32_e32 v13, 0x3cb504f3, v5
	v_add_f32_e32 v0, v0, v147
	v_add_f32_e32 v1, v1, v165
	v_cvt_pk_bf16_f32 v12, v12, v13
	v_mul_f32_e32 v13, 0x3cb504f3, v6
	v_mul_f32_e32 v14, 0x3cb504f3, v7
	v_add_f32_e32 v2, v2, v166
	v_cvt_pk_bf16_f32 v13, v13, v14
	v_mul_f32_e32 v14, 0x3cb504f3, v0
	v_mul_f32_e32 v15, 0x3cb504f3, v1
	v_add_f32_e32 v3, v3, v167
	v_cvt_pk_bf16_f32 v14, v14, v15
	v_mul_f32_e32 v15, 0x3cb504f3, v2
	v_mul_f32_e32 v16, 0x3cb504f3, v3
	v_cvt_pk_bf16_f32 v15, v15, v16
	global_store_dwordx4 v[10:11], v[12:15], off offset:512 nt
	s_and_saveexec_b64 s[8:9], vcc
	s_cbranch_execz .LBB0_512
	v_mul_f32_e32 v4, v164, v4
	v_mul_f32_e32 v5, v164, v5
	v_cvt_pk_bf16_f32 v4, v4, v5
	v_mul_f32_e32 v5, v164, v6
	v_mul_f32_e32 v6, v164, v7
	v_mul_f32_e32 v0, v164, v0
	v_mul_f32_e32 v1, v164, v1
	v_cvt_pk_bf16_f32 v5, v5, v6
	v_cvt_pk_bf16_f32 v6, v0, v1
	v_mul_f32_e32 v0, v164, v2
	v_mul_f32_e32 v1, v164, v3
	v_cvt_pk_bf16_f32 v7, v0, v1
	v_lshl_add_u64 v[0:1], v[8:9], 0, v[136:137]
	global_store_dwordx4 v[0:1], v[4:7], off offset:512 nt

; __device__ __forceinline__ unsigned cvt_pk_bf16(float lo, float hi) { unsigned r; asm("v_cvt_pk_bf16_f32 %0, %1, %2" : "=v"(r) : "v"(lo), "v"(hi)); return r; }
;     __device__ __forceinline__ void operator()(const f32x4 (&acc)[2][2][4][2], const Unit& u, int wr, int wc, int fr, int fq, LAS unsigned char* xs, int wid, int lane) const {
;     ...
;         for (int ai = 0; ai < 2; ++ai) {
;             f32x4 xf[4][2][2];
;             if (SRCF32) {
; #pragma unroll
;                 for (int m = 0; m < 4; ++m)
; #pragma unroll
;                     for (int bj = 0; bj < 2; ++bj) { const size_t o = (size_t)(row0 + ai * 128 + m * 16 + fr) * D + col0 + bj * 128; xf[m][bj][0] = *(const f32x4*)(xo + o); xf[m][bj][1] = *(const f32x4*)(xo + o + 4); }
;             }
; #pragma unroll
;             for (int m = 0; m < 4; ++m) {
;                 const size_t row = (size_t)(row0 + ai * 128 + m * 16 + fr);
;                 float ss = 0.f;
; #pragma unroll
;                 for (int bj = 0; bj < 2; ++bj) {
;                     const size_t o = row * D + col0 + bj * 128;
;                     f32x4 x0, x1;
;                     if (SRCF32) { x0 = xf[m][bj][0]; x1 = xf[m][bj][1]; }
;                     else { const u32x4 r = raw[ai][m][bj]; x0 = (f32x4){bf_lo(r.x), bf_hi(r.x), bf_lo(r.y), bf_hi(r.y)}; x1 = (f32x4){bf_lo(r.z), bf_hi(r.z), bf_lo(r.w), bf_hi(r.w)}; }
;                     const f32x4 v0 = x0 + acc[ai][bj][m][0], v1 = x1 + acc[ai][bj][m][1];
;                     if (LAST) { *(f32x4*)(out + o) = v0; *(f32x4*)(out + o + 4) = v1; }
;                     else {
;                         ss += (v0[0] * v0[0] + v0[1] * v0[1]) + (v0[2] * v0[2] + v0[3] * v0[3]) + (v1[0] * v1[0] + v1[1] * v1[1]) + (v1[2] * v1[2] + v1[3] * v1[3]);
;                         u32x4 w; w.x = cvt_pk_bf16(v0[0], v0[1]); w.y = cvt_pk_bf16(v0[2], v0[3]); w.z = cvt_pk_bf16(v1[0], v1[1]); w.w = cvt_pk_bf16(v1[2], v1[3]); *(u32x4*)(xb + o) = w;
;                     }
;                 }
;                 if (!LAST) { ss += __shfl_xor(ss, 16); ss += __shfl_xor(ss, 32);
;                     if (fq == 0) P[(ai * 128 + wr * 64 + m * 16 + fr) * 4 + wc] = ss; }
;             }
.LBB0_622:
	s_lshl_b32 s18, s60, 8
	s_add_i32 s19, s18, s23
	s_cmpk_lt_i32 s19, 0x4000
	v_lshl_or_b32 v192, s46, 8, v206
	s_cselect_b32 s35, s45, s28
	s_cselect_b32 s38, s44, s27
	v_or_b32_e32 v196, s19, v204
	v_mov_b32_e32 v128, s38
	v_mov_b32_e32 v129, s35
	v_ashrrev_i32_e32 v193, 31, v192
	v_ashrrev_i32_e32 v197, 31, v196
	v_lshl_add_u64 v[194:195], v[192:193], 2, v[128:129]
	v_lshlrev_b64 v[128:129], 13, v[196:197]
	v_lshl_add_u64 v[128:129], v[194:195], 0, v[128:129]
	global_load_dwordx4 v[216:219], v[128:129], off
	global_load_dwordx4 v[220:223], v[128:129], off offset:16
	global_load_dwordx4 v[224:227], v[128:129], off offset:512
	global_load_dwordx4 v[228:231], v[128:129], off offset:528
	v_or_b32_e32 v202, 16, v196
	v_or_b32_e32 v200, 32, v196
	v_or_b32_e32 v198, 48, v196
	v_ashrrev_i32_e32 v203, 31, v202
	v_ashrrev_i32_e32 v201, 31, v200
	v_ashrrev_i32_e32 v199, 31, v198
	v_lshlrev_b64 v[128:129], 13, v[202:203]
	v_lshlrev_b64 v[130:131], 13, v[200:201]
	v_lshlrev_b64 v[132:133], 13, v[198:199]
	v_lshl_add_u64 v[128:129], v[194:195], 0, v[128:129]
	v_lshl_add_u64 v[130:131], v[194:195], 0, v[130:131]
	v_lshl_add_u64 v[132:133], v[194:195], 0, v[132:133]
	global_load_dwordx4 v[168:171], v[128:129], off offset:16
	global_load_dwordx4 v[172:175], v[128:129], off
	global_load_dwordx4 v[160:163], v[128:129], off offset:528
	global_load_dwordx4 v[164:167], v[128:129], off offset:512
	global_load_dwordx4 v[152:155], v[130:131], off offset:16
	global_load_dwordx4 v[156:159], v[130:131], off
	global_load_dwordx4 v[144:147], v[130:131], off offset:528
	global_load_dwordx4 v[148:151], v[130:131], off offset:512
	global_load_dwordx4 v[136:139], v[132:133], off offset:16
	global_load_dwordx4 v[140:143], v[132:133], off
	s_nop 0
	global_load_dwordx4 v[128:131], v[132:133], off offset:528
	s_nop 0
	global_load_dwordx4 v[132:135], v[132:133], off offset:512
	v_and_b32_e32 v215, 64, v211
	v_xor_b32_e32 v214, 16, v211
	v_add_u32_e32 v215, 64, v215
	v_xor_b32_e32 v232, 32, v211
	v_cmp_lt_i32_e32 vcc, v214, v215
	s_waitcnt vmcnt(0)
	v_pk_add_f32 v[126:127], v[126:127], v[218:219]
	v_pk_add_f32 v[124:125], v[124:125], v[216:217]
	v_pk_add_f32 v[216:217], v[118:119], v[226:227]
	v_pk_add_f32 v[116:117], v[116:117], v[224:225]
	v_cndmask_b32_e32 v214, v211, v214, vcc
	v_cmp_lt_i32_e32 vcc, v232, v215
	v_pk_add_f32 v[120:121], v[120:121], v[220:221]
	v_pk_add_f32 v[218:219], v[114:115], v[230:231]
	v_pk_add_f32 v[220:221], v[112:113], v[228:229]
	v_mul_f32_e32 v114, v125, v125
	v_mul_f32_e32 v115, v127, v127
	v_cvt_pk_bf16_f32 v112, v124, v125
	v_cvt_pk_bf16_f32 v113, v126, v127
	v_mul_f32_e32 v125, v117, v117
	v_mul_f32_e32 v127, v217, v217
	v_cndmask_b32_e32 v215, v211, v232, vcc
	v_lshlrev_b64 v[232:233], 12, v[196:197]
	v_pk_add_f32 v[122:123], v[122:123], v[222:223]
	v_mul_f32_e32 v118, v121, v121
	v_mul_f32_e32 v197, v221, v221
	v_fmac_f32_e32 v114, v124, v124
	v_fmac_f32_e32 v115, v126, v126
	v_fmac_f32_e32 v125, v116, v116
	v_fmac_f32_e32 v127, v216, v216
	v_mul_f32_e32 v119, v123, v123
	v_mul_f32_e32 v222, v219, v219
	v_fmac_f32_e32 v118, v120, v120
	v_fmac_f32_e32 v197, v220, v220
	v_add_f32_e32 v114, v114, v115
	v_add_f32_e32 v115, v125, v127
	v_fmac_f32_e32 v119, v122, v122
	v_fmac_f32_e32 v222, v218, v218
	v_add_f32_e32 v114, v114, v118
	v_add_f32_e32 v115, v115, v197
	v_add_f32_e32 v114, v119, v114
	v_add_f32_e32 v115, v222, v115
	v_lshlrev_b32_e32 v214, 2, v214
	v_add_f32_e32 v118, v114, v115
	ds_bpermute_b32 v119, v214, v118
	v_lshl_add_u64 v[232:233], s[12:13], 0, v[232:233]
	v_lshl_add_u64 v[232:233], v[192:193], 1, v[232:233]
	v_cvt_pk_bf16_f32 v114, v120, v121
	v_cvt_pk_bf16_f32 v115, v122, v123
	global_store_dwordx4 v[232:233], v[112:115], off nt
	v_cvt_pk_bf16_f32 v120, v116, v117
	v_cvt_pk_bf16_f32 v121, v216, v217
	v_cvt_pk_bf16_f32 v122, v220, v221
	v_cvt_pk_bf16_f32 v123, v218, v219
	global_store_dwordx4 v[232:233], v[120:123], off offset:256 nt
	s_waitcnt lgkmcnt(0)
	v_add_f32_e32 v112, v118, v119
	v_lshlrev_b32_e32 v118, 2, v215
	ds_bpermute_b32 v113, v118, v112
	s_and_saveexec_b64 s[60:61], s[6:7]
	s_cbranch_execz .LBB0_624
	s_waitcnt lgkmcnt(0)
	v_add_f32_e32 v112, v112, v113
	ds_write_b32 v213, v112
.LBB0_624:
	s_or_b64 exec, exec, s[60:61]
	v_pk_add_f32 v[110:111], v[110:111], v[174:175]
	v_pk_add_f32 v[108:109], v[108:109], v[172:173]
	v_pk_add_f32 v[114:115], v[106:107], v[170:171]
	v_pk_add_f32 v[106:107], v[104:105], v[168:169]
	v_mul_f32_e32 v104, v109, v109
	v_mul_f32_e32 v105, v111, v111
	v_fmac_f32_e32 v104, v108, v108
	v_fmac_f32_e32 v105, v110, v110
	v_add_f32_e32 v104, v104, v105
	v_mul_f32_e32 v105, v107, v107
	v_fmac_f32_e32 v105, v106, v106
	v_add_f32_e32 v104, v104, v105
	v_mul_f32_e32 v105, v115, v115
	v_fmac_f32_e32 v105, v114, v114
	v_pk_add_f32 v[102:103], v[102:103], v[166:167]
	v_pk_add_f32 v[100:101], v[100:101], v[164:165]
	v_add_f32_e32 v116, v105, v104
	v_cvt_pk_bf16_f32 v105, v110, v111
	v_pk_add_f32 v[110:111], v[96:97], v[160:161]
	v_mul_f32_e32 v96, v101, v101
	v_mul_f32_e32 v97, v103, v103
	v_fmac_f32_e32 v96, v100, v100
	v_fmac_f32_e32 v97, v102, v102
	v_add_f32_e32 v96, v96, v97
	v_mul_f32_e32 v97, v111, v111
	v_cvt_pk_bf16_f32 v104, v108, v109
	v_pk_add_f32 v[108:109], v[98:99], v[162:163]
	v_fmac_f32_e32 v97, v110, v110
	v_add_f32_e32 v96, v96, v97
	v_mul_f32_e32 v97, v109, v109
	v_fmac_f32_e32 v97, v108, v108
	v_add_f32_e32 v96, v97, v96
	v_add_f32_e32 v99, v116, v96
	v_cvt_pk_bf16_f32 v106, v106, v107
	v_cvt_pk_bf16_f32 v107, v114, v115
	ds_bpermute_b32 v114, v214, v99
	s_waitcnt lgkmcnt(1)
	v_lshlrev_b64 v[112:113], 12, v[202:203]
	v_lshl_add_u64 v[96:97], s[12:13], 0, v[112:113]
	v_lshl_add_u64 v[112:113], v[192:193], 1, v[96:97]
	global_store_dwordx4 v[112:113], v[104:107], off nt
	s_waitcnt lgkmcnt(0)
	v_add_f32_e32 v96, v99, v114
	ds_bpermute_b32 v97, v118, v96
	v_cvt_pk_bf16_f32 v98, v100, v101
	v_cvt_pk_bf16_f32 v99, v102, v103
	v_cvt_pk_bf16_f32 v100, v110, v111
	v_cvt_pk_bf16_f32 v101, v108, v109
	global_store_dwordx4 v[112:113], v[98:101], off offset:256 nt
	s_and_saveexec_b64 s[60:61], s[6:7]
	s_cbranch_execz .LBB0_626
	s_waitcnt lgkmcnt(0)
	v_add_f32_e32 v96, v96, v97
	ds_write_b32 v213, v96 offset:256
; __device__ __forceinline__ unsigned cvt_pk_bf16(float lo, float hi) { unsigned r; asm("v_cvt_pk_bf16_f32 %0, %1, %2" : "=v"(r) : "v"(lo), "v"(hi)); return r; }
;     __device__ __forceinline__ void operator()(const f32x4 (&acc)[2][2][4][2], const Unit& u, int wr, int wc, int fr, int fq, LAS unsigned char* xs, int wid, int lane) const {
;     ...
; #pragma unroll
;                 for (int m = 0; m < 4; ++m)
; #pragma unroll
;                     for (int bj = 0; bj < 2; ++bj) { const size_t o = (size_t)(row0 + ai * 128 + m * 16 + fr) * D + col0 + bj * 128; xf[m][bj][0] = *(const f32x4*)(xo + o); xf[m][bj][1] = *(const f32x4*)(xo + o + 4); }
;     ...
; #pragma unroll
;             for (int m = 0; m < 4; ++m) {
;                 const size_t row = (size_t)(row0 + ai * 128 + m * 16 + fr);
;                 float ss = 0.f;
; #pragma unroll
;                 for (int bj = 0; bj < 2; ++bj) {
;                     const size_t o = row * D + col0 + bj * 128;
;                     f32x4 x0, x1;
;                     if (SRCF32) { x0 = xf[m][bj][0]; x1 = xf[m][bj][1]; }
;                     else { const u32x4 r = raw[ai][m][bj]; x0 = (f32x4){bf_lo(r.x), bf_hi(r.x), bf_lo(r.y), bf_hi(r.y)}; x1 = (f32x4){bf_lo(r.z), bf_hi(r.z), bf_lo(r.w), bf_hi(r.w)}; }
;                     const f32x4 v0 = x0 + acc[ai][bj][m][0], v1 = x1 + acc[ai][bj][m][1];
;                     if (LAST) { *(f32x4*)(out + o) = v0; *(f32x4*)(out + o + 4) = v1; }
;                     else {
;                         ss += (v0[0] * v0[0] + v0[1] * v0[1]) + (v0[2] * v0[2] + v0[3] * v0[3]) + (v1[0] * v1[0] + v1[1] * v1[1]) + (v1[2] * v1[2] + v1[3] * v1[3]);
;                         u32x4 w; w.x = cvt_pk_bf16(v0[0], v0[1]); w.y = cvt_pk_bf16(v0[2], v0[3]); w.z = cvt_pk_bf16(v1[0], v1[1]); w.w = cvt_pk_bf16(v1[2], v1[3]); *(u32x4*)(xb + o) = w;
;                     }
;                 }
;                 if (!LAST) { ss += __shfl_xor(ss, 16); ss += __shfl_xor(ss, 32);
;                     if (fq == 0) P[(ai * 128 + wr * 64 + m * 16 + fr) * 4 + wc] = ss; }
;             }
.LBB0_626:
	s_or_b64 exec, exec, s[60:61]
	v_pk_add_f32 v[94:95], v[94:95], v[158:159]
	v_pk_add_f32 v[92:93], v[92:93], v[156:157]
	v_pk_add_f32 v[98:99], v[90:91], v[154:155]
	v_pk_add_f32 v[90:91], v[88:89], v[152:153]
	v_mul_f32_e32 v88, v93, v93
	v_mul_f32_e32 v89, v95, v95
	v_fmac_f32_e32 v88, v92, v92
	v_fmac_f32_e32 v89, v94, v94
	v_add_f32_e32 v88, v88, v89
	v_mul_f32_e32 v89, v91, v91
	v_fmac_f32_e32 v89, v90, v90
	v_add_f32_e32 v88, v88, v89
	v_mul_f32_e32 v89, v99, v99
	v_fmac_f32_e32 v89, v98, v98
	v_pk_add_f32 v[86:87], v[86:87], v[150:151]
	v_pk_add_f32 v[84:85], v[84:85], v[148:149]
	v_add_f32_e32 v100, v89, v88
	v_cvt_pk_bf16_f32 v89, v94, v95
	v_pk_add_f32 v[94:95], v[80:81], v[144:145]
	v_mul_f32_e32 v80, v85, v85
	v_mul_f32_e32 v81, v87, v87
	v_fmac_f32_e32 v80, v84, v84
	v_fmac_f32_e32 v81, v86, v86
	v_add_f32_e32 v80, v80, v81
	v_mul_f32_e32 v81, v95, v95
	v_cvt_pk_bf16_f32 v88, v92, v93
	v_pk_add_f32 v[92:93], v[82:83], v[146:147]
	v_fmac_f32_e32 v81, v94, v94
	v_add_f32_e32 v80, v80, v81
	v_mul_f32_e32 v81, v93, v93
	v_fmac_f32_e32 v81, v92, v92
	v_add_f32_e32 v80, v81, v80
	v_add_f32_e32 v83, v100, v80
	v_cvt_pk_bf16_f32 v90, v90, v91
	v_cvt_pk_bf16_f32 v91, v98, v99
	ds_bpermute_b32 v98, v214, v83
	s_waitcnt lgkmcnt(1)
	v_lshlrev_b64 v[96:97], 12, v[200:201]
	v_lshl_add_u64 v[80:81], s[12:13], 0, v[96:97]
	v_lshl_add_u64 v[96:97], v[192:193], 1, v[80:81]
	global_store_dwordx4 v[96:97], v[88:91], off nt
	s_waitcnt lgkmcnt(0)
	v_add_f32_e32 v80, v83, v98
	ds_bpermute_b32 v81, v118, v80
	v_cvt_pk_bf16_f32 v82, v84, v85
	v_cvt_pk_bf16_f32 v83, v86, v87
	v_cvt_pk_bf16_f32 v84, v94, v95
	v_cvt_pk_bf16_f32 v85, v92, v93
	global_store_dwordx4 v[96:97], v[82:85], off offset:256 nt
	s_and_saveexec_b64 s[60:61], s[6:7]
	s_cbranch_execz .LBB0_628
	s_waitcnt lgkmcnt(0)
	v_add_f32_e32 v80, v80, v81
	ds_write_b32 v213, v80 offset:512
.LBB0_628:
	s_or_b64 exec, exec, s[60:61]
	v_pk_add_f32 v[78:79], v[78:79], v[142:143]
	v_pk_add_f32 v[76:77], v[76:77], v[140:141]
	v_pk_add_f32 v[82:83], v[74:75], v[138:139]
	v_pk_add_f32 v[74:75], v[72:73], v[136:137]
	v_mul_f32_e32 v72, v77, v77
	v_mul_f32_e32 v73, v79, v79
	v_fmac_f32_e32 v72, v76, v76
	v_fmac_f32_e32 v73, v78, v78
	v_add_f32_e32 v72, v72, v73
	v_mul_f32_e32 v73, v75, v75
	v_fmac_f32_e32 v73, v74, v74
	v_add_f32_e32 v72, v72, v73
	v_mul_f32_e32 v73, v83, v83
	v_fmac_f32_e32 v73, v82, v82
	v_pk_add_f32 v[70:71], v[70:71], v[134:135]
	v_pk_add_f32 v[68:69], v[68:69], v[132:133]
	v_add_f32_e32 v84, v73, v72
	v_cvt_pk_bf16_f32 v73, v78, v79
	v_pk_add_f32 v[78:79], v[64:65], v[128:129]
	v_mul_f32_e32 v64, v69, v69
	v_mul_f32_e32 v65, v71, v71
	v_fmac_f32_e32 v64, v68, v68
	v_fmac_f32_e32 v65, v70, v70
	v_add_f32_e32 v64, v64, v65
	v_mul_f32_e32 v65, v79, v79
	v_cvt_pk_bf16_f32 v72, v76, v77
	v_pk_add_f32 v[76:77], v[66:67], v[130:131]
	v_fmac_f32_e32 v65, v78, v78
	v_add_f32_e32 v64, v64, v65
	v_mul_f32_e32 v65, v77, v77
	v_fmac_f32_e32 v65, v76, v76
	v_add_f32_e32 v64, v65, v64
	v_add_f32_e32 v67, v84, v64
	v_cvt_pk_bf16_f32 v74, v74, v75
	v_cvt_pk_bf16_f32 v75, v82, v83
	ds_bpermute_b32 v82, v214, v67
	s_waitcnt lgkmcnt(1)
	v_lshlrev_b64 v[80:81], 12, v[198:199]
	v_lshl_add_u64 v[64:65], s[12:13], 0, v[80:81]
	v_lshl_add_u64 v[80:81], v[192:193], 1, v[64:65]
	global_store_dwordx4 v[80:81], v[72:75], off nt
	s_waitcnt lgkmcnt(0)
	v_add_f32_e32 v64, v67, v82
	ds_bpermute_b32 v65, v118, v64
	v_cvt_pk_bf16_f32 v66, v68, v69
	v_cvt_pk_bf16_f32 v67, v70, v71
	v_cvt_pk_bf16_f32 v68, v78, v79
	v_cvt_pk_bf16_f32 v69, v76, v77
	global_store_dwordx4 v[80:81], v[66:69], off offset:256 nt
	s_and_saveexec_b64 s[60:61], s[6:7]
	s_cbranch_execz .LBB0_630
	s_waitcnt lgkmcnt(0)
	v_add_f32_e32 v64, v64, v65
	ds_write_b32 v213, v64 offset:768
.LBB0_630:
	s_or_b64 exec, exec, s[60:61]
	v_add_u32_e32 v136, 0x80, v196
	v_ashrrev_i32_e32 v137, 31, v136
	s_waitcnt lgkmcnt(0)
	v_lshlrev_b64 v[64:65], 13, v[136:137]
	v_lshl_add_u64 v[64:65], v[194:195], 0, v[64:65]
	global_load_dwordx4 v[120:123], v[64:65], off
	global_load_dwordx4 v[124:127], v[64:65], off offset:16
	global_load_dwordx4 v[128:131], v[64:65], off offset:512
	global_load_dwordx4 v[132:135], v[64:65], off offset:528
	v_add_u32_e32 v116, 0x90, v196
	v_add_u32_e32 v114, 0xa0, v196
	v_add_u32_e32 v112, 0xb0, v196
	v_ashrrev_i32_e32 v117, 31, v116
	v_ashrrev_i32_e32 v115, 31, v114
	v_ashrrev_i32_e32 v113, 31, v112
	v_lshlrev_b64 v[64:65], 13, v[116:117]
	v_lshlrev_b64 v[66:67], 13, v[114:115]
	v_lshlrev_b64 v[68:69], 13, v[112:113]
	v_lshl_add_u64 v[64:65], v[194:195], 0, v[64:65]
	v_lshl_add_u64 v[66:67], v[194:195], 0, v[66:67]
	v_lshl_add_u64 v[68:69], v[194:195], 0, v[68:69]
	global_load_dwordx4 v[104:107], v[64:65], off offset:16
	global_load_dwordx4 v[108:111], v[64:65], off
	global_load_dwordx4 v[96:99], v[64:65], off offset:528
	global_load_dwordx4 v[100:103], v[64:65], off offset:512
	global_load_dwordx4 v[88:91], v[66:67], off offset:16
	global_load_dwordx4 v[92:95], v[66:67], off
	global_load_dwordx4 v[80:83], v[66:67], off offset:528
	global_load_dwordx4 v[84:87], v[66:67], off offset:512
	global_load_dwordx4 v[72:75], v[68:69], off offset:16
	global_load_dwordx4 v[76:79], v[68:69], off
	s_nop 0
	global_load_dwordx4 v[64:67], v[68:69], off offset:528
	s_nop 0
	global_load_dwordx4 v[68:71], v[68:69], off offset:512
	v_lshlrev_b64 v[136:137], 12, v[136:137]
	s_waitcnt vmcnt(15)
	v_pk_add_f32 v[62:63], v[62:63], v[122:123]
	v_pk_add_f32 v[60:61], v[60:61], v[120:121]
	s_waitcnt vmcnt(14)
	v_pk_add_f32 v[58:59], v[58:59], v[126:127]
	v_pk_add_f32 v[56:57], v[56:57], v[124:125]
	s_waitcnt vmcnt(13)
; __device__ __forceinline__ unsigned cvt_pk_bf16(float lo, float hi) { unsigned r; asm("v_cvt_pk_bf16_f32 %0, %1, %2" : "=v"(r) : "v"(lo), "v"(hi)); return r; }
;     __device__ __forceinline__ void operator()(const f32x4 (&acc)[2][2][4][2], const Unit& u, int wr, int wc, int fr, int fq, LAS unsigned char* xs, int wid, int lane) const {
;     ...
; #pragma unroll
;             for (int m = 0; m < 4; ++m) {
;                 const size_t row = (size_t)(row0 + ai * 128 + m * 16 + fr);
;                 float ss = 0.f;
; #pragma unroll
;                 for (int bj = 0; bj < 2; ++bj) {
;                     const size_t o = row * D + col0 + bj * 128;
;                     f32x4 x0, x1;
;                     if (SRCF32) { x0 = xf[m][bj][0]; x1 = xf[m][bj][1]; }
;                     else { const u32x4 r = raw[ai][m][bj]; x0 = (f32x4){bf_lo(r.x), bf_hi(r.x), bf_lo(r.y), bf_hi(r.y)}; x1 = (f32x4){bf_lo(r.z), bf_hi(r.z), bf_lo(r.w), bf_hi(r.w)}; }
;                     const f32x4 v0 = x0 + acc[ai][bj][m][0], v1 = x1 + acc[ai][bj][m][1];
;                     if (LAST) { *(f32x4*)(out + o) = v0; *(f32x4*)(out + o + 4) = v1; }
;                     else {
;                         ss += (v0[0] * v0[0] + v0[1] * v0[1]) + (v0[2] * v0[2] + v0[3] * v0[3]) + (v1[0] * v1[0] + v1[1] * v1[1]) + (v1[2] * v1[2] + v1[3] * v1[3]);
;                         u32x4 w; w.x = cvt_pk_bf16(v0[0], v0[1]); w.y = cvt_pk_bf16(v0[2], v0[3]); w.z = cvt_pk_bf16(v1[0], v1[1]); w.w = cvt_pk_bf16(v1[2], v1[3]); *(u32x4*)(xb + o) = w;
;                     }
;                 }
;                 if (!LAST) { ss += __shfl_xor(ss, 16); ss += __shfl_xor(ss, 32);
;                     if (fq == 0) P[(ai * 128 + wr * 64 + m * 16 + fr) * 4 + wc] = ss; }
;             }
	v_pk_add_f32 v[54:55], v[54:55], v[130:131]
	v_pk_add_f32 v[52:53], v[52:53], v[128:129]
	s_waitcnt vmcnt(12)
	v_pk_add_f32 v[120:121], v[50:51], v[134:135]
	v_pk_add_f32 v[122:123], v[48:49], v[132:133]
	v_mul_f32_e32 v119, v61, v61
	v_mul_f32_e32 v124, v63, v63
	v_mul_f32_e32 v125, v57, v57
	v_mul_f32_e32 v126, v59, v59
	v_cvt_pk_bf16_f32 v50, v56, v57
	v_cvt_pk_bf16_f32 v51, v58, v59
	v_mul_f32_e32 v57, v53, v53
	v_mul_f32_e32 v59, v55, v55
	v_cvt_pk_bf16_f32 v48, v60, v61
	v_mul_f32_e32 v61, v123, v123
	v_fmac_f32_e32 v119, v60, v60
	v_fmac_f32_e32 v124, v62, v62
	v_fmac_f32_e32 v57, v52, v52
	v_fmac_f32_e32 v59, v54, v54
	v_cvt_pk_bf16_f32 v49, v62, v63
	v_mul_f32_e32 v63, v121, v121
	v_fmac_f32_e32 v125, v56, v56
	v_fmac_f32_e32 v61, v122, v122
	v_add_f32_e32 v56, v119, v124
	v_add_f32_e32 v57, v57, v59
	v_fmac_f32_e32 v126, v58, v58
	v_fmac_f32_e32 v63, v120, v120
	v_add_f32_e32 v56, v56, v125
	v_add_f32_e32 v57, v57, v61
	v_add_f32_e32 v56, v126, v56
	v_add_f32_e32 v57, v63, v57
	v_add_f32_e32 v58, v56, v57
	ds_bpermute_b32 v59, v214, v58
	v_lshl_add_u64 v[56:57], s[12:13], 0, v[136:137]
	v_lshl_add_u64 v[56:57], v[192:193], 1, v[56:57]
	global_store_dwordx4 v[56:57], v[48:51], off nt
	s_waitcnt lgkmcnt(0)
	s_nop 0
	v_add_f32_e32 v48, v58, v59
	ds_bpermute_b32 v49, v118, v48
	v_cvt_pk_bf16_f32 v50, v52, v53
	v_cvt_pk_bf16_f32 v51, v54, v55
	v_cvt_pk_bf16_f32 v52, v122, v123
	v_cvt_pk_bf16_f32 v53, v120, v121
	global_store_dwordx4 v[56:57], v[50:53], off offset:256 nt
	s_and_saveexec_b64 s[60:61], s[6:7]
	s_cbranch_execz .LBB0_632
	s_waitcnt lgkmcnt(0)
	v_add_f32_e32 v48, v48, v49
	ds_write_b32 v213, v48 offset:2048
.LBB0_632:
	s_or_b64 exec, exec, s[60:61]
	s_waitcnt vmcnt(12)
	v_pk_add_f32 v[46:47], v[46:47], v[110:111]
	v_pk_add_f32 v[44:45], v[44:45], v[108:109]
	v_pk_add_f32 v[50:51], v[42:43], v[106:107]
	v_pk_add_f32 v[42:43], v[40:41], v[104:105]
	v_mul_f32_e32 v40, v45, v45
	v_mul_f32_e32 v41, v47, v47
	v_fmac_f32_e32 v40, v44, v44
	v_fmac_f32_e32 v41, v46, v46
	v_add_f32_e32 v40, v40, v41
	v_mul_f32_e32 v41, v43, v43
	v_fmac_f32_e32 v41, v42, v42
	v_add_f32_e32 v40, v40, v41
	v_mul_f32_e32 v41, v51, v51
	v_fmac_f32_e32 v41, v50, v50
	s_waitcnt vmcnt(10)
	v_pk_add_f32 v[38:39], v[38:39], v[102:103]
	v_pk_add_f32 v[36:37], v[36:37], v[100:101]
	v_add_f32_e32 v52, v41, v40
	v_cvt_pk_bf16_f32 v41, v46, v47
	v_pk_add_f32 v[46:47], v[32:33], v[96:97]
	v_mul_f32_e32 v32, v37, v37
	v_mul_f32_e32 v33, v39, v39
	v_fmac_f32_e32 v32, v36, v36
	v_fmac_f32_e32 v33, v38, v38
	v_add_f32_e32 v32, v32, v33
	v_mul_f32_e32 v33, v47, v47
	v_cvt_pk_bf16_f32 v40, v44, v45
	v_pk_add_f32 v[44:45], v[34:35], v[98:99]
	v_fmac_f32_e32 v33, v46, v46
	v_add_f32_e32 v32, v32, v33
	v_mul_f32_e32 v33, v45, v45
	v_fmac_f32_e32 v33, v44, v44
	v_add_f32_e32 v32, v33, v32
	v_add_f32_e32 v35, v52, v32
	v_cvt_pk_bf16_f32 v42, v42, v43
	v_cvt_pk_bf16_f32 v43, v50, v51
	ds_bpermute_b32 v50, v214, v35
	s_waitcnt lgkmcnt(1)
	v_lshlrev_b64 v[48:49], 12, v[116:117]
	v_lshl_add_u64 v[32:33], s[12:13], 0, v[48:49]
	v_lshl_add_u64 v[48:49], v[192:193], 1, v[32:33]
	global_store_dwordx4 v[48:49], v[40:43], off nt
	s_waitcnt lgkmcnt(0)
	v_add_f32_e32 v32, v35, v50
	ds_bpermute_b32 v33, v118, v32
	v_cvt_pk_bf16_f32 v34, v36, v37
	v_cvt_pk_bf16_f32 v35, v38, v39
	v_cvt_pk_bf16_f32 v36, v46, v47
	v_cvt_pk_bf16_f32 v37, v44, v45
	global_store_dwordx4 v[48:49], v[34:37], off offset:256 nt
	s_and_saveexec_b64 s[60:61], s[6:7]
	s_cbranch_execz .LBB0_634
	s_waitcnt lgkmcnt(0)
	v_add_f32_e32 v32, v32, v33
	ds_write_b32 v213, v32 offset:2304
; __device__ __forceinline__ unsigned cvt_pk_bf16(float lo, float hi) { unsigned r; asm("v_cvt_pk_bf16_f32 %0, %1, %2" : "=v"(r) : "v"(lo), "v"(hi)); return r; }
;     __device__ __forceinline__ void operator()(const f32x4 (&acc)[2][2][4][2], const Unit& u, int wr, int wc, int fr, int fq, LAS unsigned char* xs, int wid, int lane) const {
;     ...
; #pragma unroll
;             for (int m = 0; m < 4; ++m) {
;                 const size_t row = (size_t)(row0 + ai * 128 + m * 16 + fr);
;                 float ss = 0.f;
; #pragma unroll
;                 for (int bj = 0; bj < 2; ++bj) {
;                     const size_t o = row * D + col0 + bj * 128;
;                     f32x4 x0, x1;
;                     if (SRCF32) { x0 = xf[m][bj][0]; x1 = xf[m][bj][1]; }
;                     else { const u32x4 r = raw[ai][m][bj]; x0 = (f32x4){bf_lo(r.x), bf_hi(r.x), bf_lo(r.y), bf_hi(r.y)}; x1 = (f32x4){bf_lo(r.z), bf_hi(r.z), bf_lo(r.w), bf_hi(r.w)}; }
;                     const f32x4 v0 = x0 + acc[ai][bj][m][0], v1 = x1 + acc[ai][bj][m][1];
;                     if (LAST) { *(f32x4*)(out + o) = v0; *(f32x4*)(out + o + 4) = v1; }
;                     else {
;                         ss += (v0[0] * v0[0] + v0[1] * v0[1]) + (v0[2] * v0[2] + v0[3] * v0[3]) + (v1[0] * v1[0] + v1[1] * v1[1]) + (v1[2] * v1[2] + v1[3] * v1[3]);
;                         u32x4 w; w.x = cvt_pk_bf16(v0[0], v0[1]); w.y = cvt_pk_bf16(v0[2], v0[3]); w.z = cvt_pk_bf16(v1[0], v1[1]); w.w = cvt_pk_bf16(v1[2], v1[3]); *(u32x4*)(xb + o) = w;
;                     }
;                 }
;                 if (!LAST) { ss += __shfl_xor(ss, 16); ss += __shfl_xor(ss, 32);
;                     if (fq == 0) P[(ai * 128 + wr * 64 + m * 16 + fr) * 4 + wc] = ss; }
;             }
.LBB0_634:
	s_or_b64 exec, exec, s[60:61]
	s_waitcnt vmcnt(10)
	v_pk_add_f32 v[30:31], v[30:31], v[94:95]
	v_pk_add_f32 v[28:29], v[28:29], v[92:93]
	v_pk_add_f32 v[34:35], v[26:27], v[90:91]
	v_pk_add_f32 v[26:27], v[24:25], v[88:89]
	v_mul_f32_e32 v24, v29, v29
	v_mul_f32_e32 v25, v31, v31
	v_fmac_f32_e32 v24, v28, v28
	v_fmac_f32_e32 v25, v30, v30
	v_add_f32_e32 v24, v24, v25
	v_mul_f32_e32 v25, v27, v27
	v_fmac_f32_e32 v25, v26, v26
	v_add_f32_e32 v24, v24, v25
	v_mul_f32_e32 v25, v35, v35
	v_fmac_f32_e32 v25, v34, v34
	s_waitcnt vmcnt(8)
	v_pk_add_f32 v[22:23], v[22:23], v[86:87]
	v_pk_add_f32 v[20:21], v[20:21], v[84:85]
	v_add_f32_e32 v36, v25, v24
	v_cvt_pk_bf16_f32 v25, v30, v31
	v_pk_add_f32 v[30:31], v[16:17], v[80:81]
	v_mul_f32_e32 v16, v21, v21
	v_mul_f32_e32 v17, v23, v23
	v_fmac_f32_e32 v16, v20, v20
	v_fmac_f32_e32 v17, v22, v22
	v_add_f32_e32 v16, v16, v17
	v_mul_f32_e32 v17, v31, v31
	v_cvt_pk_bf16_f32 v24, v28, v29
	v_pk_add_f32 v[28:29], v[18:19], v[82:83]
	v_fmac_f32_e32 v17, v30, v30
	v_add_f32_e32 v16, v16, v17
	v_mul_f32_e32 v17, v29, v29
	v_fmac_f32_e32 v17, v28, v28
	v_add_f32_e32 v16, v17, v16
	v_add_f32_e32 v19, v36, v16
	v_cvt_pk_bf16_f32 v26, v26, v27
	v_cvt_pk_bf16_f32 v27, v34, v35
	ds_bpermute_b32 v34, v214, v19
	s_waitcnt lgkmcnt(1)
	v_lshlrev_b64 v[32:33], 12, v[114:115]
	v_lshl_add_u64 v[16:17], s[12:13], 0, v[32:33]
	v_lshl_add_u64 v[32:33], v[192:193], 1, v[16:17]
	global_store_dwordx4 v[32:33], v[24:27], off nt
	s_waitcnt lgkmcnt(0)
	v_add_f32_e32 v16, v19, v34
	ds_bpermute_b32 v17, v118, v16
	v_cvt_pk_bf16_f32 v18, v20, v21
	v_cvt_pk_bf16_f32 v19, v22, v23
	v_cvt_pk_bf16_f32 v20, v30, v31
	v_cvt_pk_bf16_f32 v21, v28, v29
	global_store_dwordx4 v[32:33], v[18:21], off offset:256 nt
	s_and_saveexec_b64 s[60:61], s[6:7]
	s_cbranch_execz .LBB0_636
	s_waitcnt lgkmcnt(0)
	v_add_f32_e32 v16, v16, v17
	ds_write_b32 v213, v16 offset:2560
.LBB0_636:
	s_or_b64 exec, exec, s[60:61]
	s_waitcnt vmcnt(8)
	v_pk_add_f32 v[14:15], v[14:15], v[78:79]
	v_pk_add_f32 v[12:13], v[12:13], v[76:77]
	v_pk_add_f32 v[18:19], v[10:11], v[74:75]
	v_pk_add_f32 v[10:11], v[8:9], v[72:73]
	v_mul_f32_e32 v8, v13, v13
	v_mul_f32_e32 v9, v15, v15
	v_fmac_f32_e32 v8, v12, v12
	v_fmac_f32_e32 v9, v14, v14
	v_add_f32_e32 v8, v8, v9
	v_mul_f32_e32 v9, v11, v11
	v_fmac_f32_e32 v9, v10, v10
	v_add_f32_e32 v8, v8, v9
	v_mul_f32_e32 v9, v19, v19
	v_fmac_f32_e32 v9, v18, v18
	s_waitcnt vmcnt(6)
	v_pk_add_f32 v[6:7], v[6:7], v[70:71]
	v_pk_add_f32 v[4:5], v[4:5], v[68:69]
	v_add_f32_e32 v20, v9, v8
	v_cvt_pk_bf16_f32 v9, v14, v15
	v_pk_add_f32 v[14:15], v[0:1], v[64:65]
	v_mul_f32_e32 v0, v5, v5
	v_mul_f32_e32 v1, v7, v7
	v_fmac_f32_e32 v0, v4, v4
	v_fmac_f32_e32 v1, v6, v6
	v_add_f32_e32 v0, v0, v1
	v_mul_f32_e32 v1, v15, v15
	v_cvt_pk_bf16_f32 v8, v12, v13
	v_pk_add_f32 v[12:13], v[2:3], v[66:67]
	v_fmac_f32_e32 v1, v14, v14
	v_add_f32_e32 v0, v0, v1
	v_mul_f32_e32 v1, v13, v13
	v_fmac_f32_e32 v1, v12, v12
	v_add_f32_e32 v0, v1, v0
	v_add_f32_e32 v3, v20, v0
	v_cvt_pk_bf16_f32 v10, v10, v11
	v_cvt_pk_bf16_f32 v11, v18, v19
	ds_bpermute_b32 v18, v214, v3
	s_waitcnt lgkmcnt(1)
	v_lshlrev_b64 v[16:17], 12, v[112:113]
	v_lshl_add_u64 v[0:1], s[12:13], 0, v[16:17]
	v_lshl_add_u64 v[16:17], v[192:193], 1, v[0:1]
	global_store_dwordx4 v[16:17], v[8:11], off nt
	s_waitcnt lgkmcnt(0)
	v_add_f32_e32 v0, v3, v18
	ds_bpermute_b32 v1, v118, v0
	v_cvt_pk_bf16_f32 v2, v4, v5
	v_cvt_pk_bf16_f32 v3, v6, v7
	v_cvt_pk_bf16_f32 v4, v14, v15
	v_cvt_pk_bf16_f32 v5, v12, v13
	global_store_dwordx4 v[16:17], v[2:5], off offset:256 nt
	s_and_saveexec_b64 s[60:61], s[6:7]
	s_cbranch_execz .LBB0_638
	s_waitcnt lgkmcnt(0)
	v_add_f32_e32 v0, v0, v1
	ds_write_b32 v213, v0 offset:2816

; #define LAS __attribute__((address_space(3)))
; __device__ __forceinline__ unsigned cvt_pk_bf16(float lo, float hi) { unsigned r; asm("v_cvt_pk_bf16_f32 %0, %1, %2" : "=v"(r) : "v"(lo), "v"(hi)); return r; }
; __device__ __forceinline__ void tstore_sub(const f32x4 (&v)[4][2], bf16_t* dst  , LAS unsigned char* x, int fr, int fq, int lane) {
; #pragma unroll
;     for (int m = 0; m < 4; ++m)
; #pragma unroll
;         for (int n = 0; n < 2; ++n)
; #pragma unroll
;             for (int j = 0; j < 4; ++j) {
;                 const int ch = 8 * fq + 4 * n + j, tok = 16 * m + fr;
;                 const unsigned b = cvt_pk_bf16(v[m][n][j], 0.f);
;                 *(LAS unsigned short*)(x + ch * 128 + ((((tok >> 3) ^ fq) << 4) | ((tok & 7) << 1))) = (unsigned short)b;
;             }
;     LDS_WAIT();
; #pragma unroll
;     for (int i = 0; i < 4; ++i) {
;         const int q = lane + 64 * i, ch = q >> 3, tc = q & 7;
;         const u32x4 o = *(const LAS u32x4*)(x + ch * 128 + ((tc ^ ((ch >> 3) & 3)) << 4));
;         *(u32x4*)(dst + (size_t)ch * T + tc * 8) = o;
;     }
;     LDS_WAIT();
; }
;     __device__ __forceinline__ void operator()(const f32x4 (&acc)[2][2][4][2], const Unit& u, int wr, int wc, int fr, int fq, LAS unsigned char* xs, int wid, int lane) const {
;     ...
; #pragma unroll
;             for (int ai = 0; ai < 2; ++ai)
; #pragma unroll
;                 for (int bj = 0; bj < 2; ++bj) {
;                     f32x4 v[4][2];
; #pragma unroll
;                     for (int m = 0; m < 4; ++m) { v[m][0] = acc[ai][bj][m][0] * rs[ai][m]; v[m][1] = acc[ai][bj][m][1] * rs[ai][m]; }
;                     if (ODD) {
;                         float* vss = (float*)(ws + OFF_VSS);
; #pragma unroll
;                         for (int m = 0; m < 4; ++m) {
;                             float s = 0.f;
; #pragma unroll
;                             for (int n = 0; n < 2; ++n) s += (v[m][n][0] * v[m][n][0] + v[m][n][1] * v[m][n][1]) + (v[m][n][2] * v[m][n][2] + v[m][n][3] * v[m][n][3]);
;                             s += __shfl_xor(s, 16); s += __shfl_xor(s, 32);
;                             if (fq == 0) vss[(size_t)(row0 + ai * 128 + m * 16 + fr) * 32 + (2 * (pn - 24) + bj) * 4 + wc] = s;
;                         }
;                     }
;                     tstore_sub(v, base + (size_t)(bj * 128 + wc * 32) * T + row0 + ai * 128, x, fr, fq, lane);
.LBB0_716:
	s_or_b64 exec, exec, s[72:73]
	v_cvt_pk_bf16_f32 v159, v184, v137
	ds_write_b16 v238, v159
	v_cvt_pk_bf16_f32 v159, v185, v137
	ds_write_b16 v238, v159 offset:128
	v_cvt_pk_bf16_f32 v159, v182, v137
	ds_write_b16 v238, v159 offset:256
	v_cvt_pk_bf16_f32 v159, v183, v137
	ds_write_b16 v238, v159 offset:384
	v_cvt_pk_bf16_f32 v159, v180, v137
	ds_write_b16 v238, v159 offset:512
	v_cvt_pk_bf16_f32 v159, v181, v137
	ds_write_b16 v238, v159 offset:640
	v_cvt_pk_bf16_f32 v159, v178, v137
	ds_write_b16 v238, v159 offset:768
	v_cvt_pk_bf16_f32 v159, v179, v137
	ds_write_b16 v238, v159 offset:896
	v_cvt_pk_bf16_f32 v159, v192, v137
	ds_write_b16 v239, v159
	v_cvt_pk_bf16_f32 v159, v193, v137
	ds_write_b16 v239, v159 offset:128
	v_cvt_pk_bf16_f32 v159, v190, v137
	ds_write_b16 v239, v159 offset:256
	v_cvt_pk_bf16_f32 v159, v191, v137
	ds_write_b16 v239, v159 offset:384
	v_cvt_pk_bf16_f32 v159, v188, v137
	ds_write_b16 v239, v159 offset:512
	v_cvt_pk_bf16_f32 v159, v189, v137
	ds_write_b16 v239, v159 offset:640
	v_cvt_pk_bf16_f32 v159, v186, v137
	ds_write_b16 v239, v159 offset:768
	v_cvt_pk_bf16_f32 v159, v187, v137
	ds_write_b16 v239, v159 offset:896
	v_cvt_pk_bf16_f32 v159, v206, v137
	ds_write_b16 v240, v159
	v_cvt_pk_bf16_f32 v159, v207, v137
	ds_write_b16 v240, v159 offset:128
	v_cvt_pk_bf16_f32 v159, v204, v137
	ds_write_b16 v240, v159 offset:256
	v_cvt_pk_bf16_f32 v159, v205, v137
	ds_write_b16 v240, v159 offset:384
	v_cvt_pk_bf16_f32 v159, v202, v137
	ds_write_b16 v240, v159 offset:512
	v_cvt_pk_bf16_f32 v159, v203, v137
	ds_write_b16 v240, v159 offset:640
	v_cvt_pk_bf16_f32 v159, v200, v137
	ds_write_b16 v240, v159 offset:768
	v_cvt_pk_bf16_f32 v159, v201, v137
	ds_write_b16 v240, v159 offset:896
	v_cvt_pk_bf16_f32 v159, v214, v137
	ds_write_b16 v241, v159
	v_cvt_pk_bf16_f32 v159, v215, v137
	ds_write_b16 v241, v159 offset:128
	v_cvt_pk_bf16_f32 v159, v212, v137
	ds_write_b16 v241, v159 offset:256
	v_cvt_pk_bf16_f32 v159, v213, v137
	ds_write_b16 v241, v159 offset:384
	v_cvt_pk_bf16_f32 v159, v210, v137
	ds_write_b16 v241, v159 offset:512
	v_cvt_pk_bf16_f32 v159, v211, v137
	ds_write_b16 v241, v159 offset:640
	v_cvt_pk_bf16_f32 v159, v208, v137
	s_ashr_i32 s69, s68, 31
	ds_write_b16 v241, v159 offset:768
	v_cvt_pk_bf16_f32 v159, v209, v137
	ds_write_b16 v241, v159 offset:896
	s_lshl_b64 s[0:1], s[68:69], 1
	s_waitcnt lgkmcnt(0)
	s_add_u32 s0, s70, s0
	ds_read_b128 v[182:185], v242
	ds_read_b128 v[190:193], v243
	s_addc_u32 s1, s71, s1
	v_lshl_add_u64 v[176:177], s[0:1], 0, v[136:137]
	v_lshl_add_u64 v[212:213], v[176:177], 0, s[48:49]
	v_lshlrev_b32_e32 v180, 1, v138
	v_mov_b32_e32 v181, v137
	ds_read_b128 v[200:203], v244
	ds_read_b128 v[208:211], v245
	v_lshl_add_u64 v[186:187], v[212:213], 0, v[180:181]
	v_mov_b32_e32 v175, v174
	s_waitcnt lgkmcnt(3)
	global_store_dwordx4 v[186:187], v[182:185], off nt
	v_lshlrev_b32_e32 v178, 1, v142
	v_mov_b32_e32 v179, v137
	v_lshlrev_b32_e32 v182, 1, v140
	v_mov_b32_e32 v183, v137
	v_mov_b32_e32 v184, v174
	v_mov_b32_e32 v185, v174
	v_lshl_add_u64 v[188:189], v[212:213], 0, v[182:183]
	v_pk_mul_f32 v[204:205], v[122:123], v[184:185]
	v_pk_mul_f32 v[206:207], v[120:121], v[174:175]
	s_waitcnt lgkmcnt(2)
	global_store_dwordx4 v[188:189], v[190:193], off nt
	v_mul_f32_e32 v159, v207, v207
	v_mul_f32_e32 v161, v205, v205
	v_lshl_add_u64 v[190:191], v[212:213], 0, v[178:179]
	s_waitcnt lgkmcnt(1)
	global_store_dwordx4 v[190:191], v[200:203], off nt
	v_fmac_f32_e32 v159, v206, v206
	v_fmac_f32_e32 v161, v204, v204
	v_pk_mul_f32 v[200:201], v[114:115], v[184:185]
	v_pk_mul_f32 v[202:203], v[112:113], v[174:175]
	v_add_f32_e32 v159, v159, v161
	v_mul_f32_e32 v161, v203, v203
	v_mul_f32_e32 v165, v201, v201
	v_fmac_f32_e32 v161, v202, v202
	v_fmac_f32_e32 v165, v200, v200
	v_add_f32_e32 v161, v161, v165
	v_add_f32_e32 v159, v159, v161
	ds_bpermute_b32 v161, v151, v159
	v_lshlrev_b32_e32 v184, 1, v144
	v_mov_b32_e32 v185, v137
	v_lshl_add_u64 v[192:193], v[212:213], 0, v[184:185]
	s_waitcnt lgkmcnt(1)
	global_store_dwordx4 v[192:193], v[208:211], off nt
	s_waitcnt lgkmcnt(0)
	v_add_f32_e32 v159, v159, v161
	ds_bpermute_b32 v161, v246, v159
	s_waitcnt lgkmcnt(0)
	s_and_saveexec_b64 s[72:73], s[8:9]
	s_cbranch_execz .LBB0_718
	v_lshlrev_b64 v[208:209], 7, v[162:163]
	v_lshl_add_u64 v[208:209], s[66:67], 0, v[208:209]
	s_waitcnt lgkmcnt(0)
	v_add_f32_e32 v159, v159, v161
	global_store_dword v[208:209], v159, off offset:-752

; #define LAS __attribute__((address_space(3)))
; __device__ __forceinline__ unsigned cvt_pk_bf16(float lo, float hi) { unsigned r; asm("v_cvt_pk_bf16_f32 %0, %1, %2" : "=v"(r) : "v"(lo), "v"(hi)); return r; }
; __device__ __forceinline__ void tstore_sub(const f32x4 (&v)[4][2], bf16_t* dst  , LAS unsigned char* x, int fr, int fq, int lane) {
; #pragma unroll
;     for (int m = 0; m < 4; ++m)
; #pragma unroll
;         for (int n = 0; n < 2; ++n)
; #pragma unroll
;             for (int j = 0; j < 4; ++j) {
;                 const int ch = 8 * fq + 4 * n + j, tok = 16 * m + fr;
;                 const unsigned b = cvt_pk_bf16(v[m][n][j], 0.f);
;                 *(LAS unsigned short*)(x + ch * 128 + ((((tok >> 3) ^ fq) << 4) | ((tok & 7) << 1))) = (unsigned short)b;
;             }
;     LDS_WAIT();
; #pragma unroll
;     for (int i = 0; i < 4; ++i) {
;         const int q = lane + 64 * i, ch = q >> 3, tc = q & 7;
;         const u32x4 o = *(const LAS u32x4*)(x + ch * 128 + ((tc ^ ((ch >> 3) & 3)) << 4));
;         *(u32x4*)(dst + (size_t)ch * T + tc * 8) = o;
;     }
;     LDS_WAIT();
; }
;     __device__ __forceinline__ void operator()(const f32x4 (&acc)[2][2][4][2], const Unit& u, int wr, int wc, int fr, int fq, LAS unsigned char* xs, int wid, int lane) const {
;     ...
; #pragma unroll
;             for (int ai = 0; ai < 2; ++ai)
; #pragma unroll
;                 for (int bj = 0; bj < 2; ++bj) {
;                     f32x4 v[4][2];
; #pragma unroll
;                     for (int m = 0; m < 4; ++m) { v[m][0] = acc[ai][bj][m][0] * rs[ai][m]; v[m][1] = acc[ai][bj][m][1] * rs[ai][m]; }
;                     if (ODD) {
;                         float* vss = (float*)(ws + OFF_VSS);
; #pragma unroll
;                         for (int m = 0; m < 4; ++m) {
;                             float s = 0.f;
; #pragma unroll
;                             for (int n = 0; n < 2; ++n) s += (v[m][n][0] * v[m][n][0] + v[m][n][1] * v[m][n][1]) + (v[m][n][2] * v[m][n][2] + v[m][n][3] * v[m][n][3]);
;                             s += __shfl_xor(s, 16); s += __shfl_xor(s, 32);
;                             if (fq == 0) vss[(size_t)(row0 + ai * 128 + m * 16 + fr) * 32 + (2 * (pn - 24) + bj) * 4 + wc] = s;
;                         }
;                     }
;                     tstore_sub(v, base + (size_t)(bj * 128 + wc * 32) * T + row0 + ai * 128, x, fr, fq, lane);
.LBB0_724:
	s_or_b64 exec, exec, s[72:73]
	v_cvt_pk_bf16_f32 v159, v206, v137
	ds_write_b16 v238, v159
	v_cvt_pk_bf16_f32 v159, v207, v137
	ds_write_b16 v238, v159 offset:128
	v_cvt_pk_bf16_f32 v159, v204, v137
	ds_write_b16 v238, v159 offset:256
	v_cvt_pk_bf16_f32 v159, v205, v137
	ds_write_b16 v238, v159 offset:384
	v_cvt_pk_bf16_f32 v159, v202, v137
	ds_write_b16 v238, v159 offset:512
	v_cvt_pk_bf16_f32 v159, v203, v137
	ds_write_b16 v238, v159 offset:640
	v_cvt_pk_bf16_f32 v159, v200, v137
	ds_write_b16 v238, v159 offset:768
	v_cvt_pk_bf16_f32 v159, v201, v137
	ds_write_b16 v238, v159 offset:896
	v_cvt_pk_bf16_f32 v159, v214, v137
	ds_write_b16 v239, v159
	v_cvt_pk_bf16_f32 v159, v215, v137
	ds_write_b16 v239, v159 offset:128
	v_cvt_pk_bf16_f32 v159, v212, v137
	ds_write_b16 v239, v159 offset:256
	v_cvt_pk_bf16_f32 v159, v213, v137
	ds_write_b16 v239, v159 offset:384
	v_cvt_pk_bf16_f32 v159, v210, v137
	ds_write_b16 v239, v159 offset:512
	v_cvt_pk_bf16_f32 v159, v211, v137
	ds_write_b16 v239, v159 offset:640
	v_cvt_pk_bf16_f32 v159, v208, v137
	ds_write_b16 v239, v159 offset:768
	v_cvt_pk_bf16_f32 v159, v209, v137
	ds_write_b16 v239, v159 offset:896
	v_cvt_pk_bf16_f32 v159, v220, v137
	ds_write_b16 v240, v159
	v_cvt_pk_bf16_f32 v159, v221, v137
	ds_write_b16 v240, v159 offset:128
	v_cvt_pk_bf16_f32 v159, v218, v137
	ds_write_b16 v240, v159 offset:256
	v_cvt_pk_bf16_f32 v159, v219, v137
	ds_write_b16 v240, v159 offset:384
	v_cvt_pk_bf16_f32 v159, v216, v137
	ds_write_b16 v240, v159 offset:512
	v_cvt_pk_bf16_f32 v159, v217, v137
	ds_write_b16 v240, v159 offset:640
	v_cvt_pk_bf16_f32 v159, v198, v137
	ds_write_b16 v240, v159 offset:768
	v_cvt_pk_bf16_f32 v159, v199, v137
	ds_write_b16 v240, v159 offset:896
	v_cvt_pk_bf16_f32 v159, v226, v137
	ds_write_b16 v241, v159
	v_cvt_pk_bf16_f32 v159, v227, v137
	ds_write_b16 v241, v159 offset:128
	v_cvt_pk_bf16_f32 v159, v224, v137
	ds_write_b16 v241, v159 offset:256
	v_cvt_pk_bf16_f32 v159, v225, v137
	ds_write_b16 v241, v159 offset:384
	v_cvt_pk_bf16_f32 v159, v222, v137
	ds_write_b16 v241, v159 offset:512
	v_cvt_pk_bf16_f32 v159, v223, v137
	ds_write_b16 v241, v159 offset:640
	v_cvt_pk_bf16_f32 v159, v196, v137
	ds_write_b16 v241, v159 offset:768
	v_cvt_pk_bf16_f32 v159, v197, v137
	ds_write_b16 v241, v159 offset:896
	s_waitcnt lgkmcnt(0)
	ds_read_b128 v[194:197], v242
	ds_read_b128 v[198:201], v243
	s_lshl_b32 s72, s34, 1
	s_mov_b32 s73, s49
	v_lshl_add_u64 v[210:211], v[176:177], 0, s[72:73]
	v_mov_b32_e32 v181, v137
	v_pk_mul_f32 v[206:207], v[62:63], v[166:167] op_sel_hi:[1,0]
	v_pk_mul_f32 v[208:209], v[60:61], v[166:167] op_sel_hi:[1,0]
	v_lshl_add_u64 v[202:203], v[210:211], 0, v[180:181]
	v_mul_f32_e32 v159, v209, v209
	s_waitcnt lgkmcnt(14)
	v_mul_f32_e32 v161, v207, v207
	s_waitcnt lgkmcnt(1)
	global_store_dwordx4 v[202:203], v[194:197], off nt
	v_pk_mul_f32 v[202:203], v[54:55], v[166:167] op_sel_hi:[1,0]
	v_pk_mul_f32 v[204:205], v[52:53], v[166:167] op_sel_hi:[1,0]
	v_fmac_f32_e32 v159, v208, v208
	v_fmac_f32_e32 v161, v206, v206
	v_add_f32_e32 v159, v159, v161
	v_mul_f32_e32 v161, v205, v205
	v_mul_f32_e32 v163, v203, v203
	v_fmac_f32_e32 v161, v204, v204
	v_fmac_f32_e32 v163, v202, v202
	v_add_f32_e32 v161, v161, v163
	v_mov_b32_e32 v183, v137
	v_add_f32_e32 v159, v159, v161
	v_lshl_add_u64 v[194:195], v[210:211], 0, v[182:183]
	ds_bpermute_b32 v161, v151, v159
	s_waitcnt lgkmcnt(1)
	global_store_dwordx4 v[194:195], v[198:201], off nt
	ds_read_b128 v[194:197], v244
	ds_read_b128 v[198:201], v245
	v_mov_b32_e32 v179, v137
	v_lshl_add_u64 v[212:213], v[210:211], 0, v[178:179]
	v_mov_b32_e32 v185, v137
	s_waitcnt lgkmcnt(2)
	v_add_f32_e32 v159, v159, v161
	s_waitcnt lgkmcnt(1)
	global_store_dwordx4 v[212:213], v[194:197], off nt
	ds_bpermute_b32 v161, v246, v159
	s_nop 0
	v_lshl_add_u64 v[194:195], v[210:211], 0, v[184:185]
	s_waitcnt lgkmcnt(1)
	global_store_dwordx4 v[194:195], v[198:201], off nt
	s_waitcnt lgkmcnt(0)
	s_nop 1
	v_add_u32_e32 v200, 0x80, v162
	v_ashrrev_i32_e32 v201, 31, v200
	s_and_saveexec_b64 s[74:75], s[8:9]
	s_cbranch_execz .LBB0_726
	v_lshlrev_b64 v[194:195], 7, v[200:201]
	v_lshl_add_u64 v[194:195], s[66:67], 0, v[194:195]
	s_waitcnt lgkmcnt(0)
	v_add_f32_e32 v159, v159, v161
	global_store_dword v[194:195], v159, off offset:-768

; #define LAS __attribute__((address_space(3)))
; __device__ __forceinline__ unsigned cvt_pk_bf16(float lo, float hi) { unsigned r; asm("v_cvt_pk_bf16_f32 %0, %1, %2" : "=v"(r) : "v"(lo), "v"(hi)); return r; }
; __device__ __forceinline__ void tstore_sub(const f32x4 (&v)[4][2], bf16_t* dst  , LAS unsigned char* x, int fr, int fq, int lane) {
; #pragma unroll
;     for (int m = 0; m < 4; ++m)
; #pragma unroll
;         for (int n = 0; n < 2; ++n)
; #pragma unroll
;             for (int j = 0; j < 4; ++j) {
;                 const int ch = 8 * fq + 4 * n + j, tok = 16 * m + fr;
;                 const unsigned b = cvt_pk_bf16(v[m][n][j], 0.f);
;                 *(LAS unsigned short*)(x + ch * 128 + ((((tok >> 3) ^ fq) << 4) | ((tok & 7) << 1))) = (unsigned short)b;
;             }
;     LDS_WAIT();
; #pragma unroll
;     for (int i = 0; i < 4; ++i) {
;         const int q = lane + 64 * i, ch = q >> 3, tc = q & 7;
;         const u32x4 o = *(const LAS u32x4*)(x + ch * 128 + ((tc ^ ((ch >> 3) & 3)) << 4));
;         *(u32x4*)(dst + (size_t)ch * T + tc * 8) = o;
;     }
;     LDS_WAIT();
; }
;     __device__ __forceinline__ void operator()(const f32x4 (&acc)[2][2][4][2], const Unit& u, int wr, int wc, int fr, int fq, LAS unsigned char* xs, int wid, int lane) const {
;     ...
; #pragma unroll
;             for (int ai = 0; ai < 2; ++ai)
; #pragma unroll
;                 for (int bj = 0; bj < 2; ++bj) {
;                     f32x4 v[4][2];
; #pragma unroll
;                     for (int m = 0; m < 4; ++m) { v[m][0] = acc[ai][bj][m][0] * rs[ai][m]; v[m][1] = acc[ai][bj][m][1] * rs[ai][m]; }
;                     if (ODD) {
;                         float* vss = (float*)(ws + OFF_VSS);
; #pragma unroll
;                         for (int m = 0; m < 4; ++m) {
;                             float s = 0.f;
; #pragma unroll
;                             for (int n = 0; n < 2; ++n) s += (v[m][n][0] * v[m][n][0] + v[m][n][1] * v[m][n][1]) + (v[m][n][2] * v[m][n][2] + v[m][n][3] * v[m][n][3]);
;                             s += __shfl_xor(s, 16); s += __shfl_xor(s, 32);
;                             if (fq == 0) vss[(size_t)(row0 + ai * 128 + m * 16 + fr) * 32 + (2 * (pn - 24) + bj) * 4 + wc] = s;
;                         }
;                     }
;                     tstore_sub(v, base + (size_t)(bj * 128 + wc * 32) * T + row0 + ai * 128, x, fr, fq, lane);
.LBB0_732:
	s_or_b64 exec, exec, s[74:75]
	v_cvt_pk_bf16_f32 v159, v208, v137
	ds_write_b16 v238, v159
	v_cvt_pk_bf16_f32 v159, v209, v137
	ds_write_b16 v238, v159 offset:128
	v_cvt_pk_bf16_f32 v159, v206, v137
	ds_write_b16 v238, v159 offset:256
	v_cvt_pk_bf16_f32 v159, v207, v137
	ds_write_b16 v238, v159 offset:384
	v_cvt_pk_bf16_f32 v159, v204, v137
	ds_write_b16 v238, v159 offset:512
	v_cvt_pk_bf16_f32 v159, v205, v137
	ds_write_b16 v238, v159 offset:640
	v_cvt_pk_bf16_f32 v159, v202, v137
	ds_write_b16 v238, v159 offset:768
	v_cvt_pk_bf16_f32 v159, v203, v137
	ds_write_b16 v238, v159 offset:896
	v_cvt_pk_bf16_f32 v159, v216, v137
	ds_write_b16 v239, v159
	v_cvt_pk_bf16_f32 v159, v217, v137
	ds_write_b16 v239, v159 offset:128
	v_cvt_pk_bf16_f32 v159, v214, v137
	ds_write_b16 v239, v159 offset:256
	v_cvt_pk_bf16_f32 v159, v215, v137
	ds_write_b16 v239, v159 offset:384
	v_cvt_pk_bf16_f32 v159, v212, v137
	ds_write_b16 v239, v159 offset:512
	v_cvt_pk_bf16_f32 v159, v213, v137
	ds_write_b16 v239, v159 offset:640
	v_cvt_pk_bf16_f32 v159, v210, v137
	ds_write_b16 v239, v159 offset:768
	v_cvt_pk_bf16_f32 v159, v211, v137
	ds_write_b16 v239, v159 offset:896
	v_cvt_pk_bf16_f32 v159, v224, v137
	ds_write_b16 v240, v159
	v_cvt_pk_bf16_f32 v159, v225, v137
	ds_write_b16 v240, v159 offset:128
	v_cvt_pk_bf16_f32 v159, v222, v137
	ds_write_b16 v240, v159 offset:256
	v_cvt_pk_bf16_f32 v159, v223, v137
	ds_write_b16 v240, v159 offset:384
	v_cvt_pk_bf16_f32 v159, v220, v137
	ds_write_b16 v240, v159 offset:512
	v_cvt_pk_bf16_f32 v159, v221, v137
	ds_write_b16 v240, v159 offset:640
	v_cvt_pk_bf16_f32 v159, v218, v137
	ds_write_b16 v240, v159 offset:768
	v_cvt_pk_bf16_f32 v159, v219, v137
	ds_write_b16 v240, v159 offset:896
	v_cvt_pk_bf16_f32 v159, v232, v137
	ds_write_b16 v241, v159
	v_cvt_pk_bf16_f32 v159, v233, v137
	ds_write_b16 v241, v159 offset:128
	v_cvt_pk_bf16_f32 v159, v230, v137
	ds_write_b16 v241, v159 offset:256
	v_cvt_pk_bf16_f32 v159, v231, v137
	ds_write_b16 v241, v159 offset:384
	v_cvt_pk_bf16_f32 v159, v228, v137
	ds_write_b16 v241, v159 offset:512
	v_cvt_pk_bf16_f32 v159, v229, v137
	v_mov_b32_e32 v167, v166
	ds_write_b16 v241, v159 offset:640
	v_cvt_pk_bf16_f32 v159, v226, v137
	v_mov_b32_e32 v202, v166
	v_mov_b32_e32 v203, v166
	ds_write_b16 v241, v159 offset:768
	v_cvt_pk_bf16_f32 v159, v227, v137
	v_pk_mul_f32 v[206:207], v[58:59], v[202:203]
	v_pk_mul_f32 v[208:209], v[56:57], v[166:167]
	ds_write_b16 v241, v159 offset:896
	v_mul_f32_e32 v159, v209, v209
	s_waitcnt lgkmcnt(14)
	v_mul_f32_e32 v161, v207, v207
	v_pk_mul_f32 v[202:203], v[50:51], v[202:203]
	v_pk_mul_f32 v[204:205], v[48:49], v[166:167]
	v_fmac_f32_e32 v159, v208, v208
	v_fmac_f32_e32 v161, v206, v206
	v_add_f32_e32 v159, v159, v161
	v_mul_f32_e32 v161, v205, v205
	v_mul_f32_e32 v163, v203, v203
	v_fmac_f32_e32 v161, v204, v204
	v_fmac_f32_e32 v163, v202, v202
	v_add_f32_e32 v161, v161, v163
	v_add_f32_e32 v159, v159, v161
	ds_bpermute_b32 v161, v151, v159
	s_waitcnt lgkmcnt(0)
	ds_read_b128 v[210:213], v242
	ds_read_b128 v[214:217], v243
	ds_read_b128 v[218:221], v244
	ds_read_b128 v[222:225], v245
	s_waitcnt lgkmcnt(3)
	global_store_dwordx4 v[186:187], v[210:213], off offset:256 nt
	s_waitcnt lgkmcnt(2)
	global_store_dwordx4 v[188:189], v[214:217], off offset:256 nt
	s_waitcnt lgkmcnt(1)
	global_store_dwordx4 v[190:191], v[218:221], off offset:256 nt
	s_waitcnt lgkmcnt(0)
	global_store_dwordx4 v[192:193], v[222:225], off offset:256 nt
	v_add_f32_e32 v159, v159, v161
	ds_bpermute_b32 v161, v246, v159
	s_waitcnt lgkmcnt(0)
	s_and_saveexec_b64 s[74:75], s[8:9]
	s_cbranch_execz .LBB0_734
	v_lshlrev_b64 v[186:187], 7, v[200:201]
	v_lshl_add_u64 v[186:187], s[66:67], 0, v[186:187]
	s_waitcnt lgkmcnt(0)
	v_add_f32_e32 v159, v159, v161
	global_store_dword v[186:187], v159, off offset:-752

; #define LAS __attribute__((address_space(3)))
; __device__ __forceinline__ unsigned cvt_pk_bf16(float lo, float hi) { unsigned r; asm("v_cvt_pk_bf16_f32 %0, %1, %2" : "=v"(r) : "v"(lo), "v"(hi)); return r; }
; __device__ __forceinline__ float silu_f(float x) { return x * __builtin_amdgcn_rcpf(1.f + __builtin_amdgcn_exp2f(-LOG2E * x)); }
; #define LDS_WAIT() asm volatile("s_waitcnt lgkmcnt(0)" ::: "memory")
; __device__ __forceinline__ void tstore_sub(const f32x4 (&v)[4][2], bf16_t* dst  , LAS unsigned char* x, int fr, int fq, int lane) {
; #pragma unroll
;     for (int m = 0; m < 4; ++m)
; #pragma unroll
;         for (int n = 0; n < 2; ++n)
; #pragma unroll
;             for (int j = 0; j < 4; ++j) {
;                 const int ch = 8 * fq + 4 * n + j, tok = 16 * m + fr;
;                 const unsigned b = cvt_pk_bf16(v[m][n][j], 0.f);
;                 *(LAS unsigned short*)(x + ch * 128 + ((((tok >> 3) ^ fq) << 4) | ((tok & 7) << 1))) = (unsigned short)b;
;             }
;     LDS_WAIT();
; #pragma unroll
;     for (int i = 0; i < 4; ++i) {
;         const int q = lane + 64 * i, ch = q >> 3, tc = q & 7;
;         const u32x4 o = *(const LAS u32x4*)(x + ch * 128 + ((tc ^ ((ch >> 3) & 3)) << 4));
;         *(u32x4*)(dst + (size_t)ch * T + tc * 8) = o;
;     }
;     LDS_WAIT();
; }
;     __device__ __forceinline__ void operator()(const f32x4 (&acc)[2][2][4][2], const Unit& u, int wr, int wc, int fr, int fq, LAS unsigned char* xs, int wid, int lane) const {
;     ...
;         } else if (mode == 1 || mode == 2) {
; #pragma unroll
;             for (int ai = 0; ai < 2; ++ai)
; #pragma unroll
;                 for (int m = 0; m < 4; ++m) {
;                     const float r = rs[ai][m];
;                     bf16_t* rowp = base + (size_t)(row0 + ai * 128 + m * 16 + fr) * ldc + wc * 32 + 8 * fq;
;                     float o[8];
; #pragma unroll
;                     for (int n = 0; n < 2; ++n)
; #pragma unroll
;                         for (int j = 0; j < 4; ++j) { const float a = acc[ai][0][m][n][j] * r, b = acc[ai][1][m][n][j] * r; o[4 * n + j] = (mode == 1) ? a * b : a * silu_f(b); }
;                     u32x4 w; w.x = cvt_pk_bf16(o[0], o[1]); w.y = cvt_pk_bf16(o[2], o[3]); w.z = cvt_pk_bf16(o[4], o[5]); w.w = cvt_pk_bf16(o[6], o[7]);
;                     *(u32x4*)rowp = w;
;                     __builtin_amdgcn_sched_barrier(0);
;                 }
.LBB0_740:
	s_or_b64 exec, exec, s[74:75]
	v_cvt_pk_bf16_f32 v151, v208, v137
	ds_write_b16 v238, v151
	v_cvt_pk_bf16_f32 v151, v209, v137
	ds_write_b16 v238, v151 offset:128
	v_cvt_pk_bf16_f32 v151, v206, v137
	ds_write_b16 v238, v151 offset:256
	v_cvt_pk_bf16_f32 v151, v207, v137
	ds_write_b16 v238, v151 offset:384
	v_cvt_pk_bf16_f32 v151, v204, v137
	ds_write_b16 v238, v151 offset:512
	v_cvt_pk_bf16_f32 v151, v205, v137
	ds_write_b16 v238, v151 offset:640
	v_cvt_pk_bf16_f32 v151, v202, v137
	ds_write_b16 v238, v151 offset:768
	v_cvt_pk_bf16_f32 v151, v203, v137
	ds_write_b16 v238, v151 offset:896
	v_cvt_pk_bf16_f32 v151, v192, v137
	ds_write_b16 v239, v151
	v_cvt_pk_bf16_f32 v151, v193, v137
	ds_write_b16 v239, v151 offset:128
	v_cvt_pk_bf16_f32 v151, v190, v137
	ds_write_b16 v239, v151 offset:256
	v_cvt_pk_bf16_f32 v151, v191, v137
	ds_write_b16 v239, v151 offset:384
	v_cvt_pk_bf16_f32 v151, v188, v137
	ds_write_b16 v239, v151 offset:512
	v_cvt_pk_bf16_f32 v151, v189, v137
	ds_write_b16 v239, v151 offset:640
	v_cvt_pk_bf16_f32 v151, v186, v137
	ds_write_b16 v239, v151 offset:768
	v_cvt_pk_bf16_f32 v151, v187, v137
	ds_write_b16 v239, v151 offset:896
	v_cvt_pk_bf16_f32 v151, v212, v137
	ds_write_b16 v240, v151
	v_cvt_pk_bf16_f32 v151, v213, v137
	ds_write_b16 v240, v151 offset:128
	v_cvt_pk_bf16_f32 v151, v210, v137
	ds_write_b16 v240, v151 offset:256
	v_cvt_pk_bf16_f32 v151, v211, v137
	ds_write_b16 v240, v151 offset:384
	v_cvt_pk_bf16_f32 v151, v200, v137
	ds_write_b16 v240, v151 offset:512
	v_cvt_pk_bf16_f32 v151, v201, v137
	ds_write_b16 v240, v151 offset:640
	v_cvt_pk_bf16_f32 v151, v198, v137
	ds_write_b16 v240, v151 offset:768
	v_cvt_pk_bf16_f32 v151, v199, v137
	ds_write_b16 v240, v151 offset:896
	v_cvt_pk_bf16_f32 v151, v218, v137
	ds_write_b16 v241, v151
	v_cvt_pk_bf16_f32 v151, v219, v137
	ds_write_b16 v241, v151 offset:128
	v_cvt_pk_bf16_f32 v151, v216, v137
	ds_write_b16 v241, v151 offset:256
	v_cvt_pk_bf16_f32 v151, v217, v137
	ds_write_b16 v241, v151 offset:384
	v_cvt_pk_bf16_f32 v151, v214, v137
	ds_write_b16 v241, v151 offset:512
	v_cvt_pk_bf16_f32 v151, v215, v137
	ds_write_b16 v241, v151 offset:640
	v_cvt_pk_bf16_f32 v151, v196, v137
	ds_write_b16 v241, v151 offset:768
	v_cvt_pk_bf16_f32 v151, v197, v137
	ds_write_b16 v241, v151 offset:896
	s_waitcnt lgkmcnt(0)
	ds_read_b128 v[186:189], v242
	ds_read_b128 v[190:193], v243
	s_mov_b32 s73, s49
	v_lshl_add_u64 v[176:177], v[176:177], 0, s[72:73]
	s_mov_b64 s[0:1], 0x100
	v_lshl_add_u64 v[176:177], v[176:177], 0, s[0:1]
	v_mov_b32_e32 v181, v137
	v_lshl_add_u64 v[180:181], v[176:177], 0, v[180:181]
	v_mov_b32_e32 v183, v137
	s_waitcnt lgkmcnt(1)
	global_store_dwordx4 v[180:181], v[186:189], off nt
	v_mov_b32_e32 v179, v137
	v_mov_b32_e32 v185, v137
	v_lshl_add_u64 v[186:187], v[176:177], 0, v[182:183]
	ds_read_b128 v[180:183], v244
	s_waitcnt lgkmcnt(1)
	global_store_dwordx4 v[186:187], v[190:193], off nt
	ds_read_b128 v[186:189], v245
	v_lshl_add_u64 v[178:179], v[176:177], 0, v[178:179]
	v_lshl_add_u64 v[176:177], v[176:177], 0, v[184:185]
	s_waitcnt lgkmcnt(1)
	global_store_dwordx4 v[178:179], v[180:183], off nt
	s_waitcnt lgkmcnt(0)
	global_store_dwordx4 v[176:177], v[186:189], off nt
	s_waitcnt lgkmcnt(0)
	s_branch .LBB0_707
.LBB0_741:
	s_waitcnt lgkmcnt(7)
	v_mul_f32_e32 v120, v120, v174
	v_mul_f32_e32 v159, 0xbfb8aa3b, v120
	s_add_u32 s0, s70, s89
	v_exp_f32_e32 v159, v159
	s_addc_u32 s1, s71, 0
	v_mov_b32_e32 v151, v137
	v_lshl_add_u64 v[176:177], s[0:1], 0, v[150:151]
	s_ashr_i32 s0, s68, 31
	v_mul_lo_u32 v151, s65, v162
	s_mul_i32 s0, s64, s0
	v_mad_u64_u32 v[178:179], s[18:19], s64, v162, 0
	v_add3_u32 v179, v179, s0, v151
	v_add_f32_e32 v151, 1.0, v159
	v_rcp_f32_e32 v151, v151
	v_mul_f32_e32 v121, v121, v174
	v_mul_f32_e32 v159, 0xbfb8aa3b, v121
	v_exp_f32_e32 v159, v159
	v_mul_f32_e32 v151, v120, v151
	v_mul_f32_e32 v124, v124, v174
	v_cndmask_b32_e64 v120, v151, v120, s[12:13]
	v_mul_f32_e32 v120, v124, v120
	v_add_f32_e32 v124, 1.0, v159
	v_mul_f32_e32 v122, v122, v174
	v_rcp_f32_e32 v124, v124
	v_mul_f32_e32 v151, 0xbfb8aa3b, v122
	v_exp_f32_e32 v151, v151
	v_mul_f32_e32 v123, v123, v174
	v_mul_f32_e32 v124, v121, v124
	v_cndmask_b32_e64 v121, v124, v121, s[12:13]
	v_add_f32_e32 v124, 1.0, v151
	v_mul_f32_e32 v151, 0xbfb8aa3b, v123
	v_exp_f32_e32 v151, v151
	v_mul_f32_e32 v125, v125, v174
	v_rcp_f32_e32 v124, v124
	v_mul_f32_e32 v121, v125, v121
	v_mul_f32_e32 v125, v126, v174
	v_add_f32_e32 v126, 1.0, v151
	v_rcp_f32_e32 v126, v126
	v_mul_f32_e32 v124, v122, v124
	v_cndmask_b32_e64 v122, v124, v122, s[12:13]
	v_mul_f32_e32 v112, v112, v174
	v_mul_f32_e32 v122, v125, v122
	v_mul_f32_e32 v125, v123, v126
	v_mul_f32_e32 v126, 0xbfb8aa3b, v112
	v_exp_f32_e32 v126, v126
	v_mul_f32_e32 v124, v127, v174
	v_cndmask_b32_e64 v123, v125, v123, s[12:13]
	v_mul_f32_e32 v123, v124, v123
	v_add_f32_e32 v124, 1.0, v126
	v_rcp_f32_e32 v124, v124
	v_mul_f32_e32 v113, v113, v174
	v_mul_f32_e32 v125, 0xbfb8aa3b, v113
	v_exp_f32_e32 v125, v125
	v_mul_f32_e32 v124, v112, v124
	v_mul_f32_e32 v116, v116, v174
	v_cndmask_b32_e64 v112, v124, v112, s[12:13]
	v_mul_f32_e32 v124, v116, v112
	v_add_f32_e32 v112, 1.0, v125
	v_mul_f32_e32 v114, v114, v174
	v_rcp_f32_e32 v112, v112
	v_mul_f32_e32 v116, 0xbfb8aa3b, v114
	v_exp_f32_e32 v116, v116
	v_mul_f32_e32 v115, v115, v174
	v_mul_f32_e32 v112, v113, v112
	v_cndmask_b32_e64 v112, v112, v113, s[12:13]
	v_add_f32_e32 v113, 1.0, v116
	v_mul_f32_e32 v116, 0xbfb8aa3b, v115
	v_exp_f32_e32 v116, v116
	v_rcp_f32_e32 v113, v113
	v_mul_f32_e32 v117, v117, v174
	v_mul_f32_e32 v125, v117, v112
	v_add_f32_e32 v116, 1.0, v116
	v_rcp_f32_e32 v116, v116
	v_mul_f32_e32 v113, v114, v113
	v_mul_f32_e32 v112, v118, v174
	v_cndmask_b32_e64 v113, v113, v114, s[12:13]
	v_mul_f32_e32 v118, v112, v113
	v_mul_f32_e32 v113, v115, v116
	v_mul_f32_e32 v112, v119, v174
	v_cndmask_b32_e64 v113, v113, v115, s[12:13]
	v_mul_f32_e32 v115, v112, v113
	v_lshl_add_u64 v[116:117], v[178:179], 1, v[176:177]
	v_cvt_pk_bf16_f32 v112, v120, v121
	v_cvt_pk_bf16_f32 v113, v122, v123
	v_cvt_pk_bf16_f32 v114, v124, v125
	v_cvt_pk_bf16_f32 v115, v118, v115
	global_store_dwordx4 v[116:117], v[112:115], off nt
	s_waitcnt lgkmcnt(6)
; __device__ __forceinline__ unsigned cvt_pk_bf16(float lo, float hi) { unsigned r; asm("v_cvt_pk_bf16_f32 %0, %1, %2" : "=v"(r) : "v"(lo), "v"(hi)); return r; }
; __device__ __forceinline__ float silu_f(float x) { return x * __builtin_amdgcn_rcpf(1.f + __builtin_amdgcn_exp2f(-LOG2E * x)); }
;     __device__ __forceinline__ void operator()(const f32x4 (&acc)[2][2][4][2], const Unit& u, int wr, int wc, int fr, int fq, LAS unsigned char* xs, int wid, int lane) const {
;     ...
;             for (int ai = 0; ai < 2; ++ai)
; #pragma unroll
;                 for (int m = 0; m < 4; ++m) {
;                     const float r = rs[ai][m];
;                     bf16_t* rowp = base + (size_t)(row0 + ai * 128 + m * 16 + fr) * ldc + wc * 32 + 8 * fq;
;                     float o[8];
; #pragma unroll
;                     for (int n = 0; n < 2; ++n)
; #pragma unroll
;                         for (int j = 0; j < 4; ++j) { const float a = acc[ai][0][m][n][j] * r, b = acc[ai][1][m][n][j] * r; o[4 * n + j] = (mode == 1) ? a * b : a * silu_f(b); }
;                     u32x4 w; w.x = cvt_pk_bf16(o[0], o[1]); w.y = cvt_pk_bf16(o[2], o[3]); w.z = cvt_pk_bf16(o[4], o[5]); w.w = cvt_pk_bf16(o[6], o[7]);
;                     *(u32x4*)rowp = w;
	v_mul_f32_e32 v104, v104, v172
	v_mul_f32_e32 v113, 0xbfb8aa3b, v104
	v_exp_f32_e32 v115, v113
	v_or_b32_e32 v112, 16, v162
	v_mul_lo_u32 v114, s65, v112
	v_mad_u64_u32 v[112:113], s[18:19], s64, v112, 0
	v_add3_u32 v113, v113, s0, v114
	v_add_f32_e32 v114, 1.0, v115
	v_rcp_f32_e32 v114, v114
	v_mul_f32_e32 v105, v105, v172
	v_mul_f32_e32 v115, 0xbfb8aa3b, v105
	v_exp_f32_e32 v115, v115
	v_mul_f32_e32 v114, v104, v114
	v_mul_f32_e32 v108, v108, v172
	v_cndmask_b32_e64 v104, v114, v104, s[12:13]
	v_mul_f32_e32 v104, v108, v104
	v_add_f32_e32 v108, 1.0, v115
	v_mul_f32_e32 v106, v106, v172
	v_rcp_f32_e32 v108, v108
	v_mul_f32_e32 v114, 0xbfb8aa3b, v106
	v_exp_f32_e32 v114, v114
	v_mul_f32_e32 v107, v107, v172
	v_mul_f32_e32 v108, v105, v108
	v_cndmask_b32_e64 v105, v108, v105, s[12:13]
	v_add_f32_e32 v108, 1.0, v114
	v_mul_f32_e32 v114, 0xbfb8aa3b, v107
	v_exp_f32_e32 v114, v114
	v_mul_f32_e32 v109, v109, v172
	v_rcp_f32_e32 v108, v108
	v_mul_f32_e32 v105, v109, v105
	v_mul_f32_e32 v109, v110, v172
	v_add_f32_e32 v110, 1.0, v114
	v_rcp_f32_e32 v110, v110
	v_mul_f32_e32 v108, v106, v108
	v_cndmask_b32_e64 v106, v108, v106, s[12:13]
	v_mul_f32_e32 v96, v96, v172
	v_mul_f32_e32 v106, v109, v106
	v_mul_f32_e32 v109, v107, v110
	v_mul_f32_e32 v110, 0xbfb8aa3b, v96
	v_exp_f32_e32 v110, v110
	v_mul_f32_e32 v108, v111, v172
	v_cndmask_b32_e64 v107, v109, v107, s[12:13]
	v_mul_f32_e32 v107, v108, v107
	v_add_f32_e32 v108, 1.0, v110
	v_rcp_f32_e32 v108, v108
	v_mul_f32_e32 v97, v97, v172
	v_mul_f32_e32 v109, 0xbfb8aa3b, v97
	v_exp_f32_e32 v109, v109
	v_mul_f32_e32 v108, v96, v108
	v_mul_f32_e32 v100, v100, v172
	v_cndmask_b32_e64 v96, v108, v96, s[12:13]
	v_mul_f32_e32 v108, v100, v96
	v_add_f32_e32 v96, 1.0, v109
	v_mul_f32_e32 v98, v98, v172
	v_rcp_f32_e32 v96, v96
	v_mul_f32_e32 v100, 0xbfb8aa3b, v98
	v_exp_f32_e32 v100, v100
	v_mul_f32_e32 v99, v99, v172
	v_mul_f32_e32 v96, v97, v96
	v_cndmask_b32_e64 v96, v96, v97, s[12:13]
	v_add_f32_e32 v97, 1.0, v100
	v_mul_f32_e32 v100, 0xbfb8aa3b, v99
	v_exp_f32_e32 v100, v100
	v_rcp_f32_e32 v97, v97
	v_mul_f32_e32 v101, v101, v172
	v_mul_f32_e32 v109, v101, v96
	v_add_f32_e32 v100, 1.0, v100
	v_rcp_f32_e32 v100, v100
	v_mul_f32_e32 v97, v98, v97
	v_mul_f32_e32 v96, v102, v172
	v_cndmask_b32_e64 v97, v97, v98, s[12:13]
	v_mul_f32_e32 v102, v96, v97
	v_mul_f32_e32 v97, v99, v100
	v_mul_f32_e32 v96, v103, v172
	v_cndmask_b32_e64 v97, v97, v99, s[12:13]
	v_mul_f32_e32 v99, v96, v97
	v_lshl_add_u64 v[100:101], v[112:113], 1, v[176:177]
	v_cvt_pk_bf16_f32 v96, v104, v105
	v_cvt_pk_bf16_f32 v97, v106, v107
	v_cvt_pk_bf16_f32 v98, v108, v109
	v_cvt_pk_bf16_f32 v99, v102, v99
	global_store_dwordx4 v[100:101], v[96:99], off nt
	s_waitcnt lgkmcnt(5)
	v_mul_f32_e32 v88, v88, v170
	v_mul_f32_e32 v97, 0xbfb8aa3b, v88
	v_exp_f32_e32 v99, v97
	v_or_b32_e32 v96, 32, v162
	v_mul_lo_u32 v98, s65, v96
	v_mad_u64_u32 v[96:97], s[18:19], s64, v96, 0
	v_add3_u32 v97, v97, s0, v98
	v_add_f32_e32 v98, 1.0, v99
	v_rcp_f32_e32 v98, v98
	v_mul_f32_e32 v89, v89, v170
	v_mul_f32_e32 v99, 0xbfb8aa3b, v89
	v_exp_f32_e32 v99, v99
	v_mul_f32_e32 v98, v88, v98
	v_mul_f32_e32 v92, v92, v170
	v_cndmask_b32_e64 v88, v98, v88, s[12:13]
	v_mul_f32_e32 v88, v92, v88
	v_add_f32_e32 v92, 1.0, v99
	v_mul_f32_e32 v90, v90, v170
	v_rcp_f32_e32 v92, v92
	v_mul_f32_e32 v98, 0xbfb8aa3b, v90
	v_exp_f32_e32 v98, v98
	v_mul_f32_e32 v91, v91, v170
	v_mul_f32_e32 v92, v89, v92
	v_cndmask_b32_e64 v89, v92, v89, s[12:13]
	v_add_f32_e32 v92, 1.0, v98
	v_mul_f32_e32 v98, 0xbfb8aa3b, v91
	v_exp_f32_e32 v98, v98
	v_mul_f32_e32 v93, v93, v170
	v_rcp_f32_e32 v92, v92
	v_mul_f32_e32 v89, v93, v89
	v_mul_f32_e32 v93, v94, v170
	v_add_f32_e32 v94, 1.0, v98
	v_rcp_f32_e32 v94, v94
	v_mul_f32_e32 v92, v90, v92
	v_cndmask_b32_e64 v90, v92, v90, s[12:13]
	v_mul_f32_e32 v80, v80, v170
	v_mul_f32_e32 v90, v93, v90
	v_mul_f32_e32 v93, v91, v94
	v_mul_f32_e32 v94, 0xbfb8aa3b, v80
	v_exp_f32_e32 v94, v94
	v_mul_f32_e32 v92, v95, v170
	v_cndmask_b32_e64 v91, v93, v91, s[12:13]
	v_mul_f32_e32 v91, v92, v91
	v_add_f32_e32 v92, 1.0, v94
	v_rcp_f32_e32 v92, v92
	v_mul_f32_e32 v81, v81, v170
	v_mul_f32_e32 v93, 0xbfb8aa3b, v81
	v_exp_f32_e32 v93, v93
	v_mul_f32_e32 v92, v80, v92
	v_mul_f32_e32 v84, v84, v170
	v_cndmask_b32_e64 v80, v92, v80, s[12:13]
	v_mul_f32_e32 v92, v84, v80
	v_add_f32_e32 v80, 1.0, v93
	v_mul_f32_e32 v82, v82, v170
	v_rcp_f32_e32 v80, v80
	v_mul_f32_e32 v84, 0xbfb8aa3b, v82
	v_exp_f32_e32 v84, v84
	v_mul_f32_e32 v83, v83, v170
	v_mul_f32_e32 v80, v81, v80
	v_cndmask_b32_e64 v80, v80, v81, s[12:13]
	v_add_f32_e32 v81, 1.0, v84
	v_mul_f32_e32 v84, 0xbfb8aa3b, v83
	v_exp_f32_e32 v84, v84
	v_rcp_f32_e32 v81, v81
	v_mul_f32_e32 v85, v85, v170
	v_mul_f32_e32 v93, v85, v80
	v_add_f32_e32 v84, 1.0, v84
	v_rcp_f32_e32 v84, v84
	v_mul_f32_e32 v81, v82, v81
	v_mul_f32_e32 v80, v86, v170
	v_cndmask_b32_e64 v81, v81, v82, s[12:13]
	v_mul_f32_e32 v86, v80, v81
	v_mul_f32_e32 v81, v83, v84
	v_mul_f32_e32 v80, v87, v170
	v_cndmask_b32_e64 v81, v81, v83, s[12:13]
	v_mul_f32_e32 v83, v80, v81
	v_lshl_add_u64 v[84:85], v[96:97], 1, v[176:177]
	v_cvt_pk_bf16_f32 v80, v88, v89
	v_cvt_pk_bf16_f32 v81, v90, v91
	v_cvt_pk_bf16_f32 v82, v92, v93
	v_cvt_pk_bf16_f32 v83, v86, v83
	global_store_dwordx4 v[84:85], v[80:83], off nt
	s_waitcnt lgkmcnt(4)
; __device__ __forceinline__ unsigned cvt_pk_bf16(float lo, float hi) { unsigned r; asm("v_cvt_pk_bf16_f32 %0, %1, %2" : "=v"(r) : "v"(lo), "v"(hi)); return r; }
; __device__ __forceinline__ float silu_f(float x) { return x * __builtin_amdgcn_rcpf(1.f + __builtin_amdgcn_exp2f(-LOG2E * x)); }
;     __device__ __forceinline__ void operator()(const f32x4 (&acc)[2][2][4][2], const Unit& u, int wr, int wc, int fr, int fq, LAS unsigned char* xs, int wid, int lane) const {
;     ...
;             for (int ai = 0; ai < 2; ++ai)
; #pragma unroll
;                 for (int m = 0; m < 4; ++m) {
;                     const float r = rs[ai][m];
;                     bf16_t* rowp = base + (size_t)(row0 + ai * 128 + m * 16 + fr) * ldc + wc * 32 + 8 * fq;
;                     float o[8];
; #pragma unroll
;                     for (int n = 0; n < 2; ++n)
; #pragma unroll
;                         for (int j = 0; j < 4; ++j) { const float a = acc[ai][0][m][n][j] * r, b = acc[ai][1][m][n][j] * r; o[4 * n + j] = (mode == 1) ? a * b : a * silu_f(b); }
;                     u32x4 w; w.x = cvt_pk_bf16(o[0], o[1]); w.y = cvt_pk_bf16(o[2], o[3]); w.z = cvt_pk_bf16(o[4], o[5]); w.w = cvt_pk_bf16(o[6], o[7]);
;                     *(u32x4*)rowp = w;
	v_mul_f32_e32 v72, v72, v168
	v_mul_f32_e32 v81, 0xbfb8aa3b, v72
	v_exp_f32_e32 v83, v81
	v_or_b32_e32 v80, 48, v162
	v_mul_lo_u32 v82, s65, v80
	v_mad_u64_u32 v[80:81], s[18:19], s64, v80, 0
	v_add3_u32 v81, v81, s0, v82
	v_add_f32_e32 v82, 1.0, v83
	v_rcp_f32_e32 v82, v82
	v_mul_f32_e32 v73, v73, v168
	v_mul_f32_e32 v83, 0xbfb8aa3b, v73
	v_exp_f32_e32 v83, v83
	v_mul_f32_e32 v82, v72, v82
	v_mul_f32_e32 v76, v76, v168
	v_cndmask_b32_e64 v72, v82, v72, s[12:13]
	v_mul_f32_e32 v72, v76, v72
	v_add_f32_e32 v76, 1.0, v83
	v_mul_f32_e32 v74, v74, v168
	v_rcp_f32_e32 v76, v76
	v_mul_f32_e32 v82, 0xbfb8aa3b, v74
	v_exp_f32_e32 v82, v82
	v_mul_f32_e32 v75, v75, v168
	v_mul_f32_e32 v76, v73, v76
	v_cndmask_b32_e64 v73, v76, v73, s[12:13]
	v_add_f32_e32 v76, 1.0, v82
	v_mul_f32_e32 v82, 0xbfb8aa3b, v75
	v_exp_f32_e32 v82, v82
	v_mul_f32_e32 v77, v77, v168
	v_rcp_f32_e32 v76, v76
	v_mul_f32_e32 v73, v77, v73
	v_mul_f32_e32 v77, v78, v168
	v_add_f32_e32 v78, 1.0, v82
	v_rcp_f32_e32 v78, v78
	v_mul_f32_e32 v76, v74, v76
	v_cndmask_b32_e64 v74, v76, v74, s[12:13]
	v_mul_f32_e32 v64, v64, v168
	v_mul_f32_e32 v74, v77, v74
	v_mul_f32_e32 v77, v75, v78
	v_mul_f32_e32 v78, 0xbfb8aa3b, v64
	v_exp_f32_e32 v78, v78
	v_mul_f32_e32 v76, v79, v168
	v_cndmask_b32_e64 v75, v77, v75, s[12:13]
	v_mul_f32_e32 v75, v76, v75
	v_add_f32_e32 v76, 1.0, v78
	v_rcp_f32_e32 v76, v76
	v_mul_f32_e32 v65, v65, v168
	v_mul_f32_e32 v77, 0xbfb8aa3b, v65
	v_exp_f32_e32 v77, v77
	v_mul_f32_e32 v76, v64, v76
	v_mul_f32_e32 v68, v68, v168
	v_cndmask_b32_e64 v64, v76, v64, s[12:13]
	v_mul_f32_e32 v76, v68, v64
	v_add_f32_e32 v64, 1.0, v77
	v_mul_f32_e32 v66, v66, v168
	v_rcp_f32_e32 v64, v64
	v_mul_f32_e32 v68, 0xbfb8aa3b, v66
	v_exp_f32_e32 v68, v68
	v_mul_f32_e32 v67, v67, v168
	v_mul_f32_e32 v64, v65, v64
	v_cndmask_b32_e64 v64, v64, v65, s[12:13]
	v_add_f32_e32 v65, 1.0, v68
	v_mul_f32_e32 v68, 0xbfb8aa3b, v67
	v_exp_f32_e32 v68, v68
	v_rcp_f32_e32 v65, v65
	v_mul_f32_e32 v69, v69, v168
	v_mul_f32_e32 v77, v69, v64
	v_add_f32_e32 v68, 1.0, v68
	v_rcp_f32_e32 v68, v68
	v_mul_f32_e32 v65, v66, v65
	v_mul_f32_e32 v64, v70, v168
	v_cndmask_b32_e64 v65, v65, v66, s[12:13]
	v_mul_f32_e32 v70, v64, v65
	v_mul_f32_e32 v65, v67, v68
	v_mul_f32_e32 v64, v71, v168
	v_cndmask_b32_e64 v65, v65, v67, s[12:13]
	v_mul_f32_e32 v67, v64, v65
	v_lshl_add_u64 v[68:69], v[80:81], 1, v[176:177]
	v_cvt_pk_bf16_f32 v64, v72, v73
	v_cvt_pk_bf16_f32 v65, v74, v75
	v_cvt_pk_bf16_f32 v66, v76, v77
	v_cvt_pk_bf16_f32 v67, v70, v67
	global_store_dwordx4 v[68:69], v[64:67], off nt
	s_nop 1
	v_add_u32_e32 v64, 0x80, v162
	v_ashrrev_i32_e32 v65, 31, v64
	s_waitcnt lgkmcnt(3)
	v_mul_f32_e32 v56, v56, v166
	v_mul_lo_u32 v66, s64, v65
	v_mul_f32_e32 v65, 0xbfb8aa3b, v56
	v_exp_f32_e32 v68, v65
	v_mul_lo_u32 v67, s65, v64
	v_mad_u64_u32 v[64:65], s[0:1], s64, v64, 0
	v_add3_u32 v65, v65, v66, v67
	v_add_f32_e32 v66, 1.0, v68
	v_rcp_f32_e32 v66, v66
	v_mul_f32_e32 v57, v57, v166
	v_mul_f32_e32 v67, 0xbfb8aa3b, v57
	v_exp_f32_e32 v67, v67
	v_mul_f32_e32 v66, v56, v66
	v_mul_f32_e32 v60, v60, v166
	v_cndmask_b32_e64 v56, v66, v56, s[12:13]
	v_mul_f32_e32 v56, v60, v56
	v_add_f32_e32 v60, 1.0, v67
	v_mul_f32_e32 v58, v58, v166
	v_rcp_f32_e32 v60, v60
	v_mul_f32_e32 v66, 0xbfb8aa3b, v58
	v_exp_f32_e32 v66, v66
	v_mul_f32_e32 v59, v59, v166
	v_mul_f32_e32 v60, v57, v60
	v_cndmask_b32_e64 v57, v60, v57, s[12:13]
	v_add_f32_e32 v60, 1.0, v66
	v_mul_f32_e32 v66, 0xbfb8aa3b, v59
	v_exp_f32_e32 v66, v66
	v_mul_f32_e32 v61, v61, v166
	v_rcp_f32_e32 v60, v60
	v_mul_f32_e32 v57, v61, v57
	v_mul_f32_e32 v61, v62, v166
	v_add_f32_e32 v62, 1.0, v66
	v_rcp_f32_e32 v62, v62
	v_mul_f32_e32 v60, v58, v60
	v_cndmask_b32_e64 v58, v60, v58, s[12:13]
	v_mul_f32_e32 v48, v48, v166
	v_mul_f32_e32 v58, v61, v58
	v_mul_f32_e32 v61, v59, v62
	v_mul_f32_e32 v62, 0xbfb8aa3b, v48
	v_exp_f32_e32 v62, v62
	v_mul_f32_e32 v60, v63, v166
	v_cndmask_b32_e64 v59, v61, v59, s[12:13]
	v_mul_f32_e32 v59, v60, v59
	v_add_f32_e32 v60, 1.0, v62
	v_rcp_f32_e32 v60, v60
	v_mul_f32_e32 v49, v49, v166
	v_mul_f32_e32 v61, 0xbfb8aa3b, v49
	v_exp_f32_e32 v61, v61
	v_mul_f32_e32 v60, v48, v60
	v_mul_f32_e32 v52, v52, v166
	v_cndmask_b32_e64 v48, v60, v48, s[12:13]
	v_mul_f32_e32 v60, v52, v48
	v_add_f32_e32 v48, 1.0, v61
	v_mul_f32_e32 v50, v50, v166
	v_rcp_f32_e32 v48, v48
	v_mul_f32_e32 v52, 0xbfb8aa3b, v50
	v_exp_f32_e32 v52, v52
	v_mul_f32_e32 v51, v51, v166
	v_mul_f32_e32 v48, v49, v48
	v_cndmask_b32_e64 v48, v48, v49, s[12:13]
	v_add_f32_e32 v49, 1.0, v52
	v_mul_f32_e32 v52, 0xbfb8aa3b, v51
	v_exp_f32_e32 v52, v52
	v_rcp_f32_e32 v49, v49
	v_mul_f32_e32 v53, v53, v166
	v_mul_f32_e32 v61, v53, v48
	v_add_f32_e32 v52, 1.0, v52
	v_rcp_f32_e32 v52, v52
	v_mul_f32_e32 v49, v50, v49
	v_mul_f32_e32 v48, v54, v166
	v_cndmask_b32_e64 v49, v49, v50, s[12:13]
	v_mul_f32_e32 v54, v48, v49
	v_mul_f32_e32 v49, v51, v52
	v_mul_f32_e32 v48, v55, v166
	v_cndmask_b32_e64 v49, v49, v51, s[12:13]
	v_mul_f32_e32 v51, v48, v49
	v_lshl_add_u64 v[52:53], v[64:65], 1, v[176:177]
	v_cvt_pk_bf16_f32 v48, v56, v57
	v_cvt_pk_bf16_f32 v49, v58, v59
	v_cvt_pk_bf16_f32 v50, v60, v61
	v_cvt_pk_bf16_f32 v51, v54, v51
	global_store_dwordx4 v[52:53], v[48:51], off nt
	s_nop 1
	v_add_u32_e32 v48, 0x90, v162
	v_ashrrev_i32_e32 v49, 31, v48
	s_waitcnt lgkmcnt(2)
; __device__ __forceinline__ unsigned cvt_pk_bf16(float lo, float hi) { unsigned r; asm("v_cvt_pk_bf16_f32 %0, %1, %2" : "=v"(r) : "v"(lo), "v"(hi)); return r; }
; __device__ __forceinline__ float silu_f(float x) { return x * __builtin_amdgcn_rcpf(1.f + __builtin_amdgcn_exp2f(-LOG2E * x)); }
;     __device__ __forceinline__ void operator()(const f32x4 (&acc)[2][2][4][2], const Unit& u, int wr, int wc, int fr, int fq, LAS unsigned char* xs, int wid, int lane) const {
;     ...
;             for (int ai = 0; ai < 2; ++ai)
; #pragma unroll
;                 for (int m = 0; m < 4; ++m) {
;                     const float r = rs[ai][m];
;                     bf16_t* rowp = base + (size_t)(row0 + ai * 128 + m * 16 + fr) * ldc + wc * 32 + 8 * fq;
;                     float o[8];
; #pragma unroll
;                     for (int n = 0; n < 2; ++n)
; #pragma unroll
;                         for (int j = 0; j < 4; ++j) { const float a = acc[ai][0][m][n][j] * r, b = acc[ai][1][m][n][j] * r; o[4 * n + j] = (mode == 1) ? a * b : a * silu_f(b); }
;                     u32x4 w; w.x = cvt_pk_bf16(o[0], o[1]); w.y = cvt_pk_bf16(o[2], o[3]); w.z = cvt_pk_bf16(o[4], o[5]); w.w = cvt_pk_bf16(o[6], o[7]);
;                     *(u32x4*)rowp = w;
	v_mul_f32_e32 v40, v40, v164
	v_mul_lo_u32 v50, s64, v49
	v_mul_f32_e32 v49, 0xbfb8aa3b, v40
	v_exp_f32_e32 v52, v49
	v_mul_lo_u32 v51, s65, v48
	v_mad_u64_u32 v[48:49], s[0:1], s64, v48, 0
	v_add3_u32 v49, v49, v50, v51
	v_add_f32_e32 v50, 1.0, v52
	v_rcp_f32_e32 v50, v50
	v_mul_f32_e32 v41, v41, v164
	v_mul_f32_e32 v51, 0xbfb8aa3b, v41
	v_exp_f32_e32 v51, v51
	v_mul_f32_e32 v50, v40, v50
	v_mul_f32_e32 v44, v44, v164
	v_cndmask_b32_e64 v40, v50, v40, s[12:13]
	v_mul_f32_e32 v40, v44, v40
	v_add_f32_e32 v44, 1.0, v51
	v_mul_f32_e32 v42, v42, v164
	v_rcp_f32_e32 v44, v44
	v_mul_f32_e32 v50, 0xbfb8aa3b, v42
	v_exp_f32_e32 v50, v50
	v_mul_f32_e32 v43, v43, v164
	v_mul_f32_e32 v44, v41, v44
	v_cndmask_b32_e64 v41, v44, v41, s[12:13]
	v_add_f32_e32 v44, 1.0, v50
	v_mul_f32_e32 v50, 0xbfb8aa3b, v43
	v_exp_f32_e32 v50, v50
	v_mul_f32_e32 v45, v45, v164
	v_rcp_f32_e32 v44, v44
	v_mul_f32_e32 v41, v45, v41
	v_mul_f32_e32 v45, v46, v164
	v_add_f32_e32 v46, 1.0, v50
	v_rcp_f32_e32 v46, v46
	v_mul_f32_e32 v44, v42, v44
	v_cndmask_b32_e64 v42, v44, v42, s[12:13]
	v_mul_f32_e32 v32, v32, v164
	v_mul_f32_e32 v42, v45, v42
	v_mul_f32_e32 v45, v43, v46
	v_mul_f32_e32 v46, 0xbfb8aa3b, v32
	v_exp_f32_e32 v46, v46
	v_mul_f32_e32 v44, v47, v164
	v_cndmask_b32_e64 v43, v45, v43, s[12:13]
	v_mul_f32_e32 v43, v44, v43
	v_add_f32_e32 v44, 1.0, v46
	v_rcp_f32_e32 v44, v44
	v_mul_f32_e32 v33, v33, v164
	v_mul_f32_e32 v45, 0xbfb8aa3b, v33
	v_exp_f32_e32 v45, v45
	v_mul_f32_e32 v44, v32, v44
	v_mul_f32_e32 v36, v36, v164
	v_cndmask_b32_e64 v32, v44, v32, s[12:13]
	v_mul_f32_e32 v44, v36, v32
	v_add_f32_e32 v32, 1.0, v45
	v_mul_f32_e32 v34, v34, v164
	v_rcp_f32_e32 v32, v32
	v_mul_f32_e32 v36, 0xbfb8aa3b, v34
	v_exp_f32_e32 v36, v36
	v_mul_f32_e32 v35, v35, v164
	v_mul_f32_e32 v32, v33, v32
	v_cndmask_b32_e64 v32, v32, v33, s[12:13]
	v_add_f32_e32 v33, 1.0, v36
	v_mul_f32_e32 v36, 0xbfb8aa3b, v35
	v_exp_f32_e32 v36, v36
	v_rcp_f32_e32 v33, v33
	v_mul_f32_e32 v37, v37, v164
	v_mul_f32_e32 v45, v37, v32
	v_add_f32_e32 v36, 1.0, v36
	v_rcp_f32_e32 v36, v36
	v_mul_f32_e32 v33, v34, v33
	v_mul_f32_e32 v32, v38, v164
	v_cndmask_b32_e64 v33, v33, v34, s[12:13]
	v_mul_f32_e32 v38, v32, v33
	v_mul_f32_e32 v33, v35, v36
	v_mul_f32_e32 v32, v39, v164
	v_cndmask_b32_e64 v33, v33, v35, s[12:13]
	v_mul_f32_e32 v35, v32, v33
	v_lshl_add_u64 v[36:37], v[48:49], 1, v[176:177]
	v_cvt_pk_bf16_f32 v32, v40, v41
	v_cvt_pk_bf16_f32 v33, v42, v43
	v_cvt_pk_bf16_f32 v34, v44, v45
	v_cvt_pk_bf16_f32 v35, v38, v35
	global_store_dwordx4 v[36:37], v[32:35], off nt
	s_nop 1
	v_add_u32_e32 v32, 0xa0, v162
	v_ashrrev_i32_e32 v33, 31, v32
	s_waitcnt lgkmcnt(1)
; __device__ __forceinline__ unsigned cvt_pk_bf16(float lo, float hi) { unsigned r; asm("v_cvt_pk_bf16_f32 %0, %1, %2" : "=v"(r) : "v"(lo), "v"(hi)); return r; }
; __device__ __forceinline__ float silu_f(float x) { return x * __builtin_amdgcn_rcpf(1.f + __builtin_amdgcn_exp2f(-LOG2E * x)); }
;     __device__ __forceinline__ void operator()(const f32x4 (&acc)[2][2][4][2], const Unit& u, int wr, int wc, int fr, int fq, LAS unsigned char* xs, int wid, int lane) const {
;     ...
;             for (int ai = 0; ai < 2; ++ai)
; #pragma unroll
;                 for (int m = 0; m < 4; ++m) {
;                     const float r = rs[ai][m];
;                     bf16_t* rowp = base + (size_t)(row0 + ai * 128 + m * 16 + fr) * ldc + wc * 32 + 8 * fq;
;                     float o[8];
; #pragma unroll
;                     for (int n = 0; n < 2; ++n)
; #pragma unroll
;                         for (int j = 0; j < 4; ++j) { const float a = acc[ai][0][m][n][j] * r, b = acc[ai][1][m][n][j] * r; o[4 * n + j] = (mode == 1) ? a * b : a * silu_f(b); }
;                     u32x4 w; w.x = cvt_pk_bf16(o[0], o[1]); w.y = cvt_pk_bf16(o[2], o[3]); w.z = cvt_pk_bf16(o[4], o[5]); w.w = cvt_pk_bf16(o[6], o[7]);
;                     *(u32x4*)rowp = w;
	v_mul_f32_e32 v24, v24, v160
	v_mul_lo_u32 v34, s64, v33
	v_mul_f32_e32 v33, 0xbfb8aa3b, v24
	v_exp_f32_e32 v36, v33
	v_mul_lo_u32 v35, s65, v32
	v_mad_u64_u32 v[32:33], s[0:1], s64, v32, 0
	v_add3_u32 v33, v33, v34, v35
	v_add_f32_e32 v34, 1.0, v36
	v_rcp_f32_e32 v34, v34
	v_mul_f32_e32 v25, v25, v160
	v_mul_f32_e32 v35, 0xbfb8aa3b, v25
	v_exp_f32_e32 v35, v35
	v_mul_f32_e32 v34, v24, v34
	v_mul_f32_e32 v28, v28, v160
	v_cndmask_b32_e64 v24, v34, v24, s[12:13]
	v_mul_f32_e32 v24, v28, v24
	v_add_f32_e32 v28, 1.0, v35
	v_mul_f32_e32 v26, v26, v160
	v_rcp_f32_e32 v28, v28
	v_mul_f32_e32 v34, 0xbfb8aa3b, v26
	v_exp_f32_e32 v34, v34
	v_mul_f32_e32 v27, v27, v160
	v_mul_f32_e32 v28, v25, v28
	v_cndmask_b32_e64 v25, v28, v25, s[12:13]
	v_add_f32_e32 v28, 1.0, v34
	v_mul_f32_e32 v34, 0xbfb8aa3b, v27
	v_exp_f32_e32 v34, v34
	v_mul_f32_e32 v29, v29, v160
	v_rcp_f32_e32 v28, v28
	v_mul_f32_e32 v25, v29, v25
	v_mul_f32_e32 v29, v30, v160
	v_add_f32_e32 v30, 1.0, v34
	v_rcp_f32_e32 v30, v30
	v_mul_f32_e32 v28, v26, v28
	v_cndmask_b32_e64 v26, v28, v26, s[12:13]
	v_mul_f32_e32 v16, v16, v160
	v_mul_f32_e32 v26, v29, v26
	v_mul_f32_e32 v29, v27, v30
	v_mul_f32_e32 v30, 0xbfb8aa3b, v16
	v_exp_f32_e32 v30, v30
	v_mul_f32_e32 v28, v31, v160
	v_cndmask_b32_e64 v27, v29, v27, s[12:13]
	v_mul_f32_e32 v27, v28, v27
	v_add_f32_e32 v28, 1.0, v30
	v_rcp_f32_e32 v28, v28
	v_mul_f32_e32 v17, v17, v160
	v_mul_f32_e32 v29, 0xbfb8aa3b, v17
	v_exp_f32_e32 v29, v29
	v_mul_f32_e32 v28, v16, v28
	v_mul_f32_e32 v20, v20, v160
	v_cndmask_b32_e64 v16, v28, v16, s[12:13]
	v_mul_f32_e32 v28, v20, v16
	v_add_f32_e32 v16, 1.0, v29
	v_mul_f32_e32 v18, v18, v160
	v_rcp_f32_e32 v16, v16
	v_mul_f32_e32 v20, 0xbfb8aa3b, v18
	v_exp_f32_e32 v20, v20
	v_mul_f32_e32 v19, v19, v160
	v_mul_f32_e32 v16, v17, v16
	v_cndmask_b32_e64 v16, v16, v17, s[12:13]
	v_add_f32_e32 v17, 1.0, v20
	v_mul_f32_e32 v20, 0xbfb8aa3b, v19
	v_exp_f32_e32 v20, v20
	v_rcp_f32_e32 v17, v17
	v_mul_f32_e32 v21, v21, v160
	v_mul_f32_e32 v29, v21, v16
	v_add_f32_e32 v20, 1.0, v20
	v_rcp_f32_e32 v20, v20
	v_mul_f32_e32 v17, v18, v17
	v_mul_f32_e32 v16, v22, v160
	v_cndmask_b32_e64 v17, v17, v18, s[12:13]
	v_mul_f32_e32 v22, v16, v17
	v_mul_f32_e32 v17, v19, v20
	v_mul_f32_e32 v16, v23, v160
	v_cndmask_b32_e64 v17, v17, v19, s[12:13]
	v_mul_f32_e32 v19, v16, v17
	v_lshl_add_u64 v[20:21], v[32:33], 1, v[176:177]
	v_cvt_pk_bf16_f32 v16, v24, v25
	v_cvt_pk_bf16_f32 v17, v26, v27
	v_cvt_pk_bf16_f32 v18, v28, v29
	v_cvt_pk_bf16_f32 v19, v22, v19
	global_store_dwordx4 v[20:21], v[16:19], off nt
	s_nop 1
	v_add_u32_e32 v16, 0xb0, v162
	v_ashrrev_i32_e32 v17, 31, v16
	s_waitcnt lgkmcnt(0)
	v_mul_f32_e32 v8, v8, v158
	v_mul_lo_u32 v18, s64, v17
	v_mul_f32_e32 v17, 0xbfb8aa3b, v8
	v_exp_f32_e32 v20, v17
	v_mul_lo_u32 v19, s65, v16
	v_mad_u64_u32 v[16:17], s[0:1], s64, v16, 0
	v_add3_u32 v17, v17, v18, v19
	v_add_f32_e32 v18, 1.0, v20
	v_rcp_f32_e32 v18, v18
	v_mul_f32_e32 v9, v9, v158
	v_mul_f32_e32 v19, 0xbfb8aa3b, v9
	v_exp_f32_e32 v19, v19
	v_mul_f32_e32 v18, v8, v18
	v_mul_f32_e32 v12, v12, v158
	v_cndmask_b32_e64 v8, v18, v8, s[12:13]
	v_mul_f32_e32 v8, v12, v8
	v_add_f32_e32 v12, 1.0, v19
	v_mul_f32_e32 v10, v10, v158
	v_rcp_f32_e32 v12, v12
	v_mul_f32_e32 v18, 0xbfb8aa3b, v10
	v_exp_f32_e32 v18, v18
	v_mul_f32_e32 v11, v11, v158
	v_mul_f32_e32 v12, v9, v12
	v_cndmask_b32_e64 v9, v12, v9, s[12:13]
	v_add_f32_e32 v12, 1.0, v18
	v_mul_f32_e32 v18, 0xbfb8aa3b, v11
	v_exp_f32_e32 v18, v18
	v_mul_f32_e32 v13, v13, v158
	v_rcp_f32_e32 v12, v12
	v_mul_f32_e32 v9, v13, v9
	v_mul_f32_e32 v13, v14, v158
	v_add_f32_e32 v14, 1.0, v18
	v_rcp_f32_e32 v14, v14
	v_mul_f32_e32 v12, v10, v12
	v_cndmask_b32_e64 v10, v12, v10, s[12:13]
	v_mul_f32_e32 v0, v0, v158
	v_mul_f32_e32 v10, v13, v10
	v_mul_f32_e32 v13, v11, v14
	v_mul_f32_e32 v14, 0xbfb8aa3b, v0
	v_exp_f32_e32 v14, v14
	v_mul_f32_e32 v12, v15, v158
	v_cndmask_b32_e64 v11, v13, v11, s[12:13]
	v_mul_f32_e32 v11, v12, v11
	v_add_f32_e32 v12, 1.0, v14
	v_rcp_f32_e32 v12, v12
	v_mul_f32_e32 v1, v1, v158
	v_mul_f32_e32 v13, 0xbfb8aa3b, v1
	v_exp_f32_e32 v13, v13
	v_mul_f32_e32 v12, v0, v12
	v_mul_f32_e32 v4, v4, v158
	v_cndmask_b32_e64 v0, v12, v0, s[12:13]
	v_mul_f32_e32 v12, v4, v0
	v_add_f32_e32 v0, 1.0, v13
	v_mul_f32_e32 v2, v2, v158
	v_rcp_f32_e32 v0, v0
	v_mul_f32_e32 v4, 0xbfb8aa3b, v2
	v_exp_f32_e32 v4, v4
	v_mul_f32_e32 v3, v3, v158
	v_mul_f32_e32 v0, v1, v0
	v_cndmask_b32_e64 v0, v0, v1, s[12:13]
	v_add_f32_e32 v1, 1.0, v4
	v_mul_f32_e32 v4, 0xbfb8aa3b, v3
	v_exp_f32_e32 v4, v4
	v_rcp_f32_e32 v1, v1
	v_mul_f32_e32 v5, v5, v158
	v_mul_f32_e32 v13, v5, v0
	v_add_f32_e32 v4, 1.0, v4
	v_rcp_f32_e32 v4, v4
	v_mul_f32_e32 v1, v2, v1
	v_mul_f32_e32 v0, v6, v158
	v_cndmask_b32_e64 v1, v1, v2, s[12:13]
	v_mul_f32_e32 v6, v0, v1
	v_mul_f32_e32 v1, v3, v4
	v_mul_f32_e32 v0, v7, v158
	v_cndmask_b32_e64 v1, v1, v3, s[12:13]
	v_mul_f32_e32 v3, v0, v1
	v_lshl_add_u64 v[4:5], v[16:17], 1, v[176:177]
	v_cvt_pk_bf16_f32 v0, v8, v9
	v_cvt_pk_bf16_f32 v1, v10, v11
	v_cvt_pk_bf16_f32 v2, v12, v13
	v_cvt_pk_bf16_f32 v3, v6, v3
	global_store_dwordx4 v[4:5], v[0:3], off nt
	s_andn2_b64 vcc, exec, s[10:11]
	s_mov_b64 s[10:11], -1
	s_cbranch_vccnz .LBB0_691

;     __device__ __forceinline__ void operator()(const f32x4 (&acc)[2][2][4][2], const Unit& u, int wr, int wc, int fr, int fq, LAS unsigned char* xs, int wid, int lane) const {
;     ...
;         u32x4 raw[2][4][2];
;         if (!SRCF32) {
; #pragma unroll
;             for (int ai = 0; ai < 2; ++ai)
; #pragma unroll
;                 for (int m = 0; m < 4; ++m)
; #pragma unroll
;                     for (int bj = 0; bj < 2; ++bj) raw[ai][m][bj] = *(const u32x4*)(xb + (size_t)(row0 + ai * 128 + m * 16 + fr) * D + col0 + bj * 128);
;         }
; #pragma unroll
;         for (int ai = 0; ai < 2; ++ai) {
;             f32x4 xf[4][2][2];
;             if (SRCF32) {
; #pragma unroll
;                 for (int m = 0; m < 4; ++m)
; #pragma unroll
;                     for (int bj = 0; bj < 2; ++bj) { const size_t o = (size_t)(row0 + ai * 128 + m * 16 + fr) * D + col0 + bj * 128; xf[m][bj][0] = *(const f32x4*)(xo + o); xf[m][bj][1] = *(const f32x4*)(xo + o + 4); }
;             }
; #pragma unroll
;             for (int m = 0; m < 4; ++m) {
;                 const size_t row = (size_t)(row0 + ai * 128 + m * 16 + fr);
;                 float ss = 0.f;
; #pragma unroll
;                 for (int bj = 0; bj < 2; ++bj) {
;                     const size_t o = row * D + col0 + bj * 128;
;                     f32x4 x0, x1;
;                     if (SRCF32) { x0 = xf[m][bj][0]; x1 = xf[m][bj][1]; }
;                     else { const u32x4 r = raw[ai][m][bj]; x0 = (f32x4){bf_lo(r.x), bf_hi(r.x), bf_lo(r.y), bf_hi(r.y)}; x1 = (f32x4){bf_lo(r.z), bf_hi(r.z), bf_lo(r.w), bf_hi(r.w)}; }
;                     const f32x4 v0 = x0 + acc[ai][bj][m][0], v1 = x1 + acc[ai][bj][m][1];
;                     if (LAST) { *(f32x4*)(out + o) = v0; *(f32x4*)(out + o + 4) = v1; }
;                     else {
;                         ss += (v0[0] * v0[0] + v0[1] * v0[1]) + (v0[2] * v0[2] + v0[3] * v0[3]) + (v1[0] * v1[0] + v1[1] * v1[1]) + (v1[2] * v1[2] + v1[3] * v1[3]);
;                         u32x4 w; w.x = cvt_pk_bf16(v0[0], v0[1]); w.y = cvt_pk_bf16(v0[2], v0[3]); w.z = cvt_pk_bf16(v1[0], v1[1]); w.w = cvt_pk_bf16(v1[2], v1[3]); *(u32x4*)(xb + o) = w;
;                     }
;                 }
;                 if (!LAST) { ss += __shfl_xor(ss, 16); ss += __shfl_xor(ss, 32);
;                     if (fq == 0) P[(ai * 128 + wr * 64 + m * 16 + fr) * 4 + wc] = ss; }
.LBB0_892:
	s_lshl_b32 s18, s64, 8
	v_lshl_or_b32 v200, s48, 8, v218
	v_add_u32_e32 v104, s18, v216
	v_ashrrev_i32_e32 v201, 31, v200
	v_lshlrev_b64 v[234:235], 1, v[200:201]
	v_ashrrev_i32_e32 v105, 31, v104
	v_lshl_add_u64 v[106:107], s[42:43], 0, v[234:235]
	v_lshlrev_b64 v[236:237], 12, v[104:105]
	v_lshl_add_u64 v[112:113], v[106:107], 0, v[236:237]
	global_load_dwordx4 v[226:229], v[112:113], off
	global_load_dwordx4 v[230:233], v[112:113], off offset:256
	v_or_b32_e32 v112, 16, v104
	v_or_b32_e32 v114, 32, v104
	v_or_b32_e32 v124, 48, v104
	v_add_u32_e32 v126, 0x80, v104
	v_add_u32_e32 v140, 0x90, v104
	v_add_u32_e32 v142, 0xa0, v104
	v_add_u32_e32 v104, 0xb0, v104
	v_ashrrev_i32_e32 v113, 31, v112
	v_ashrrev_i32_e32 v115, 31, v114
	v_ashrrev_i32_e32 v125, 31, v124
	v_ashrrev_i32_e32 v127, 31, v126
	v_ashrrev_i32_e32 v141, 31, v140
	v_ashrrev_i32_e32 v143, 31, v142
	v_ashrrev_i32_e32 v105, 31, v104
	v_lshlrev_b64 v[214:215], 12, v[112:113]
	v_lshlrev_b64 v[212:213], 12, v[114:115]
	v_lshlrev_b64 v[210:211], 12, v[124:125]
	v_lshlrev_b64 v[208:209], 12, v[126:127]
	v_lshlrev_b64 v[206:207], 12, v[140:141]
	v_lshlrev_b64 v[204:205], 12, v[142:143]
	v_lshlrev_b64 v[202:203], 12, v[104:105]
	v_lshl_add_u64 v[104:105], v[106:107], 0, v[214:215]
	v_lshl_add_u64 v[112:113], v[106:107], 0, v[212:213]
	v_lshl_add_u64 v[114:115], v[106:107], 0, v[210:211]
	v_lshl_add_u64 v[124:125], v[106:107], 0, v[208:209]
	v_lshl_add_u64 v[126:127], v[106:107], 0, v[206:207]
	v_lshl_add_u64 v[238:239], v[106:107], 0, v[204:205]
	v_lshl_add_u64 v[106:107], v[106:107], 0, v[202:203]
	global_load_dwordx4 v[180:183], v[104:105], off
	global_load_dwordx4 v[176:179], v[104:105], off offset:256
	global_load_dwordx4 v[172:175], v[112:113], off
	global_load_dwordx4 v[168:171], v[112:113], off offset:256
	global_load_dwordx4 v[164:167], v[114:115], off
	global_load_dwordx4 v[160:163], v[114:115], off offset:256
	global_load_dwordx4 v[156:159], v[124:125], off
	global_load_dwordx4 v[152:155], v[124:125], off offset:256
	global_load_dwordx4 v[148:151], v[126:127], off
	global_load_dwordx4 v[144:147], v[126:127], off offset:256
	global_load_dwordx4 v[140:143], v[238:239], off
	s_nop 0
	global_load_dwordx4 v[124:127], v[238:239], off offset:256
	global_load_dwordx4 v[112:115], v[106:107], off
	s_nop 0
	global_load_dwordx4 v[104:107], v[106:107], off offset:256
	s_waitcnt vmcnt(0)
	v_lshlrev_b32_e32 v238, 16, v226
	v_and_b32_e32 v239, 0xffff0000, v226
	v_lshlrev_b32_e32 v226, 16, v227
	v_and_b32_e32 v227, 0xffff0000, v227
	v_lshlrev_b32_e32 v240, 16, v228
	v_and_b32_e32 v241, 0xffff0000, v228
	v_lshlrev_b32_e32 v242, 16, v230
	v_and_b32_e32 v243, 0xffff0000, v230
	v_lshlrev_b32_e32 v230, 16, v231
	v_and_b32_e32 v231, 0xffff0000, v231
	v_lshlrev_b32_e32 v244, 16, v232
	v_and_b32_e32 v245, 0xffff0000, v232
	v_lshlrev_b32_e32 v232, 16, v233
	v_and_b32_e32 v233, 0xffff0000, v233
	v_pk_add_f32 v[138:139], v[138:139], v[226:227]
	v_pk_add_f32 v[136:137], v[136:137], v[238:239]
	v_pk_add_f32 v[132:133], v[132:133], v[240:241]
	v_pk_add_f32 v[226:227], v[130:131], v[230:231]
	v_pk_add_f32 v[230:231], v[122:123], v[232:233]
	v_pk_add_f32 v[232:233], v[120:121], v[244:245]
	v_mul_f32_e32 v120, v137, v137
	v_mul_f32_e32 v121, v139, v139
	v_lshlrev_b32_e32 v228, 16, v229
	v_and_b32_e32 v229, 0xffff0000, v229
	v_mul_f32_e32 v122, v133, v133
	v_fmac_f32_e32 v120, v136, v136
	v_fmac_f32_e32 v121, v138, v138
	v_pk_add_f32 v[134:135], v[134:135], v[228:229]
	v_pk_add_f32 v[228:229], v[128:129], v[242:243]
	v_fmac_f32_e32 v122, v132, v132
	v_add_f32_e32 v120, v120, v121
	v_add_f32_e32 v120, v122, v120
	v_mul_f32_e32 v121, v229, v229
	v_mul_f32_e32 v122, v227, v227
	v_fmac_f32_e32 v121, v228, v228
	v_fmac_f32_e32 v122, v226, v226
	v_add_f32_e32 v121, v121, v122
	v_mul_f32_e32 v122, v233, v233
	v_fmac_f32_e32 v122, v232, v232
	v_mul_f32_e32 v123, v135, v135
	v_add_f32_e32 v121, v122, v121
	v_mul_f32_e32 v122, v231, v231
	v_fmac_f32_e32 v123, v134, v134
	v_fmac_f32_e32 v122, v230, v230
	v_add_f32_e32 v120, v123, v120
	v_add_f32_e32 v121, v122, v121
	v_and_b32_e32 v122, 64, v223
	v_cvt_pk_bf16_f32 v131, v134, v135
	v_add_f32_e32 v121, v120, v121
	v_xor_b32_e32 v120, 16, v223
	v_add_u32_e32 v134, 64, v122
	v_cmp_lt_i32_e32 vcc, v120, v134
	v_lshl_add_u64 v[122:123], s[42:43], 0, v[236:237]
	v_cvt_pk_bf16_f32 v130, v132, v133
	v_lshl_add_u64 v[132:133], v[122:123], 0, v[234:235]
	v_cndmask_b32_e32 v120, v223, v120, vcc
	v_lshlrev_b32_e32 v120, 2, v120
	ds_bpermute_b32 v135, v120, v121
	v_cvt_pk_bf16_f32 v128, v136, v137
	v_cvt_pk_bf16_f32 v129, v138, v139
	global_store_dwordx4 v[132:133], v[128:131], off nt
	s_waitcnt lgkmcnt(0)
	v_add_f32_e32 v122, v121, v135
	v_xor_b32_e32 v121, 32, v223
	v_cmp_lt_i32_e32 vcc, v121, v134
	v_cvt_pk_bf16_f32 v128, v228, v229
	v_cvt_pk_bf16_f32 v129, v226, v227
	v_cvt_pk_bf16_f32 v130, v232, v233
	v_cvt_pk_bf16_f32 v131, v230, v231
	global_store_dwordx4 v[132:133], v[128:131], off offset:256 nt
	s_nop 0
	v_cndmask_b32_e32 v121, v223, v121, vcc
	v_lshlrev_b32_e32 v121, 2, v121
	ds_bpermute_b32 v123, v121, v122
	s_and_saveexec_b64 s[64:65], s[8:9]
	s_cbranch_execz .LBB0_894
	s_waitcnt lgkmcnt(0)
	v_add_f32_e32 v122, v122, v123
	ds_write_b32 v225, v122
; __device__ __forceinline__ unsigned cvt_pk_bf16(float lo, float hi) { unsigned r; asm("v_cvt_pk_bf16_f32 %0, %1, %2" : "=v"(r) : "v"(lo), "v"(hi)); return r; }
;     __device__ __forceinline__ void operator()(const f32x4 (&acc)[2][2][4][2], const Unit& u, int wr, int wc, int fr, int fq, LAS unsigned char* xs, int wid, int lane) const {
;     ...
; #pragma unroll
;             for (int m = 0; m < 4; ++m) {
;                 const size_t row = (size_t)(row0 + ai * 128 + m * 16 + fr);
;                 float ss = 0.f;
; #pragma unroll
;                 for (int bj = 0; bj < 2; ++bj) {
;                     const size_t o = row * D + col0 + bj * 128;
;                     f32x4 x0, x1;
;                     if (SRCF32) { x0 = xf[m][bj][0]; x1 = xf[m][bj][1]; }
;                     else { const u32x4 r = raw[ai][m][bj]; x0 = (f32x4){bf_lo(r.x), bf_hi(r.x), bf_lo(r.y), bf_hi(r.y)}; x1 = (f32x4){bf_lo(r.z), bf_hi(r.z), bf_lo(r.w), bf_hi(r.w)}; }
;                     const f32x4 v0 = x0 + acc[ai][bj][m][0], v1 = x1 + acc[ai][bj][m][1];
;                     if (LAST) { *(f32x4*)(out + o) = v0; *(f32x4*)(out + o + 4) = v1; }
;                     else {
;                         ss += (v0[0] * v0[0] + v0[1] * v0[1]) + (v0[2] * v0[2] + v0[3] * v0[3]) + (v1[0] * v1[0] + v1[1] * v1[1]) + (v1[2] * v1[2] + v1[3] * v1[3]);
;                         u32x4 w; w.x = cvt_pk_bf16(v0[0], v0[1]); w.y = cvt_pk_bf16(v0[2], v0[3]); w.z = cvt_pk_bf16(v1[0], v1[1]); w.w = cvt_pk_bf16(v1[2], v1[3]); *(u32x4*)(xb + o) = w;
;                     }
;                 }
;                 if (!LAST) { ss += __shfl_xor(ss, 16); ss += __shfl_xor(ss, 32);
;                     if (fq == 0) P[(ai * 128 + wr * 64 + m * 16 + fr) * 4 + wc] = ss; }
.LBB0_894:
	s_or_b64 exec, exec, s[64:65]
	v_lshlrev_b32_e32 v122, 16, v180
	s_waitcnt lgkmcnt(0)
	v_and_b32_e32 v123, 0xffff0000, v180
	v_lshlrev_b32_e32 v128, 16, v181
	v_and_b32_e32 v129, 0xffff0000, v181
	v_lshlrev_b32_e32 v130, 16, v182
	v_and_b32_e32 v131, 0xffff0000, v182
	v_lshlrev_b32_e32 v132, 16, v183
	v_and_b32_e32 v133, 0xffff0000, v183
	v_pk_add_f32 v[118:119], v[118:119], v[128:129]
	v_pk_add_f32 v[116:117], v[116:117], v[122:123]
	v_pk_add_f32 v[122:123], v[110:111], v[132:133]
	v_pk_add_f32 v[110:111], v[108:109], v[130:131]
	v_mul_f32_e32 v108, v117, v117
	v_mul_f32_e32 v109, v119, v119
	v_fmac_f32_e32 v108, v116, v116
	v_fmac_f32_e32 v109, v118, v118
	v_add_f32_e32 v108, v108, v109
	v_mul_f32_e32 v109, v111, v111
	v_fmac_f32_e32 v109, v110, v110
	v_add_f32_e32 v108, v109, v108
	v_mul_f32_e32 v109, v123, v123
	v_fmac_f32_e32 v109, v122, v122
	v_add_f32_e32 v130, v109, v108
	v_cvt_pk_bf16_f32 v108, v116, v117
	v_cvt_pk_bf16_f32 v109, v118, v119
	v_lshlrev_b32_e32 v116, 16, v176
	v_and_b32_e32 v117, 0xffff0000, v176
	v_lshlrev_b32_e32 v118, 16, v177
	v_and_b32_e32 v119, 0xffff0000, v177
	v_cvt_pk_bf16_f32 v110, v110, v111
	v_cvt_pk_bf16_f32 v111, v122, v123
	v_lshlrev_b32_e32 v122, 16, v178
	v_and_b32_e32 v123, 0xffff0000, v178
	v_pk_add_f32 v[102:103], v[102:103], v[118:119]
	v_pk_add_f32 v[100:101], v[100:101], v[116:117]
	v_pk_add_f32 v[118:119], v[96:97], v[122:123]
	v_mul_f32_e32 v96, v101, v101
	v_mul_f32_e32 v97, v103, v103
	v_fmac_f32_e32 v96, v100, v100
	v_fmac_f32_e32 v97, v102, v102
	v_lshlrev_b32_e32 v128, 16, v179
	v_and_b32_e32 v129, 0xffff0000, v179
	v_add_f32_e32 v96, v96, v97
	v_mul_f32_e32 v97, v119, v119
	v_pk_add_f32 v[116:117], v[98:99], v[128:129]
	v_fmac_f32_e32 v97, v118, v118
	v_add_f32_e32 v96, v97, v96
	v_mul_f32_e32 v97, v117, v117
	v_fmac_f32_e32 v97, v116, v116
	v_add_f32_e32 v96, v97, v96
	v_add_f32_e32 v99, v130, v96
	ds_bpermute_b32 v128, v120, v99
	v_lshl_add_u64 v[96:97], s[42:43], 0, v[214:215]
	v_lshl_add_u64 v[122:123], v[200:201], 1, v[96:97]
	global_store_dwordx4 v[122:123], v[108:111], off nt
	v_cvt_pk_bf16_f32 v98, v100, v101
	s_waitcnt lgkmcnt(0)
	v_add_f32_e32 v96, v99, v128
	ds_bpermute_b32 v97, v121, v96
	v_cvt_pk_bf16_f32 v99, v102, v103
	v_cvt_pk_bf16_f32 v100, v118, v119
	v_cvt_pk_bf16_f32 v101, v116, v117
	global_store_dwordx4 v[122:123], v[98:101], off offset:256 nt
	s_and_saveexec_b64 s[64:65], s[8:9]
	s_cbranch_execz .LBB0_896
	s_waitcnt lgkmcnt(0)
	v_add_f32_e32 v96, v96, v97
	ds_write_b32 v225, v96 offset:256
.LBB0_896:
	s_or_b64 exec, exec, s[64:65]
	v_lshlrev_b32_e32 v96, 16, v172
	s_waitcnt lgkmcnt(0)
	v_and_b32_e32 v97, 0xffff0000, v172
	v_lshlrev_b32_e32 v98, 16, v173
	v_and_b32_e32 v99, 0xffff0000, v173
	v_lshlrev_b32_e32 v100, 16, v174
	v_and_b32_e32 v101, 0xffff0000, v174
	v_lshlrev_b32_e32 v102, 16, v175
	v_and_b32_e32 v103, 0xffff0000, v175
	v_pk_add_f32 v[94:95], v[94:95], v[98:99]
	v_pk_add_f32 v[92:93], v[92:93], v[96:97]
	v_pk_add_f32 v[96:97], v[90:91], v[102:103]
	v_pk_add_f32 v[90:91], v[88:89], v[100:101]
	v_mul_f32_e32 v88, v93, v93
	v_mul_f32_e32 v89, v95, v95
	v_fmac_f32_e32 v88, v92, v92
	v_fmac_f32_e32 v89, v94, v94
	v_add_f32_e32 v88, v88, v89
	v_mul_f32_e32 v89, v91, v91
	v_fmac_f32_e32 v89, v90, v90
	v_add_f32_e32 v88, v89, v88
	v_mul_f32_e32 v89, v97, v97
	v_fmac_f32_e32 v89, v96, v96
	v_add_f32_e32 v100, v89, v88
	v_cvt_pk_bf16_f32 v88, v92, v93
	v_cvt_pk_bf16_f32 v89, v94, v95
	v_lshlrev_b32_e32 v92, 16, v168
	v_and_b32_e32 v93, 0xffff0000, v168
	v_lshlrev_b32_e32 v94, 16, v169
	v_and_b32_e32 v95, 0xffff0000, v169
	v_cvt_pk_bf16_f32 v90, v90, v91
	v_cvt_pk_bf16_f32 v91, v96, v97
	v_lshlrev_b32_e32 v96, 16, v170
	v_and_b32_e32 v97, 0xffff0000, v170
	v_pk_add_f32 v[86:87], v[86:87], v[94:95]
	v_pk_add_f32 v[84:85], v[84:85], v[92:93]
	v_pk_add_f32 v[94:95], v[80:81], v[96:97]
	v_mul_f32_e32 v80, v85, v85
	v_mul_f32_e32 v81, v87, v87
	v_fmac_f32_e32 v80, v84, v84
	v_fmac_f32_e32 v81, v86, v86
	v_lshlrev_b32_e32 v98, 16, v171
	v_and_b32_e32 v99, 0xffff0000, v171
	v_add_f32_e32 v80, v80, v81
	v_mul_f32_e32 v81, v95, v95
	v_pk_add_f32 v[92:93], v[82:83], v[98:99]
	v_fmac_f32_e32 v81, v94, v94
	v_add_f32_e32 v80, v81, v80
	v_mul_f32_e32 v81, v93, v93
	v_fmac_f32_e32 v81, v92, v92
	v_add_f32_e32 v80, v81, v80
	v_add_f32_e32 v83, v100, v80
	ds_bpermute_b32 v98, v120, v83
	v_lshl_add_u64 v[80:81], s[42:43], 0, v[212:213]
	v_lshl_add_u64 v[96:97], v[200:201], 1, v[80:81]
	global_store_dwordx4 v[96:97], v[88:91], off nt
	v_cvt_pk_bf16_f32 v82, v84, v85
	s_waitcnt lgkmcnt(0)
	v_add_f32_e32 v80, v83, v98
	ds_bpermute_b32 v81, v121, v80
	v_cvt_pk_bf16_f32 v83, v86, v87
	v_cvt_pk_bf16_f32 v84, v94, v95
	v_cvt_pk_bf16_f32 v85, v92, v93
	global_store_dwordx4 v[96:97], v[82:85], off offset:256 nt
	s_and_saveexec_b64 s[64:65], s[8:9]
	s_cbranch_execz .LBB0_898
	s_waitcnt lgkmcnt(0)
	v_add_f32_e32 v80, v80, v81
	ds_write_b32 v225, v80 offset:512
; __device__ __forceinline__ unsigned cvt_pk_bf16(float lo, float hi) { unsigned r; asm("v_cvt_pk_bf16_f32 %0, %1, %2" : "=v"(r) : "v"(lo), "v"(hi)); return r; }
;     __device__ __forceinline__ void operator()(const f32x4 (&acc)[2][2][4][2], const Unit& u, int wr, int wc, int fr, int fq, LAS unsigned char* xs, int wid, int lane) const {
;     ...
; #pragma unroll
;             for (int m = 0; m < 4; ++m) {
;                 const size_t row = (size_t)(row0 + ai * 128 + m * 16 + fr);
;                 float ss = 0.f;
; #pragma unroll
;                 for (int bj = 0; bj < 2; ++bj) {
;                     const size_t o = row * D + col0 + bj * 128;
;                     f32x4 x0, x1;
;                     if (SRCF32) { x0 = xf[m][bj][0]; x1 = xf[m][bj][1]; }
;                     else { const u32x4 r = raw[ai][m][bj]; x0 = (f32x4){bf_lo(r.x), bf_hi(r.x), bf_lo(r.y), bf_hi(r.y)}; x1 = (f32x4){bf_lo(r.z), bf_hi(r.z), bf_lo(r.w), bf_hi(r.w)}; }
;                     const f32x4 v0 = x0 + acc[ai][bj][m][0], v1 = x1 + acc[ai][bj][m][1];
;                     if (LAST) { *(f32x4*)(out + o) = v0; *(f32x4*)(out + o + 4) = v1; }
;                     else {
;                         ss += (v0[0] * v0[0] + v0[1] * v0[1]) + (v0[2] * v0[2] + v0[3] * v0[3]) + (v1[0] * v1[0] + v1[1] * v1[1]) + (v1[2] * v1[2] + v1[3] * v1[3]);
;                         u32x4 w; w.x = cvt_pk_bf16(v0[0], v0[1]); w.y = cvt_pk_bf16(v0[2], v0[3]); w.z = cvt_pk_bf16(v1[0], v1[1]); w.w = cvt_pk_bf16(v1[2], v1[3]); *(u32x4*)(xb + o) = w;
;                     }
;                 }
;                 if (!LAST) { ss += __shfl_xor(ss, 16); ss += __shfl_xor(ss, 32);
;                     if (fq == 0) P[(ai * 128 + wr * 64 + m * 16 + fr) * 4 + wc] = ss; }
.LBB0_898:
	s_or_b64 exec, exec, s[64:65]
	v_lshlrev_b32_e32 v80, 16, v164
	s_waitcnt lgkmcnt(0)
	v_and_b32_e32 v81, 0xffff0000, v164
	v_lshlrev_b32_e32 v82, 16, v165
	v_and_b32_e32 v83, 0xffff0000, v165
	v_lshlrev_b32_e32 v84, 16, v166
	v_and_b32_e32 v85, 0xffff0000, v166
	v_lshlrev_b32_e32 v86, 16, v167
	v_and_b32_e32 v87, 0xffff0000, v167
	v_pk_add_f32 v[78:79], v[78:79], v[82:83]
	v_pk_add_f32 v[76:77], v[76:77], v[80:81]
	v_pk_add_f32 v[80:81], v[74:75], v[86:87]
	v_pk_add_f32 v[74:75], v[72:73], v[84:85]
	v_mul_f32_e32 v72, v77, v77
	v_mul_f32_e32 v73, v79, v79
	v_fmac_f32_e32 v72, v76, v76
	v_fmac_f32_e32 v73, v78, v78
	v_add_f32_e32 v72, v72, v73
	v_mul_f32_e32 v73, v75, v75
	v_fmac_f32_e32 v73, v74, v74
	v_add_f32_e32 v72, v73, v72
	v_mul_f32_e32 v73, v81, v81
	v_fmac_f32_e32 v73, v80, v80
	v_add_f32_e32 v84, v73, v72
	v_cvt_pk_bf16_f32 v72, v76, v77
	v_cvt_pk_bf16_f32 v73, v78, v79
	v_lshlrev_b32_e32 v76, 16, v160
	v_and_b32_e32 v77, 0xffff0000, v160
	v_lshlrev_b32_e32 v78, 16, v161
	v_and_b32_e32 v79, 0xffff0000, v161
	v_cvt_pk_bf16_f32 v74, v74, v75
	v_cvt_pk_bf16_f32 v75, v80, v81
	v_lshlrev_b32_e32 v80, 16, v162
	v_and_b32_e32 v81, 0xffff0000, v162
	v_pk_add_f32 v[70:71], v[70:71], v[78:79]
	v_pk_add_f32 v[68:69], v[68:69], v[76:77]
	v_pk_add_f32 v[78:79], v[64:65], v[80:81]
	v_mul_f32_e32 v64, v69, v69
	v_mul_f32_e32 v65, v71, v71
	v_fmac_f32_e32 v64, v68, v68
	v_fmac_f32_e32 v65, v70, v70
	v_lshlrev_b32_e32 v82, 16, v163
	v_and_b32_e32 v83, 0xffff0000, v163
	v_add_f32_e32 v64, v64, v65
	v_mul_f32_e32 v65, v79, v79
	v_pk_add_f32 v[76:77], v[66:67], v[82:83]
	v_fmac_f32_e32 v65, v78, v78
	v_add_f32_e32 v64, v65, v64
	v_mul_f32_e32 v65, v77, v77
	v_fmac_f32_e32 v65, v76, v76
	v_add_f32_e32 v64, v65, v64
	v_add_f32_e32 v67, v84, v64
	ds_bpermute_b32 v82, v120, v67
	v_lshl_add_u64 v[64:65], s[42:43], 0, v[210:211]
	v_lshl_add_u64 v[80:81], v[200:201], 1, v[64:65]
	global_store_dwordx4 v[80:81], v[72:75], off nt
	v_cvt_pk_bf16_f32 v66, v68, v69
	s_waitcnt lgkmcnt(0)
	v_add_f32_e32 v64, v67, v82
	ds_bpermute_b32 v65, v121, v64
	v_cvt_pk_bf16_f32 v67, v70, v71
	v_cvt_pk_bf16_f32 v68, v78, v79
	v_cvt_pk_bf16_f32 v69, v76, v77
	global_store_dwordx4 v[80:81], v[66:69], off offset:256 nt
	s_and_saveexec_b64 s[64:65], s[8:9]
	s_cbranch_execz .LBB0_900
	s_waitcnt lgkmcnt(0)
	v_add_f32_e32 v64, v64, v65
	ds_write_b32 v225, v64 offset:768
.LBB0_900:
	s_or_b64 exec, exec, s[64:65]
	v_lshlrev_b32_e32 v64, 16, v156
	s_waitcnt lgkmcnt(0)
	v_and_b32_e32 v65, 0xffff0000, v156
	v_lshlrev_b32_e32 v66, 16, v157
	v_and_b32_e32 v67, 0xffff0000, v157
	v_lshlrev_b32_e32 v68, 16, v158
	v_and_b32_e32 v69, 0xffff0000, v158
	v_lshlrev_b32_e32 v70, 16, v159
	v_and_b32_e32 v71, 0xffff0000, v159
	v_pk_add_f32 v[62:63], v[62:63], v[66:67]
	v_pk_add_f32 v[60:61], v[60:61], v[64:65]
	v_pk_add_f32 v[64:65], v[58:59], v[70:71]
	v_pk_add_f32 v[58:59], v[56:57], v[68:69]
	v_mul_f32_e32 v56, v61, v61
	v_mul_f32_e32 v57, v63, v63
	v_fmac_f32_e32 v56, v60, v60
	v_fmac_f32_e32 v57, v62, v62
	v_add_f32_e32 v56, v56, v57
	v_mul_f32_e32 v57, v59, v59
	v_fmac_f32_e32 v57, v58, v58
	v_add_f32_e32 v56, v57, v56
	v_mul_f32_e32 v57, v65, v65
	v_fmac_f32_e32 v57, v64, v64
	v_add_f32_e32 v68, v57, v56
	v_cvt_pk_bf16_f32 v56, v60, v61
	v_cvt_pk_bf16_f32 v57, v62, v63
	v_lshlrev_b32_e32 v60, 16, v152
	v_and_b32_e32 v61, 0xffff0000, v152
	v_lshlrev_b32_e32 v62, 16, v153
	v_and_b32_e32 v63, 0xffff0000, v153
	v_cvt_pk_bf16_f32 v58, v58, v59
	v_cvt_pk_bf16_f32 v59, v64, v65
	v_lshlrev_b32_e32 v64, 16, v154
	v_and_b32_e32 v65, 0xffff0000, v154
	v_pk_add_f32 v[54:55], v[54:55], v[62:63]
	v_pk_add_f32 v[52:53], v[52:53], v[60:61]
	v_pk_add_f32 v[62:63], v[48:49], v[64:65]
	v_mul_f32_e32 v48, v53, v53
	v_mul_f32_e32 v49, v55, v55
	v_fmac_f32_e32 v48, v52, v52
	v_fmac_f32_e32 v49, v54, v54
	v_lshlrev_b32_e32 v66, 16, v155
	v_and_b32_e32 v67, 0xffff0000, v155
	v_add_f32_e32 v48, v48, v49
	v_mul_f32_e32 v49, v63, v63
	v_pk_add_f32 v[60:61], v[50:51], v[66:67]
	v_fmac_f32_e32 v49, v62, v62
	v_add_f32_e32 v48, v49, v48
	v_mul_f32_e32 v49, v61, v61
	v_fmac_f32_e32 v49, v60, v60
	v_add_f32_e32 v48, v49, v48
	v_add_f32_e32 v51, v68, v48
	ds_bpermute_b32 v66, v120, v51
	v_lshl_add_u64 v[48:49], s[42:43], 0, v[208:209]
	v_lshl_add_u64 v[64:65], v[200:201], 1, v[48:49]
	global_store_dwordx4 v[64:65], v[56:59], off nt
	v_cvt_pk_bf16_f32 v50, v52, v53
	s_waitcnt lgkmcnt(0)
	v_add_f32_e32 v48, v51, v66
	ds_bpermute_b32 v49, v121, v48
	v_cvt_pk_bf16_f32 v51, v54, v55
	v_cvt_pk_bf16_f32 v52, v62, v63
	v_cvt_pk_bf16_f32 v53, v60, v61
	global_store_dwordx4 v[64:65], v[50:53], off offset:256 nt
	s_and_saveexec_b64 s[64:65], s[8:9]
	s_cbranch_execz .LBB0_902
	s_waitcnt lgkmcnt(0)
	v_add_f32_e32 v48, v48, v49
	ds_write_b32 v225, v48 offset:2048
; __device__ __forceinline__ unsigned cvt_pk_bf16(float lo, float hi) { unsigned r; asm("v_cvt_pk_bf16_f32 %0, %1, %2" : "=v"(r) : "v"(lo), "v"(hi)); return r; }
;     __device__ __forceinline__ void operator()(const f32x4 (&acc)[2][2][4][2], const Unit& u, int wr, int wc, int fr, int fq, LAS unsigned char* xs, int wid, int lane) const {
;     ...
; #pragma unroll
;             for (int m = 0; m < 4; ++m) {
;                 const size_t row = (size_t)(row0 + ai * 128 + m * 16 + fr);
;                 float ss = 0.f;
; #pragma unroll
;                 for (int bj = 0; bj < 2; ++bj) {
;                     const size_t o = row * D + col0 + bj * 128;
;                     f32x4 x0, x1;
;                     if (SRCF32) { x0 = xf[m][bj][0]; x1 = xf[m][bj][1]; }
;                     else { const u32x4 r = raw[ai][m][bj]; x0 = (f32x4){bf_lo(r.x), bf_hi(r.x), bf_lo(r.y), bf_hi(r.y)}; x1 = (f32x4){bf_lo(r.z), bf_hi(r.z), bf_lo(r.w), bf_hi(r.w)}; }
;                     const f32x4 v0 = x0 + acc[ai][bj][m][0], v1 = x1 + acc[ai][bj][m][1];
;                     if (LAST) { *(f32x4*)(out + o) = v0; *(f32x4*)(out + o + 4) = v1; }
;                     else {
;                         ss += (v0[0] * v0[0] + v0[1] * v0[1]) + (v0[2] * v0[2] + v0[3] * v0[3]) + (v1[0] * v1[0] + v1[1] * v1[1]) + (v1[2] * v1[2] + v1[3] * v1[3]);
;                         u32x4 w; w.x = cvt_pk_bf16(v0[0], v0[1]); w.y = cvt_pk_bf16(v0[2], v0[3]); w.z = cvt_pk_bf16(v1[0], v1[1]); w.w = cvt_pk_bf16(v1[2], v1[3]); *(u32x4*)(xb + o) = w;
;                     }
;                 }
;                 if (!LAST) { ss += __shfl_xor(ss, 16); ss += __shfl_xor(ss, 32);
;                     if (fq == 0) P[(ai * 128 + wr * 64 + m * 16 + fr) * 4 + wc] = ss; }
.LBB0_902:
	s_or_b64 exec, exec, s[64:65]
	v_lshlrev_b32_e32 v48, 16, v148
	s_waitcnt lgkmcnt(0)
	v_and_b32_e32 v49, 0xffff0000, v148
	v_lshlrev_b32_e32 v50, 16, v149
	v_and_b32_e32 v51, 0xffff0000, v149
	v_lshlrev_b32_e32 v52, 16, v150
	v_and_b32_e32 v53, 0xffff0000, v150
	v_lshlrev_b32_e32 v54, 16, v151
	v_and_b32_e32 v55, 0xffff0000, v151
	v_pk_add_f32 v[46:47], v[46:47], v[50:51]
	v_pk_add_f32 v[44:45], v[44:45], v[48:49]
	v_pk_add_f32 v[48:49], v[42:43], v[54:55]
	v_pk_add_f32 v[42:43], v[40:41], v[52:53]
	v_mul_f32_e32 v40, v45, v45
	v_mul_f32_e32 v41, v47, v47
	v_fmac_f32_e32 v40, v44, v44
	v_fmac_f32_e32 v41, v46, v46
	v_add_f32_e32 v40, v40, v41
	v_mul_f32_e32 v41, v43, v43
	v_fmac_f32_e32 v41, v42, v42
	v_add_f32_e32 v40, v41, v40
	v_mul_f32_e32 v41, v49, v49
	v_fmac_f32_e32 v41, v48, v48
	v_add_f32_e32 v52, v41, v40
	v_cvt_pk_bf16_f32 v40, v44, v45
	v_cvt_pk_bf16_f32 v41, v46, v47
	v_lshlrev_b32_e32 v44, 16, v144
	v_and_b32_e32 v45, 0xffff0000, v144
	v_lshlrev_b32_e32 v46, 16, v145
	v_and_b32_e32 v47, 0xffff0000, v145
	v_cvt_pk_bf16_f32 v42, v42, v43
	v_cvt_pk_bf16_f32 v43, v48, v49
	v_lshlrev_b32_e32 v48, 16, v146
	v_and_b32_e32 v49, 0xffff0000, v146
	v_pk_add_f32 v[38:39], v[38:39], v[46:47]
	v_pk_add_f32 v[36:37], v[36:37], v[44:45]
	v_pk_add_f32 v[46:47], v[32:33], v[48:49]
	v_mul_f32_e32 v32, v37, v37
	v_mul_f32_e32 v33, v39, v39
	v_fmac_f32_e32 v32, v36, v36
	v_fmac_f32_e32 v33, v38, v38
	v_lshlrev_b32_e32 v50, 16, v147
	v_and_b32_e32 v51, 0xffff0000, v147
	v_add_f32_e32 v32, v32, v33
	v_mul_f32_e32 v33, v47, v47
	v_pk_add_f32 v[44:45], v[34:35], v[50:51]
	v_fmac_f32_e32 v33, v46, v46
	v_add_f32_e32 v32, v33, v32
	v_mul_f32_e32 v33, v45, v45
	v_fmac_f32_e32 v33, v44, v44
	v_add_f32_e32 v32, v33, v32
	v_add_f32_e32 v35, v52, v32
	ds_bpermute_b32 v50, v120, v35
	v_lshl_add_u64 v[32:33], s[42:43], 0, v[206:207]
	v_lshl_add_u64 v[48:49], v[200:201], 1, v[32:33]
	global_store_dwordx4 v[48:49], v[40:43], off nt
	v_cvt_pk_bf16_f32 v34, v36, v37
	s_waitcnt lgkmcnt(0)
	v_add_f32_e32 v32, v35, v50
	ds_bpermute_b32 v33, v121, v32
	v_cvt_pk_bf16_f32 v35, v38, v39
	v_cvt_pk_bf16_f32 v36, v46, v47
	v_cvt_pk_bf16_f32 v37, v44, v45
	global_store_dwordx4 v[48:49], v[34:37], off offset:256 nt
	s_and_saveexec_b64 s[64:65], s[8:9]
	s_cbranch_execz .LBB0_904
	s_waitcnt lgkmcnt(0)
	v_add_f32_e32 v32, v32, v33
	ds_write_b32 v225, v32 offset:2304
; __device__ __forceinline__ unsigned cvt_pk_bf16(float lo, float hi) { unsigned r; asm("v_cvt_pk_bf16_f32 %0, %1, %2" : "=v"(r) : "v"(lo), "v"(hi)); return r; }
;     __device__ __forceinline__ void operator()(const f32x4 (&acc)[2][2][4][2], const Unit& u, int wr, int wc, int fr, int fq, LAS unsigned char* xs, int wid, int lane) const {
;     ...
; #pragma unroll
;             for (int m = 0; m < 4; ++m) {
;                 const size_t row = (size_t)(row0 + ai * 128 + m * 16 + fr);
;                 float ss = 0.f;
; #pragma unroll
;                 for (int bj = 0; bj < 2; ++bj) {
;                     const size_t o = row * D + col0 + bj * 128;
;                     f32x4 x0, x1;
;                     if (SRCF32) { x0 = xf[m][bj][0]; x1 = xf[m][bj][1]; }
;                     else { const u32x4 r = raw[ai][m][bj]; x0 = (f32x4){bf_lo(r.x), bf_hi(r.x), bf_lo(r.y), bf_hi(r.y)}; x1 = (f32x4){bf_lo(r.z), bf_hi(r.z), bf_lo(r.w), bf_hi(r.w)}; }
;                     const f32x4 v0 = x0 + acc[ai][bj][m][0], v1 = x1 + acc[ai][bj][m][1];
;                     if (LAST) { *(f32x4*)(out + o) = v0; *(f32x4*)(out + o + 4) = v1; }
;                     else {
;                         ss += (v0[0] * v0[0] + v0[1] * v0[1]) + (v0[2] * v0[2] + v0[3] * v0[3]) + (v1[0] * v1[0] + v1[1] * v1[1]) + (v1[2] * v1[2] + v1[3] * v1[3]);
;                         u32x4 w; w.x = cvt_pk_bf16(v0[0], v0[1]); w.y = cvt_pk_bf16(v0[2], v0[3]); w.z = cvt_pk_bf16(v1[0], v1[1]); w.w = cvt_pk_bf16(v1[2], v1[3]); *(u32x4*)(xb + o) = w;
;                     }
;                 }
;                 if (!LAST) { ss += __shfl_xor(ss, 16); ss += __shfl_xor(ss, 32);
;                     if (fq == 0) P[(ai * 128 + wr * 64 + m * 16 + fr) * 4 + wc] = ss; }
.LBB0_904:
	s_or_b64 exec, exec, s[64:65]
	v_lshlrev_b32_e32 v32, 16, v140
	s_waitcnt lgkmcnt(0)
	v_and_b32_e32 v33, 0xffff0000, v140
	v_lshlrev_b32_e32 v34, 16, v141
	v_and_b32_e32 v35, 0xffff0000, v141
	v_lshlrev_b32_e32 v36, 16, v142
	v_and_b32_e32 v37, 0xffff0000, v142
	v_lshlrev_b32_e32 v38, 16, v143
	v_and_b32_e32 v39, 0xffff0000, v143
	v_pk_add_f32 v[30:31], v[30:31], v[34:35]
	v_pk_add_f32 v[28:29], v[28:29], v[32:33]
	v_pk_add_f32 v[32:33], v[26:27], v[38:39]
	v_pk_add_f32 v[26:27], v[24:25], v[36:37]
	v_mul_f32_e32 v24, v29, v29
	v_mul_f32_e32 v25, v31, v31
	v_fmac_f32_e32 v24, v28, v28
	v_fmac_f32_e32 v25, v30, v30
	v_add_f32_e32 v24, v24, v25
	v_mul_f32_e32 v25, v27, v27
	v_fmac_f32_e32 v25, v26, v26
	v_add_f32_e32 v24, v25, v24
	v_mul_f32_e32 v25, v33, v33
	v_fmac_f32_e32 v25, v32, v32
	v_add_f32_e32 v36, v25, v24
	v_cvt_pk_bf16_f32 v24, v28, v29
	v_cvt_pk_bf16_f32 v25, v30, v31
	v_lshlrev_b32_e32 v28, 16, v124
	v_and_b32_e32 v29, 0xffff0000, v124
	v_lshlrev_b32_e32 v30, 16, v125
	v_and_b32_e32 v31, 0xffff0000, v125
	v_cvt_pk_bf16_f32 v26, v26, v27
	v_cvt_pk_bf16_f32 v27, v32, v33
	v_lshlrev_b32_e32 v32, 16, v126
	v_and_b32_e32 v33, 0xffff0000, v126
	v_pk_add_f32 v[22:23], v[22:23], v[30:31]
	v_pk_add_f32 v[20:21], v[20:21], v[28:29]
	v_pk_add_f32 v[30:31], v[16:17], v[32:33]
	v_mul_f32_e32 v16, v21, v21
	v_mul_f32_e32 v17, v23, v23
	v_fmac_f32_e32 v16, v20, v20
	v_fmac_f32_e32 v17, v22, v22
	v_lshlrev_b32_e32 v34, 16, v127
	v_and_b32_e32 v35, 0xffff0000, v127
	v_add_f32_e32 v16, v16, v17
	v_mul_f32_e32 v17, v31, v31
	v_pk_add_f32 v[28:29], v[18:19], v[34:35]
	v_fmac_f32_e32 v17, v30, v30
	v_add_f32_e32 v16, v17, v16
	v_mul_f32_e32 v17, v29, v29
	v_fmac_f32_e32 v17, v28, v28
	v_add_f32_e32 v16, v17, v16
	v_add_f32_e32 v19, v36, v16
	ds_bpermute_b32 v34, v120, v19
	v_lshl_add_u64 v[16:17], s[42:43], 0, v[204:205]
	v_lshl_add_u64 v[32:33], v[200:201], 1, v[16:17]
	global_store_dwordx4 v[32:33], v[24:27], off nt
	v_cvt_pk_bf16_f32 v18, v20, v21
	s_waitcnt lgkmcnt(0)
	v_add_f32_e32 v16, v19, v34
	ds_bpermute_b32 v17, v121, v16
	v_cvt_pk_bf16_f32 v19, v22, v23
	v_cvt_pk_bf16_f32 v20, v30, v31
	v_cvt_pk_bf16_f32 v21, v28, v29
	global_store_dwordx4 v[32:33], v[18:21], off offset:256 nt
	s_and_saveexec_b64 s[64:65], s[8:9]
	s_cbranch_execz .LBB0_906
	s_waitcnt lgkmcnt(0)
	v_add_f32_e32 v16, v16, v17
	ds_write_b32 v225, v16 offset:2560
.LBB0_906:
	s_or_b64 exec, exec, s[64:65]
	v_lshlrev_b32_e32 v16, 16, v112
	s_waitcnt lgkmcnt(0)
	v_and_b32_e32 v17, 0xffff0000, v112
	v_lshlrev_b32_e32 v18, 16, v113
	v_and_b32_e32 v19, 0xffff0000, v113
	v_lshlrev_b32_e32 v20, 16, v114
	v_and_b32_e32 v21, 0xffff0000, v114
	v_lshlrev_b32_e32 v22, 16, v115
	v_and_b32_e32 v23, 0xffff0000, v115
	v_pk_add_f32 v[14:15], v[14:15], v[18:19]
	v_pk_add_f32 v[12:13], v[12:13], v[16:17]
	v_pk_add_f32 v[16:17], v[10:11], v[22:23]
	v_pk_add_f32 v[10:11], v[8:9], v[20:21]
	v_mul_f32_e32 v8, v13, v13
	v_mul_f32_e32 v9, v15, v15
	v_fmac_f32_e32 v8, v12, v12
	v_fmac_f32_e32 v9, v14, v14
	v_add_f32_e32 v8, v8, v9
	v_mul_f32_e32 v9, v11, v11
	v_fmac_f32_e32 v9, v10, v10
	v_add_f32_e32 v8, v9, v8
	v_mul_f32_e32 v9, v17, v17
	v_fmac_f32_e32 v9, v16, v16
	v_add_f32_e32 v20, v9, v8
	v_cvt_pk_bf16_f32 v8, v12, v13
	v_cvt_pk_bf16_f32 v9, v14, v15
	v_lshlrev_b32_e32 v12, 16, v104
	v_and_b32_e32 v13, 0xffff0000, v104
	v_lshlrev_b32_e32 v14, 16, v105
	v_and_b32_e32 v15, 0xffff0000, v105
	v_cvt_pk_bf16_f32 v10, v10, v11
	v_cvt_pk_bf16_f32 v11, v16, v17
	v_lshlrev_b32_e32 v16, 16, v106
	v_and_b32_e32 v17, 0xffff0000, v106
	v_pk_add_f32 v[6:7], v[6:7], v[14:15]
	v_pk_add_f32 v[4:5], v[4:5], v[12:13]
	v_pk_add_f32 v[14:15], v[0:1], v[16:17]
	v_mul_f32_e32 v0, v5, v5
	v_mul_f32_e32 v1, v7, v7
	v_fmac_f32_e32 v0, v4, v4
	v_fmac_f32_e32 v1, v6, v6
	v_lshlrev_b32_e32 v18, 16, v107
	v_and_b32_e32 v19, 0xffff0000, v107
	v_add_f32_e32 v0, v0, v1
	v_mul_f32_e32 v1, v15, v15
	v_pk_add_f32 v[12:13], v[2:3], v[18:19]
	v_fmac_f32_e32 v1, v14, v14
	v_add_f32_e32 v0, v1, v0
	v_mul_f32_e32 v1, v13, v13
	v_fmac_f32_e32 v1, v12, v12
	v_add_f32_e32 v0, v1, v0
	v_add_f32_e32 v3, v20, v0
	ds_bpermute_b32 v18, v120, v3
	v_lshl_add_u64 v[0:1], s[42:43], 0, v[202:203]
	v_lshl_add_u64 v[16:17], v[200:201], 1, v[0:1]
	global_store_dwordx4 v[16:17], v[8:11], off nt
	v_cvt_pk_bf16_f32 v2, v4, v5
	s_waitcnt lgkmcnt(0)
	v_add_f32_e32 v0, v3, v18
	ds_bpermute_b32 v1, v121, v0
	v_cvt_pk_bf16_f32 v3, v6, v7
	v_cvt_pk_bf16_f32 v4, v14, v15
	v_cvt_pk_bf16_f32 v5, v12, v13
	global_store_dwordx4 v[16:17], v[2:5], off offset:256 nt
	s_and_saveexec_b64 s[64:65], s[8:9]
	s_cbranch_execz .LBB0_908
	s_waitcnt lgkmcnt(0)
	v_add_f32_e32 v0, v0, v1
	ds_write_b32 v225, v0 offset:2816

; #define LAS __attribute__((address_space(3)))
; __device__ __forceinline__ unsigned cvt_pk_bf16(float lo, float hi) { unsigned r; asm("v_cvt_pk_bf16_f32 %0, %1, %2" : "=v"(r) : "v"(lo), "v"(hi)); return r; }
; #define LDS_WAIT() asm volatile("s_waitcnt lgkmcnt(0)" ::: "memory")
; __device__ __forceinline__ void tstore_sub(const f32x4 (&v)[4][2], bf16_t* dst  , LAS unsigned char* x, int fr, int fq, int lane) {
; #pragma unroll
;     for (int m = 0; m < 4; ++m)
; #pragma unroll
;         for (int n = 0; n < 2; ++n)
; #pragma unroll
;             for (int j = 0; j < 4; ++j) {
;                 const int ch = 8 * fq + 4 * n + j, tok = 16 * m + fr;
;                 const unsigned b = cvt_pk_bf16(v[m][n][j], 0.f);
;                 *(LAS unsigned short*)(x + ch * 128 + ((((tok >> 3) ^ fq) << 4) | ((tok & 7) << 1))) = (unsigned short)b;
;             }
;     LDS_WAIT();
; #pragma unroll
;     for (int i = 0; i < 4; ++i) {
;         const int q = lane + 64 * i, ch = q >> 3, tc = q & 7;
;         const u32x4 o = *(const LAS u32x4*)(x + ch * 128 + ((tc ^ ((ch >> 3) & 3)) << 4));
;         *(u32x4*)(dst + (size_t)ch * T + tc * 8) = o;
;     }
;     LDS_WAIT();
; }
;     __device__ __forceinline__ void operator()(const f32x4 (&acc)[2][2][4][2], const Unit& u, int wr, int wc, int fr, int fq, LAS unsigned char* xs, int wid, int lane) const {
;     ...
;                     f32x4 v[4][2];
; #pragma unroll
;                     for (int m = 0; m < 4; ++m) { v[m][0] = acc[ai][bj][m][0] * rs[ai][m]; v[m][1] = acc[ai][bj][m][1] * rs[ai][m]; }
.LBB0_984:
	s_waitcnt lgkmcnt(7)
	v_pk_mul_f32 v[176:177], v[124:125], v[172:173] op_sel_hi:[1,0]
	v_pk_mul_f32 v[174:175], v[126:127], v[172:173] op_sel_hi:[1,0]
	v_cvt_pk_bf16_f32 v143, v176, v137
	ds_write_b16 v167, v143
	v_cvt_pk_bf16_f32 v143, v177, v137
	ds_write_b16 v167, v143 offset:128
	v_cvt_pk_bf16_f32 v143, v174, v137
	ds_write_b16 v167, v143 offset:256
	v_cvt_pk_bf16_f32 v143, v175, v137
	v_pk_mul_f32 v[180:181], v[120:121], v[172:173] op_sel_hi:[1,0]
	ds_write_b16 v167, v143 offset:384
	v_cvt_pk_bf16_f32 v143, v180, v137
	ds_write_b16 v167, v143 offset:512
	v_cvt_pk_bf16_f32 v143, v181, v137
	v_pk_mul_f32 v[178:179], v[122:123], v[172:173] op_sel_hi:[1,0]
	ds_write_b16 v167, v143 offset:640
	v_cvt_pk_bf16_f32 v143, v178, v137
	ds_write_b16 v167, v143 offset:768
	v_cvt_pk_bf16_f32 v143, v179, v137
	s_waitcnt lgkmcnt(13)
	v_pk_mul_f32 v[192:193], v[108:109], v[170:171] op_sel_hi:[1,0]
	ds_write_b16 v167, v143 offset:896
	v_cvt_pk_bf16_f32 v143, v192, v137
	ds_write_b16 v169, v143
	v_cvt_pk_bf16_f32 v143, v193, v137
	v_pk_mul_f32 v[190:191], v[110:111], v[170:171] op_sel_hi:[1,0]
	ds_write_b16 v169, v143 offset:128
	v_cvt_pk_bf16_f32 v143, v190, v137
	ds_write_b16 v169, v143 offset:256
	v_cvt_pk_bf16_f32 v143, v191, v137
	v_pk_mul_f32 v[196:197], v[104:105], v[170:171] op_sel_hi:[1,0]
	ds_write_b16 v169, v143 offset:384
	v_cvt_pk_bf16_f32 v143, v196, v137
	ds_write_b16 v169, v143 offset:512
	v_cvt_pk_bf16_f32 v143, v197, v137
	v_pk_mul_f32 v[194:195], v[106:107], v[170:171] op_sel_hi:[1,0]
	ds_write_b16 v169, v143 offset:640
	v_cvt_pk_bf16_f32 v143, v194, v137
	ds_write_b16 v169, v143 offset:768
	v_cvt_pk_bf16_f32 v143, v195, v137
	s_waitcnt lgkmcnt(14)
	v_pk_mul_f32 v[200:201], v[92:93], v[168:169] op_sel_hi:[1,0]
	ds_write_b16 v169, v143 offset:896
	v_cvt_pk_bf16_f32 v143, v200, v137
	ds_write_b16 v171, v143
	v_cvt_pk_bf16_f32 v143, v201, v137
	v_pk_mul_f32 v[198:199], v[94:95], v[168:169] op_sel_hi:[1,0]
	ds_write_b16 v171, v143 offset:128
	v_cvt_pk_bf16_f32 v143, v198, v137
	ds_write_b16 v171, v143 offset:256
	v_cvt_pk_bf16_f32 v143, v199, v137
	v_pk_mul_f32 v[204:205], v[88:89], v[168:169] op_sel_hi:[1,0]
	ds_write_b16 v171, v143 offset:384
	v_cvt_pk_bf16_f32 v143, v204, v137
	ds_write_b16 v171, v143 offset:512
	v_cvt_pk_bf16_f32 v143, v205, v137
	v_pk_mul_f32 v[202:203], v[90:91], v[168:169] op_sel_hi:[1,0]
	ds_write_b16 v171, v143 offset:640
	v_cvt_pk_bf16_f32 v143, v202, v137
	ds_write_b16 v171, v143 offset:768
	v_cvt_pk_bf16_f32 v143, v203, v137
	v_pk_mul_f32 v[208:209], v[76:77], v[166:167] op_sel_hi:[1,0]
	ds_write_b16 v171, v143 offset:896
	v_cvt_pk_bf16_f32 v143, v208, v137
	ds_write_b16 v173, v143
	v_cvt_pk_bf16_f32 v143, v209, v137
	v_pk_mul_f32 v[206:207], v[78:79], v[166:167] op_sel_hi:[1,0]
	ds_write_b16 v173, v143 offset:128
	v_cvt_pk_bf16_f32 v143, v206, v137
	ds_write_b16 v173, v143 offset:256
	v_cvt_pk_bf16_f32 v143, v207, v137
	v_pk_mul_f32 v[212:213], v[72:73], v[166:167] op_sel_hi:[1,0]
	ds_write_b16 v173, v143 offset:384
	v_cvt_pk_bf16_f32 v143, v212, v137
	ds_write_b16 v173, v143 offset:512
	v_cvt_pk_bf16_f32 v143, v213, v137
	v_pk_mul_f32 v[210:211], v[74:75], v[166:167] op_sel_hi:[1,0]
	ds_write_b16 v173, v143 offset:640
	v_cvt_pk_bf16_f32 v143, v210, v137
	s_ashr_i32 s67, s66, 31
	ds_write_b16 v173, v143 offset:768
	v_cvt_pk_bf16_f32 v143, v211, v137
	ds_write_b16 v173, v143 offset:896
	s_lshl_b64 s[70:71], s[66:67], 1
	s_waitcnt lgkmcnt(0)
	s_add_u32 s70, s68, s70
	ds_read_b128 v[176:179], v184
	ds_read_b128 v[190:193], v185
	s_addc_u32 s71, s69, s71
	v_lshl_add_u64 v[182:183], s[70:71], 0, v[136:137]
	s_mov_b32 s55, s19
	v_lshl_add_u64 v[180:181], v[182:183], 0, s[54:55]
	v_mov_b32_e32 v143, v137
	v_lshl_add_u64 v[174:175], v[180:181], 0, v[142:143]
	v_mov_b32_e32 v145, v137
	s_waitcnt lgkmcnt(1)
	global_store_dwordx4 v[174:175], v[176:179], off nt
	ds_read_b128 v[194:197], v186
	v_mov_b32_e32 v147, v137
	v_lshl_add_u64 v[176:177], v[180:181], 0, v[144:145]
	s_waitcnt lgkmcnt(1)
	global_store_dwordx4 v[176:177], v[190:193], off nt
	ds_read_b128 v[190:193], v187
	v_mov_b32_e32 v149, v137
	v_lshl_add_u64 v[178:179], v[180:181], 0, v[146:147]
	v_lshl_add_u64 v[180:181], v[180:181], 0, v[148:149]
	s_waitcnt lgkmcnt(1)
	global_store_dwordx4 v[178:179], v[194:197], off nt
	s_waitcnt lgkmcnt(0)
	global_store_dwordx4 v[180:181], v[190:193], off nt
	s_waitcnt lgkmcnt(0)
; #define LAS __attribute__((address_space(3)))
; __device__ __forceinline__ unsigned cvt_pk_bf16(float lo, float hi) { unsigned r; asm("v_cvt_pk_bf16_f32 %0, %1, %2" : "=v"(r) : "v"(lo), "v"(hi)); return r; }
; #define LDS_WAIT() asm volatile("s_waitcnt lgkmcnt(0)" ::: "memory")
; __device__ __forceinline__ void tstore_sub(const f32x4 (&v)[4][2], bf16_t* dst  , LAS unsigned char* x, int fr, int fq, int lane) {
; #pragma unroll
;     for (int m = 0; m < 4; ++m)
; #pragma unroll
;         for (int n = 0; n < 2; ++n)
; #pragma unroll
;             for (int j = 0; j < 4; ++j) {
;                 const int ch = 8 * fq + 4 * n + j, tok = 16 * m + fr;
;                 const unsigned b = cvt_pk_bf16(v[m][n][j], 0.f);
;                 *(LAS unsigned short*)(x + ch * 128 + ((((tok >> 3) ^ fq) << 4) | ((tok & 7) << 1))) = (unsigned short)b;
;             }
;     LDS_WAIT();
; #pragma unroll
;     for (int i = 0; i < 4; ++i) {
;         const int q = lane + 64 * i, ch = q >> 3, tc = q & 7;
;         const u32x4 o = *(const LAS u32x4*)(x + ch * 128 + ((tc ^ ((ch >> 3) & 3)) << 4));
;         *(u32x4*)(dst + (size_t)ch * T + tc * 8) = o;
;     }
;     LDS_WAIT();
; }
;     __device__ __forceinline__ void operator()(const f32x4 (&acc)[2][2][4][2], const Unit& u, int wr, int wc, int fr, int fq, LAS unsigned char* xs, int wid, int lane) const {
;     ...
;                     f32x4 v[4][2];
; #pragma unroll
;                     for (int m = 0; m < 4; ++m) { v[m][0] = acc[ai][bj][m][0] * rs[ai][m]; v[m][1] = acc[ai][bj][m][1] * rs[ai][m]; }
;                     if (ODD) {
;                         float* vss = (float*)(ws + OFF_VSS);
; #pragma unroll
;                         for (int m = 0; m < 4; ++m) {
;                             float s = 0.f;
; #pragma unroll
;                             for (int n = 0; n < 2; ++n) s += (v[m][n][0] * v[m][n][0] + v[m][n][1] * v[m][n][1]) + (v[m][n][2] * v[m][n][2] + v[m][n][3] * v[m][n][3]);
;                             s += __shfl_xor(s, 16); s += __shfl_xor(s, 32);
;                             if (fq == 0) vss[(size_t)(row0 + ai * 128 + m * 16 + fr) * 32 + (2 * (pn - 24) + bj) * 4 + wc] = s;
;                         }
;                     }
;                     tstore_sub(v, base + (size_t)(bj * 128 + wc * 32) * T + row0 + ai * 128, x, fr, fq, lane);
	v_pk_mul_f32 v[200:201], v[100:101], v[170:171] op_sel_hi:[1,0]
	v_pk_mul_f32 v[196:197], v[112:113], v[172:173] op_sel_hi:[1,0]
	v_pk_mul_f32 v[192:193], v[116:117], v[172:173] op_sel_hi:[1,0]
	v_pk_mul_f32 v[190:191], v[118:119], v[172:173] op_sel_hi:[1,0]
	v_cvt_pk_bf16_f32 v151, v192, v137
	ds_write_b16 v167, v151
	v_cvt_pk_bf16_f32 v151, v193, v137
	ds_write_b16 v167, v151 offset:128
	v_cvt_pk_bf16_f32 v151, v190, v137
	ds_write_b16 v167, v151 offset:256
	v_cvt_pk_bf16_f32 v151, v191, v137
	ds_write_b16 v167, v151 offset:384
	v_cvt_pk_bf16_f32 v151, v196, v137
	ds_write_b16 v167, v151 offset:512
	v_cvt_pk_bf16_f32 v151, v197, v137
	v_pk_mul_f32 v[194:195], v[114:115], v[172:173] op_sel_hi:[1,0]
	ds_write_b16 v167, v151 offset:640
	v_cvt_pk_bf16_f32 v151, v194, v137
	ds_write_b16 v167, v151 offset:768
	v_cvt_pk_bf16_f32 v151, v195, v137
	ds_write_b16 v167, v151 offset:896
	v_cvt_pk_bf16_f32 v151, v200, v137
	ds_write_b16 v169, v151
	v_cvt_pk_bf16_f32 v151, v201, v137
	v_pk_mul_f32 v[198:199], v[102:103], v[170:171] op_sel_hi:[1,0]
	ds_write_b16 v169, v151 offset:128
	v_cvt_pk_bf16_f32 v151, v198, v137
	ds_write_b16 v169, v151 offset:256
	v_cvt_pk_bf16_f32 v151, v199, v137
	v_pk_mul_f32 v[204:205], v[96:97], v[170:171] op_sel_hi:[1,0]
	ds_write_b16 v169, v151 offset:384
	v_cvt_pk_bf16_f32 v151, v204, v137
	ds_write_b16 v169, v151 offset:512
	v_cvt_pk_bf16_f32 v151, v205, v137
	v_pk_mul_f32 v[202:203], v[98:99], v[170:171] op_sel_hi:[1,0]
	ds_write_b16 v169, v151 offset:640
	v_cvt_pk_bf16_f32 v151, v202, v137
	ds_write_b16 v169, v151 offset:768
	v_cvt_pk_bf16_f32 v151, v203, v137
	v_pk_mul_f32 v[208:209], v[84:85], v[168:169] op_sel_hi:[1,0]
	ds_write_b16 v169, v151 offset:896
	v_cvt_pk_bf16_f32 v151, v208, v137
	ds_write_b16 v171, v151
	v_cvt_pk_bf16_f32 v151, v209, v137
	v_pk_mul_f32 v[206:207], v[86:87], v[168:169] op_sel_hi:[1,0]
	ds_write_b16 v171, v151 offset:128
	v_cvt_pk_bf16_f32 v151, v206, v137
	ds_write_b16 v171, v151 offset:256
	v_cvt_pk_bf16_f32 v151, v207, v137
	v_pk_mul_f32 v[212:213], v[80:81], v[168:169] op_sel_hi:[1,0]
	ds_write_b16 v171, v151 offset:384
	v_cvt_pk_bf16_f32 v151, v212, v137
	ds_write_b16 v171, v151 offset:512
	v_cvt_pk_bf16_f32 v151, v213, v137
	v_pk_mul_f32 v[210:211], v[82:83], v[168:169] op_sel_hi:[1,0]
	ds_write_b16 v171, v151 offset:640
	v_cvt_pk_bf16_f32 v151, v210, v137
	ds_write_b16 v171, v151 offset:768
	v_cvt_pk_bf16_f32 v151, v211, v137
	v_pk_mul_f32 v[216:217], v[68:69], v[166:167] op_sel_hi:[1,0]
	ds_write_b16 v171, v151 offset:896
	v_cvt_pk_bf16_f32 v151, v216, v137
	ds_write_b16 v173, v151
	v_cvt_pk_bf16_f32 v151, v217, v137
	v_pk_mul_f32 v[214:215], v[70:71], v[166:167] op_sel_hi:[1,0]
	ds_write_b16 v173, v151 offset:128
	v_cvt_pk_bf16_f32 v151, v214, v137
	ds_write_b16 v173, v151 offset:256
	v_cvt_pk_bf16_f32 v151, v215, v137
	v_pk_mul_f32 v[220:221], v[64:65], v[166:167] op_sel_hi:[1,0]
	ds_write_b16 v173, v151 offset:384
	v_cvt_pk_bf16_f32 v151, v220, v137
	ds_write_b16 v173, v151 offset:512
	v_cvt_pk_bf16_f32 v151, v221, v137
	v_pk_mul_f32 v[218:219], v[66:67], v[166:167] op_sel_hi:[1,0]
	ds_write_b16 v173, v151 offset:640
	v_cvt_pk_bf16_f32 v151, v218, v137
	ds_write_b16 v173, v151 offset:768
	v_cvt_pk_bf16_f32 v151, v219, v137
	ds_write_b16 v173, v151 offset:896
	s_waitcnt lgkmcnt(0)
	ds_read_b128 v[190:193], v184
	ds_read_b128 v[194:197], v185
	s_mov_b32 s57, s19
	v_lshl_add_u64 v[182:183], v[182:183], 0, s[56:57]
	v_lshl_add_u64 v[198:199], v[182:183], 0, v[142:143]
	s_waitcnt lgkmcnt(1)
	global_store_dwordx4 v[198:199], v[190:193], off nt
	ds_read_b128 v[190:193], v186
	ds_read_b128 v[198:201], v187
	v_lshl_add_u64 v[202:203], v[182:183], 0, v[144:145]
	s_waitcnt lgkmcnt(2)
	global_store_dwordx4 v[202:203], v[194:197], off nt
	v_pk_mul_f32 v[204:205], v[40:41], v[162:163] op_sel_hi:[1,0]
	v_pk_mul_f32 v[202:203], v[42:43], v[162:163] op_sel_hi:[1,0]
	v_lshl_add_u64 v[194:195], v[182:183], 0, v[146:147]
	s_waitcnt lgkmcnt(1)
	global_store_dwordx4 v[194:195], v[190:193], off nt
	v_pk_mul_f32 v[196:197], v[56:57], v[164:165] op_sel_hi:[1,0]
	v_pk_mul_f32 v[194:195], v[58:59], v[164:165] op_sel_hi:[1,0]
	v_lshl_add_u64 v[190:191], v[182:183], 0, v[148:149]
	s_waitcnt lgkmcnt(0)
	global_store_dwordx4 v[190:191], v[198:201], off nt
	v_pk_mul_f32 v[192:193], v[60:61], v[164:165] op_sel_hi:[1,0]
	s_waitcnt lgkmcnt(0)
; #define LAS __attribute__((address_space(3)))
; __device__ __forceinline__ unsigned cvt_pk_bf16(float lo, float hi) { unsigned r; asm("v_cvt_pk_bf16_f32 %0, %1, %2" : "=v"(r) : "v"(lo), "v"(hi)); return r; }
; #define LDS_WAIT() asm volatile("s_waitcnt lgkmcnt(0)" ::: "memory")
; __device__ __forceinline__ void tstore_sub(const f32x4 (&v)[4][2], bf16_t* dst  , LAS unsigned char* x, int fr, int fq, int lane) {
; #pragma unroll
;     for (int m = 0; m < 4; ++m)
; #pragma unroll
;         for (int n = 0; n < 2; ++n)
; #pragma unroll
;             for (int j = 0; j < 4; ++j) {
;                 const int ch = 8 * fq + 4 * n + j, tok = 16 * m + fr;
;                 const unsigned b = cvt_pk_bf16(v[m][n][j], 0.f);
;                 *(LAS unsigned short*)(x + ch * 128 + ((((tok >> 3) ^ fq) << 4) | ((tok & 7) << 1))) = (unsigned short)b;
;             }
;     LDS_WAIT();
; #pragma unroll
;     for (int i = 0; i < 4; ++i) {
;         const int q = lane + 64 * i, ch = q >> 3, tc = q & 7;
;         const u32x4 o = *(const LAS u32x4*)(x + ch * 128 + ((tc ^ ((ch >> 3) & 3)) << 4));
;         *(u32x4*)(dst + (size_t)ch * T + tc * 8) = o;
;     }
;     LDS_WAIT();
; }
;     __device__ __forceinline__ void operator()(const f32x4 (&acc)[2][2][4][2], const Unit& u, int wr, int wc, int fr, int fq, LAS unsigned char* xs, int wid, int lane) const {
;     ...
;                     f32x4 v[4][2];
; #pragma unroll
;                     for (int m = 0; m < 4; ++m) { v[m][0] = acc[ai][bj][m][0] * rs[ai][m]; v[m][1] = acc[ai][bj][m][1] * rs[ai][m]; }
;                     if (ODD) {
;                         float* vss = (float*)(ws + OFF_VSS);
; #pragma unroll
;                         for (int m = 0; m < 4; ++m) {
;                             float s = 0.f;
; #pragma unroll
;                             for (int n = 0; n < 2; ++n) s += (v[m][n][0] * v[m][n][0] + v[m][n][1] * v[m][n][1]) + (v[m][n][2] * v[m][n][2] + v[m][n][3] * v[m][n][3]);
;                             s += __shfl_xor(s, 16); s += __shfl_xor(s, 32);
;                             if (fq == 0) vss[(size_t)(row0 + ai * 128 + m * 16 + fr) * 32 + (2 * (pn - 24) + bj) * 4 + wc] = s;
;                         }
;                     }
;                     tstore_sub(v, base + (size_t)(bj * 128 + wc * 32) * T + row0 + ai * 128, x, fr, fq, lane);
	v_pk_mul_f32 v[190:191], v[62:63], v[164:165] op_sel_hi:[1,0]
	v_cvt_pk_bf16_f32 v151, v192, v137
	ds_write_b16 v167, v151
	v_cvt_pk_bf16_f32 v151, v193, v137
	ds_write_b16 v167, v151 offset:128
	v_cvt_pk_bf16_f32 v151, v190, v137
	ds_write_b16 v167, v151 offset:256
	v_cvt_pk_bf16_f32 v151, v191, v137
	ds_write_b16 v167, v151 offset:384
	v_cvt_pk_bf16_f32 v151, v196, v137
	ds_write_b16 v167, v151 offset:512
	v_cvt_pk_bf16_f32 v151, v197, v137
	ds_write_b16 v167, v151 offset:640
	v_cvt_pk_bf16_f32 v151, v194, v137
	ds_write_b16 v167, v151 offset:768
	v_cvt_pk_bf16_f32 v151, v195, v137
	v_pk_mul_f32 v[200:201], v[44:45], v[162:163] op_sel_hi:[1,0]
	ds_write_b16 v167, v151 offset:896
	v_cvt_pk_bf16_f32 v151, v200, v137
	ds_write_b16 v169, v151
	v_cvt_pk_bf16_f32 v151, v201, v137
	v_pk_mul_f32 v[198:199], v[46:47], v[162:163] op_sel_hi:[1,0]
	ds_write_b16 v169, v151 offset:128
	v_cvt_pk_bf16_f32 v151, v198, v137
	ds_write_b16 v169, v151 offset:256
	v_cvt_pk_bf16_f32 v151, v199, v137
	ds_write_b16 v169, v151 offset:384
	v_cvt_pk_bf16_f32 v151, v204, v137
	ds_write_b16 v169, v151 offset:512
	v_cvt_pk_bf16_f32 v151, v205, v137
	ds_write_b16 v169, v151 offset:640
	v_cvt_pk_bf16_f32 v151, v202, v137
	ds_write_b16 v169, v151 offset:768
	v_cvt_pk_bf16_f32 v151, v203, v137
	v_pk_mul_f32 v[208:209], v[28:29], v[160:161] op_sel_hi:[1,0]
	ds_write_b16 v169, v151 offset:896
	v_cvt_pk_bf16_f32 v151, v208, v137
	ds_write_b16 v171, v151
	v_cvt_pk_bf16_f32 v151, v209, v137
	v_pk_mul_f32 v[206:207], v[30:31], v[160:161] op_sel_hi:[1,0]
	ds_write_b16 v171, v151 offset:128
	v_cvt_pk_bf16_f32 v151, v206, v137
	ds_write_b16 v171, v151 offset:256
	v_cvt_pk_bf16_f32 v151, v207, v137
	v_pk_mul_f32 v[212:213], v[24:25], v[160:161] op_sel_hi:[1,0]
	ds_write_b16 v171, v151 offset:384
	v_cvt_pk_bf16_f32 v151, v212, v137
	ds_write_b16 v171, v151 offset:512
	v_cvt_pk_bf16_f32 v151, v213, v137
	v_pk_mul_f32 v[210:211], v[26:27], v[160:161] op_sel_hi:[1,0]
	ds_write_b16 v171, v151 offset:640
	v_cvt_pk_bf16_f32 v151, v210, v137
	ds_write_b16 v171, v151 offset:768
	v_cvt_pk_bf16_f32 v151, v211, v137
	v_pk_mul_f32 v[216:217], v[12:13], v[158:159] op_sel_hi:[1,0]
	ds_write_b16 v171, v151 offset:896
	v_cvt_pk_bf16_f32 v151, v216, v137
	ds_write_b16 v173, v151
	v_cvt_pk_bf16_f32 v151, v217, v137
	v_pk_mul_f32 v[214:215], v[14:15], v[158:159] op_sel_hi:[1,0]
	ds_write_b16 v173, v151 offset:128
	v_cvt_pk_bf16_f32 v151, v214, v137
	ds_write_b16 v173, v151 offset:256
	v_cvt_pk_bf16_f32 v151, v215, v137
	v_pk_mul_f32 v[220:221], v[8:9], v[158:159] op_sel_hi:[1,0]
	ds_write_b16 v173, v151 offset:384
	v_cvt_pk_bf16_f32 v151, v220, v137
	ds_write_b16 v173, v151 offset:512
	v_cvt_pk_bf16_f32 v151, v221, v137
	v_pk_mul_f32 v[218:219], v[10:11], v[158:159] op_sel_hi:[1,0]
	ds_write_b16 v173, v151 offset:640
	v_cvt_pk_bf16_f32 v151, v218, v137
	ds_write_b16 v173, v151 offset:768
	v_cvt_pk_bf16_f32 v151, v219, v137
	ds_write_b16 v173, v151 offset:896
	s_waitcnt lgkmcnt(0)
	ds_read_b128 v[190:193], v184
	ds_read_b128 v[194:197], v185
	ds_read_b128 v[198:201], v186
	ds_read_b128 v[202:205], v187
	s_waitcnt lgkmcnt(3)
	global_store_dwordx4 v[174:175], v[190:193], off offset:256 nt
	s_waitcnt lgkmcnt(2)
	global_store_dwordx4 v[176:177], v[194:197], off offset:256 nt
	s_waitcnt lgkmcnt(1)
	global_store_dwordx4 v[178:179], v[198:201], off offset:256 nt
	s_waitcnt lgkmcnt(0)
	global_store_dwordx4 v[180:181], v[202:205], off offset:256 nt
	v_pk_mul_f32 v[176:177], v[52:53], v[164:165] op_sel_hi:[1,0]
	s_waitcnt lgkmcnt(0)
	v_pk_mul_f32 v[174:175], v[54:55], v[164:165] op_sel_hi:[1,0]
	v_cvt_pk_bf16_f32 v151, v176, v137
	ds_write_b16 v167, v151
	v_cvt_pk_bf16_f32 v151, v177, v137
	ds_write_b16 v167, v151 offset:128
	v_cvt_pk_bf16_f32 v151, v174, v137
	ds_write_b16 v167, v151 offset:256
	v_cvt_pk_bf16_f32 v151, v175, v137
	v_pk_mul_f32 v[180:181], v[48:49], v[164:165] op_sel_hi:[1,0]
	ds_write_b16 v167, v151 offset:384
	v_cvt_pk_bf16_f32 v151, v180, v137
	ds_write_b16 v167, v151 offset:512
	v_cvt_pk_bf16_f32 v151, v181, v137
	v_pk_mul_f32 v[178:179], v[50:51], v[164:165] op_sel_hi:[1,0]
	ds_write_b16 v167, v151 offset:640
	v_cvt_pk_bf16_f32 v151, v178, v137
	ds_write_b16 v167, v151 offset:768
	v_cvt_pk_bf16_f32 v151, v179, v137
	v_pk_mul_f32 v[192:193], v[36:37], v[162:163] op_sel_hi:[1,0]
	ds_write_b16 v167, v151 offset:896
	v_cvt_pk_bf16_f32 v151, v192, v137
	ds_write_b16 v169, v151
	v_cvt_pk_bf16_f32 v151, v193, v137
	v_pk_mul_f32 v[190:191], v[38:39], v[162:163] op_sel_hi:[1,0]
	ds_write_b16 v169, v151 offset:128
	v_cvt_pk_bf16_f32 v151, v190, v137
	ds_write_b16 v169, v151 offset:256
	v_cvt_pk_bf16_f32 v151, v191, v137
	v_pk_mul_f32 v[196:197], v[32:33], v[162:163] op_sel_hi:[1,0]
	ds_write_b16 v169, v151 offset:384
	v_cvt_pk_bf16_f32 v151, v196, v137
	ds_write_b16 v169, v151 offset:512
	v_cvt_pk_bf16_f32 v151, v197, v137
	v_pk_mul_f32 v[194:195], v[34:35], v[162:163] op_sel_hi:[1,0]
	ds_write_b16 v169, v151 offset:640
	v_cvt_pk_bf16_f32 v151, v194, v137
	ds_write_b16 v169, v151 offset:768
	v_cvt_pk_bf16_f32 v151, v195, v137
	v_pk_mul_f32 v[200:201], v[20:21], v[160:161] op_sel_hi:[1,0]
	ds_write_b16 v169, v151 offset:896
	v_cvt_pk_bf16_f32 v151, v200, v137
	ds_write_b16 v171, v151
	v_cvt_pk_bf16_f32 v151, v201, v137
	v_pk_mul_f32 v[198:199], v[22:23], v[160:161] op_sel_hi:[1,0]
	ds_write_b16 v171, v151 offset:128
	v_cvt_pk_bf16_f32 v151, v198, v137
	ds_write_b16 v171, v151 offset:256
	v_cvt_pk_bf16_f32 v151, v199, v137
	v_pk_mul_f32 v[204:205], v[16:17], v[160:161] op_sel_hi:[1,0]
	ds_write_b16 v171, v151 offset:384
	v_cvt_pk_bf16_f32 v151, v204, v137
	ds_write_b16 v171, v151 offset:512
	v_cvt_pk_bf16_f32 v151, v205, v137
	v_pk_mul_f32 v[202:203], v[18:19], v[160:161] op_sel_hi:[1,0]
	ds_write_b16 v171, v151 offset:640
	v_cvt_pk_bf16_f32 v151, v202, v137
	ds_write_b16 v171, v151 offset:768
	v_cvt_pk_bf16_f32 v151, v203, v137
	v_pk_mul_f32 v[208:209], v[4:5], v[158:159] op_sel_hi:[1,0]
	ds_write_b16 v171, v151 offset:896
	v_cvt_pk_bf16_f32 v151, v208, v137
	ds_write_b16 v173, v151
	v_cvt_pk_bf16_f32 v151, v209, v137
	v_pk_mul_f32 v[206:207], v[6:7], v[158:159] op_sel_hi:[1,0]
	ds_write_b16 v173, v151 offset:128
	v_cvt_pk_bf16_f32 v151, v206, v137
	ds_write_b16 v173, v151 offset:256
	v_cvt_pk_bf16_f32 v151, v207, v137
	v_pk_mul_f32 v[212:213], v[0:1], v[158:159] op_sel_hi:[1,0]
	ds_write_b16 v173, v151 offset:384
	v_cvt_pk_bf16_f32 v151, v212, v137
	ds_write_b16 v173, v151 offset:512
	v_cvt_pk_bf16_f32 v151, v213, v137
	v_pk_mul_f32 v[210:211], v[2:3], v[158:159] op_sel_hi:[1,0]
	ds_write_b16 v173, v151 offset:640
	v_cvt_pk_bf16_f32 v151, v210, v137
	ds_write_b16 v173, v151 offset:768
	v_cvt_pk_bf16_f32 v151, v211, v137
	ds_write_b16 v173, v151 offset:896
	s_waitcnt lgkmcnt(0)
; #define LAS __attribute__((address_space(3)))
; __device__ __forceinline__ unsigned cvt_pk_bf16(float lo, float hi) { unsigned r; asm("v_cvt_pk_bf16_f32 %0, %1, %2" : "=v"(r) : "v"(lo), "v"(hi)); return r; }
; #define LDS_WAIT() asm volatile("s_waitcnt lgkmcnt(0)" ::: "memory")
; __device__ __forceinline__ void tstore_sub(const f32x4 (&v)[4][2], bf16_t* dst  , LAS unsigned char* x, int fr, int fq, int lane) {
; #pragma unroll
;     for (int m = 0; m < 4; ++m)
; #pragma unroll
;         for (int n = 0; n < 2; ++n)
; #pragma unroll
;             for (int j = 0; j < 4; ++j) {
;                 const int ch = 8 * fq + 4 * n + j, tok = 16 * m + fr;
;                 const unsigned b = cvt_pk_bf16(v[m][n][j], 0.f);
;                 *(LAS unsigned short*)(x + ch * 128 + ((((tok >> 3) ^ fq) << 4) | ((tok & 7) << 1))) = (unsigned short)b;
;             }
;     LDS_WAIT();
; #pragma unroll
;     for (int i = 0; i < 4; ++i) {
;         const int q = lane + 64 * i, ch = q >> 3, tc = q & 7;
;         const u32x4 o = *(const LAS u32x4*)(x + ch * 128 + ((tc ^ ((ch >> 3) & 3)) << 4));
;         *(u32x4*)(dst + (size_t)ch * T + tc * 8) = o;
;     }
;     LDS_WAIT();
; }
;     __device__ __forceinline__ void operator()(const f32x4 (&acc)[2][2][4][2], const Unit& u, int wr, int wc, int fr, int fq, LAS unsigned char* xs, int wid, int lane) const {
;     ...
;         if (mode == 0) {
; #pragma unroll
;             for (int ai = 0; ai < 2; ++ai)
; #pragma unroll
;                 for (int m = 0; m < 4; ++m) {
;                     const float r = rs[ai][m];
;                     bf16_t* rowp = base + (size_t)(row0 + ai * 128 + m * 16 + fr) * ldc + wc * 32 + 8 * fq;
; #pragma unroll
;                     for (int bj = 0; bj < 2; ++bj) { const f32x4 v0 = acc[ai][bj][m][0] * r, v1 = acc[ai][bj][m][1] * r;
;                         u32x4 w; w.x = cvt_pk_bf16(v0[0], v0[1]); w.y = cvt_pk_bf16(v0[2], v0[3]); w.z = cvt_pk_bf16(v1[0], v1[1]); w.w = cvt_pk_bf16(v1[2], v1[3]);
;                         *(u32x4*)(rowp + bj * 128) = w; }
;                     __builtin_amdgcn_sched_barrier(0);
;                 }
	ds_read_b128 v[174:177], v184
	ds_read_b128 v[178:181], v185
	s_mov_b64 s[70:71], 0x100
	v_lshl_add_u64 v[182:183], v[182:183], 0, s[70:71]
	v_lshl_add_u64 v[190:191], v[182:183], 0, v[142:143]
	s_waitcnt lgkmcnt(1)
	global_store_dwordx4 v[190:191], v[174:177], off nt
	ds_read_b128 v[174:177], v186
	ds_read_b128 v[190:193], v187
	v_lshl_add_u64 v[194:195], v[182:183], 0, v[144:145]
	s_waitcnt lgkmcnt(2)
	global_store_dwordx4 v[194:195], v[178:181], off nt
	s_nop 1
	v_lshl_add_u64 v[178:179], v[182:183], 0, v[146:147]
	s_waitcnt lgkmcnt(1)
	global_store_dwordx4 v[178:179], v[174:177], off nt
	s_nop 1
	v_lshl_add_u64 v[174:175], v[182:183], 0, v[148:149]
	s_waitcnt lgkmcnt(0)
	global_store_dwordx4 v[174:175], v[190:193], off nt
	s_waitcnt lgkmcnt(0)
	s_cbranch_execnz .LBB0_970
.LBB0_985:
	s_add_u32 s68, s68, s35
	v_or_b32_e32 v143, s66, v157
	s_addc_u32 s69, s69, 0
	s_ashr_i32 s0, s66, 31
	v_mov_b32_e32 v151, v137
	v_mul_lo_u32 v145, s11, v143
	s_mul_i32 s0, s10, s0
	v_mad_u64_u32 v[176:177], s[66:67], s10, v143, 0
	v_lshl_add_u64 v[174:175], s[68:69], 0, v[150:151]
	v_add3_u32 v177, v177, s0, v145
	v_lshl_add_u64 v[176:177], v[176:177], 1, v[174:175]
	s_waitcnt lgkmcnt(7)
	v_pk_mul_f32 v[126:127], v[126:127], v[172:173] op_sel_hi:[1,0]
	v_pk_mul_f32 v[124:125], v[124:125], v[172:173] op_sel_hi:[1,0]
	v_pk_mul_f32 v[178:179], v[122:123], v[172:173] op_sel_hi:[1,0]
	v_pk_mul_f32 v[122:123], v[120:121], v[172:173] op_sel_hi:[1,0]
	v_cvt_pk_bf16_f32 v120, v124, v125
	v_cvt_pk_bf16_f32 v121, v126, v127
	v_pk_mul_f32 v[118:119], v[118:119], v[172:173] op_sel_hi:[1,0]
	v_cvt_pk_bf16_f32 v122, v122, v123
	v_cvt_pk_bf16_f32 v123, v178, v179
	global_store_dwordx4 v[176:177], v[120:123], off nt
	v_pk_mul_f32 v[116:117], v[116:117], v[172:173] op_sel_hi:[1,0]
	s_nop 0
	v_pk_mul_f32 v[120:121], v[114:115], v[172:173] op_sel_hi:[1,0]
	v_pk_mul_f32 v[114:115], v[112:113], v[172:173] op_sel_hi:[1,0]
	v_cvt_pk_bf16_f32 v112, v116, v117
	v_cvt_pk_bf16_f32 v113, v118, v119
	s_nop 0
	v_cvt_pk_bf16_f32 v114, v114, v115
	v_cvt_pk_bf16_f32 v115, v120, v121
	global_store_dwordx4 v[176:177], v[112:115], off offset:256 nt
	s_nop 1
	v_or_b32_e32 v112, 16, v143
	v_mul_lo_u32 v114, s11, v112
	v_mad_u64_u32 v[112:113], s[66:67], s10, v112, 0
	v_add3_u32 v113, v113, s0, v114
	v_lshl_add_u64 v[112:113], v[112:113], 1, v[174:175]
	s_waitcnt lgkmcnt(6)
	v_pk_mul_f32 v[110:111], v[110:111], v[170:171] op_sel_hi:[1,0]
	v_pk_mul_f32 v[108:109], v[108:109], v[170:171] op_sel_hi:[1,0]
	v_pk_mul_f32 v[114:115], v[106:107], v[170:171] op_sel_hi:[1,0]
	v_pk_mul_f32 v[106:107], v[104:105], v[170:171] op_sel_hi:[1,0]
	v_cvt_pk_bf16_f32 v104, v108, v109
	v_cvt_pk_bf16_f32 v105, v110, v111
	v_pk_mul_f32 v[102:103], v[102:103], v[170:171] op_sel_hi:[1,0]
	v_cvt_pk_bf16_f32 v106, v106, v107
	v_cvt_pk_bf16_f32 v107, v114, v115
	global_store_dwordx4 v[112:113], v[104:107], off nt
	v_pk_mul_f32 v[100:101], v[100:101], v[170:171] op_sel_hi:[1,0]
	s_nop 0
	v_pk_mul_f32 v[104:105], v[98:99], v[170:171] op_sel_hi:[1,0]
	v_pk_mul_f32 v[98:99], v[96:97], v[170:171] op_sel_hi:[1,0]
	v_cvt_pk_bf16_f32 v96, v100, v101
	v_cvt_pk_bf16_f32 v97, v102, v103
	s_nop 0
	v_cvt_pk_bf16_f32 v98, v98, v99
	v_cvt_pk_bf16_f32 v99, v104, v105
	global_store_dwordx4 v[112:113], v[96:99], off offset:256 nt
	s_nop 1
	v_or_b32_e32 v96, 32, v143
	v_mul_lo_u32 v98, s11, v96
	v_mad_u64_u32 v[96:97], s[66:67], s10, v96, 0
	v_add3_u32 v97, v97, s0, v98
	v_lshl_add_u64 v[96:97], v[96:97], 1, v[174:175]
	s_waitcnt lgkmcnt(5)
	v_pk_mul_f32 v[94:95], v[94:95], v[168:169] op_sel_hi:[1,0]
	v_pk_mul_f32 v[92:93], v[92:93], v[168:169] op_sel_hi:[1,0]
	v_pk_mul_f32 v[98:99], v[90:91], v[168:169] op_sel_hi:[1,0]
	v_pk_mul_f32 v[90:91], v[88:89], v[168:169] op_sel_hi:[1,0]
	v_cvt_pk_bf16_f32 v88, v92, v93
	v_cvt_pk_bf16_f32 v89, v94, v95
	v_pk_mul_f32 v[86:87], v[86:87], v[168:169] op_sel_hi:[1,0]
	v_cvt_pk_bf16_f32 v90, v90, v91
	v_cvt_pk_bf16_f32 v91, v98, v99
	global_store_dwordx4 v[96:97], v[88:91], off nt
	v_pk_mul_f32 v[84:85], v[84:85], v[168:169] op_sel_hi:[1,0]
	s_nop 0
	v_pk_mul_f32 v[88:89], v[82:83], v[168:169] op_sel_hi:[1,0]
	v_pk_mul_f32 v[82:83], v[80:81], v[168:169] op_sel_hi:[1,0]
	v_cvt_pk_bf16_f32 v80, v84, v85
	v_cvt_pk_bf16_f32 v81, v86, v87
	s_nop 0
	v_cvt_pk_bf16_f32 v82, v82, v83
	v_cvt_pk_bf16_f32 v83, v88, v89
	global_store_dwordx4 v[96:97], v[80:83], off offset:256 nt
	s_nop 1
	v_or_b32_e32 v80, 48, v143
	v_mul_lo_u32 v82, s11, v80
	v_mad_u64_u32 v[80:81], s[66:67], s10, v80, 0
	v_add3_u32 v81, v81, s0, v82
	v_lshl_add_u64 v[80:81], v[80:81], 1, v[174:175]
	s_waitcnt lgkmcnt(4)
; __device__ __forceinline__ unsigned cvt_pk_bf16(float lo, float hi) { unsigned r; asm("v_cvt_pk_bf16_f32 %0, %1, %2" : "=v"(r) : "v"(lo), "v"(hi)); return r; }
;     __device__ __forceinline__ void operator()(const f32x4 (&acc)[2][2][4][2], const Unit& u, int wr, int wc, int fr, int fq, LAS unsigned char* xs, int wid, int lane) const {
;     ...
;         if (mode == 0) {
; #pragma unroll
;             for (int ai = 0; ai < 2; ++ai)
; #pragma unroll
;                 for (int m = 0; m < 4; ++m) {
;                     const float r = rs[ai][m];
;                     bf16_t* rowp = base + (size_t)(row0 + ai * 128 + m * 16 + fr) * ldc + wc * 32 + 8 * fq;
; #pragma unroll
;                     for (int bj = 0; bj < 2; ++bj) { const f32x4 v0 = acc[ai][bj][m][0] * r, v1 = acc[ai][bj][m][1] * r;
;                         u32x4 w; w.x = cvt_pk_bf16(v0[0], v0[1]); w.y = cvt_pk_bf16(v0[2], v0[3]); w.z = cvt_pk_bf16(v1[0], v1[1]); w.w = cvt_pk_bf16(v1[2], v1[3]);
;                         *(u32x4*)(rowp + bj * 128) = w; }
;                     __builtin_amdgcn_sched_barrier(0);
;                 }
	v_pk_mul_f32 v[78:79], v[78:79], v[166:167] op_sel_hi:[1,0]
	v_pk_mul_f32 v[76:77], v[76:77], v[166:167] op_sel_hi:[1,0]
	v_pk_mul_f32 v[82:83], v[74:75], v[166:167] op_sel_hi:[1,0]
	v_pk_mul_f32 v[74:75], v[72:73], v[166:167] op_sel_hi:[1,0]
	v_cvt_pk_bf16_f32 v72, v76, v77
	v_cvt_pk_bf16_f32 v73, v78, v79
	v_pk_mul_f32 v[70:71], v[70:71], v[166:167] op_sel_hi:[1,0]
	v_cvt_pk_bf16_f32 v74, v74, v75
	v_cvt_pk_bf16_f32 v75, v82, v83
	global_store_dwordx4 v[80:81], v[72:75], off nt
	v_pk_mul_f32 v[68:69], v[68:69], v[166:167] op_sel_hi:[1,0]
	s_nop 0
	v_pk_mul_f32 v[72:73], v[66:67], v[166:167] op_sel_hi:[1,0]
	v_pk_mul_f32 v[66:67], v[64:65], v[166:167] op_sel_hi:[1,0]
	v_cvt_pk_bf16_f32 v64, v68, v69
	v_cvt_pk_bf16_f32 v65, v70, v71
	s_nop 0
	v_cvt_pk_bf16_f32 v66, v66, v67
	v_cvt_pk_bf16_f32 v67, v72, v73
	global_store_dwordx4 v[80:81], v[64:67], off offset:256 nt
	s_nop 1
	v_add_u32_e32 v64, 0x80, v143
	v_ashrrev_i32_e32 v65, 31, v64
	v_mul_lo_u32 v66, s10, v65
	v_mul_lo_u32 v67, s11, v64
	v_mad_u64_u32 v[64:65], s[66:67], s10, v64, 0
	v_add3_u32 v65, v65, v66, v67
	v_lshl_add_u64 v[64:65], v[64:65], 1, v[174:175]
	s_waitcnt lgkmcnt(3)
	v_pk_mul_f32 v[62:63], v[62:63], v[164:165] op_sel_hi:[1,0]
	v_pk_mul_f32 v[60:61], v[60:61], v[164:165] op_sel_hi:[1,0]
	v_pk_mul_f32 v[66:67], v[58:59], v[164:165] op_sel_hi:[1,0]
	v_pk_mul_f32 v[58:59], v[56:57], v[164:165] op_sel_hi:[1,0]
	v_cvt_pk_bf16_f32 v56, v60, v61
	v_cvt_pk_bf16_f32 v57, v62, v63
	v_pk_mul_f32 v[54:55], v[54:55], v[164:165] op_sel_hi:[1,0]
	v_cvt_pk_bf16_f32 v58, v58, v59
	v_cvt_pk_bf16_f32 v59, v66, v67
	global_store_dwordx4 v[64:65], v[56:59], off nt
	v_pk_mul_f32 v[52:53], v[52:53], v[164:165] op_sel_hi:[1,0]
	s_nop 0
	v_pk_mul_f32 v[56:57], v[50:51], v[164:165] op_sel_hi:[1,0]
	v_pk_mul_f32 v[50:51], v[48:49], v[164:165] op_sel_hi:[1,0]
	v_cvt_pk_bf16_f32 v48, v52, v53
	v_cvt_pk_bf16_f32 v49, v54, v55
	s_nop 0
	v_cvt_pk_bf16_f32 v50, v50, v51
	v_cvt_pk_bf16_f32 v51, v56, v57
	global_store_dwordx4 v[64:65], v[48:51], off offset:256 nt
	s_nop 1
	v_add_u32_e32 v48, 0x90, v143
	v_ashrrev_i32_e32 v49, 31, v48
	v_mul_lo_u32 v50, s10, v49
	v_mul_lo_u32 v51, s11, v48
	v_mad_u64_u32 v[48:49], s[66:67], s10, v48, 0
	v_add3_u32 v49, v49, v50, v51
	v_lshl_add_u64 v[48:49], v[48:49], 1, v[174:175]
	s_waitcnt lgkmcnt(2)
	v_pk_mul_f32 v[46:47], v[46:47], v[162:163] op_sel_hi:[1,0]
	v_pk_mul_f32 v[44:45], v[44:45], v[162:163] op_sel_hi:[1,0]
	v_pk_mul_f32 v[50:51], v[42:43], v[162:163] op_sel_hi:[1,0]
	v_pk_mul_f32 v[42:43], v[40:41], v[162:163] op_sel_hi:[1,0]
	v_cvt_pk_bf16_f32 v40, v44, v45
	v_cvt_pk_bf16_f32 v41, v46, v47
	v_pk_mul_f32 v[38:39], v[38:39], v[162:163] op_sel_hi:[1,0]
	v_cvt_pk_bf16_f32 v42, v42, v43
	v_cvt_pk_bf16_f32 v43, v50, v51
	global_store_dwordx4 v[48:49], v[40:43], off nt
	v_pk_mul_f32 v[36:37], v[36:37], v[162:163] op_sel_hi:[1,0]
	s_nop 0
	v_pk_mul_f32 v[40:41], v[34:35], v[162:163] op_sel_hi:[1,0]
	v_pk_mul_f32 v[34:35], v[32:33], v[162:163] op_sel_hi:[1,0]
	v_cvt_pk_bf16_f32 v32, v36, v37
	v_cvt_pk_bf16_f32 v33, v38, v39
	s_nop 0
	v_cvt_pk_bf16_f32 v34, v34, v35
	v_cvt_pk_bf16_f32 v35, v40, v41
	global_store_dwordx4 v[48:49], v[32:35], off offset:256 nt
	s_nop 1
	v_add_u32_e32 v32, 0xa0, v143
	v_ashrrev_i32_e32 v33, 31, v32
	v_mul_lo_u32 v34, s10, v33
	v_mul_lo_u32 v35, s11, v32
	v_mad_u64_u32 v[32:33], s[66:67], s10, v32, 0
	v_add3_u32 v33, v33, v34, v35
	v_lshl_add_u64 v[32:33], v[32:33], 1, v[174:175]
	s_waitcnt lgkmcnt(1)
	v_pk_mul_f32 v[30:31], v[30:31], v[160:161] op_sel_hi:[1,0]
	v_pk_mul_f32 v[28:29], v[28:29], v[160:161] op_sel_hi:[1,0]
	v_pk_mul_f32 v[34:35], v[26:27], v[160:161] op_sel_hi:[1,0]
	v_pk_mul_f32 v[26:27], v[24:25], v[160:161] op_sel_hi:[1,0]
	v_cvt_pk_bf16_f32 v24, v28, v29
	v_cvt_pk_bf16_f32 v25, v30, v31
	v_pk_mul_f32 v[22:23], v[22:23], v[160:161] op_sel_hi:[1,0]
	v_cvt_pk_bf16_f32 v26, v26, v27
	v_cvt_pk_bf16_f32 v27, v34, v35
	global_store_dwordx4 v[32:33], v[24:27], off nt
	v_pk_mul_f32 v[20:21], v[20:21], v[160:161] op_sel_hi:[1,0]
	s_nop 0
	v_pk_mul_f32 v[24:25], v[18:19], v[160:161] op_sel_hi:[1,0]
	v_pk_mul_f32 v[18:19], v[16:17], v[160:161] op_sel_hi:[1,0]
	v_cvt_pk_bf16_f32 v16, v20, v21
	v_cvt_pk_bf16_f32 v17, v22, v23
	s_nop 0
	v_cvt_pk_bf16_f32 v18, v18, v19
	v_cvt_pk_bf16_f32 v19, v24, v25
	global_store_dwordx4 v[32:33], v[16:19], off offset:256 nt
	s_nop 1
	v_add_u32_e32 v16, 0xb0, v143
	v_ashrrev_i32_e32 v17, 31, v16
	v_mul_lo_u32 v18, s10, v17
	v_mul_lo_u32 v19, s11, v16
	v_mad_u64_u32 v[16:17], s[10:11], s10, v16, 0
	v_add3_u32 v17, v17, v18, v19
	v_lshl_add_u64 v[16:17], v[16:17], 1, v[174:175]
	s_waitcnt lgkmcnt(0)
	v_pk_mul_f32 v[14:15], v[14:15], v[158:159] op_sel_hi:[1,0]
	v_pk_mul_f32 v[12:13], v[12:13], v[158:159] op_sel_hi:[1,0]
	v_pk_mul_f32 v[18:19], v[10:11], v[158:159] op_sel_hi:[1,0]
	v_pk_mul_f32 v[10:11], v[8:9], v[158:159] op_sel_hi:[1,0]
	v_cvt_pk_bf16_f32 v8, v12, v13
	v_cvt_pk_bf16_f32 v9, v14, v15
	v_pk_mul_f32 v[6:7], v[6:7], v[158:159] op_sel_hi:[1,0]
	v_cvt_pk_bf16_f32 v10, v10, v11
	v_cvt_pk_bf16_f32 v11, v18, v19
	global_store_dwordx4 v[16:17], v[8:11], off nt
	v_pk_mul_f32 v[4:5], v[4:5], v[158:159] op_sel_hi:[1,0]
	s_nop 0
	v_pk_mul_f32 v[8:9], v[2:3], v[158:159] op_sel_hi:[1,0]
	v_pk_mul_f32 v[2:3], v[0:1], v[158:159] op_sel_hi:[1,0]
	v_cvt_pk_bf16_f32 v0, v4, v5
	v_cvt_pk_bf16_f32 v1, v6, v7
	s_nop 0
	v_cvt_pk_bf16_f32 v2, v2, v3
	v_cvt_pk_bf16_f32 v3, v8, v9
	global_store_dwordx4 v[16:17], v[0:3], off offset:256 nt
	s_andn2_b64 vcc, exec, s[8:9]
	s_mov_b64 s[8:9], -1
	s_cbranch_vccnz .LBB0_959

; #define LAS __attribute__((address_space(3)))
; __device__ __forceinline__ unsigned cvt_pk_bf16(float lo, float hi) { unsigned r; asm("v_cvt_pk_bf16_f32 %0, %1, %2" : "=v"(r) : "v"(lo), "v"(hi)); return r; }
;     __device__ __forceinline__ void operator()(const f32x4 (&acc)[2][2][4][2], const Unit& u, int wr, int wc, int fr, int fq, LAS unsigned char* xs, int wid, int lane) const {
;         const int S = lng ? 4096 : 2048, hp = lng ? 8 : 4;
;         const int cs = u.pm >= hp, k0 = (u.pm - hp * cs) * 256 + wr * 64;
;         const size_t tok0 = lng ? (size_t)TP + (size_t)u.aux * 4096 : (size_t)u.aux * 2048;
;         const float sc = lng ? 0.015625f : 0.02209708691207961f;
;         const float scm = cs ? -sc : sc;
;         float hv[2][8];
;         const float csm = cs ? 0.f : 1.f;
; #pragma unroll
;         for (int bj = 0; bj < 2; ++bj)
; #pragma unroll
;             for (int e = 0; e < 8; ++e) {
;                 const unsigned short h = ft[(size_t)(u.pn * 256 + bj * 128 + wc * 32 + 8 * fq + e) * T + tok0 + S / 2];
;                 const float v = __builtin_bit_cast(float, (unsigned)h << 16) * csm;
;                 hv[bj][e] = (fr & 1) ? -v : v;
;             }
; #pragma unroll
;         for (int ai = 0; ai < 2; ++ai)
; #pragma unroll
;             for (int m = 0; m < 4; ++m) {
;                 const int k = k0 + ai * 128 + m * 16 + fr;
; #pragma unroll
;                 for (int bj = 0; bj < 2; ++bj) {
;                     const int col = (2 * u.pn + bj) * 256 + cs * 128 + wc * 32 + 8 * fq;
;                     f32x4 a = acc[ai][bj][m][0], b = acc[ai][bj][m][1];
; #pragma unroll
;                     for (int j = 0; j < 4; ++j) { a[j] += hv[bj][j]; b[j] += hv[bj][4 + j]; }
;                     u32x4 w; w.x = cvt_pk_bf16(a[0] * sc, a[1] * sc); w.y = cvt_pk_bf16(a[2] * sc, a[3] * sc); w.z = cvt_pk_bf16(b[0] * sc, b[1] * sc); w.w = cvt_pk_bf16(b[2] * sc, b[3] * sc);
;                     *(u32x4*)(pq + (tok0 + k) * 1024 + col) = w;
;                     if (k > 0) {
;                         u32x4 w2; w2.x = cvt_pk_bf16(a[0] * scm, a[1] * scm); w2.y = cvt_pk_bf16(a[2] * scm, a[3] * scm); w2.z = cvt_pk_bf16(b[0] * scm, b[1] * scm); w2.w = cvt_pk_bf16(b[2] * scm, b[3] * scm);
;                         *(u32x4*)(pq + (tok0 + S - k) * 1024 + col) = w2;
.LBB0_1183:
	s_lshl_b32 s12, s85, 8
	s_and_b32 s63, s12, 0x700
	s_ashr_i32 s21, s20, 31
	s_add_i32 s63, s63, s27
	s_lshl_b64 s[12:13], s[20:21], 12
	s_add_u32 s20, s12, 0x4000
	s_addc_u32 s21, s13, 0
	s_lshl_b64 s[60:61], s[20:21], 1
	s_add_u32 s60, s46, s60
	v_lshlrev_b32_e32 v136, 16, v150
	v_readlane_b32 s74, v255, 20
	s_addc_u32 s61, s47, s61
	s_movk_i32 s57, 0x1000
	v_lshl_or_b32 v136, s74, 24, v136
	v_lshl_add_u64 v[146:147], s[60:61], 0, v[136:137]
	v_add_co_u32_e32 v156, vcc, s57, v146
	s_mov_b32 s57, 0x11000
	s_nop 0
	v_addc_co_u32_e32 v157, vcc, 0, v147, vcc
	global_load_ushort v136, v[156:157], off
	v_add_co_u32_e32 v156, vcc, s57, v146
	s_mov_b32 s57, 0x21000
	s_nop 0
	v_addc_co_u32_e32 v157, vcc, 0, v147, vcc
	global_load_ushort v158, v[156:157], off
	v_add_co_u32_e32 v156, vcc, s57, v146
	s_mov_b32 s57, 0x31000
	s_nop 0
	v_addc_co_u32_e32 v157, vcc, 0, v147, vcc
	global_load_ushort v159, v[156:157], off
	v_add_co_u32_e32 v156, vcc, s57, v146
	s_mov_b32 s57, 0x41000
	s_nop 0
	v_addc_co_u32_e32 v157, vcc, 0, v147, vcc
	global_load_ushort v160, v[156:157], off
	v_add_co_u32_e32 v156, vcc, s57, v146
	s_mov_b32 s57, 0x51000
	s_nop 0
	v_addc_co_u32_e32 v157, vcc, 0, v147, vcc
	global_load_ushort v161, v[156:157], off
	v_add_co_u32_e32 v156, vcc, s57, v146
	s_mov_b32 s57, 0x61000
	s_nop 0
	v_addc_co_u32_e32 v157, vcc, 0, v147, vcc
	global_load_ushort v162, v[156:157], off
	v_add_co_u32_e32 v156, vcc, s57, v146
	s_mov_b32 s57, 0x71000
	s_nop 0
	v_addc_co_u32_e32 v157, vcc, 0, v147, vcc
	global_load_ushort v163, v[156:157], off
	v_add_co_u32_e32 v156, vcc, s57, v146
	s_cmp_lt_u32 s85, 8
	s_nop 0
	v_addc_co_u32_e32 v157, vcc, 0, v147, vcc
	global_load_ushort v164, v[156:157], off
	v_add_co_u32_e32 v156, vcc, s39, v146
	s_waitcnt vmcnt(0)
	v_lshlrev_b32_e32 v136, 16, v136
	v_addc_co_u32_e32 v157, vcc, 0, v147, vcc
	global_load_ushort v165, v[156:157], off
	v_add_co_u32_e32 v156, vcc, s41, v146
	s_nop 1
	v_addc_co_u32_e32 v157, vcc, 0, v147, vcc
	global_load_ushort v166, v[156:157], off
	v_add_co_u32_e32 v156, vcc, s64, v146
	s_nop 1
	v_addc_co_u32_e32 v157, vcc, 0, v147, vcc
	global_load_ushort v167, v[156:157], off
	v_add_co_u32_e32 v156, vcc, s65, v146
	s_nop 1
	v_addc_co_u32_e32 v157, vcc, 0, v147, vcc
	global_load_ushort v168, v[156:157], off
	v_add_co_u32_e32 v156, vcc, s66, v146
	s_nop 1
	v_addc_co_u32_e32 v157, vcc, 0, v147, vcc
	global_load_ushort v169, v[156:157], off
	v_add_co_u32_e32 v156, vcc, s67, v146
	s_nop 1
	v_addc_co_u32_e32 v157, vcc, 0, v147, vcc
	global_load_ushort v170, v[156:157], off
	v_add_co_u32_e32 v156, vcc, s68, v146
	s_nop 1
	v_addc_co_u32_e32 v157, vcc, 0, v147, vcc
	v_add_co_u32_e32 v146, vcc, s69, v146
	global_load_ushort v171, v[156:157], off
	s_nop 0
	v_addc_co_u32_e32 v147, vcc, 0, v147, vcc
	global_load_ushort v172, v[146:147], off
	s_cselect_b64 vcc, -1, 0
	v_cndmask_b32_e64 v173, 0, 1.0, vcc
	v_mul_f32_e32 v136, v173, v136
	v_cndmask_b32_e64 v157, -v136, v136, s[8:9]
	v_lshlrev_b32_e32 v136, 16, v158
	v_mul_f32_e32 v136, v173, v136
	v_cndmask_b32_e64 v158, -v136, v136, s[8:9]
	v_lshlrev_b32_e32 v136, 16, v159
	v_mul_f32_e32 v136, v173, v136
	v_cndmask_b32_e64 v159, -v136, v136, s[8:9]
	v_lshlrev_b32_e32 v136, 16, v160
	v_mul_f32_e32 v136, v173, v136
	v_cndmask_b32_e64 v160, -v136, v136, s[8:9]
	v_lshlrev_b32_e32 v136, 16, v161
	v_mul_f32_e32 v136, v173, v136
	v_cndmask_b32_e64 v161, -v136, v136, s[8:9]
	v_lshlrev_b32_e32 v136, 16, v162
	v_mul_f32_e32 v136, v173, v136
	v_cndmask_b32_e64 v162, -v136, v136, s[8:9]
	v_lshlrev_b32_e32 v136, 16, v163
	v_mul_f32_e32 v136, v173, v136
	v_or_b32_e32 v146, s63, v148
	s_and_b64 s[60:61], vcc, exec
	v_cndmask_b32_e64 v163, -v136, v136, s[8:9]
	v_lshlrev_b32_e32 v136, 16, v164
	s_cselect_b32 s60, 0, 0x80
	s_add_u32 s57, s12, 0x5000
	v_ashrrev_i32_e32 v147, 31, v146
	v_mul_f32_e32 v136, v173, v136
	s_addc_u32 s62, s13, 0
	v_lshl_add_u64 v[174:175], s[20:21], 0, v[146:147]
	v_cndmask_b32_e64 v164, -v136, v136, s[8:9]
	v_lshlrev_b64 v[182:183], 11, v[174:175]
	v_sub_co_u32_e64 v174, s[12:13], s57, v146
	v_mov_b32_e32 v136, s62
	s_nop 0
	v_subb_co_u32_e64 v175, s[12:13], v136, v147, s[12:13]
	v_lshlrev_b64 v[184:185], 11, v[174:175]
	v_add_f32_e32 v147, v124, v157
	v_add_f32_e32 v174, v125, v158
	v_add_f32_e32 v124, v120, v161
	v_add_f32_e32 v125, v121, v162
	v_add_f32_e32 v175, v126, v159
	v_add_f32_e32 v176, v127, v160
	v_mul_f32_e32 v120, 0x3c800000, v147
	v_mul_f32_e32 v121, 0x3c800000, v174
	s_lshl_b32 s12, s74, 9
	v_cvt_pk_bf16_f32 v178, v120, v121
	v_mul_f32_e32 v120, 0x3c800000, v175
	v_mul_f32_e32 v121, 0x3c800000, v176
	v_add_f32_e32 v126, v122, v163
	v_add_f32_e32 v127, v123, v164
	s_or_b32 s12, s60, s12
	v_cvt_pk_bf16_f32 v179, v120, v121
	v_mul_f32_e32 v120, 0x3c800000, v124
	v_mul_f32_e32 v121, 0x3c800000, v125
	v_or_b32_e32 v122, s12, v150
	v_cvt_pk_bf16_f32 v180, v120, v121
	v_mul_f32_e32 v120, 0x3c800000, v126
	v_mul_f32_e32 v121, 0x3c800000, v127
	v_cvt_pk_bf16_f32 v181, v120, v121
	v_lshl_add_u64 v[120:121], s[16:17], 0, v[182:183]
	v_lshlrev_b32_e32 v136, 1, v122
	v_cndmask_b32_e32 v156, v154, v155, vcc
	v_cmp_lt_i32_e32 vcc, 0, v146
	v_lshl_add_u64 v[122:123], v[120:121], 0, v[136:137]
	v_lshl_add_u64 v[120:121], s[16:17], 0, v[184:185]
	global_store_dwordx4 v[122:123], v[178:181], off nt
	s_and_saveexec_b64 s[12:13], vcc
	s_cbranch_execz .LBB0_1185
	v_mul_f32_e32 v147, v156, v147
	v_mul_f32_e32 v174, v156, v174
	v_mul_f32_e32 v124, v156, v124
	v_mul_f32_e32 v125, v156, v125
	v_cvt_pk_bf16_f32 v174, v147, v174
	v_mul_f32_e32 v147, v156, v175
	v_mul_f32_e32 v175, v156, v176
	v_cvt_pk_bf16_f32 v176, v124, v125
	v_mul_f32_e32 v124, v156, v126
	v_mul_f32_e32 v125, v156, v127
	v_cvt_pk_bf16_f32 v177, v124, v125
	v_lshl_add_u64 v[124:125], v[120:121], 0, v[136:137]
	v_cvt_pk_bf16_f32 v175, v147, v175
	global_store_dwordx4 v[124:125], v[174:177], off nt
; __device__ __forceinline__ unsigned cvt_pk_bf16(float lo, float hi) { unsigned r; asm("v_cvt_pk_bf16_f32 %0, %1, %2" : "=v"(r) : "v"(lo), "v"(hi)); return r; }
;     __device__ __forceinline__ void operator()(const f32x4 (&acc)[2][2][4][2], const Unit& u, int wr, int wc, int fr, int fq, LAS unsigned char* xs, int wid, int lane) const {
;     ...
; #pragma unroll
;         for (int ai = 0; ai < 2; ++ai)
; #pragma unroll
;             for (int m = 0; m < 4; ++m) {
;                 const int k = k0 + ai * 128 + m * 16 + fr;
; #pragma unroll
;                 for (int bj = 0; bj < 2; ++bj) {
;                     const int col = (2 * u.pn + bj) * 256 + cs * 128 + wc * 32 + 8 * fq;
;                     f32x4 a = acc[ai][bj][m][0], b = acc[ai][bj][m][1];
; #pragma unroll
;                     for (int j = 0; j < 4; ++j) { a[j] += hv[bj][j]; b[j] += hv[bj][4 + j]; }
;                     u32x4 w; w.x = cvt_pk_bf16(a[0] * sc, a[1] * sc); w.y = cvt_pk_bf16(a[2] * sc, a[3] * sc); w.z = cvt_pk_bf16(b[0] * sc, b[1] * sc); w.w = cvt_pk_bf16(b[2] * sc, b[3] * sc);
;                     *(u32x4*)(pq + (tok0 + k) * 1024 + col) = w;
;                     if (k > 0) {
;                         u32x4 w2; w2.x = cvt_pk_bf16(a[0] * scm, a[1] * scm); w2.y = cvt_pk_bf16(a[2] * scm, a[3] * scm); w2.z = cvt_pk_bf16(b[0] * scm, b[1] * scm); w2.w = cvt_pk_bf16(b[2] * scm, b[3] * scm);
;                         *(u32x4*)(pq + (tok0 + S - k) * 1024 + col) = w2;
;                     }
;                 }
.LBB0_1185:
	s_or_b64 exec, exec, s[12:13]
	s_waitcnt vmcnt(8)
	v_lshlrev_b32_e32 v124, 16, v165
	s_waitcnt vmcnt(7)
	v_lshlrev_b32_e32 v125, 16, v166
	v_mul_f32_e32 v124, v173, v124
	v_mul_f32_e32 v125, v173, v125
	s_waitcnt vmcnt(6)
	v_lshlrev_b32_e32 v126, 16, v167
	s_waitcnt vmcnt(5)
	v_lshlrev_b32_e32 v127, 16, v168
	v_cndmask_b32_e64 v124, -v124, v124, s[8:9]
	v_cndmask_b32_e64 v125, -v125, v125, s[8:9]
	v_mul_f32_e32 v126, v173, v126
	v_mul_f32_e32 v127, v173, v127
	s_waitcnt vmcnt(4)
	v_lshlrev_b32_e32 v147, 16, v169
	s_waitcnt vmcnt(3)
	v_lshlrev_b32_e32 v165, 16, v170
	v_cndmask_b32_e64 v126, -v126, v126, s[8:9]
	v_cndmask_b32_e64 v127, -v127, v127, s[8:9]
	v_mul_f32_e32 v147, v173, v147
	v_mul_f32_e32 v165, v173, v165
	s_waitcnt vmcnt(2)
	v_lshlrev_b32_e32 v166, 16, v171
	v_add_f32_e32 v116, v116, v124
	v_add_f32_e32 v117, v117, v125
	v_cndmask_b32_e64 v147, -v147, v147, s[8:9]
	v_cndmask_b32_e64 v165, -v165, v165, s[8:9]
	v_mul_f32_e32 v166, v173, v166
	s_waitcnt vmcnt(1)
	v_lshlrev_b32_e32 v167, 16, v172
	v_add_f32_e32 v118, v118, v126
	v_add_f32_e32 v119, v119, v127
	v_mul_f32_e32 v168, 0x3c800000, v116
	v_mul_f32_e32 v169, 0x3c800000, v117
	v_cndmask_b32_e64 v166, -v166, v166, s[8:9]
	v_mul_f32_e32 v167, v173, v167
	v_add_f32_e32 v112, v112, v147
	v_add_f32_e32 v113, v113, v165
	v_cvt_pk_bf16_f32 v168, v168, v169
	v_mul_f32_e32 v169, 0x3c800000, v118
	v_mul_f32_e32 v170, 0x3c800000, v119
	v_cndmask_b32_e64 v167, -v167, v167, s[8:9]
	v_add_f32_e32 v114, v114, v166
	v_cvt_pk_bf16_f32 v169, v169, v170
	v_mul_f32_e32 v170, 0x3c800000, v112
	v_mul_f32_e32 v171, 0x3c800000, v113
	v_add_f32_e32 v115, v115, v167
	v_cvt_pk_bf16_f32 v170, v170, v171
	v_mul_f32_e32 v171, 0x3c800000, v114
	v_mul_f32_e32 v172, 0x3c800000, v115
	v_cvt_pk_bf16_f32 v171, v171, v172
	global_store_dwordx4 v[122:123], v[168:171], off offset:512 nt
	s_and_saveexec_b64 s[12:13], vcc
	s_cbranch_execz .LBB0_1187
	v_mul_f32_e32 v116, v156, v116
	v_mul_f32_e32 v117, v156, v117
	v_cvt_pk_bf16_f32 v116, v116, v117
	v_mul_f32_e32 v117, v156, v118
	v_mul_f32_e32 v118, v156, v119
	v_mul_f32_e32 v112, v156, v112
	v_mul_f32_e32 v113, v156, v113
	v_cvt_pk_bf16_f32 v117, v117, v118
	v_cvt_pk_bf16_f32 v118, v112, v113
	v_mul_f32_e32 v112, v156, v114
	v_mul_f32_e32 v113, v156, v115
	v_cvt_pk_bf16_f32 v119, v112, v113
	v_lshl_add_u64 v[112:113], v[120:121], 0, v[136:137]
	global_store_dwordx4 v[112:113], v[116:119], off offset:512 nt
.LBB0_1187:
	s_or_b64 exec, exec, s[12:13]
	v_or_b32_e32 v112, 16, v146
	v_ashrrev_i32_e32 v113, 31, v112
	v_lshl_add_u64 v[114:115], s[20:21], 0, v[112:113]
	v_lshlrev_b64 v[120:121], 11, v[114:115]
	v_mov_b32_e32 v114, s62
	v_sub_co_u32_e32 v112, vcc, s57, v112
	v_add_f32_e32 v115, v111, v160
	s_nop 0
	v_subb_co_u32_e32 v113, vcc, v114, v113, vcc
	v_lshlrev_b64 v[122:123], 11, v[112:113]
	v_add_f32_e32 v112, v108, v157
	v_add_f32_e32 v113, v109, v158
	v_add_f32_e32 v108, v104, v161
	v_add_f32_e32 v109, v105, v162
	v_add_f32_e32 v114, v110, v159
	v_mul_f32_e32 v104, 0x3c800000, v112
	v_mul_f32_e32 v105, 0x3c800000, v113
	v_cvt_pk_bf16_f32 v116, v104, v105
	v_mul_f32_e32 v104, 0x3c800000, v114
	v_mul_f32_e32 v105, 0x3c800000, v115
	v_add_f32_e32 v110, v106, v163
	v_add_f32_e32 v111, v107, v164
	v_cvt_pk_bf16_f32 v117, v104, v105
	v_mul_f32_e32 v104, 0x3c800000, v108
	v_mul_f32_e32 v105, 0x3c800000, v109
	v_cvt_pk_bf16_f32 v118, v104, v105
	v_mul_f32_e32 v104, 0x3c800000, v110
	v_mul_f32_e32 v105, 0x3c800000, v111
	s_cmp_gt_i32 s63, -1
	v_cvt_pk_bf16_f32 v119, v104, v105
	v_lshl_add_u64 v[104:105], s[16:17], 0, v[120:121]
	s_cselect_b64 s[60:61], -1, 0
	s_cmp_lt_i32 s63, 0
	v_lshl_add_u64 v[106:107], v[104:105], 0, v[136:137]
	v_lshl_add_u64 v[104:105], s[16:17], 0, v[122:123]
	global_store_dwordx4 v[106:107], v[116:119], off nt
	s_cbranch_scc1 .LBB0_1189
	v_mul_f32_e32 v112, v156, v112
	v_mul_f32_e32 v113, v156, v113
	v_cvt_pk_bf16_f32 v112, v112, v113
	v_mul_f32_e32 v113, v156, v114
	v_mul_f32_e32 v114, v156, v115
	v_mul_f32_e32 v108, v156, v108
	v_mul_f32_e32 v109, v156, v109
	v_cvt_pk_bf16_f32 v113, v113, v114
	v_cvt_pk_bf16_f32 v114, v108, v109
	v_mul_f32_e32 v108, v156, v110
	v_mul_f32_e32 v109, v156, v111
	v_cvt_pk_bf16_f32 v115, v108, v109
	v_lshl_add_u64 v[108:109], v[104:105], 0, v[136:137]
	global_store_dwordx4 v[108:109], v[112:115], off nt
.LBB0_1189:
	v_add_f32_e32 v100, v100, v124
	v_add_f32_e32 v101, v101, v125
	v_add_f32_e32 v102, v102, v126
	v_add_f32_e32 v103, v103, v127
	v_mul_f32_e32 v108, 0x3c800000, v100
	v_mul_f32_e32 v109, 0x3c800000, v101
	v_add_f32_e32 v96, v96, v147
	v_add_f32_e32 v97, v97, v165
	v_cvt_pk_bf16_f32 v108, v108, v109
	v_mul_f32_e32 v109, 0x3c800000, v102
	v_mul_f32_e32 v110, 0x3c800000, v103
	v_add_f32_e32 v98, v98, v166
	v_add_f32_e32 v99, v99, v167
	v_cvt_pk_bf16_f32 v109, v109, v110
	v_mul_f32_e32 v110, 0x3c800000, v96
	v_mul_f32_e32 v111, 0x3c800000, v97
	v_cvt_pk_bf16_f32 v110, v110, v111
	v_mul_f32_e32 v111, 0x3c800000, v98
	v_mul_f32_e32 v112, 0x3c800000, v99
	v_cvt_pk_bf16_f32 v111, v111, v112
	v_cndmask_b32_e64 v112, 0, 1, s[60:61]
	v_cmp_ne_u32_e64 s[12:13], 1, v112
	s_andn2_b64 vcc, exec, s[60:61]
	global_store_dwordx4 v[106:107], v[108:111], off offset:512 nt
	s_cbranch_vccnz .LBB0_1191
	v_mul_f32_e32 v100, v156, v100
	v_mul_f32_e32 v101, v156, v101
	v_cvt_pk_bf16_f32 v100, v100, v101
	v_mul_f32_e32 v101, v156, v102
	v_mul_f32_e32 v102, v156, v103
	v_mul_f32_e32 v96, v156, v96
	v_mul_f32_e32 v97, v156, v97
	v_cvt_pk_bf16_f32 v101, v101, v102
	v_cvt_pk_bf16_f32 v102, v96, v97
	v_mul_f32_e32 v96, v156, v98
	v_mul_f32_e32 v97, v156, v99
	v_cvt_pk_bf16_f32 v103, v96, v97
	v_lshl_add_u64 v[96:97], v[104:105], 0, v[136:137]
	global_store_dwordx4 v[96:97], v[100:103], off offset:512 nt
; __device__ __forceinline__ unsigned cvt_pk_bf16(float lo, float hi) { unsigned r; asm("v_cvt_pk_bf16_f32 %0, %1, %2" : "=v"(r) : "v"(lo), "v"(hi)); return r; }
;     __device__ __forceinline__ void operator()(const f32x4 (&acc)[2][2][4][2], const Unit& u, int wr, int wc, int fr, int fq, LAS unsigned char* xs, int wid, int lane) const {
;     ...
; #pragma unroll
;         for (int ai = 0; ai < 2; ++ai)
; #pragma unroll
;             for (int m = 0; m < 4; ++m) {
;                 const int k = k0 + ai * 128 + m * 16 + fr;
; #pragma unroll
;                 for (int bj = 0; bj < 2; ++bj) {
;                     const int col = (2 * u.pn + bj) * 256 + cs * 128 + wc * 32 + 8 * fq;
;                     f32x4 a = acc[ai][bj][m][0], b = acc[ai][bj][m][1];
; #pragma unroll
;                     for (int j = 0; j < 4; ++j) { a[j] += hv[bj][j]; b[j] += hv[bj][4 + j]; }
;                     u32x4 w; w.x = cvt_pk_bf16(a[0] * sc, a[1] * sc); w.y = cvt_pk_bf16(a[2] * sc, a[3] * sc); w.z = cvt_pk_bf16(b[0] * sc, b[1] * sc); w.w = cvt_pk_bf16(b[2] * sc, b[3] * sc);
;                     *(u32x4*)(pq + (tok0 + k) * 1024 + col) = w;
;                     if (k > 0) {
;                         u32x4 w2; w2.x = cvt_pk_bf16(a[0] * scm, a[1] * scm); w2.y = cvt_pk_bf16(a[2] * scm, a[3] * scm); w2.z = cvt_pk_bf16(b[0] * scm, b[1] * scm); w2.w = cvt_pk_bf16(b[2] * scm, b[3] * scm);
;                         *(u32x4*)(pq + (tok0 + S - k) * 1024 + col) = w2;
;                     }
;                 }
.LBB0_1191:
	v_or_b32_e32 v96, 32, v146
	v_ashrrev_i32_e32 v97, 31, v96
	v_lshl_add_u64 v[98:99], s[20:21], 0, v[96:97]
	v_lshlrev_b64 v[104:105], 11, v[98:99]
	v_mov_b32_e32 v98, s62
	v_sub_co_u32_e32 v96, vcc, s57, v96
	v_add_f32_e32 v99, v95, v160
	s_nop 0
	v_subb_co_u32_e32 v97, vcc, v98, v97, vcc
	v_lshlrev_b64 v[106:107], 11, v[96:97]
	v_add_f32_e32 v96, v92, v157
	v_add_f32_e32 v97, v93, v158
	v_add_f32_e32 v92, v88, v161
	v_add_f32_e32 v93, v89, v162
	v_add_f32_e32 v98, v94, v159
	v_mul_f32_e32 v88, 0x3c800000, v96
	v_mul_f32_e32 v89, 0x3c800000, v97
	v_cvt_pk_bf16_f32 v100, v88, v89
	v_mul_f32_e32 v88, 0x3c800000, v98
	v_mul_f32_e32 v89, 0x3c800000, v99
	v_add_f32_e32 v94, v90, v163
	v_add_f32_e32 v95, v91, v164
	v_cvt_pk_bf16_f32 v101, v88, v89
	v_mul_f32_e32 v88, 0x3c800000, v92
	v_mul_f32_e32 v89, 0x3c800000, v93
	v_cvt_pk_bf16_f32 v102, v88, v89
	v_mul_f32_e32 v88, 0x3c800000, v94
	v_mul_f32_e32 v89, 0x3c800000, v95
	v_cvt_pk_bf16_f32 v103, v88, v89
	v_lshl_add_u64 v[88:89], s[16:17], 0, v[104:105]
	v_lshl_add_u64 v[90:91], v[88:89], 0, v[136:137]
	s_and_b64 vcc, exec, s[12:13]
	v_lshl_add_u64 v[88:89], s[16:17], 0, v[106:107]
	global_store_dwordx4 v[90:91], v[100:103], off nt
	s_cbranch_vccnz .LBB0_1193
	v_mul_f32_e32 v96, v156, v96
	v_mul_f32_e32 v97, v156, v97
	v_cvt_pk_bf16_f32 v96, v96, v97
	v_mul_f32_e32 v97, v156, v98
	v_mul_f32_e32 v98, v156, v99
	v_mul_f32_e32 v92, v156, v92
	v_mul_f32_e32 v93, v156, v93
	v_cvt_pk_bf16_f32 v97, v97, v98
	v_cvt_pk_bf16_f32 v98, v92, v93
	v_mul_f32_e32 v92, v156, v94
	v_mul_f32_e32 v93, v156, v95
	v_cvt_pk_bf16_f32 v99, v92, v93
	v_lshl_add_u64 v[92:93], v[88:89], 0, v[136:137]
	global_store_dwordx4 v[92:93], v[96:99], off nt
.LBB0_1193:
	v_add_f32_e32 v84, v84, v124
	v_add_f32_e32 v85, v85, v125
	v_add_f32_e32 v86, v86, v126
	v_add_f32_e32 v87, v87, v127
	v_mul_f32_e32 v92, 0x3c800000, v84
	v_mul_f32_e32 v93, 0x3c800000, v85
	v_add_f32_e32 v80, v80, v147
	v_add_f32_e32 v81, v81, v165
	v_cvt_pk_bf16_f32 v92, v92, v93
	v_mul_f32_e32 v93, 0x3c800000, v86
	v_mul_f32_e32 v94, 0x3c800000, v87
	v_add_f32_e32 v82, v82, v166
	v_cvt_pk_bf16_f32 v93, v93, v94
	v_mul_f32_e32 v94, 0x3c800000, v80
	v_mul_f32_e32 v95, 0x3c800000, v81
	v_add_f32_e32 v83, v83, v167
	v_cvt_pk_bf16_f32 v94, v94, v95
	v_mul_f32_e32 v95, 0x3c800000, v82
	s_and_b64 vcc, exec, s[12:13]
	v_mul_f32_e32 v96, 0x3c800000, v83
	v_cvt_pk_bf16_f32 v95, v95, v96
	global_store_dwordx4 v[90:91], v[92:95], off offset:512 nt
	s_cbranch_vccnz .LBB0_1195
	v_mul_f32_e32 v84, v156, v84
	v_mul_f32_e32 v85, v156, v85
	v_cvt_pk_bf16_f32 v84, v84, v85
	v_mul_f32_e32 v85, v156, v86
	v_mul_f32_e32 v86, v156, v87
	v_mul_f32_e32 v80, v156, v80
	v_mul_f32_e32 v81, v156, v81
	v_cvt_pk_bf16_f32 v85, v85, v86
	v_cvt_pk_bf16_f32 v86, v80, v81
	v_mul_f32_e32 v80, v156, v82
	v_mul_f32_e32 v81, v156, v83
	v_cvt_pk_bf16_f32 v87, v80, v81
	v_lshl_add_u64 v[80:81], v[88:89], 0, v[136:137]
	global_store_dwordx4 v[80:81], v[84:87], off offset:512 nt
.LBB0_1195:
	v_or_b32_e32 v80, 48, v146
	v_ashrrev_i32_e32 v81, 31, v80
	v_lshl_add_u64 v[82:83], s[20:21], 0, v[80:81]
	v_lshlrev_b64 v[88:89], 11, v[82:83]
	v_mov_b32_e32 v82, s62
	v_sub_co_u32_e32 v80, vcc, s57, v80
	v_add_f32_e32 v83, v79, v160
	s_nop 0
	v_subb_co_u32_e32 v81, vcc, v82, v81, vcc
	v_lshlrev_b64 v[90:91], 11, v[80:81]
	v_add_f32_e32 v80, v76, v157
	v_add_f32_e32 v81, v77, v158
	v_add_f32_e32 v76, v72, v161
	v_add_f32_e32 v77, v73, v162
	v_add_f32_e32 v82, v78, v159
	v_mul_f32_e32 v72, 0x3c800000, v80
	v_mul_f32_e32 v73, 0x3c800000, v81
	v_cvt_pk_bf16_f32 v84, v72, v73
	v_mul_f32_e32 v72, 0x3c800000, v82
	v_mul_f32_e32 v73, 0x3c800000, v83
	v_add_f32_e32 v78, v74, v163
	v_add_f32_e32 v79, v75, v164
	v_cvt_pk_bf16_f32 v85, v72, v73
	v_mul_f32_e32 v72, 0x3c800000, v76
	v_mul_f32_e32 v73, 0x3c800000, v77
	v_cvt_pk_bf16_f32 v86, v72, v73
	v_mul_f32_e32 v72, 0x3c800000, v78
	v_mul_f32_e32 v73, 0x3c800000, v79
	v_cvt_pk_bf16_f32 v87, v72, v73
	v_lshl_add_u64 v[72:73], s[16:17], 0, v[88:89]
	v_lshl_add_u64 v[74:75], v[72:73], 0, v[136:137]
	s_and_b64 vcc, exec, s[12:13]
	v_lshl_add_u64 v[72:73], s[16:17], 0, v[90:91]
	global_store_dwordx4 v[74:75], v[84:87], off nt
	s_cbranch_vccnz .LBB0_1197
	v_mul_f32_e32 v80, v156, v80
	v_mul_f32_e32 v81, v156, v81
	v_cvt_pk_bf16_f32 v80, v80, v81
	v_mul_f32_e32 v81, v156, v82
	v_mul_f32_e32 v82, v156, v83
	v_mul_f32_e32 v76, v156, v76
	v_mul_f32_e32 v77, v156, v77
	v_cvt_pk_bf16_f32 v81, v81, v82
	v_cvt_pk_bf16_f32 v82, v76, v77
	v_mul_f32_e32 v76, v156, v78
	v_mul_f32_e32 v77, v156, v79
	v_cvt_pk_bf16_f32 v83, v76, v77
	v_lshl_add_u64 v[76:77], v[72:73], 0, v[136:137]
	global_store_dwordx4 v[76:77], v[80:83], off nt
.LBB0_1197:
	v_add_f32_e32 v68, v68, v124
	v_add_f32_e32 v69, v69, v125
	v_add_f32_e32 v70, v70, v126
	v_add_f32_e32 v71, v71, v127
	v_mul_f32_e32 v76, 0x3c800000, v68
	v_mul_f32_e32 v77, 0x3c800000, v69
	v_add_f32_e32 v64, v64, v147
	v_add_f32_e32 v65, v65, v165
	v_cvt_pk_bf16_f32 v76, v76, v77
	v_mul_f32_e32 v77, 0x3c800000, v70
	v_mul_f32_e32 v78, 0x3c800000, v71
	v_add_f32_e32 v66, v66, v166
	v_cvt_pk_bf16_f32 v77, v77, v78
	v_mul_f32_e32 v78, 0x3c800000, v64
	v_mul_f32_e32 v79, 0x3c800000, v65
	v_add_f32_e32 v67, v67, v167
	v_cvt_pk_bf16_f32 v78, v78, v79
	v_mul_f32_e32 v79, 0x3c800000, v66
	s_and_b64 vcc, exec, s[12:13]
	v_mul_f32_e32 v80, 0x3c800000, v67
	v_cvt_pk_bf16_f32 v79, v79, v80
	global_store_dwordx4 v[74:75], v[76:79], off offset:512 nt
	s_cbranch_vccnz .LBB0_1199
	v_mul_f32_e32 v68, v156, v68
	v_mul_f32_e32 v69, v156, v69
	v_cvt_pk_bf16_f32 v68, v68, v69
	v_mul_f32_e32 v69, v156, v70
	v_mul_f32_e32 v70, v156, v71
	v_mul_f32_e32 v64, v156, v64
	v_mul_f32_e32 v65, v156, v65
	v_cvt_pk_bf16_f32 v69, v69, v70
	v_cvt_pk_bf16_f32 v70, v64, v65
	v_mul_f32_e32 v64, v156, v66
	v_mul_f32_e32 v65, v156, v67
	v_cvt_pk_bf16_f32 v71, v64, v65
	v_lshl_add_u64 v[64:65], v[72:73], 0, v[136:137]
	global_store_dwordx4 v[64:65], v[68:71], off offset:512 nt
; __device__ __forceinline__ unsigned cvt_pk_bf16(float lo, float hi) { unsigned r; asm("v_cvt_pk_bf16_f32 %0, %1, %2" : "=v"(r) : "v"(lo), "v"(hi)); return r; }
;     __device__ __forceinline__ void operator()(const f32x4 (&acc)[2][2][4][2], const Unit& u, int wr, int wc, int fr, int fq, LAS unsigned char* xs, int wid, int lane) const {
;     ...
; #pragma unroll
;         for (int ai = 0; ai < 2; ++ai)
; #pragma unroll
;             for (int m = 0; m < 4; ++m) {
;                 const int k = k0 + ai * 128 + m * 16 + fr;
; #pragma unroll
;                 for (int bj = 0; bj < 2; ++bj) {
;                     const int col = (2 * u.pn + bj) * 256 + cs * 128 + wc * 32 + 8 * fq;
;                     f32x4 a = acc[ai][bj][m][0], b = acc[ai][bj][m][1];
; #pragma unroll
;                     for (int j = 0; j < 4; ++j) { a[j] += hv[bj][j]; b[j] += hv[bj][4 + j]; }
;                     u32x4 w; w.x = cvt_pk_bf16(a[0] * sc, a[1] * sc); w.y = cvt_pk_bf16(a[2] * sc, a[3] * sc); w.z = cvt_pk_bf16(b[0] * sc, b[1] * sc); w.w = cvt_pk_bf16(b[2] * sc, b[3] * sc);
;                     *(u32x4*)(pq + (tok0 + k) * 1024 + col) = w;
;                     if (k > 0) {
;                         u32x4 w2; w2.x = cvt_pk_bf16(a[0] * scm, a[1] * scm); w2.y = cvt_pk_bf16(a[2] * scm, a[3] * scm); w2.z = cvt_pk_bf16(b[0] * scm, b[1] * scm); w2.w = cvt_pk_bf16(b[2] * scm, b[3] * scm);
;                         *(u32x4*)(pq + (tok0 + S - k) * 1024 + col) = w2;
;                     }
;                 }
.LBB0_1199:
	v_add_u32_e32 v64, 0x80, v146
	v_ashrrev_i32_e32 v65, 31, v64
	v_lshl_add_u64 v[66:67], s[20:21], 0, v[64:65]
	v_lshlrev_b64 v[72:73], 11, v[66:67]
	v_mov_b32_e32 v66, s62
	v_sub_co_u32_e64 v64, s[12:13], s57, v64
	v_add_f32_e32 v67, v63, v160
	s_nop 0
	v_subb_co_u32_e64 v65, s[12:13], v66, v65, s[12:13]
	v_lshlrev_b64 v[74:75], 11, v[64:65]
	v_add_f32_e32 v64, v60, v157
	v_add_f32_e32 v65, v61, v158
	v_add_f32_e32 v60, v56, v161
	v_add_f32_e32 v61, v57, v162
	v_add_f32_e32 v66, v62, v159
	v_mul_f32_e32 v56, 0x3c800000, v64
	v_mul_f32_e32 v57, 0x3c800000, v65
	v_cvt_pk_bf16_f32 v68, v56, v57
	v_mul_f32_e32 v56, 0x3c800000, v66
	v_mul_f32_e32 v57, 0x3c800000, v67
	v_add_f32_e32 v62, v58, v163
	v_add_f32_e32 v63, v59, v164
	v_cvt_pk_bf16_f32 v69, v56, v57
	v_mul_f32_e32 v56, 0x3c800000, v60
	v_mul_f32_e32 v57, 0x3c800000, v61
	v_cvt_pk_bf16_f32 v70, v56, v57
	v_mul_f32_e32 v56, 0x3c800000, v62
	v_mul_f32_e32 v57, 0x3c800000, v63
	v_cvt_pk_bf16_f32 v71, v56, v57
	v_lshl_add_u64 v[56:57], s[16:17], 0, v[72:73]
	v_cmp_lt_i32_e32 vcc, s70, v146
	v_lshl_add_u64 v[58:59], v[56:57], 0, v[136:137]
	v_lshl_add_u64 v[56:57], s[16:17], 0, v[74:75]
	global_store_dwordx4 v[58:59], v[68:71], off nt
	s_and_saveexec_b64 s[12:13], vcc
	s_cbranch_execz .LBB0_1201
	v_mul_f32_e32 v64, v156, v64
	v_mul_f32_e32 v65, v156, v65
	v_cvt_pk_bf16_f32 v64, v64, v65
	v_mul_f32_e32 v65, v156, v66
	v_mul_f32_e32 v66, v156, v67
	v_mul_f32_e32 v60, v156, v60
	v_mul_f32_e32 v61, v156, v61
	v_cvt_pk_bf16_f32 v65, v65, v66
	v_cvt_pk_bf16_f32 v66, v60, v61
	v_mul_f32_e32 v60, v156, v62
	v_mul_f32_e32 v61, v156, v63
	v_cvt_pk_bf16_f32 v67, v60, v61
	v_lshl_add_u64 v[60:61], v[56:57], 0, v[136:137]
	global_store_dwordx4 v[60:61], v[64:67], off nt
.LBB0_1201:
	s_or_b64 exec, exec, s[12:13]
	v_add_f32_e32 v52, v52, v124
	v_add_f32_e32 v53, v53, v125
	v_add_f32_e32 v54, v54, v126
	v_add_f32_e32 v55, v55, v127
	v_mul_f32_e32 v60, 0x3c800000, v52
	v_mul_f32_e32 v61, 0x3c800000, v53
	v_add_f32_e32 v48, v48, v147
	v_add_f32_e32 v49, v49, v165
	v_cvt_pk_bf16_f32 v60, v60, v61
	v_mul_f32_e32 v61, 0x3c800000, v54
	v_mul_f32_e32 v62, 0x3c800000, v55
	v_add_f32_e32 v50, v50, v166
	v_cvt_pk_bf16_f32 v61, v61, v62
	v_mul_f32_e32 v62, 0x3c800000, v48
	v_mul_f32_e32 v63, 0x3c800000, v49
	v_add_f32_e32 v51, v51, v167
	v_cvt_pk_bf16_f32 v62, v62, v63
	v_mul_f32_e32 v63, 0x3c800000, v50
	v_mul_f32_e32 v64, 0x3c800000, v51
	v_cvt_pk_bf16_f32 v63, v63, v64
	global_store_dwordx4 v[58:59], v[60:63], off offset:512 nt
	s_and_saveexec_b64 s[12:13], vcc
	s_cbranch_execz .LBB0_1203
	v_mul_f32_e32 v52, v156, v52
	v_mul_f32_e32 v53, v156, v53
	v_cvt_pk_bf16_f32 v52, v52, v53
	v_mul_f32_e32 v53, v156, v54
	v_mul_f32_e32 v54, v156, v55
	v_mul_f32_e32 v48, v156, v48
	v_mul_f32_e32 v49, v156, v49
	v_cvt_pk_bf16_f32 v53, v53, v54
	v_cvt_pk_bf16_f32 v54, v48, v49
	v_mul_f32_e32 v48, v156, v50
	v_mul_f32_e32 v49, v156, v51
	v_cvt_pk_bf16_f32 v55, v48, v49
	v_lshl_add_u64 v[48:49], v[56:57], 0, v[136:137]
	global_store_dwordx4 v[48:49], v[52:55], off offset:512 nt
.LBB0_1203:
	s_or_b64 exec, exec, s[12:13]
	v_add_u32_e32 v48, 0x90, v146
	v_ashrrev_i32_e32 v49, 31, v48
	v_lshl_add_u64 v[50:51], s[20:21], 0, v[48:49]
	v_lshlrev_b64 v[56:57], 11, v[50:51]
	v_mov_b32_e32 v50, s62
	v_sub_co_u32_e64 v48, s[12:13], s57, v48
	v_add_f32_e32 v51, v47, v160
	s_nop 0
	v_subb_co_u32_e64 v49, s[12:13], v50, v49, s[12:13]
	v_lshlrev_b64 v[58:59], 11, v[48:49]
	v_add_f32_e32 v48, v44, v157
	v_add_f32_e32 v49, v45, v158
	v_add_f32_e32 v44, v40, v161
	v_add_f32_e32 v45, v41, v162
	v_add_f32_e32 v50, v46, v159
	v_mul_f32_e32 v40, 0x3c800000, v48
	v_mul_f32_e32 v41, 0x3c800000, v49
	v_cvt_pk_bf16_f32 v52, v40, v41
	v_mul_f32_e32 v40, 0x3c800000, v50
	v_mul_f32_e32 v41, 0x3c800000, v51
	v_add_f32_e32 v46, v42, v163
	v_add_f32_e32 v47, v43, v164
	v_cvt_pk_bf16_f32 v53, v40, v41
	v_mul_f32_e32 v40, 0x3c800000, v44
	v_mul_f32_e32 v41, 0x3c800000, v45
	v_cvt_pk_bf16_f32 v54, v40, v41
	v_mul_f32_e32 v40, 0x3c800000, v46
	v_mul_f32_e32 v41, 0x3c800000, v47
	v_cvt_pk_bf16_f32 v55, v40, v41
	v_lshl_add_u64 v[40:41], s[16:17], 0, v[56:57]
	v_cmp_lt_i32_e32 vcc, s71, v146
	v_lshl_add_u64 v[42:43], v[40:41], 0, v[136:137]
	v_lshl_add_u64 v[40:41], s[16:17], 0, v[58:59]
	global_store_dwordx4 v[42:43], v[52:55], off nt
	s_and_saveexec_b64 s[12:13], vcc
	s_cbranch_execz .LBB0_1205
	v_mul_f32_e32 v48, v156, v48
	v_mul_f32_e32 v49, v156, v49
	v_cvt_pk_bf16_f32 v48, v48, v49
	v_mul_f32_e32 v49, v156, v50
	v_mul_f32_e32 v50, v156, v51
	v_mul_f32_e32 v44, v156, v44
	v_mul_f32_e32 v45, v156, v45
	v_cvt_pk_bf16_f32 v49, v49, v50
	v_cvt_pk_bf16_f32 v50, v44, v45
	v_mul_f32_e32 v44, v156, v46
	v_mul_f32_e32 v45, v156, v47
	v_cvt_pk_bf16_f32 v51, v44, v45
	v_lshl_add_u64 v[44:45], v[40:41], 0, v[136:137]
	global_store_dwordx4 v[44:45], v[48:51], off nt
.LBB0_1205:
	s_or_b64 exec, exec, s[12:13]
	v_add_f32_e32 v36, v36, v124
	v_add_f32_e32 v37, v37, v125
	v_add_f32_e32 v38, v38, v126
	v_add_f32_e32 v39, v39, v127
	v_mul_f32_e32 v44, 0x3c800000, v36
	v_mul_f32_e32 v45, 0x3c800000, v37
	v_add_f32_e32 v32, v32, v147
	v_add_f32_e32 v33, v33, v165
	v_cvt_pk_bf16_f32 v44, v44, v45
	v_mul_f32_e32 v45, 0x3c800000, v38
	v_mul_f32_e32 v46, 0x3c800000, v39
	v_add_f32_e32 v34, v34, v166
	v_cvt_pk_bf16_f32 v45, v45, v46
	v_mul_f32_e32 v46, 0x3c800000, v32
	v_mul_f32_e32 v47, 0x3c800000, v33
	v_add_f32_e32 v35, v35, v167
	v_cvt_pk_bf16_f32 v46, v46, v47
	v_mul_f32_e32 v47, 0x3c800000, v34
	v_mul_f32_e32 v48, 0x3c800000, v35
	v_cvt_pk_bf16_f32 v47, v47, v48
	global_store_dwordx4 v[42:43], v[44:47], off offset:512 nt
	s_and_saveexec_b64 s[12:13], vcc
	s_cbranch_execz .LBB0_1207
	v_mul_f32_e32 v36, v156, v36
	v_mul_f32_e32 v37, v156, v37
	v_cvt_pk_bf16_f32 v36, v36, v37
	v_mul_f32_e32 v37, v156, v38
	v_mul_f32_e32 v38, v156, v39
	v_mul_f32_e32 v32, v156, v32
	v_mul_f32_e32 v33, v156, v33
	v_cvt_pk_bf16_f32 v37, v37, v38
	v_cvt_pk_bf16_f32 v38, v32, v33
	v_mul_f32_e32 v32, v156, v34
	v_mul_f32_e32 v33, v156, v35
	v_cvt_pk_bf16_f32 v39, v32, v33
	v_lshl_add_u64 v[32:33], v[40:41], 0, v[136:137]
	global_store_dwordx4 v[32:33], v[36:39], off offset:512 nt
; __device__ __forceinline__ unsigned cvt_pk_bf16(float lo, float hi) { unsigned r; asm("v_cvt_pk_bf16_f32 %0, %1, %2" : "=v"(r) : "v"(lo), "v"(hi)); return r; }
;     __device__ __forceinline__ void operator()(const f32x4 (&acc)[2][2][4][2], const Unit& u, int wr, int wc, int fr, int fq, LAS unsigned char* xs, int wid, int lane) const {
;     ...
; #pragma unroll
;         for (int ai = 0; ai < 2; ++ai)
; #pragma unroll
;             for (int m = 0; m < 4; ++m) {
;                 const int k = k0 + ai * 128 + m * 16 + fr;
; #pragma unroll
;                 for (int bj = 0; bj < 2; ++bj) {
;                     const int col = (2 * u.pn + bj) * 256 + cs * 128 + wc * 32 + 8 * fq;
;                     f32x4 a = acc[ai][bj][m][0], b = acc[ai][bj][m][1];
; #pragma unroll
;                     for (int j = 0; j < 4; ++j) { a[j] += hv[bj][j]; b[j] += hv[bj][4 + j]; }
;                     u32x4 w; w.x = cvt_pk_bf16(a[0] * sc, a[1] * sc); w.y = cvt_pk_bf16(a[2] * sc, a[3] * sc); w.z = cvt_pk_bf16(b[0] * sc, b[1] * sc); w.w = cvt_pk_bf16(b[2] * sc, b[3] * sc);
;                     *(u32x4*)(pq + (tok0 + k) * 1024 + col) = w;
;                     if (k > 0) {
;                         u32x4 w2; w2.x = cvt_pk_bf16(a[0] * scm, a[1] * scm); w2.y = cvt_pk_bf16(a[2] * scm, a[3] * scm); w2.z = cvt_pk_bf16(b[0] * scm, b[1] * scm); w2.w = cvt_pk_bf16(b[2] * scm, b[3] * scm);
;                         *(u32x4*)(pq + (tok0 + S - k) * 1024 + col) = w2;
;                     }
;                 }
.LBB0_1207:
	s_or_b64 exec, exec, s[12:13]
	v_add_u32_e32 v32, 0xa0, v146
	v_ashrrev_i32_e32 v33, 31, v32
	v_lshl_add_u64 v[34:35], s[20:21], 0, v[32:33]
	v_lshlrev_b64 v[40:41], 11, v[34:35]
	v_mov_b32_e32 v34, s62
	v_sub_co_u32_e64 v32, s[12:13], s57, v32
	v_add_f32_e32 v35, v31, v160
	s_nop 0
	v_subb_co_u32_e64 v33, s[12:13], v34, v33, s[12:13]
	v_lshlrev_b64 v[42:43], 11, v[32:33]
	v_add_f32_e32 v32, v28, v157
	v_add_f32_e32 v33, v29, v158
	v_add_f32_e32 v28, v24, v161
	v_add_f32_e32 v29, v25, v162
	v_add_f32_e32 v34, v30, v159
	v_mul_f32_e32 v24, 0x3c800000, v32
	v_mul_f32_e32 v25, 0x3c800000, v33
	v_cvt_pk_bf16_f32 v36, v24, v25
	v_mul_f32_e32 v24, 0x3c800000, v34
	v_mul_f32_e32 v25, 0x3c800000, v35
	v_add_f32_e32 v30, v26, v163
	v_add_f32_e32 v31, v27, v164
	v_cvt_pk_bf16_f32 v37, v24, v25
	v_mul_f32_e32 v24, 0x3c800000, v28
	v_mul_f32_e32 v25, 0x3c800000, v29
	v_cvt_pk_bf16_f32 v38, v24, v25
	v_mul_f32_e32 v24, 0x3c800000, v30
	v_mul_f32_e32 v25, 0x3c800000, v31
	v_cvt_pk_bf16_f32 v39, v24, v25
	v_lshl_add_u64 v[24:25], s[16:17], 0, v[40:41]
	v_cmp_lt_i32_e32 vcc, s72, v146
	v_lshl_add_u64 v[26:27], v[24:25], 0, v[136:137]
	v_lshl_add_u64 v[24:25], s[16:17], 0, v[42:43]
	global_store_dwordx4 v[26:27], v[36:39], off nt
	s_and_saveexec_b64 s[12:13], vcc
	s_cbranch_execz .LBB0_1209
	v_mul_f32_e32 v32, v156, v32
	v_mul_f32_e32 v33, v156, v33
	v_cvt_pk_bf16_f32 v32, v32, v33
	v_mul_f32_e32 v33, v156, v34
	v_mul_f32_e32 v34, v156, v35
	v_mul_f32_e32 v28, v156, v28
	v_mul_f32_e32 v29, v156, v29
	v_cvt_pk_bf16_f32 v33, v33, v34
	v_cvt_pk_bf16_f32 v34, v28, v29
	v_mul_f32_e32 v28, v156, v30
	v_mul_f32_e32 v29, v156, v31
	v_cvt_pk_bf16_f32 v35, v28, v29
	v_lshl_add_u64 v[28:29], v[24:25], 0, v[136:137]
	global_store_dwordx4 v[28:29], v[32:35], off nt
.LBB0_1209:
	s_or_b64 exec, exec, s[12:13]
	v_add_f32_e32 v20, v20, v124
	v_add_f32_e32 v21, v21, v125
	v_add_f32_e32 v22, v22, v126
	v_add_f32_e32 v23, v23, v127
	v_mul_f32_e32 v28, 0x3c800000, v20
	v_mul_f32_e32 v29, 0x3c800000, v21
	v_add_f32_e32 v16, v16, v147
	v_add_f32_e32 v17, v17, v165
	v_cvt_pk_bf16_f32 v28, v28, v29
	v_mul_f32_e32 v29, 0x3c800000, v22
	v_mul_f32_e32 v30, 0x3c800000, v23
	v_add_f32_e32 v18, v18, v166
	v_cvt_pk_bf16_f32 v29, v29, v30
	v_mul_f32_e32 v30, 0x3c800000, v16
	v_mul_f32_e32 v31, 0x3c800000, v17
	v_add_f32_e32 v19, v19, v167
	v_cvt_pk_bf16_f32 v30, v30, v31
	v_mul_f32_e32 v31, 0x3c800000, v18
	v_mul_f32_e32 v32, 0x3c800000, v19
	v_cvt_pk_bf16_f32 v31, v31, v32
	global_store_dwordx4 v[26:27], v[28:31], off offset:512 nt
	s_and_saveexec_b64 s[12:13], vcc
	s_cbranch_execz .LBB0_1211
	v_mul_f32_e32 v20, v156, v20
	v_mul_f32_e32 v21, v156, v21
	v_cvt_pk_bf16_f32 v20, v20, v21
	v_mul_f32_e32 v21, v156, v22
	v_mul_f32_e32 v22, v156, v23
	v_mul_f32_e32 v16, v156, v16
	v_mul_f32_e32 v17, v156, v17
	v_cvt_pk_bf16_f32 v21, v21, v22
	v_cvt_pk_bf16_f32 v22, v16, v17
	v_mul_f32_e32 v16, v156, v18
	v_mul_f32_e32 v17, v156, v19
	v_cvt_pk_bf16_f32 v23, v16, v17
	v_lshl_add_u64 v[16:17], v[24:25], 0, v[136:137]
	global_store_dwordx4 v[16:17], v[20:23], off offset:512 nt
.LBB0_1211:
	s_or_b64 exec, exec, s[12:13]
	v_add_u32_e32 v16, 0xb0, v146
	v_ashrrev_i32_e32 v17, 31, v16
	v_lshl_add_u64 v[18:19], s[20:21], 0, v[16:17]
	v_lshlrev_b64 v[24:25], 11, v[18:19]
	v_mov_b32_e32 v18, s62
	v_sub_co_u32_e64 v16, s[12:13], s57, v16
	v_add_f32_e32 v19, v15, v160
	s_nop 0
	v_subb_co_u32_e64 v17, s[12:13], v18, v17, s[12:13]
	v_lshlrev_b64 v[26:27], 11, v[16:17]
	v_add_f32_e32 v16, v12, v157
	v_add_f32_e32 v17, v13, v158
	v_add_f32_e32 v12, v8, v161
	v_add_f32_e32 v13, v9, v162
	v_add_f32_e32 v18, v14, v159
	v_mul_f32_e32 v8, 0x3c800000, v16
	v_mul_f32_e32 v9, 0x3c800000, v17
	v_cvt_pk_bf16_f32 v20, v8, v9
	v_mul_f32_e32 v8, 0x3c800000, v18
	v_mul_f32_e32 v9, 0x3c800000, v19
	v_add_f32_e32 v14, v10, v163
	v_add_f32_e32 v15, v11, v164
	v_cvt_pk_bf16_f32 v21, v8, v9
	v_mul_f32_e32 v8, 0x3c800000, v12
	v_mul_f32_e32 v9, 0x3c800000, v13
	v_cvt_pk_bf16_f32 v22, v8, v9
	v_mul_f32_e32 v8, 0x3c800000, v14
	v_mul_f32_e32 v9, 0x3c800000, v15
	v_cvt_pk_bf16_f32 v23, v8, v9
	v_lshl_add_u64 v[8:9], s[16:17], 0, v[24:25]
	v_cmp_lt_i32_e32 vcc, s73, v146
	v_lshl_add_u64 v[10:11], v[8:9], 0, v[136:137]
	v_lshl_add_u64 v[8:9], s[16:17], 0, v[26:27]
	global_store_dwordx4 v[10:11], v[20:23], off nt
	s_and_saveexec_b64 s[12:13], vcc
	s_cbranch_execz .LBB0_1213
	v_mul_f32_e32 v16, v156, v16
	v_mul_f32_e32 v17, v156, v17
	v_cvt_pk_bf16_f32 v16, v16, v17
	v_mul_f32_e32 v17, v156, v18
	v_mul_f32_e32 v18, v156, v19
	v_mul_f32_e32 v12, v156, v12
	v_mul_f32_e32 v13, v156, v13
	v_cvt_pk_bf16_f32 v17, v17, v18
	v_cvt_pk_bf16_f32 v18, v12, v13
	v_mul_f32_e32 v12, v156, v14
	v_mul_f32_e32 v13, v156, v15
	v_cvt_pk_bf16_f32 v19, v12, v13
	v_lshl_add_u64 v[12:13], v[8:9], 0, v[136:137]
	global_store_dwordx4 v[12:13], v[16:19], off nt
.LBB0_1213:
	s_or_b64 exec, exec, s[12:13]
	v_add_f32_e32 v4, v4, v124
	v_add_f32_e32 v5, v5, v125
	v_add_f32_e32 v6, v6, v126
	v_add_f32_e32 v7, v7, v127
	v_mul_f32_e32 v12, 0x3c800000, v4
	v_mul_f32_e32 v13, 0x3c800000, v5
	v_add_f32_e32 v0, v0, v147
	v_add_f32_e32 v1, v1, v165
	v_cvt_pk_bf16_f32 v12, v12, v13
	v_mul_f32_e32 v13, 0x3c800000, v6
	v_mul_f32_e32 v14, 0x3c800000, v7
	v_add_f32_e32 v2, v2, v166
	v_cvt_pk_bf16_f32 v13, v13, v14
	v_mul_f32_e32 v14, 0x3c800000, v0
	v_mul_f32_e32 v15, 0x3c800000, v1
	v_add_f32_e32 v3, v3, v167
	v_cvt_pk_bf16_f32 v14, v14, v15
	v_mul_f32_e32 v15, 0x3c800000, v2
	v_mul_f32_e32 v16, 0x3c800000, v3
	v_cvt_pk_bf16_f32 v15, v15, v16
	global_store_dwordx4 v[10:11], v[12:15], off offset:512 nt
	s_and_saveexec_b64 s[12:13], vcc
	s_cbranch_execz .LBB0_1215
	v_mul_f32_e32 v4, v156, v4
	v_mul_f32_e32 v5, v156, v5
	v_cvt_pk_bf16_f32 v4, v4, v5
	v_mul_f32_e32 v5, v156, v6
	v_mul_f32_e32 v6, v156, v7
	v_mul_f32_e32 v0, v156, v0
	v_mul_f32_e32 v1, v156, v1
	v_cvt_pk_bf16_f32 v5, v5, v6
	v_cvt_pk_bf16_f32 v6, v0, v1
	v_mul_f32_e32 v0, v156, v2
	v_mul_f32_e32 v1, v156, v3
	v_cvt_pk_bf16_f32 v7, v0, v1
	v_lshl_add_u64 v[0:1], v[8:9], 0, v[136:137]
	global_store_dwordx4 v[0:1], v[4:7], off offset:512 nt

; #define LAS __attribute__((address_space(3)))
; __device__ __forceinline__ unsigned cvt_pk_bf16(float lo, float hi) { unsigned r; asm("v_cvt_pk_bf16_f32 %0, %1, %2" : "=v"(r) : "v"(lo), "v"(hi)); return r; }
;     __device__ __forceinline__ void operator()(const f32x4 (&acc)[2][2][4][2], const Unit& u, int wr, int wc, int fr, int fq, LAS unsigned char* xs, int wid, int lane) const {
;         const int S = lng ? 4096 : 2048, hp = lng ? 8 : 4;
;         const int cs = u.pm >= hp, k0 = (u.pm - hp * cs) * 256 + wr * 64;
;         const size_t tok0 = lng ? (size_t)TP + (size_t)u.aux * 4096 : (size_t)u.aux * 2048;
;         const float sc = lng ? 0.015625f : 0.02209708691207961f;
;         const float scm = cs ? -sc : sc;
;         float hv[2][8];
;         const float csm = cs ? 0.f : 1.f;
; #pragma unroll
;         for (int bj = 0; bj < 2; ++bj)
; #pragma unroll
;             for (int e = 0; e < 8; ++e) {
;                 const unsigned short h = ft[(size_t)(u.pn * 256 + bj * 128 + wc * 32 + 8 * fq + e) * T + tok0 + S / 2];
;                 const float v = __builtin_bit_cast(float, (unsigned)h << 16) * csm;
;                 hv[bj][e] = (fr & 1) ? -v : v;
;             }
; #pragma unroll
;         for (int ai = 0; ai < 2; ++ai)
; #pragma unroll
;             for (int m = 0; m < 4; ++m) {
;                 const int k = k0 + ai * 128 + m * 16 + fr;
; #pragma unroll
;                 for (int bj = 0; bj < 2; ++bj) {
;                     const int col = (2 * u.pn + bj) * 256 + cs * 128 + wc * 32 + 8 * fq;
;                     f32x4 a = acc[ai][bj][m][0], b = acc[ai][bj][m][1];
; #pragma unroll
;                     for (int j = 0; j < 4; ++j) { a[j] += hv[bj][j]; b[j] += hv[bj][4 + j]; }
;                     u32x4 w; w.x = cvt_pk_bf16(a[0] * sc, a[1] * sc); w.y = cvt_pk_bf16(a[2] * sc, a[3] * sc); w.z = cvt_pk_bf16(b[0] * sc, b[1] * sc); w.w = cvt_pk_bf16(b[2] * sc, b[3] * sc);
;                     *(u32x4*)(pq + (tok0 + k) * 1024 + col) = w;
;                     if (k > 0) {
;                         u32x4 w2; w2.x = cvt_pk_bf16(a[0] * scm, a[1] * scm); w2.y = cvt_pk_bf16(a[2] * scm, a[3] * scm); w2.z = cvt_pk_bf16(b[0] * scm, b[1] * scm); w2.w = cvt_pk_bf16(b[2] * scm, b[3] * scm);
;                         *(u32x4*)(pq + (tok0 + S - k) * 1024 + col) = w2;
.LBB0_1233:
	s_lshl_b32 s12, s87, 8
	s_and_b32 s57, s12, 0x300
	s_ashr_i32 s23, s22, 31
	s_add_i32 s57, s57, s35
	s_lshl_b64 s[54:55], s[22:23], 11
	s_lshl_b64 s[12:13], s[22:23], 12
	s_add_u32 s12, s46, s12
	v_lshlrev_b32_e32 v136, 16, v150
	s_addc_u32 s13, s47, s13
	v_lshl_or_b32 v136, s86, 24, v136
	v_lshl_add_u64 v[146:147], s[12:13], 0, v[136:137]
	global_load_ushort v136, v136, s[12:13] offset:2048
	s_mov_b32 s12, 0x10000
	v_add_co_u32_e32 v156, vcc, s12, v146
	s_mov_b32 s12, 0x800000
	s_nop 0
	v_addc_co_u32_e32 v157, vcc, 0, v147, vcc
	v_add_co_u32_e32 v158, vcc, s61, v146
	s_cmp_lt_u32 s87, 4
	s_nop 0
	v_addc_co_u32_e32 v159, vcc, 0, v147, vcc
	v_add_co_u32_e32 v160, vcc, s62, v146
	s_waitcnt vmcnt(0)
	v_lshlrev_b32_e32 v136, 16, v136
	v_addc_co_u32_e32 v161, vcc, 0, v147, vcc
	v_add_co_u32_e32 v162, vcc, s63, v146
	s_nop 1
	v_addc_co_u32_e32 v163, vcc, 0, v147, vcc
	global_load_ushort v164, v[156:157], off offset:2048
	global_load_ushort v176, v[158:159], off offset:2048
	global_load_ushort v177, v[160:161], off offset:2048
	global_load_ushort v178, v[162:163], off offset:2048
	v_add_co_u32_e32 v156, vcc, s64, v146
	s_nop 1
	v_addc_co_u32_e32 v157, vcc, 0, v147, vcc
	v_add_co_u32_e32 v158, vcc, s65, v146
	s_nop 1
	v_addc_co_u32_e32 v159, vcc, 0, v147, vcc
	global_load_ushort v179, v[156:157], off offset:2048
	global_load_ushort v180, v[158:159], off offset:2048
	v_add_co_u32_e32 v156, vcc, s66, v146
	s_nop 1
	v_addc_co_u32_e32 v157, vcc, 0, v147, vcc
	global_load_ushort v181, v[156:157], off offset:2048
	v_add_co_u32_e32 v156, vcc, s12, v146
	s_nop 1
	v_addc_co_u32_e32 v157, vcc, 0, v147, vcc
	global_load_ushort v165, v[156:157], off offset:2048
	v_add_co_u32_e32 v156, vcc, s67, v146
	s_nop 1
	v_addc_co_u32_e32 v157, vcc, 0, v147, vcc
	v_add_co_u32_e32 v158, vcc, s68, v146
	s_nop 1
	v_addc_co_u32_e32 v159, vcc, 0, v147, vcc
	v_add_co_u32_e32 v160, vcc, s69, v146
	s_nop 1
	v_addc_co_u32_e32 v161, vcc, 0, v147, vcc
	v_add_co_u32_e32 v162, vcc, s70, v146
	s_nop 1
	v_addc_co_u32_e32 v163, vcc, 0, v147, vcc
	v_add_co_u32_e32 v166, vcc, s71, v146
	s_nop 1
	v_addc_co_u32_e32 v167, vcc, 0, v147, vcc
	v_add_co_u32_e32 v174, vcc, s72, v146
	s_nop 1
	v_addc_co_u32_e32 v175, vcc, 0, v147, vcc
	v_add_co_u32_e32 v146, vcc, s73, v146
	s_nop 1
	v_addc_co_u32_e32 v147, vcc, 0, v147, vcc
	global_load_ushort v173, v[156:157], off offset:2048
	global_load_ushort v172, v[158:159], off offset:2048
	global_load_ushort v171, v[160:161], off offset:2048
	global_load_ushort v170, v[162:163], off offset:2048
	global_load_ushort v168, v[166:167], off offset:2048
	s_nop 0
	global_load_ushort v166, v[174:175], off offset:2048
	global_load_ushort v167, v[146:147], off offset:2048
	s_cselect_b64 vcc, -1, 0
	v_cndmask_b32_e64 v169, 0, 1.0, vcc
	v_mul_f32_e32 v136, v169, v136
	v_cndmask_b32_e64 v157, -v136, v136, s[8:9]
	v_or_b32_e32 v146, s57, v148
	s_and_b64 s[12:13], vcc, exec
	s_cselect_b32 s22, 0, 0x80
	s_add_u32 s51, s54, 0x800
	v_ashrrev_i32_e32 v147, 31, v146
	s_addc_u32 s56, s55, 0
	v_lshl_add_u64 v[174:175], s[54:55], 0, v[146:147]
	v_lshlrev_b64 v[182:183], 11, v[174:175]
	v_sub_co_u32_e64 v174, s[12:13], s51, v146
	v_cndmask_b32_e32 v156, v154, v155, vcc
	v_cmp_lt_i32_e32 vcc, 0, v146
	s_waitcnt vmcnt(14)
	v_lshlrev_b32_e32 v136, 16, v164
	v_mul_f32_e32 v136, v169, v136
	v_cndmask_b32_e64 v158, -v136, v136, s[8:9]
	s_waitcnt vmcnt(13)
	v_lshlrev_b32_e32 v136, 16, v176
	v_mul_f32_e32 v136, v169, v136
	v_cndmask_b32_e64 v159, -v136, v136, s[8:9]
	s_waitcnt vmcnt(12)
	v_lshlrev_b32_e32 v136, 16, v177
	v_mul_f32_e32 v136, v169, v136
	v_cndmask_b32_e64 v160, -v136, v136, s[8:9]
	s_waitcnt vmcnt(11)
	v_lshlrev_b32_e32 v136, 16, v178
	v_mul_f32_e32 v136, v169, v136
	v_cndmask_b32_e64 v161, -v136, v136, s[8:9]
	v_add_f32_e32 v176, v127, v160
	s_waitcnt vmcnt(10)
	v_lshlrev_b32_e32 v136, 16, v179
	v_mul_f32_e32 v136, v169, v136
	v_cndmask_b32_e64 v162, -v136, v136, s[8:9]
	s_waitcnt vmcnt(9)
	v_lshlrev_b32_e32 v136, 16, v180
	v_mul_f32_e32 v136, v169, v136
	v_cndmask_b32_e64 v163, -v136, v136, s[8:9]
	s_waitcnt vmcnt(8)
	v_lshlrev_b32_e32 v136, 16, v181
	v_mul_f32_e32 v136, v169, v136
	v_cndmask_b32_e64 v164, -v136, v136, s[8:9]
	v_mov_b32_e32 v136, s56
	v_subb_co_u32_e64 v175, s[12:13], v136, v147, s[12:13]
	v_lshlrev_b64 v[184:185], 11, v[174:175]
	v_add_f32_e32 v147, v124, v157
	v_add_f32_e32 v174, v125, v158
	v_add_f32_e32 v124, v120, v161
	v_add_f32_e32 v125, v121, v162
	v_add_f32_e32 v175, v126, v159
	v_mul_f32_e32 v120, 0x3cb504f3, v147
	v_mul_f32_e32 v121, 0x3cb504f3, v174
	s_lshl_b32 s12, s86, 9
	v_cvt_pk_bf16_f32 v178, v120, v121
	v_mul_f32_e32 v120, 0x3cb504f3, v175
	v_mul_f32_e32 v121, 0x3cb504f3, v176
	v_add_f32_e32 v126, v122, v163
	v_add_f32_e32 v127, v123, v164
	s_or_b32 s12, s22, s12
	v_cvt_pk_bf16_f32 v179, v120, v121
	v_mul_f32_e32 v120, 0x3cb504f3, v124
	v_mul_f32_e32 v121, 0x3cb504f3, v125
	v_or_b32_e32 v122, s12, v150
	v_cvt_pk_bf16_f32 v180, v120, v121
	v_mul_f32_e32 v120, 0x3cb504f3, v126
	v_mul_f32_e32 v121, 0x3cb504f3, v127
	v_cvt_pk_bf16_f32 v181, v120, v121
	v_lshl_add_u64 v[120:121], s[16:17], 0, v[182:183]
	v_lshlrev_b32_e32 v136, 1, v122
	v_lshl_add_u64 v[122:123], v[120:121], 0, v[136:137]
	v_lshl_add_u64 v[120:121], s[16:17], 0, v[184:185]
	global_store_dwordx4 v[122:123], v[178:181], off nt
	s_and_saveexec_b64 s[12:13], vcc
	s_cbranch_execz .LBB0_1235
	v_mul_f32_e32 v147, v156, v147
	v_mul_f32_e32 v174, v156, v174
	v_mul_f32_e32 v124, v156, v124
	v_mul_f32_e32 v125, v156, v125
	v_cvt_pk_bf16_f32 v174, v147, v174
	v_mul_f32_e32 v147, v156, v175
	v_mul_f32_e32 v175, v156, v176
	v_cvt_pk_bf16_f32 v176, v124, v125
	v_mul_f32_e32 v124, v156, v126
	v_mul_f32_e32 v125, v156, v127
	v_cvt_pk_bf16_f32 v177, v124, v125
	v_lshl_add_u64 v[124:125], v[120:121], 0, v[136:137]
	v_cvt_pk_bf16_f32 v175, v147, v175
	global_store_dwordx4 v[124:125], v[174:177], off nt
; __device__ __forceinline__ unsigned cvt_pk_bf16(float lo, float hi) { unsigned r; asm("v_cvt_pk_bf16_f32 %0, %1, %2" : "=v"(r) : "v"(lo), "v"(hi)); return r; }
;     __device__ __forceinline__ void operator()(const f32x4 (&acc)[2][2][4][2], const Unit& u, int wr, int wc, int fr, int fq, LAS unsigned char* xs, int wid, int lane) const {
;     ...
; #pragma unroll
;         for (int ai = 0; ai < 2; ++ai)
; #pragma unroll
;             for (int m = 0; m < 4; ++m) {
;                 const int k = k0 + ai * 128 + m * 16 + fr;
; #pragma unroll
;                 for (int bj = 0; bj < 2; ++bj) {
;                     const int col = (2 * u.pn + bj) * 256 + cs * 128 + wc * 32 + 8 * fq;
;                     f32x4 a = acc[ai][bj][m][0], b = acc[ai][bj][m][1];
; #pragma unroll
;                     for (int j = 0; j < 4; ++j) { a[j] += hv[bj][j]; b[j] += hv[bj][4 + j]; }
;                     u32x4 w; w.x = cvt_pk_bf16(a[0] * sc, a[1] * sc); w.y = cvt_pk_bf16(a[2] * sc, a[3] * sc); w.z = cvt_pk_bf16(b[0] * sc, b[1] * sc); w.w = cvt_pk_bf16(b[2] * sc, b[3] * sc);
;                     *(u32x4*)(pq + (tok0 + k) * 1024 + col) = w;
;                     if (k > 0) {
;                         u32x4 w2; w2.x = cvt_pk_bf16(a[0] * scm, a[1] * scm); w2.y = cvt_pk_bf16(a[2] * scm, a[3] * scm); w2.z = cvt_pk_bf16(b[0] * scm, b[1] * scm); w2.w = cvt_pk_bf16(b[2] * scm, b[3] * scm);
;                         *(u32x4*)(pq + (tok0 + S - k) * 1024 + col) = w2;
;                     }
;                 }
.LBB0_1235:
	s_or_b64 exec, exec, s[12:13]
	s_waitcnt vmcnt(8)
	v_lshlrev_b32_e32 v124, 16, v165
	s_waitcnt vmcnt(7)
	v_lshlrev_b32_e32 v125, 16, v173
	v_mul_f32_e32 v124, v169, v124
	v_mul_f32_e32 v125, v169, v125
	s_waitcnt vmcnt(6)
	v_lshlrev_b32_e32 v126, 16, v172
	s_waitcnt vmcnt(5)
	v_lshlrev_b32_e32 v127, 16, v171
	v_cndmask_b32_e64 v124, -v124, v124, s[8:9]
	v_cndmask_b32_e64 v125, -v125, v125, s[8:9]
	v_mul_f32_e32 v126, v169, v126
	v_mul_f32_e32 v127, v169, v127
	s_waitcnt vmcnt(4)
	v_lshlrev_b32_e32 v147, 16, v170
	s_waitcnt vmcnt(3)
	v_lshlrev_b32_e32 v165, 16, v168
	v_cndmask_b32_e64 v126, -v126, v126, s[8:9]
	v_cndmask_b32_e64 v127, -v127, v127, s[8:9]
	v_mul_f32_e32 v147, v169, v147
	v_mul_f32_e32 v165, v169, v165
	s_waitcnt vmcnt(2)
	v_lshlrev_b32_e32 v166, 16, v166
	s_waitcnt vmcnt(1)
	v_lshlrev_b32_e32 v167, 16, v167
	v_add_f32_e32 v116, v116, v124
	v_add_f32_e32 v117, v117, v125
	v_cndmask_b32_e64 v147, -v147, v147, s[8:9]
	v_cndmask_b32_e64 v165, -v165, v165, s[8:9]
	v_mul_f32_e32 v166, v169, v166
	v_mul_f32_e32 v167, v169, v167
	v_add_f32_e32 v118, v118, v126
	v_add_f32_e32 v119, v119, v127
	v_mul_f32_e32 v168, 0x3cb504f3, v116
	v_mul_f32_e32 v169, 0x3cb504f3, v117
	v_cndmask_b32_e64 v166, -v166, v166, s[8:9]
	v_add_f32_e32 v112, v112, v147
	v_add_f32_e32 v113, v113, v165
	v_cvt_pk_bf16_f32 v168, v168, v169
	v_mul_f32_e32 v169, 0x3cb504f3, v118
	v_mul_f32_e32 v170, 0x3cb504f3, v119
	v_cndmask_b32_e64 v167, -v167, v167, s[8:9]
	v_add_f32_e32 v114, v114, v166
	v_cvt_pk_bf16_f32 v169, v169, v170
	v_mul_f32_e32 v170, 0x3cb504f3, v112
	v_mul_f32_e32 v171, 0x3cb504f3, v113
	v_add_f32_e32 v115, v115, v167
	v_cvt_pk_bf16_f32 v170, v170, v171
	v_mul_f32_e32 v171, 0x3cb504f3, v114
	v_mul_f32_e32 v172, 0x3cb504f3, v115
	v_cvt_pk_bf16_f32 v171, v171, v172
	global_store_dwordx4 v[122:123], v[168:171], off offset:512 nt
	s_and_saveexec_b64 s[12:13], vcc
	s_cbranch_execz .LBB0_1237
	v_mul_f32_e32 v116, v156, v116
	v_mul_f32_e32 v117, v156, v117
	v_cvt_pk_bf16_f32 v116, v116, v117
	v_mul_f32_e32 v117, v156, v118
	v_mul_f32_e32 v118, v156, v119
	v_mul_f32_e32 v112, v156, v112
	v_mul_f32_e32 v113, v156, v113
	v_cvt_pk_bf16_f32 v117, v117, v118
	v_cvt_pk_bf16_f32 v118, v112, v113
	v_mul_f32_e32 v112, v156, v114
	v_mul_f32_e32 v113, v156, v115
	v_cvt_pk_bf16_f32 v119, v112, v113
	v_lshl_add_u64 v[112:113], v[120:121], 0, v[136:137]
	global_store_dwordx4 v[112:113], v[116:119], off offset:512 nt
.LBB0_1237:
	s_or_b64 exec, exec, s[12:13]
	v_or_b32_e32 v112, 16, v146
	v_ashrrev_i32_e32 v113, 31, v112
	v_lshl_add_u64 v[114:115], s[54:55], 0, v[112:113]
	v_lshlrev_b64 v[120:121], 11, v[114:115]
	v_mov_b32_e32 v114, s56
	v_sub_co_u32_e32 v112, vcc, s51, v112
	v_add_f32_e32 v115, v111, v160
	s_nop 0
	v_subb_co_u32_e32 v113, vcc, v114, v113, vcc
	v_lshlrev_b64 v[122:123], 11, v[112:113]
	v_add_f32_e32 v112, v108, v157
	v_add_f32_e32 v113, v109, v158
	v_add_f32_e32 v108, v104, v161
	v_add_f32_e32 v109, v105, v162
	v_add_f32_e32 v114, v110, v159
	v_mul_f32_e32 v104, 0x3cb504f3, v112
	v_mul_f32_e32 v105, 0x3cb504f3, v113
	v_cvt_pk_bf16_f32 v116, v104, v105
	v_mul_f32_e32 v104, 0x3cb504f3, v114
	v_mul_f32_e32 v105, 0x3cb504f3, v115
	v_add_f32_e32 v110, v106, v163
	v_add_f32_e32 v111, v107, v164
	v_cvt_pk_bf16_f32 v117, v104, v105
	v_mul_f32_e32 v104, 0x3cb504f3, v108
	v_mul_f32_e32 v105, 0x3cb504f3, v109
	v_cvt_pk_bf16_f32 v118, v104, v105
	v_mul_f32_e32 v104, 0x3cb504f3, v110
	v_mul_f32_e32 v105, 0x3cb504f3, v111
	s_cmp_gt_i32 s57, -1
	v_cvt_pk_bf16_f32 v119, v104, v105
	v_lshl_add_u64 v[104:105], s[16:17], 0, v[120:121]
	s_cselect_b64 s[22:23], -1, 0
	s_cmp_lt_i32 s57, 0
	v_lshl_add_u64 v[106:107], v[104:105], 0, v[136:137]
	v_lshl_add_u64 v[104:105], s[16:17], 0, v[122:123]
	global_store_dwordx4 v[106:107], v[116:119], off nt
	s_cbranch_scc1 .LBB0_1239
	v_mul_f32_e32 v112, v156, v112
	v_mul_f32_e32 v113, v156, v113
	v_cvt_pk_bf16_f32 v112, v112, v113
	v_mul_f32_e32 v113, v156, v114
	v_mul_f32_e32 v114, v156, v115
	v_mul_f32_e32 v108, v156, v108
	v_mul_f32_e32 v109, v156, v109
	v_cvt_pk_bf16_f32 v113, v113, v114
	v_cvt_pk_bf16_f32 v114, v108, v109
	v_mul_f32_e32 v108, v156, v110
	v_mul_f32_e32 v109, v156, v111
	v_cvt_pk_bf16_f32 v115, v108, v109
	v_lshl_add_u64 v[108:109], v[104:105], 0, v[136:137]
	global_store_dwordx4 v[108:109], v[112:115], off nt
.LBB0_1239:
	v_add_f32_e32 v100, v100, v124
	v_add_f32_e32 v101, v101, v125
	v_add_f32_e32 v102, v102, v126
	v_add_f32_e32 v103, v103, v127
	v_mul_f32_e32 v108, 0x3cb504f3, v100
	v_mul_f32_e32 v109, 0x3cb504f3, v101
	v_add_f32_e32 v96, v96, v147
	v_add_f32_e32 v97, v97, v165
	v_cvt_pk_bf16_f32 v108, v108, v109
	v_mul_f32_e32 v109, 0x3cb504f3, v102
	v_mul_f32_e32 v110, 0x3cb504f3, v103
	v_add_f32_e32 v98, v98, v166
	v_add_f32_e32 v99, v99, v167
	v_cvt_pk_bf16_f32 v109, v109, v110
	v_mul_f32_e32 v110, 0x3cb504f3, v96
	v_mul_f32_e32 v111, 0x3cb504f3, v97
	v_cvt_pk_bf16_f32 v110, v110, v111
	v_mul_f32_e32 v111, 0x3cb504f3, v98
	v_mul_f32_e32 v112, 0x3cb504f3, v99
	v_cvt_pk_bf16_f32 v111, v111, v112
	v_cndmask_b32_e64 v112, 0, 1, s[22:23]
	v_cmp_ne_u32_e64 s[12:13], 1, v112
	s_andn2_b64 vcc, exec, s[22:23]
	global_store_dwordx4 v[106:107], v[108:111], off offset:512 nt
	s_cbranch_vccnz .LBB0_1241
	v_mul_f32_e32 v100, v156, v100
	v_mul_f32_e32 v101, v156, v101
	v_cvt_pk_bf16_f32 v100, v100, v101
	v_mul_f32_e32 v101, v156, v102
	v_mul_f32_e32 v102, v156, v103
	v_mul_f32_e32 v96, v156, v96
	v_mul_f32_e32 v97, v156, v97
	v_cvt_pk_bf16_f32 v101, v101, v102
	v_cvt_pk_bf16_f32 v102, v96, v97
	v_mul_f32_e32 v96, v156, v98
	v_mul_f32_e32 v97, v156, v99
	v_cvt_pk_bf16_f32 v103, v96, v97
	v_lshl_add_u64 v[96:97], v[104:105], 0, v[136:137]
	global_store_dwordx4 v[96:97], v[100:103], off offset:512 nt
; __device__ __forceinline__ unsigned cvt_pk_bf16(float lo, float hi) { unsigned r; asm("v_cvt_pk_bf16_f32 %0, %1, %2" : "=v"(r) : "v"(lo), "v"(hi)); return r; }
;     __device__ __forceinline__ void operator()(const f32x4 (&acc)[2][2][4][2], const Unit& u, int wr, int wc, int fr, int fq, LAS unsigned char* xs, int wid, int lane) const {
;     ...
; #pragma unroll
;         for (int ai = 0; ai < 2; ++ai)
; #pragma unroll
;             for (int m = 0; m < 4; ++m) {
;                 const int k = k0 + ai * 128 + m * 16 + fr;
; #pragma unroll
;                 for (int bj = 0; bj < 2; ++bj) {
;                     const int col = (2 * u.pn + bj) * 256 + cs * 128 + wc * 32 + 8 * fq;
;                     f32x4 a = acc[ai][bj][m][0], b = acc[ai][bj][m][1];
; #pragma unroll
;                     for (int j = 0; j < 4; ++j) { a[j] += hv[bj][j]; b[j] += hv[bj][4 + j]; }
;                     u32x4 w; w.x = cvt_pk_bf16(a[0] * sc, a[1] * sc); w.y = cvt_pk_bf16(a[2] * sc, a[3] * sc); w.z = cvt_pk_bf16(b[0] * sc, b[1] * sc); w.w = cvt_pk_bf16(b[2] * sc, b[3] * sc);
;                     *(u32x4*)(pq + (tok0 + k) * 1024 + col) = w;
;                     if (k > 0) {
;                         u32x4 w2; w2.x = cvt_pk_bf16(a[0] * scm, a[1] * scm); w2.y = cvt_pk_bf16(a[2] * scm, a[3] * scm); w2.z = cvt_pk_bf16(b[0] * scm, b[1] * scm); w2.w = cvt_pk_bf16(b[2] * scm, b[3] * scm);
;                         *(u32x4*)(pq + (tok0 + S - k) * 1024 + col) = w2;
;                     }
;                 }
.LBB0_1241:
	v_or_b32_e32 v96, 32, v146
	v_ashrrev_i32_e32 v97, 31, v96
	v_lshl_add_u64 v[98:99], s[54:55], 0, v[96:97]
	v_lshlrev_b64 v[104:105], 11, v[98:99]
	v_mov_b32_e32 v98, s56
	v_sub_co_u32_e32 v96, vcc, s51, v96
	v_add_f32_e32 v99, v95, v160
	s_nop 0
	v_subb_co_u32_e32 v97, vcc, v98, v97, vcc
	v_lshlrev_b64 v[106:107], 11, v[96:97]
	v_add_f32_e32 v96, v92, v157
	v_add_f32_e32 v97, v93, v158
	v_add_f32_e32 v92, v88, v161
	v_add_f32_e32 v93, v89, v162
	v_add_f32_e32 v98, v94, v159
	v_mul_f32_e32 v88, 0x3cb504f3, v96
	v_mul_f32_e32 v89, 0x3cb504f3, v97
	v_cvt_pk_bf16_f32 v100, v88, v89
	v_mul_f32_e32 v88, 0x3cb504f3, v98
	v_mul_f32_e32 v89, 0x3cb504f3, v99
	v_add_f32_e32 v94, v90, v163
	v_add_f32_e32 v95, v91, v164
	v_cvt_pk_bf16_f32 v101, v88, v89
	v_mul_f32_e32 v88, 0x3cb504f3, v92
	v_mul_f32_e32 v89, 0x3cb504f3, v93
	v_cvt_pk_bf16_f32 v102, v88, v89
	v_mul_f32_e32 v88, 0x3cb504f3, v94
	v_mul_f32_e32 v89, 0x3cb504f3, v95
	v_cvt_pk_bf16_f32 v103, v88, v89
	v_lshl_add_u64 v[88:89], s[16:17], 0, v[104:105]
	v_lshl_add_u64 v[90:91], v[88:89], 0, v[136:137]
	s_and_b64 vcc, exec, s[12:13]
	v_lshl_add_u64 v[88:89], s[16:17], 0, v[106:107]
	global_store_dwordx4 v[90:91], v[100:103], off nt
	s_cbranch_vccnz .LBB0_1243
	v_mul_f32_e32 v96, v156, v96
	v_mul_f32_e32 v97, v156, v97
	v_cvt_pk_bf16_f32 v96, v96, v97
	v_mul_f32_e32 v97, v156, v98
	v_mul_f32_e32 v98, v156, v99
	v_mul_f32_e32 v92, v156, v92
	v_mul_f32_e32 v93, v156, v93
	v_cvt_pk_bf16_f32 v97, v97, v98
	v_cvt_pk_bf16_f32 v98, v92, v93
	v_mul_f32_e32 v92, v156, v94
	v_mul_f32_e32 v93, v156, v95
	v_cvt_pk_bf16_f32 v99, v92, v93
	v_lshl_add_u64 v[92:93], v[88:89], 0, v[136:137]
	global_store_dwordx4 v[92:93], v[96:99], off nt
.LBB0_1243:
	v_add_f32_e32 v84, v84, v124
	v_add_f32_e32 v85, v85, v125
	v_add_f32_e32 v86, v86, v126
	v_add_f32_e32 v87, v87, v127
	v_mul_f32_e32 v92, 0x3cb504f3, v84
	v_mul_f32_e32 v93, 0x3cb504f3, v85
	v_add_f32_e32 v80, v80, v147
	v_add_f32_e32 v81, v81, v165
	v_cvt_pk_bf16_f32 v92, v92, v93
	v_mul_f32_e32 v93, 0x3cb504f3, v86
	v_mul_f32_e32 v94, 0x3cb504f3, v87
	v_add_f32_e32 v82, v82, v166
	v_cvt_pk_bf16_f32 v93, v93, v94
	v_mul_f32_e32 v94, 0x3cb504f3, v80
	v_mul_f32_e32 v95, 0x3cb504f3, v81
	v_add_f32_e32 v83, v83, v167
	v_cvt_pk_bf16_f32 v94, v94, v95
	v_mul_f32_e32 v95, 0x3cb504f3, v82
	s_and_b64 vcc, exec, s[12:13]
	v_mul_f32_e32 v96, 0x3cb504f3, v83
	v_cvt_pk_bf16_f32 v95, v95, v96
	global_store_dwordx4 v[90:91], v[92:95], off offset:512 nt
	s_cbranch_vccnz .LBB0_1245
	v_mul_f32_e32 v84, v156, v84
	v_mul_f32_e32 v85, v156, v85
	v_cvt_pk_bf16_f32 v84, v84, v85
	v_mul_f32_e32 v85, v156, v86
	v_mul_f32_e32 v86, v156, v87
	v_mul_f32_e32 v80, v156, v80
	v_mul_f32_e32 v81, v156, v81
	v_cvt_pk_bf16_f32 v85, v85, v86
	v_cvt_pk_bf16_f32 v86, v80, v81
	v_mul_f32_e32 v80, v156, v82
	v_mul_f32_e32 v81, v156, v83
	v_cvt_pk_bf16_f32 v87, v80, v81
	v_lshl_add_u64 v[80:81], v[88:89], 0, v[136:137]
	global_store_dwordx4 v[80:81], v[84:87], off offset:512 nt
.LBB0_1245:
	v_or_b32_e32 v80, 48, v146
	v_ashrrev_i32_e32 v81, 31, v80
	v_lshl_add_u64 v[82:83], s[54:55], 0, v[80:81]
	v_lshlrev_b64 v[88:89], 11, v[82:83]
	v_mov_b32_e32 v82, s56
	v_sub_co_u32_e32 v80, vcc, s51, v80
	v_add_f32_e32 v83, v79, v160
	s_nop 0
	v_subb_co_u32_e32 v81, vcc, v82, v81, vcc
	v_lshlrev_b64 v[90:91], 11, v[80:81]
	v_add_f32_e32 v80, v76, v157
	v_add_f32_e32 v81, v77, v158
	v_add_f32_e32 v76, v72, v161
	v_add_f32_e32 v77, v73, v162
	v_add_f32_e32 v82, v78, v159
	v_mul_f32_e32 v72, 0x3cb504f3, v80
	v_mul_f32_e32 v73, 0x3cb504f3, v81
	v_cvt_pk_bf16_f32 v84, v72, v73
	v_mul_f32_e32 v72, 0x3cb504f3, v82
	v_mul_f32_e32 v73, 0x3cb504f3, v83
	v_add_f32_e32 v78, v74, v163
	v_add_f32_e32 v79, v75, v164
	v_cvt_pk_bf16_f32 v85, v72, v73
	v_mul_f32_e32 v72, 0x3cb504f3, v76
	v_mul_f32_e32 v73, 0x3cb504f3, v77
	v_cvt_pk_bf16_f32 v86, v72, v73
	v_mul_f32_e32 v72, 0x3cb504f3, v78
	v_mul_f32_e32 v73, 0x3cb504f3, v79
	v_cvt_pk_bf16_f32 v87, v72, v73
	v_lshl_add_u64 v[72:73], s[16:17], 0, v[88:89]
	v_lshl_add_u64 v[74:75], v[72:73], 0, v[136:137]
	s_and_b64 vcc, exec, s[12:13]
	v_lshl_add_u64 v[72:73], s[16:17], 0, v[90:91]
	global_store_dwordx4 v[74:75], v[84:87], off nt
	s_cbranch_vccnz .LBB0_1247
	v_mul_f32_e32 v80, v156, v80
	v_mul_f32_e32 v81, v156, v81
	v_cvt_pk_bf16_f32 v80, v80, v81
	v_mul_f32_e32 v81, v156, v82
	v_mul_f32_e32 v82, v156, v83
	v_mul_f32_e32 v76, v156, v76
	v_mul_f32_e32 v77, v156, v77
	v_cvt_pk_bf16_f32 v81, v81, v82
	v_cvt_pk_bf16_f32 v82, v76, v77
	v_mul_f32_e32 v76, v156, v78
	v_mul_f32_e32 v77, v156, v79
	v_cvt_pk_bf16_f32 v83, v76, v77
	v_lshl_add_u64 v[76:77], v[72:73], 0, v[136:137]
	global_store_dwordx4 v[76:77], v[80:83], off nt
.LBB0_1247:
	v_add_f32_e32 v68, v68, v124
	v_add_f32_e32 v69, v69, v125
	v_add_f32_e32 v70, v70, v126
	v_add_f32_e32 v71, v71, v127
	v_mul_f32_e32 v76, 0x3cb504f3, v68
	v_mul_f32_e32 v77, 0x3cb504f3, v69
	v_add_f32_e32 v64, v64, v147
	v_add_f32_e32 v65, v65, v165
	v_cvt_pk_bf16_f32 v76, v76, v77
	v_mul_f32_e32 v77, 0x3cb504f3, v70
	v_mul_f32_e32 v78, 0x3cb504f3, v71
	v_add_f32_e32 v66, v66, v166
	v_cvt_pk_bf16_f32 v77, v77, v78
	v_mul_f32_e32 v78, 0x3cb504f3, v64
	v_mul_f32_e32 v79, 0x3cb504f3, v65
	v_add_f32_e32 v67, v67, v167
	v_cvt_pk_bf16_f32 v78, v78, v79
	v_mul_f32_e32 v79, 0x3cb504f3, v66
	s_and_b64 vcc, exec, s[12:13]
	v_mul_f32_e32 v80, 0x3cb504f3, v67
	v_cvt_pk_bf16_f32 v79, v79, v80
	global_store_dwordx4 v[74:75], v[76:79], off offset:512 nt
	s_cbranch_vccnz .LBB0_1249
	v_mul_f32_e32 v68, v156, v68
	v_mul_f32_e32 v69, v156, v69
	v_cvt_pk_bf16_f32 v68, v68, v69
	v_mul_f32_e32 v69, v156, v70
	v_mul_f32_e32 v70, v156, v71
	v_mul_f32_e32 v64, v156, v64
	v_mul_f32_e32 v65, v156, v65
	v_cvt_pk_bf16_f32 v69, v69, v70
	v_cvt_pk_bf16_f32 v70, v64, v65
	v_mul_f32_e32 v64, v156, v66
	v_mul_f32_e32 v65, v156, v67
	v_cvt_pk_bf16_f32 v71, v64, v65
	v_lshl_add_u64 v[64:65], v[72:73], 0, v[136:137]
	global_store_dwordx4 v[64:65], v[68:71], off offset:512 nt
; __device__ __forceinline__ unsigned cvt_pk_bf16(float lo, float hi) { unsigned r; asm("v_cvt_pk_bf16_f32 %0, %1, %2" : "=v"(r) : "v"(lo), "v"(hi)); return r; }
;     __device__ __forceinline__ void operator()(const f32x4 (&acc)[2][2][4][2], const Unit& u, int wr, int wc, int fr, int fq, LAS unsigned char* xs, int wid, int lane) const {
;     ...
; #pragma unroll
;         for (int ai = 0; ai < 2; ++ai)
; #pragma unroll
;             for (int m = 0; m < 4; ++m) {
;                 const int k = k0 + ai * 128 + m * 16 + fr;
; #pragma unroll
;                 for (int bj = 0; bj < 2; ++bj) {
;                     const int col = (2 * u.pn + bj) * 256 + cs * 128 + wc * 32 + 8 * fq;
;                     f32x4 a = acc[ai][bj][m][0], b = acc[ai][bj][m][1];
; #pragma unroll
;                     for (int j = 0; j < 4; ++j) { a[j] += hv[bj][j]; b[j] += hv[bj][4 + j]; }
;                     u32x4 w; w.x = cvt_pk_bf16(a[0] * sc, a[1] * sc); w.y = cvt_pk_bf16(a[2] * sc, a[3] * sc); w.z = cvt_pk_bf16(b[0] * sc, b[1] * sc); w.w = cvt_pk_bf16(b[2] * sc, b[3] * sc);
;                     *(u32x4*)(pq + (tok0 + k) * 1024 + col) = w;
;                     if (k > 0) {
;                         u32x4 w2; w2.x = cvt_pk_bf16(a[0] * scm, a[1] * scm); w2.y = cvt_pk_bf16(a[2] * scm, a[3] * scm); w2.z = cvt_pk_bf16(b[0] * scm, b[1] * scm); w2.w = cvt_pk_bf16(b[2] * scm, b[3] * scm);
;                         *(u32x4*)(pq + (tok0 + S - k) * 1024 + col) = w2;
;                     }
;                 }
;                 __builtin_amdgcn_sched_barrier(0);
;             }
.LBB0_1249:
	v_add_u32_e32 v64, 0x80, v146
	v_ashrrev_i32_e32 v65, 31, v64
	v_lshl_add_u64 v[66:67], s[54:55], 0, v[64:65]
	v_lshlrev_b64 v[72:73], 11, v[66:67]
	v_mov_b32_e32 v66, s56
	v_sub_co_u32_e64 v64, s[12:13], s51, v64
	v_add_f32_e32 v67, v63, v160
	s_nop 0
	v_subb_co_u32_e64 v65, s[12:13], v66, v65, s[12:13]
	v_lshlrev_b64 v[74:75], 11, v[64:65]
	v_add_f32_e32 v64, v60, v157
	v_add_f32_e32 v65, v61, v158
	v_add_f32_e32 v60, v56, v161
	v_add_f32_e32 v61, v57, v162
	v_add_f32_e32 v66, v62, v159
	v_mul_f32_e32 v56, 0x3cb504f3, v64
	v_mul_f32_e32 v57, 0x3cb504f3, v65
	v_cvt_pk_bf16_f32 v68, v56, v57
	v_mul_f32_e32 v56, 0x3cb504f3, v66
	v_mul_f32_e32 v57, 0x3cb504f3, v67
	v_add_f32_e32 v62, v58, v163
	v_add_f32_e32 v63, v59, v164
	v_cvt_pk_bf16_f32 v69, v56, v57
	v_mul_f32_e32 v56, 0x3cb504f3, v60
	v_mul_f32_e32 v57, 0x3cb504f3, v61
	v_cvt_pk_bf16_f32 v70, v56, v57
	v_mul_f32_e32 v56, 0x3cb504f3, v62
	v_mul_f32_e32 v57, 0x3cb504f3, v63
	v_cvt_pk_bf16_f32 v71, v56, v57
	v_lshl_add_u64 v[56:57], s[16:17], 0, v[72:73]
	v_cmp_lt_i32_e32 vcc, s74, v146
	v_lshl_add_u64 v[58:59], v[56:57], 0, v[136:137]
	v_lshl_add_u64 v[56:57], s[16:17], 0, v[74:75]
	global_store_dwordx4 v[58:59], v[68:71], off nt
	s_and_saveexec_b64 s[12:13], vcc
	s_cbranch_execz .LBB0_1251
	v_mul_f32_e32 v64, v156, v64
	v_mul_f32_e32 v65, v156, v65
	v_cvt_pk_bf16_f32 v64, v64, v65
	v_mul_f32_e32 v65, v156, v66
	v_mul_f32_e32 v66, v156, v67
	v_mul_f32_e32 v60, v156, v60
	v_mul_f32_e32 v61, v156, v61
	v_cvt_pk_bf16_f32 v65, v65, v66
	v_cvt_pk_bf16_f32 v66, v60, v61
	v_mul_f32_e32 v60, v156, v62
	v_mul_f32_e32 v61, v156, v63
	v_cvt_pk_bf16_f32 v67, v60, v61
	v_lshl_add_u64 v[60:61], v[56:57], 0, v[136:137]
	global_store_dwordx4 v[60:61], v[64:67], off nt
.LBB0_1251:
	s_or_b64 exec, exec, s[12:13]
	v_add_f32_e32 v52, v52, v124
	v_add_f32_e32 v53, v53, v125
	v_add_f32_e32 v54, v54, v126
	v_add_f32_e32 v55, v55, v127
	v_mul_f32_e32 v60, 0x3cb504f3, v52
	v_mul_f32_e32 v61, 0x3cb504f3, v53
	v_add_f32_e32 v48, v48, v147
	v_add_f32_e32 v49, v49, v165
	v_cvt_pk_bf16_f32 v60, v60, v61
	v_mul_f32_e32 v61, 0x3cb504f3, v54
	v_mul_f32_e32 v62, 0x3cb504f3, v55
	v_add_f32_e32 v50, v50, v166
	v_cvt_pk_bf16_f32 v61, v61, v62
	v_mul_f32_e32 v62, 0x3cb504f3, v48
	v_mul_f32_e32 v63, 0x3cb504f3, v49
	v_add_f32_e32 v51, v51, v167
	v_cvt_pk_bf16_f32 v62, v62, v63
	v_mul_f32_e32 v63, 0x3cb504f3, v50
	v_mul_f32_e32 v64, 0x3cb504f3, v51
	v_cvt_pk_bf16_f32 v63, v63, v64
	global_store_dwordx4 v[58:59], v[60:63], off offset:512 nt
	s_and_saveexec_b64 s[12:13], vcc
	s_cbranch_execz .LBB0_1253
	v_mul_f32_e32 v52, v156, v52
	v_mul_f32_e32 v53, v156, v53
	v_cvt_pk_bf16_f32 v52, v52, v53
	v_mul_f32_e32 v53, v156, v54
	v_mul_f32_e32 v54, v156, v55
	v_mul_f32_e32 v48, v156, v48
	v_mul_f32_e32 v49, v156, v49
	v_cvt_pk_bf16_f32 v53, v53, v54
	v_cvt_pk_bf16_f32 v54, v48, v49
	v_mul_f32_e32 v48, v156, v50
	v_mul_f32_e32 v49, v156, v51
	v_cvt_pk_bf16_f32 v55, v48, v49
	v_lshl_add_u64 v[48:49], v[56:57], 0, v[136:137]
	global_store_dwordx4 v[48:49], v[52:55], off offset:512 nt
.LBB0_1253:
	s_or_b64 exec, exec, s[12:13]
	v_add_u32_e32 v48, 0x90, v146
	v_ashrrev_i32_e32 v49, 31, v48
	v_lshl_add_u64 v[50:51], s[54:55], 0, v[48:49]
	v_lshlrev_b64 v[56:57], 11, v[50:51]
	v_mov_b32_e32 v50, s56
	v_sub_co_u32_e64 v48, s[12:13], s51, v48
	v_add_f32_e32 v51, v47, v160
	s_nop 0
	v_subb_co_u32_e64 v49, s[12:13], v50, v49, s[12:13]
	v_lshlrev_b64 v[58:59], 11, v[48:49]
	v_add_f32_e32 v48, v44, v157
	v_add_f32_e32 v49, v45, v158
	v_add_f32_e32 v44, v40, v161
	v_add_f32_e32 v45, v41, v162
	v_add_f32_e32 v50, v46, v159
	v_mul_f32_e32 v40, 0x3cb504f3, v48
	v_mul_f32_e32 v41, 0x3cb504f3, v49
	v_cvt_pk_bf16_f32 v52, v40, v41
	v_mul_f32_e32 v40, 0x3cb504f3, v50
	v_mul_f32_e32 v41, 0x3cb504f3, v51
	v_add_f32_e32 v46, v42, v163
	v_add_f32_e32 v47, v43, v164
	v_cvt_pk_bf16_f32 v53, v40, v41
	v_mul_f32_e32 v40, 0x3cb504f3, v44
	v_mul_f32_e32 v41, 0x3cb504f3, v45
	v_cvt_pk_bf16_f32 v54, v40, v41
	v_mul_f32_e32 v40, 0x3cb504f3, v46
	v_mul_f32_e32 v41, 0x3cb504f3, v47
	v_cvt_pk_bf16_f32 v55, v40, v41
	v_lshl_add_u64 v[40:41], s[16:17], 0, v[56:57]
	v_cmp_lt_i32_e32 vcc, s75, v146
	v_lshl_add_u64 v[42:43], v[40:41], 0, v[136:137]
	v_lshl_add_u64 v[40:41], s[16:17], 0, v[58:59]
	global_store_dwordx4 v[42:43], v[52:55], off nt
	s_and_saveexec_b64 s[12:13], vcc
	s_cbranch_execz .LBB0_1255
	v_mul_f32_e32 v48, v156, v48
	v_mul_f32_e32 v49, v156, v49
	v_cvt_pk_bf16_f32 v48, v48, v49
	v_mul_f32_e32 v49, v156, v50
	v_mul_f32_e32 v50, v156, v51
	v_mul_f32_e32 v44, v156, v44
	v_mul_f32_e32 v45, v156, v45
	v_cvt_pk_bf16_f32 v49, v49, v50
	v_cvt_pk_bf16_f32 v50, v44, v45
	v_mul_f32_e32 v44, v156, v46
	v_mul_f32_e32 v45, v156, v47
	v_cvt_pk_bf16_f32 v51, v44, v45
	v_lshl_add_u64 v[44:45], v[40:41], 0, v[136:137]
	global_store_dwordx4 v[44:45], v[48:51], off nt
.LBB0_1255:
	s_or_b64 exec, exec, s[12:13]
	v_add_f32_e32 v36, v36, v124
	v_add_f32_e32 v37, v37, v125
	v_add_f32_e32 v38, v38, v126
	v_add_f32_e32 v39, v39, v127
	v_mul_f32_e32 v44, 0x3cb504f3, v36
	v_mul_f32_e32 v45, 0x3cb504f3, v37
	v_add_f32_e32 v32, v32, v147
	v_add_f32_e32 v33, v33, v165
	v_cvt_pk_bf16_f32 v44, v44, v45
	v_mul_f32_e32 v45, 0x3cb504f3, v38
	v_mul_f32_e32 v46, 0x3cb504f3, v39
	v_add_f32_e32 v34, v34, v166
	v_cvt_pk_bf16_f32 v45, v45, v46
	v_mul_f32_e32 v46, 0x3cb504f3, v32
	v_mul_f32_e32 v47, 0x3cb504f3, v33
	v_add_f32_e32 v35, v35, v167
	v_cvt_pk_bf16_f32 v46, v46, v47
	v_mul_f32_e32 v47, 0x3cb504f3, v34
	v_mul_f32_e32 v48, 0x3cb504f3, v35
	v_cvt_pk_bf16_f32 v47, v47, v48
	global_store_dwordx4 v[42:43], v[44:47], off offset:512 nt
	s_and_saveexec_b64 s[12:13], vcc
	s_cbranch_execz .LBB0_1257
	v_mul_f32_e32 v36, v156, v36
	v_mul_f32_e32 v37, v156, v37
	v_cvt_pk_bf16_f32 v36, v36, v37
	v_mul_f32_e32 v37, v156, v38
	v_mul_f32_e32 v38, v156, v39
	v_mul_f32_e32 v32, v156, v32
	v_mul_f32_e32 v33, v156, v33
	v_cvt_pk_bf16_f32 v37, v37, v38
	v_cvt_pk_bf16_f32 v38, v32, v33
	v_mul_f32_e32 v32, v156, v34
	v_mul_f32_e32 v33, v156, v35
	v_cvt_pk_bf16_f32 v39, v32, v33
	v_lshl_add_u64 v[32:33], v[40:41], 0, v[136:137]
	global_store_dwordx4 v[32:33], v[36:39], off offset:512 nt
; __device__ __forceinline__ unsigned cvt_pk_bf16(float lo, float hi) { unsigned r; asm("v_cvt_pk_bf16_f32 %0, %1, %2" : "=v"(r) : "v"(lo), "v"(hi)); return r; }
;     __device__ __forceinline__ void operator()(const f32x4 (&acc)[2][2][4][2], const Unit& u, int wr, int wc, int fr, int fq, LAS unsigned char* xs, int wid, int lane) const {
;     ...
; #pragma unroll
;         for (int ai = 0; ai < 2; ++ai)
; #pragma unroll
;             for (int m = 0; m < 4; ++m) {
;                 const int k = k0 + ai * 128 + m * 16 + fr;
; #pragma unroll
;                 for (int bj = 0; bj < 2; ++bj) {
;                     const int col = (2 * u.pn + bj) * 256 + cs * 128 + wc * 32 + 8 * fq;
;                     f32x4 a = acc[ai][bj][m][0], b = acc[ai][bj][m][1];
; #pragma unroll
;                     for (int j = 0; j < 4; ++j) { a[j] += hv[bj][j]; b[j] += hv[bj][4 + j]; }
;                     u32x4 w; w.x = cvt_pk_bf16(a[0] * sc, a[1] * sc); w.y = cvt_pk_bf16(a[2] * sc, a[3] * sc); w.z = cvt_pk_bf16(b[0] * sc, b[1] * sc); w.w = cvt_pk_bf16(b[2] * sc, b[3] * sc);
;                     *(u32x4*)(pq + (tok0 + k) * 1024 + col) = w;
;                     if (k > 0) {
;                         u32x4 w2; w2.x = cvt_pk_bf16(a[0] * scm, a[1] * scm); w2.y = cvt_pk_bf16(a[2] * scm, a[3] * scm); w2.z = cvt_pk_bf16(b[0] * scm, b[1] * scm); w2.w = cvt_pk_bf16(b[2] * scm, b[3] * scm);
;                         *(u32x4*)(pq + (tok0 + S - k) * 1024 + col) = w2;
;                     }
;                 }
;                 __builtin_amdgcn_sched_barrier(0);
;             }
.LBB0_1257:
	s_or_b64 exec, exec, s[12:13]
	v_add_u32_e32 v32, 0xa0, v146
	v_ashrrev_i32_e32 v33, 31, v32
	v_lshl_add_u64 v[34:35], s[54:55], 0, v[32:33]
	v_lshlrev_b64 v[40:41], 11, v[34:35]
	v_mov_b32_e32 v34, s56
	v_sub_co_u32_e64 v32, s[12:13], s51, v32
	v_add_f32_e32 v35, v31, v160
	s_nop 0
	v_subb_co_u32_e64 v33, s[12:13], v34, v33, s[12:13]
	v_lshlrev_b64 v[42:43], 11, v[32:33]
	v_add_f32_e32 v32, v28, v157
	v_add_f32_e32 v33, v29, v158
	v_add_f32_e32 v28, v24, v161
	v_add_f32_e32 v29, v25, v162
	v_add_f32_e32 v34, v30, v159
	v_mul_f32_e32 v24, 0x3cb504f3, v32
	v_mul_f32_e32 v25, 0x3cb504f3, v33
	v_cvt_pk_bf16_f32 v36, v24, v25
	v_mul_f32_e32 v24, 0x3cb504f3, v34
	v_mul_f32_e32 v25, 0x3cb504f3, v35
	v_add_f32_e32 v30, v26, v163
	v_add_f32_e32 v31, v27, v164
	v_cvt_pk_bf16_f32 v37, v24, v25
	v_mul_f32_e32 v24, 0x3cb504f3, v28
	v_mul_f32_e32 v25, 0x3cb504f3, v29
	v_cvt_pk_bf16_f32 v38, v24, v25
	v_mul_f32_e32 v24, 0x3cb504f3, v30
	v_mul_f32_e32 v25, 0x3cb504f3, v31
	v_cvt_pk_bf16_f32 v39, v24, v25
	v_lshl_add_u64 v[24:25], s[16:17], 0, v[40:41]
	v_cmp_lt_i32_e32 vcc, s76, v146
	v_lshl_add_u64 v[26:27], v[24:25], 0, v[136:137]
	v_lshl_add_u64 v[24:25], s[16:17], 0, v[42:43]
	global_store_dwordx4 v[26:27], v[36:39], off nt
	s_and_saveexec_b64 s[12:13], vcc
	s_cbranch_execz .LBB0_1259
	v_mul_f32_e32 v32, v156, v32
	v_mul_f32_e32 v33, v156, v33
	v_cvt_pk_bf16_f32 v32, v32, v33
	v_mul_f32_e32 v33, v156, v34
	v_mul_f32_e32 v34, v156, v35
	v_mul_f32_e32 v28, v156, v28
	v_mul_f32_e32 v29, v156, v29
	v_cvt_pk_bf16_f32 v33, v33, v34
	v_cvt_pk_bf16_f32 v34, v28, v29
	v_mul_f32_e32 v28, v156, v30
	v_mul_f32_e32 v29, v156, v31
	v_cvt_pk_bf16_f32 v35, v28, v29
	v_lshl_add_u64 v[28:29], v[24:25], 0, v[136:137]
	global_store_dwordx4 v[28:29], v[32:35], off nt
.LBB0_1259:
	s_or_b64 exec, exec, s[12:13]
	v_add_f32_e32 v20, v20, v124
	v_add_f32_e32 v21, v21, v125
	v_add_f32_e32 v22, v22, v126
	v_add_f32_e32 v23, v23, v127
	v_mul_f32_e32 v28, 0x3cb504f3, v20
	v_mul_f32_e32 v29, 0x3cb504f3, v21
	v_add_f32_e32 v16, v16, v147
	v_add_f32_e32 v17, v17, v165
	v_cvt_pk_bf16_f32 v28, v28, v29
	v_mul_f32_e32 v29, 0x3cb504f3, v22
	v_mul_f32_e32 v30, 0x3cb504f3, v23
	v_add_f32_e32 v18, v18, v166
	v_cvt_pk_bf16_f32 v29, v29, v30
	v_mul_f32_e32 v30, 0x3cb504f3, v16
	v_mul_f32_e32 v31, 0x3cb504f3, v17
	v_add_f32_e32 v19, v19, v167
	v_cvt_pk_bf16_f32 v30, v30, v31
	v_mul_f32_e32 v31, 0x3cb504f3, v18
	v_mul_f32_e32 v32, 0x3cb504f3, v19
	v_cvt_pk_bf16_f32 v31, v31, v32
	global_store_dwordx4 v[26:27], v[28:31], off offset:512 nt
	s_and_saveexec_b64 s[12:13], vcc
	s_cbranch_execz .LBB0_1261
	v_mul_f32_e32 v20, v156, v20
	v_mul_f32_e32 v21, v156, v21
	v_cvt_pk_bf16_f32 v20, v20, v21
	v_mul_f32_e32 v21, v156, v22
	v_mul_f32_e32 v22, v156, v23
	v_mul_f32_e32 v16, v156, v16
	v_mul_f32_e32 v17, v156, v17
	v_cvt_pk_bf16_f32 v21, v21, v22
	v_cvt_pk_bf16_f32 v22, v16, v17
	v_mul_f32_e32 v16, v156, v18
	v_mul_f32_e32 v17, v156, v19
	v_cvt_pk_bf16_f32 v23, v16, v17
	v_lshl_add_u64 v[16:17], v[24:25], 0, v[136:137]
	global_store_dwordx4 v[16:17], v[20:23], off offset:512 nt
.LBB0_1261:
	s_or_b64 exec, exec, s[12:13]
	v_add_u32_e32 v16, 0xb0, v146
	v_ashrrev_i32_e32 v17, 31, v16
	v_lshl_add_u64 v[18:19], s[54:55], 0, v[16:17]
	v_lshlrev_b64 v[24:25], 11, v[18:19]
	v_mov_b32_e32 v18, s56
	v_sub_co_u32_e64 v16, s[12:13], s51, v16
	v_add_f32_e32 v19, v15, v160
	s_nop 0
	v_subb_co_u32_e64 v17, s[12:13], v18, v17, s[12:13]
	v_lshlrev_b64 v[26:27], 11, v[16:17]
	v_add_f32_e32 v16, v12, v157
	v_add_f32_e32 v17, v13, v158
	v_add_f32_e32 v12, v8, v161
	v_add_f32_e32 v13, v9, v162
	v_add_f32_e32 v18, v14, v159
	v_mul_f32_e32 v8, 0x3cb504f3, v16
	v_mul_f32_e32 v9, 0x3cb504f3, v17
	v_cvt_pk_bf16_f32 v20, v8, v9
	v_mul_f32_e32 v8, 0x3cb504f3, v18
	v_mul_f32_e32 v9, 0x3cb504f3, v19
	v_add_f32_e32 v14, v10, v163
	v_add_f32_e32 v15, v11, v164
	v_cvt_pk_bf16_f32 v21, v8, v9
	v_mul_f32_e32 v8, 0x3cb504f3, v12
	v_mul_f32_e32 v9, 0x3cb504f3, v13
	v_cvt_pk_bf16_f32 v22, v8, v9
	v_mul_f32_e32 v8, 0x3cb504f3, v14
	v_mul_f32_e32 v9, 0x3cb504f3, v15
	v_cvt_pk_bf16_f32 v23, v8, v9
	v_lshl_add_u64 v[8:9], s[16:17], 0, v[24:25]
	v_cmp_lt_i32_e32 vcc, s77, v146
	v_lshl_add_u64 v[10:11], v[8:9], 0, v[136:137]
	v_lshl_add_u64 v[8:9], s[16:17], 0, v[26:27]
	global_store_dwordx4 v[10:11], v[20:23], off nt
	s_and_saveexec_b64 s[12:13], vcc
	s_cbranch_execz .LBB0_1263
	v_mul_f32_e32 v16, v156, v16
	v_mul_f32_e32 v17, v156, v17
	v_cvt_pk_bf16_f32 v16, v16, v17
	v_mul_f32_e32 v17, v156, v18
	v_mul_f32_e32 v18, v156, v19
	v_mul_f32_e32 v12, v156, v12
	v_mul_f32_e32 v13, v156, v13
	v_cvt_pk_bf16_f32 v17, v17, v18
	v_cvt_pk_bf16_f32 v18, v12, v13
	v_mul_f32_e32 v12, v156, v14
	v_mul_f32_e32 v13, v156, v15
	v_cvt_pk_bf16_f32 v19, v12, v13
	v_lshl_add_u64 v[12:13], v[8:9], 0, v[136:137]
	global_store_dwordx4 v[12:13], v[16:19], off nt
.LBB0_1263:
	s_or_b64 exec, exec, s[12:13]
	v_add_f32_e32 v4, v4, v124
	v_add_f32_e32 v5, v5, v125
	v_add_f32_e32 v6, v6, v126
	v_add_f32_e32 v7, v7, v127
	v_mul_f32_e32 v12, 0x3cb504f3, v4
	v_mul_f32_e32 v13, 0x3cb504f3, v5
	v_add_f32_e32 v0, v0, v147
	v_add_f32_e32 v1, v1, v165
	v_cvt_pk_bf16_f32 v12, v12, v13
	v_mul_f32_e32 v13, 0x3cb504f3, v6
	v_mul_f32_e32 v14, 0x3cb504f3, v7
	v_add_f32_e32 v2, v2, v166
	v_cvt_pk_bf16_f32 v13, v13, v14
	v_mul_f32_e32 v14, 0x3cb504f3, v0
	v_mul_f32_e32 v15, 0x3cb504f3, v1
	v_add_f32_e32 v3, v3, v167
	v_cvt_pk_bf16_f32 v14, v14, v15
	v_mul_f32_e32 v15, 0x3cb504f3, v2
	v_mul_f32_e32 v16, 0x3cb504f3, v3
	v_cvt_pk_bf16_f32 v15, v15, v16
	global_store_dwordx4 v[10:11], v[12:15], off offset:512 nt
	s_and_saveexec_b64 s[12:13], vcc
	s_cbranch_execz .LBB0_1265
	v_mul_f32_e32 v4, v156, v4
	v_mul_f32_e32 v5, v156, v5
	v_cvt_pk_bf16_f32 v4, v4, v5
	v_mul_f32_e32 v5, v156, v6
	v_mul_f32_e32 v6, v156, v7
	v_mul_f32_e32 v0, v156, v0
	v_mul_f32_e32 v1, v156, v1
	v_cvt_pk_bf16_f32 v5, v5, v6
	v_cvt_pk_bf16_f32 v6, v0, v1
	v_mul_f32_e32 v0, v156, v2
	v_mul_f32_e32 v1, v156, v3
	v_cvt_pk_bf16_f32 v7, v0, v1
	v_lshl_add_u64 v[0:1], v[8:9], 0, v[136:137]
	global_store_dwordx4 v[0:1], v[4:7], off offset:512 nt

;     __device__ __forceinline__ void operator()(const f32x4 (&acc)[2][2][4][2], const Unit& u, int wr, int wc, int fr, int fq, LAS unsigned char* xs, int wid, int lane) const {
;     ...
;         if (!SRCF32) {
; #pragma unroll
;             for (int ai = 0; ai < 2; ++ai)
; #pragma unroll
;                 for (int m = 0; m < 4; ++m)
; #pragma unroll
;                     for (int bj = 0; bj < 2; ++bj) raw[ai][m][bj] = *(const u32x4*)(xb + (size_t)(row0 + ai * 128 + m * 16 + fr) * D + col0 + bj * 128);
;         }
; #pragma unroll
;         for (int ai = 0; ai < 2; ++ai) {
;             f32x4 xf[4][2][2];
;             if (SRCF32) {
; #pragma unroll
;                 for (int m = 0; m < 4; ++m)
; #pragma unroll
;                     for (int bj = 0; bj < 2; ++bj) { const size_t o = (size_t)(row0 + ai * 128 + m * 16 + fr) * D + col0 + bj * 128; xf[m][bj][0] = *(const f32x4*)(xo + o); xf[m][bj][1] = *(const f32x4*)(xo + o + 4); }
;             }
; #pragma unroll
;             for (int m = 0; m < 4; ++m) {
;                 const size_t row = (size_t)(row0 + ai * 128 + m * 16 + fr);
;                 float ss = 0.f;
; #pragma unroll
;                 for (int bj = 0; bj < 2; ++bj) {
;                     const size_t o = row * D + col0 + bj * 128;
;                     f32x4 x0, x1;
;                     if (SRCF32) { x0 = xf[m][bj][0]; x1 = xf[m][bj][1]; }
;                     else { const u32x4 r = raw[ai][m][bj]; x0 = (f32x4){bf_lo(r.x), bf_hi(r.x), bf_lo(r.y), bf_hi(r.y)}; x1 = (f32x4){bf_lo(r.z), bf_hi(r.z), bf_lo(r.w), bf_hi(r.w)}; }
;                     const f32x4 v0 = x0 + acc[ai][bj][m][0], v1 = x1 + acc[ai][bj][m][1];
;                     if (LAST) { *(f32x4*)(out + o) = v0; *(f32x4*)(out + o + 4) = v1; }
;                     else {
;                         ss += (v0[0] * v0[0] + v0[1] * v0[1]) + (v0[2] * v0[2] + v0[3] * v0[3]) + (v1[0] * v1[0] + v1[1] * v1[1]) + (v1[2] * v1[2] + v1[3] * v1[3]);
;                         u32x4 w; w.x = cvt_pk_bf16(v0[0], v0[1]); w.y = cvt_pk_bf16(v0[2], v0[3]); w.z = cvt_pk_bf16(v1[0], v1[1]); w.w = cvt_pk_bf16(v1[2], v1[3]); *(u32x4*)(xb + o) = w;
;                     }
;                 }
;                 if (!LAST) { ss += __shfl_xor(ss, 16); ss += __shfl_xor(ss, 32);
;                     if (fq == 0) P[(ai * 128 + wr * 64 + m * 16 + fr) * 4 + wc] = ss; }
.LBB0_1375:
	s_lshl_b32 s17, s50, 8
	v_lshl_or_b32 v200, s16, 8, v218
	v_add_u32_e32 v104, s17, v216
	v_ashrrev_i32_e32 v201, 31, v200
	v_lshlrev_b64 v[234:235], 1, v[200:201]
	v_ashrrev_i32_e32 v105, 31, v104
	v_lshl_add_u64 v[106:107], s[42:43], 0, v[234:235]
	v_lshlrev_b64 v[236:237], 12, v[104:105]
	v_lshl_add_u64 v[112:113], v[106:107], 0, v[236:237]
	global_load_dwordx4 v[226:229], v[112:113], off
	global_load_dwordx4 v[230:233], v[112:113], off offset:256
	v_or_b32_e32 v112, 16, v104
	v_or_b32_e32 v114, 32, v104
	v_or_b32_e32 v124, 48, v104
	v_add_u32_e32 v126, 0x80, v104
	v_add_u32_e32 v140, 0x90, v104
	v_add_u32_e32 v142, 0xa0, v104
	v_add_u32_e32 v104, 0xb0, v104
	v_ashrrev_i32_e32 v113, 31, v112
	v_ashrrev_i32_e32 v115, 31, v114
	v_ashrrev_i32_e32 v125, 31, v124
	v_ashrrev_i32_e32 v127, 31, v126
	v_ashrrev_i32_e32 v141, 31, v140
	v_ashrrev_i32_e32 v143, 31, v142
	v_ashrrev_i32_e32 v105, 31, v104
	v_lshlrev_b64 v[214:215], 12, v[112:113]
	v_lshlrev_b64 v[212:213], 12, v[114:115]
	v_lshlrev_b64 v[210:211], 12, v[124:125]
	v_lshlrev_b64 v[208:209], 12, v[126:127]
	v_lshlrev_b64 v[206:207], 12, v[140:141]
	v_lshlrev_b64 v[204:205], 12, v[142:143]
	v_lshlrev_b64 v[202:203], 12, v[104:105]
	v_lshl_add_u64 v[104:105], v[106:107], 0, v[214:215]
	v_lshl_add_u64 v[112:113], v[106:107], 0, v[212:213]
	v_lshl_add_u64 v[114:115], v[106:107], 0, v[210:211]
	v_lshl_add_u64 v[124:125], v[106:107], 0, v[208:209]
	v_lshl_add_u64 v[126:127], v[106:107], 0, v[206:207]
	v_lshl_add_u64 v[238:239], v[106:107], 0, v[204:205]
	v_lshl_add_u64 v[106:107], v[106:107], 0, v[202:203]
	global_load_dwordx4 v[180:183], v[104:105], off
	global_load_dwordx4 v[176:179], v[104:105], off offset:256
	global_load_dwordx4 v[172:175], v[112:113], off
	global_load_dwordx4 v[168:171], v[112:113], off offset:256
	global_load_dwordx4 v[164:167], v[114:115], off
	global_load_dwordx4 v[160:163], v[114:115], off offset:256
	global_load_dwordx4 v[156:159], v[124:125], off
	global_load_dwordx4 v[152:155], v[124:125], off offset:256
	global_load_dwordx4 v[148:151], v[126:127], off
	global_load_dwordx4 v[144:147], v[126:127], off offset:256
	global_load_dwordx4 v[140:143], v[238:239], off
	s_nop 0
	global_load_dwordx4 v[124:127], v[238:239], off offset:256
	global_load_dwordx4 v[112:115], v[106:107], off
	s_nop 0
	global_load_dwordx4 v[104:107], v[106:107], off offset:256
	s_waitcnt vmcnt(0)
	v_lshlrev_b32_e32 v238, 16, v226
	v_and_b32_e32 v239, 0xffff0000, v226
	v_lshlrev_b32_e32 v226, 16, v227
	v_and_b32_e32 v227, 0xffff0000, v227
	v_lshlrev_b32_e32 v240, 16, v228
	v_and_b32_e32 v241, 0xffff0000, v228
	v_lshlrev_b32_e32 v242, 16, v230
	v_and_b32_e32 v243, 0xffff0000, v230
	v_lshlrev_b32_e32 v230, 16, v231
	v_and_b32_e32 v231, 0xffff0000, v231
	v_lshlrev_b32_e32 v244, 16, v232
	v_and_b32_e32 v245, 0xffff0000, v232
	v_lshlrev_b32_e32 v232, 16, v233
	v_and_b32_e32 v233, 0xffff0000, v233
	v_pk_add_f32 v[138:139], v[138:139], v[226:227]
	v_pk_add_f32 v[136:137], v[136:137], v[238:239]
	v_pk_add_f32 v[132:133], v[132:133], v[240:241]
	v_pk_add_f32 v[226:227], v[130:131], v[230:231]
	v_pk_add_f32 v[230:231], v[122:123], v[232:233]
	v_pk_add_f32 v[232:233], v[120:121], v[244:245]
	v_mul_f32_e32 v120, v137, v137
	v_mul_f32_e32 v121, v139, v139
	v_lshlrev_b32_e32 v228, 16, v229
	v_and_b32_e32 v229, 0xffff0000, v229
	v_mul_f32_e32 v122, v133, v133
	v_fmac_f32_e32 v120, v136, v136
	v_fmac_f32_e32 v121, v138, v138
	v_pk_add_f32 v[134:135], v[134:135], v[228:229]
	v_pk_add_f32 v[228:229], v[128:129], v[242:243]
	v_fmac_f32_e32 v122, v132, v132
	v_add_f32_e32 v120, v120, v121
	v_add_f32_e32 v120, v122, v120
	v_mul_f32_e32 v121, v229, v229
	v_mul_f32_e32 v122, v227, v227
	v_fmac_f32_e32 v121, v228, v228
	v_fmac_f32_e32 v122, v226, v226
	v_add_f32_e32 v121, v121, v122
	v_mul_f32_e32 v122, v233, v233
	v_fmac_f32_e32 v122, v232, v232
	v_mul_f32_e32 v123, v135, v135
	v_add_f32_e32 v121, v122, v121
	v_mul_f32_e32 v122, v231, v231
	v_fmac_f32_e32 v123, v134, v134
	v_fmac_f32_e32 v122, v230, v230
	v_add_f32_e32 v120, v123, v120
	v_add_f32_e32 v121, v122, v121
	v_and_b32_e32 v122, 64, v223
	v_cvt_pk_bf16_f32 v131, v134, v135
	v_add_f32_e32 v121, v120, v121
	v_xor_b32_e32 v120, 16, v223
	v_add_u32_e32 v134, 64, v122
	v_cmp_lt_i32_e32 vcc, v120, v134
	v_lshl_add_u64 v[122:123], s[42:43], 0, v[236:237]
	v_cvt_pk_bf16_f32 v130, v132, v133
	v_lshl_add_u64 v[132:133], v[122:123], 0, v[234:235]
	v_cndmask_b32_e32 v120, v223, v120, vcc
	v_lshlrev_b32_e32 v120, 2, v120
	ds_bpermute_b32 v135, v120, v121
	v_cvt_pk_bf16_f32 v128, v136, v137
	v_cvt_pk_bf16_f32 v129, v138, v139
	global_store_dwordx4 v[132:133], v[128:131], off nt
	s_waitcnt lgkmcnt(0)
	v_add_f32_e32 v122, v121, v135
	v_xor_b32_e32 v121, 32, v223
	v_cmp_lt_i32_e32 vcc, v121, v134
	v_cvt_pk_bf16_f32 v128, v228, v229
	v_cvt_pk_bf16_f32 v129, v226, v227
	v_cvt_pk_bf16_f32 v130, v232, v233
	v_cvt_pk_bf16_f32 v131, v230, v231
	global_store_dwordx4 v[132:133], v[128:131], off offset:256 nt
	s_nop 0
	v_cndmask_b32_e32 v121, v223, v121, vcc
	v_lshlrev_b32_e32 v121, 2, v121
	ds_bpermute_b32 v123, v121, v122
	s_and_saveexec_b64 s[50:51], s[8:9]
	s_cbranch_execz .LBB0_1377
	s_waitcnt lgkmcnt(0)
	v_add_f32_e32 v122, v122, v123
	ds_write_b32 v225, v122
; __device__ __forceinline__ unsigned cvt_pk_bf16(float lo, float hi) { unsigned r; asm("v_cvt_pk_bf16_f32 %0, %1, %2" : "=v"(r) : "v"(lo), "v"(hi)); return r; }
;     __device__ __forceinline__ void operator()(const f32x4 (&acc)[2][2][4][2], const Unit& u, int wr, int wc, int fr, int fq, LAS unsigned char* xs, int wid, int lane) const {
;     ...
; #pragma unroll
;             for (int m = 0; m < 4; ++m) {
;                 const size_t row = (size_t)(row0 + ai * 128 + m * 16 + fr);
;                 float ss = 0.f;
; #pragma unroll
;                 for (int bj = 0; bj < 2; ++bj) {
;                     const size_t o = row * D + col0 + bj * 128;
;                     f32x4 x0, x1;
;                     if (SRCF32) { x0 = xf[m][bj][0]; x1 = xf[m][bj][1]; }
;                     else { const u32x4 r = raw[ai][m][bj]; x0 = (f32x4){bf_lo(r.x), bf_hi(r.x), bf_lo(r.y), bf_hi(r.y)}; x1 = (f32x4){bf_lo(r.z), bf_hi(r.z), bf_lo(r.w), bf_hi(r.w)}; }
;                     const f32x4 v0 = x0 + acc[ai][bj][m][0], v1 = x1 + acc[ai][bj][m][1];
;                     if (LAST) { *(f32x4*)(out + o) = v0; *(f32x4*)(out + o + 4) = v1; }
;                     else {
;                         ss += (v0[0] * v0[0] + v0[1] * v0[1]) + (v0[2] * v0[2] + v0[3] * v0[3]) + (v1[0] * v1[0] + v1[1] * v1[1]) + (v1[2] * v1[2] + v1[3] * v1[3]);
;                         u32x4 w; w.x = cvt_pk_bf16(v0[0], v0[1]); w.y = cvt_pk_bf16(v0[2], v0[3]); w.z = cvt_pk_bf16(v1[0], v1[1]); w.w = cvt_pk_bf16(v1[2], v1[3]); *(u32x4*)(xb + o) = w;
;                     }
;                 }
;                 if (!LAST) { ss += __shfl_xor(ss, 16); ss += __shfl_xor(ss, 32);
;                     if (fq == 0) P[(ai * 128 + wr * 64 + m * 16 + fr) * 4 + wc] = ss; }
.LBB0_1377:
	s_or_b64 exec, exec, s[50:51]
	v_lshlrev_b32_e32 v122, 16, v180
	s_waitcnt lgkmcnt(0)
	v_and_b32_e32 v123, 0xffff0000, v180
	v_lshlrev_b32_e32 v128, 16, v181
	v_and_b32_e32 v129, 0xffff0000, v181
	v_lshlrev_b32_e32 v130, 16, v182
	v_and_b32_e32 v131, 0xffff0000, v182
	v_lshlrev_b32_e32 v132, 16, v183
	v_and_b32_e32 v133, 0xffff0000, v183
	v_pk_add_f32 v[118:119], v[118:119], v[128:129]
	v_pk_add_f32 v[116:117], v[116:117], v[122:123]
	v_pk_add_f32 v[122:123], v[110:111], v[132:133]
	v_pk_add_f32 v[110:111], v[108:109], v[130:131]
	v_mul_f32_e32 v108, v117, v117
	v_mul_f32_e32 v109, v119, v119
	v_fmac_f32_e32 v108, v116, v116
	v_fmac_f32_e32 v109, v118, v118
	v_add_f32_e32 v108, v108, v109
	v_mul_f32_e32 v109, v111, v111
	v_fmac_f32_e32 v109, v110, v110
	v_add_f32_e32 v108, v109, v108
	v_mul_f32_e32 v109, v123, v123
	v_fmac_f32_e32 v109, v122, v122
	v_add_f32_e32 v130, v109, v108
	v_cvt_pk_bf16_f32 v108, v116, v117
	v_cvt_pk_bf16_f32 v109, v118, v119
	v_lshlrev_b32_e32 v116, 16, v176
	v_and_b32_e32 v117, 0xffff0000, v176
	v_lshlrev_b32_e32 v118, 16, v177
	v_and_b32_e32 v119, 0xffff0000, v177
	v_cvt_pk_bf16_f32 v110, v110, v111
	v_cvt_pk_bf16_f32 v111, v122, v123
	v_lshlrev_b32_e32 v122, 16, v178
	v_and_b32_e32 v123, 0xffff0000, v178
	v_pk_add_f32 v[102:103], v[102:103], v[118:119]
	v_pk_add_f32 v[100:101], v[100:101], v[116:117]
	v_pk_add_f32 v[118:119], v[96:97], v[122:123]
	v_mul_f32_e32 v96, v101, v101
	v_mul_f32_e32 v97, v103, v103
	v_fmac_f32_e32 v96, v100, v100
	v_fmac_f32_e32 v97, v102, v102
	v_lshlrev_b32_e32 v128, 16, v179
	v_and_b32_e32 v129, 0xffff0000, v179
	v_add_f32_e32 v96, v96, v97
	v_mul_f32_e32 v97, v119, v119
	v_pk_add_f32 v[116:117], v[98:99], v[128:129]
	v_fmac_f32_e32 v97, v118, v118
	v_add_f32_e32 v96, v97, v96
	v_mul_f32_e32 v97, v117, v117
	v_fmac_f32_e32 v97, v116, v116
	v_add_f32_e32 v96, v97, v96
	v_add_f32_e32 v99, v130, v96
	ds_bpermute_b32 v128, v120, v99
	v_lshl_add_u64 v[96:97], s[42:43], 0, v[214:215]
	v_lshl_add_u64 v[122:123], v[200:201], 1, v[96:97]
	global_store_dwordx4 v[122:123], v[108:111], off nt
	v_cvt_pk_bf16_f32 v98, v100, v101
	s_waitcnt lgkmcnt(0)
	v_add_f32_e32 v96, v99, v128
	ds_bpermute_b32 v97, v121, v96
	v_cvt_pk_bf16_f32 v99, v102, v103
	v_cvt_pk_bf16_f32 v100, v118, v119
	v_cvt_pk_bf16_f32 v101, v116, v117
	global_store_dwordx4 v[122:123], v[98:101], off offset:256 nt
	s_and_saveexec_b64 s[50:51], s[8:9]
	s_cbranch_execz .LBB0_1379
	s_waitcnt lgkmcnt(0)
	v_add_f32_e32 v96, v96, v97
	ds_write_b32 v225, v96 offset:256
.LBB0_1379:
	s_or_b64 exec, exec, s[50:51]
	v_lshlrev_b32_e32 v96, 16, v172
	s_waitcnt lgkmcnt(0)
	v_and_b32_e32 v97, 0xffff0000, v172
	v_lshlrev_b32_e32 v98, 16, v173
	v_and_b32_e32 v99, 0xffff0000, v173
	v_lshlrev_b32_e32 v100, 16, v174
	v_and_b32_e32 v101, 0xffff0000, v174
	v_lshlrev_b32_e32 v102, 16, v175
	v_and_b32_e32 v103, 0xffff0000, v175
	v_pk_add_f32 v[94:95], v[94:95], v[98:99]
	v_pk_add_f32 v[92:93], v[92:93], v[96:97]
	v_pk_add_f32 v[96:97], v[90:91], v[102:103]
	v_pk_add_f32 v[90:91], v[88:89], v[100:101]
	v_mul_f32_e32 v88, v93, v93
	v_mul_f32_e32 v89, v95, v95
	v_fmac_f32_e32 v88, v92, v92
	v_fmac_f32_e32 v89, v94, v94
	v_add_f32_e32 v88, v88, v89
	v_mul_f32_e32 v89, v91, v91
	v_fmac_f32_e32 v89, v90, v90
	v_add_f32_e32 v88, v89, v88
	v_mul_f32_e32 v89, v97, v97
	v_fmac_f32_e32 v89, v96, v96
	v_add_f32_e32 v100, v89, v88
	v_cvt_pk_bf16_f32 v88, v92, v93
	v_cvt_pk_bf16_f32 v89, v94, v95
	v_lshlrev_b32_e32 v92, 16, v168
	v_and_b32_e32 v93, 0xffff0000, v168
	v_lshlrev_b32_e32 v94, 16, v169
	v_and_b32_e32 v95, 0xffff0000, v169
	v_cvt_pk_bf16_f32 v90, v90, v91
	v_cvt_pk_bf16_f32 v91, v96, v97
	v_lshlrev_b32_e32 v96, 16, v170
	v_and_b32_e32 v97, 0xffff0000, v170
	v_pk_add_f32 v[86:87], v[86:87], v[94:95]
	v_pk_add_f32 v[84:85], v[84:85], v[92:93]
	v_pk_add_f32 v[94:95], v[80:81], v[96:97]
	v_mul_f32_e32 v80, v85, v85
	v_mul_f32_e32 v81, v87, v87
	v_fmac_f32_e32 v80, v84, v84
	v_fmac_f32_e32 v81, v86, v86
	v_lshlrev_b32_e32 v98, 16, v171
	v_and_b32_e32 v99, 0xffff0000, v171
	v_add_f32_e32 v80, v80, v81
	v_mul_f32_e32 v81, v95, v95
	v_pk_add_f32 v[92:93], v[82:83], v[98:99]
	v_fmac_f32_e32 v81, v94, v94
	v_add_f32_e32 v80, v81, v80
	v_mul_f32_e32 v81, v93, v93
	v_fmac_f32_e32 v81, v92, v92
	v_add_f32_e32 v80, v81, v80
	v_add_f32_e32 v83, v100, v80
	ds_bpermute_b32 v98, v120, v83
	v_lshl_add_u64 v[80:81], s[42:43], 0, v[212:213]
	v_lshl_add_u64 v[96:97], v[200:201], 1, v[80:81]
	global_store_dwordx4 v[96:97], v[88:91], off nt
	v_cvt_pk_bf16_f32 v82, v84, v85
	s_waitcnt lgkmcnt(0)
	v_add_f32_e32 v80, v83, v98
	ds_bpermute_b32 v81, v121, v80
	v_cvt_pk_bf16_f32 v83, v86, v87
	v_cvt_pk_bf16_f32 v84, v94, v95
	v_cvt_pk_bf16_f32 v85, v92, v93
	global_store_dwordx4 v[96:97], v[82:85], off offset:256 nt
	s_and_saveexec_b64 s[50:51], s[8:9]
	s_cbranch_execz .LBB0_1381
	s_waitcnt lgkmcnt(0)
	v_add_f32_e32 v80, v80, v81
	ds_write_b32 v225, v80 offset:512
; __device__ __forceinline__ unsigned cvt_pk_bf16(float lo, float hi) { unsigned r; asm("v_cvt_pk_bf16_f32 %0, %1, %2" : "=v"(r) : "v"(lo), "v"(hi)); return r; }
;     __device__ __forceinline__ void operator()(const f32x4 (&acc)[2][2][4][2], const Unit& u, int wr, int wc, int fr, int fq, LAS unsigned char* xs, int wid, int lane) const {
;     ...
; #pragma unroll
;             for (int m = 0; m < 4; ++m) {
;                 const size_t row = (size_t)(row0 + ai * 128 + m * 16 + fr);
;                 float ss = 0.f;
; #pragma unroll
;                 for (int bj = 0; bj < 2; ++bj) {
;                     const size_t o = row * D + col0 + bj * 128;
;                     f32x4 x0, x1;
;                     if (SRCF32) { x0 = xf[m][bj][0]; x1 = xf[m][bj][1]; }
;                     else { const u32x4 r = raw[ai][m][bj]; x0 = (f32x4){bf_lo(r.x), bf_hi(r.x), bf_lo(r.y), bf_hi(r.y)}; x1 = (f32x4){bf_lo(r.z), bf_hi(r.z), bf_lo(r.w), bf_hi(r.w)}; }
;                     const f32x4 v0 = x0 + acc[ai][bj][m][0], v1 = x1 + acc[ai][bj][m][1];
;                     if (LAST) { *(f32x4*)(out + o) = v0; *(f32x4*)(out + o + 4) = v1; }
;                     else {
;                         ss += (v0[0] * v0[0] + v0[1] * v0[1]) + (v0[2] * v0[2] + v0[3] * v0[3]) + (v1[0] * v1[0] + v1[1] * v1[1]) + (v1[2] * v1[2] + v1[3] * v1[3]);
;                         u32x4 w; w.x = cvt_pk_bf16(v0[0], v0[1]); w.y = cvt_pk_bf16(v0[2], v0[3]); w.z = cvt_pk_bf16(v1[0], v1[1]); w.w = cvt_pk_bf16(v1[2], v1[3]); *(u32x4*)(xb + o) = w;
;                     }
;                 }
;                 if (!LAST) { ss += __shfl_xor(ss, 16); ss += __shfl_xor(ss, 32);
;                     if (fq == 0) P[(ai * 128 + wr * 64 + m * 16 + fr) * 4 + wc] = ss; }
.LBB0_1381:
	s_or_b64 exec, exec, s[50:51]
	v_lshlrev_b32_e32 v80, 16, v164
	s_waitcnt lgkmcnt(0)
	v_and_b32_e32 v81, 0xffff0000, v164
	v_lshlrev_b32_e32 v82, 16, v165
	v_and_b32_e32 v83, 0xffff0000, v165
	v_lshlrev_b32_e32 v84, 16, v166
	v_and_b32_e32 v85, 0xffff0000, v166
	v_lshlrev_b32_e32 v86, 16, v167
	v_and_b32_e32 v87, 0xffff0000, v167
	v_pk_add_f32 v[78:79], v[78:79], v[82:83]
	v_pk_add_f32 v[76:77], v[76:77], v[80:81]
	v_pk_add_f32 v[80:81], v[74:75], v[86:87]
	v_pk_add_f32 v[74:75], v[72:73], v[84:85]
	v_mul_f32_e32 v72, v77, v77
	v_mul_f32_e32 v73, v79, v79
	v_fmac_f32_e32 v72, v76, v76
	v_fmac_f32_e32 v73, v78, v78
	v_add_f32_e32 v72, v72, v73
	v_mul_f32_e32 v73, v75, v75
	v_fmac_f32_e32 v73, v74, v74
	v_add_f32_e32 v72, v73, v72
	v_mul_f32_e32 v73, v81, v81
	v_fmac_f32_e32 v73, v80, v80
	v_add_f32_e32 v84, v73, v72
	v_cvt_pk_bf16_f32 v72, v76, v77
	v_cvt_pk_bf16_f32 v73, v78, v79
	v_lshlrev_b32_e32 v76, 16, v160
	v_and_b32_e32 v77, 0xffff0000, v160
	v_lshlrev_b32_e32 v78, 16, v161
	v_and_b32_e32 v79, 0xffff0000, v161
	v_cvt_pk_bf16_f32 v74, v74, v75
	v_cvt_pk_bf16_f32 v75, v80, v81
	v_lshlrev_b32_e32 v80, 16, v162
	v_and_b32_e32 v81, 0xffff0000, v162
	v_pk_add_f32 v[70:71], v[70:71], v[78:79]
	v_pk_add_f32 v[68:69], v[68:69], v[76:77]
	v_pk_add_f32 v[78:79], v[64:65], v[80:81]
	v_mul_f32_e32 v64, v69, v69
	v_mul_f32_e32 v65, v71, v71
	v_fmac_f32_e32 v64, v68, v68
	v_fmac_f32_e32 v65, v70, v70
	v_lshlrev_b32_e32 v82, 16, v163
	v_and_b32_e32 v83, 0xffff0000, v163
	v_add_f32_e32 v64, v64, v65
	v_mul_f32_e32 v65, v79, v79
	v_pk_add_f32 v[76:77], v[66:67], v[82:83]
	v_fmac_f32_e32 v65, v78, v78
	v_add_f32_e32 v64, v65, v64
	v_mul_f32_e32 v65, v77, v77
	v_fmac_f32_e32 v65, v76, v76
	v_add_f32_e32 v64, v65, v64
	v_add_f32_e32 v67, v84, v64
	ds_bpermute_b32 v82, v120, v67
	v_lshl_add_u64 v[64:65], s[42:43], 0, v[210:211]
	v_lshl_add_u64 v[80:81], v[200:201], 1, v[64:65]
	global_store_dwordx4 v[80:81], v[72:75], off nt
	v_cvt_pk_bf16_f32 v66, v68, v69
	s_waitcnt lgkmcnt(0)
	v_add_f32_e32 v64, v67, v82
	ds_bpermute_b32 v65, v121, v64
	v_cvt_pk_bf16_f32 v67, v70, v71
	v_cvt_pk_bf16_f32 v68, v78, v79
	v_cvt_pk_bf16_f32 v69, v76, v77
	global_store_dwordx4 v[80:81], v[66:69], off offset:256 nt
	s_and_saveexec_b64 s[50:51], s[8:9]
	s_cbranch_execz .LBB0_1383
	s_waitcnt lgkmcnt(0)
	v_add_f32_e32 v64, v64, v65
	ds_write_b32 v225, v64 offset:768
.LBB0_1383:
	s_or_b64 exec, exec, s[50:51]
	v_lshlrev_b32_e32 v64, 16, v156
	s_waitcnt lgkmcnt(0)
	v_and_b32_e32 v65, 0xffff0000, v156
	v_lshlrev_b32_e32 v66, 16, v157
	v_and_b32_e32 v67, 0xffff0000, v157
	v_lshlrev_b32_e32 v68, 16, v158
	v_and_b32_e32 v69, 0xffff0000, v158
	v_lshlrev_b32_e32 v70, 16, v159
	v_and_b32_e32 v71, 0xffff0000, v159
	v_pk_add_f32 v[62:63], v[62:63], v[66:67]
	v_pk_add_f32 v[60:61], v[60:61], v[64:65]
	v_pk_add_f32 v[64:65], v[58:59], v[70:71]
	v_pk_add_f32 v[58:59], v[56:57], v[68:69]
	v_mul_f32_e32 v56, v61, v61
	v_mul_f32_e32 v57, v63, v63
	v_fmac_f32_e32 v56, v60, v60
	v_fmac_f32_e32 v57, v62, v62
	v_add_f32_e32 v56, v56, v57
	v_mul_f32_e32 v57, v59, v59
	v_fmac_f32_e32 v57, v58, v58
	v_add_f32_e32 v56, v57, v56
	v_mul_f32_e32 v57, v65, v65
	v_fmac_f32_e32 v57, v64, v64
	v_add_f32_e32 v68, v57, v56
	v_cvt_pk_bf16_f32 v56, v60, v61
	v_cvt_pk_bf16_f32 v57, v62, v63
	v_lshlrev_b32_e32 v60, 16, v152
	v_and_b32_e32 v61, 0xffff0000, v152
	v_lshlrev_b32_e32 v62, 16, v153
	v_and_b32_e32 v63, 0xffff0000, v153
	v_cvt_pk_bf16_f32 v58, v58, v59
	v_cvt_pk_bf16_f32 v59, v64, v65
	v_lshlrev_b32_e32 v64, 16, v154
	v_and_b32_e32 v65, 0xffff0000, v154
	v_pk_add_f32 v[54:55], v[54:55], v[62:63]
	v_pk_add_f32 v[52:53], v[52:53], v[60:61]
	v_pk_add_f32 v[62:63], v[48:49], v[64:65]
	v_mul_f32_e32 v48, v53, v53
	v_mul_f32_e32 v49, v55, v55
	v_fmac_f32_e32 v48, v52, v52
	v_fmac_f32_e32 v49, v54, v54
	v_lshlrev_b32_e32 v66, 16, v155
	v_and_b32_e32 v67, 0xffff0000, v155
	v_add_f32_e32 v48, v48, v49
	v_mul_f32_e32 v49, v63, v63
	v_pk_add_f32 v[60:61], v[50:51], v[66:67]
	v_fmac_f32_e32 v49, v62, v62
	v_add_f32_e32 v48, v49, v48
	v_mul_f32_e32 v49, v61, v61
	v_fmac_f32_e32 v49, v60, v60
	v_add_f32_e32 v48, v49, v48
	v_add_f32_e32 v51, v68, v48
	ds_bpermute_b32 v66, v120, v51
	v_lshl_add_u64 v[48:49], s[42:43], 0, v[208:209]
	v_lshl_add_u64 v[64:65], v[200:201], 1, v[48:49]
	global_store_dwordx4 v[64:65], v[56:59], off nt
	v_cvt_pk_bf16_f32 v50, v52, v53
	s_waitcnt lgkmcnt(0)
	v_add_f32_e32 v48, v51, v66
	ds_bpermute_b32 v49, v121, v48
	v_cvt_pk_bf16_f32 v51, v54, v55
	v_cvt_pk_bf16_f32 v52, v62, v63
	v_cvt_pk_bf16_f32 v53, v60, v61
	global_store_dwordx4 v[64:65], v[50:53], off offset:256 nt
	s_and_saveexec_b64 s[50:51], s[8:9]
	s_cbranch_execz .LBB0_1385
	s_waitcnt lgkmcnt(0)
	v_add_f32_e32 v48, v48, v49
	ds_write_b32 v225, v48 offset:2048
; __device__ __forceinline__ unsigned cvt_pk_bf16(float lo, float hi) { unsigned r; asm("v_cvt_pk_bf16_f32 %0, %1, %2" : "=v"(r) : "v"(lo), "v"(hi)); return r; }
;     __device__ __forceinline__ void operator()(const f32x4 (&acc)[2][2][4][2], const Unit& u, int wr, int wc, int fr, int fq, LAS unsigned char* xs, int wid, int lane) const {
;     ...
; #pragma unroll
;             for (int m = 0; m < 4; ++m) {
;                 const size_t row = (size_t)(row0 + ai * 128 + m * 16 + fr);
;                 float ss = 0.f;
; #pragma unroll
;                 for (int bj = 0; bj < 2; ++bj) {
;                     const size_t o = row * D + col0 + bj * 128;
;                     f32x4 x0, x1;
;                     if (SRCF32) { x0 = xf[m][bj][0]; x1 = xf[m][bj][1]; }
;                     else { const u32x4 r = raw[ai][m][bj]; x0 = (f32x4){bf_lo(r.x), bf_hi(r.x), bf_lo(r.y), bf_hi(r.y)}; x1 = (f32x4){bf_lo(r.z), bf_hi(r.z), bf_lo(r.w), bf_hi(r.w)}; }
;                     const f32x4 v0 = x0 + acc[ai][bj][m][0], v1 = x1 + acc[ai][bj][m][1];
;                     if (LAST) { *(f32x4*)(out + o) = v0; *(f32x4*)(out + o + 4) = v1; }
;                     else {
;                         ss += (v0[0] * v0[0] + v0[1] * v0[1]) + (v0[2] * v0[2] + v0[3] * v0[3]) + (v1[0] * v1[0] + v1[1] * v1[1]) + (v1[2] * v1[2] + v1[3] * v1[3]);
;                         u32x4 w; w.x = cvt_pk_bf16(v0[0], v0[1]); w.y = cvt_pk_bf16(v0[2], v0[3]); w.z = cvt_pk_bf16(v1[0], v1[1]); w.w = cvt_pk_bf16(v1[2], v1[3]); *(u32x4*)(xb + o) = w;
;                     }
;                 }
;                 if (!LAST) { ss += __shfl_xor(ss, 16); ss += __shfl_xor(ss, 32);
;                     if (fq == 0) P[(ai * 128 + wr * 64 + m * 16 + fr) * 4 + wc] = ss; }
.LBB0_1385:
	s_or_b64 exec, exec, s[50:51]
	v_lshlrev_b32_e32 v48, 16, v148
	s_waitcnt lgkmcnt(0)
	v_and_b32_e32 v49, 0xffff0000, v148
	v_lshlrev_b32_e32 v50, 16, v149
	v_and_b32_e32 v51, 0xffff0000, v149
	v_lshlrev_b32_e32 v52, 16, v150
	v_and_b32_e32 v53, 0xffff0000, v150
	v_lshlrev_b32_e32 v54, 16, v151
	v_and_b32_e32 v55, 0xffff0000, v151
	v_pk_add_f32 v[46:47], v[46:47], v[50:51]
	v_pk_add_f32 v[44:45], v[44:45], v[48:49]
	v_pk_add_f32 v[48:49], v[42:43], v[54:55]
	v_pk_add_f32 v[42:43], v[40:41], v[52:53]
	v_mul_f32_e32 v40, v45, v45
	v_mul_f32_e32 v41, v47, v47
	v_fmac_f32_e32 v40, v44, v44
	v_fmac_f32_e32 v41, v46, v46
	v_add_f32_e32 v40, v40, v41
	v_mul_f32_e32 v41, v43, v43
	v_fmac_f32_e32 v41, v42, v42
	v_add_f32_e32 v40, v41, v40
	v_mul_f32_e32 v41, v49, v49
	v_fmac_f32_e32 v41, v48, v48
	v_add_f32_e32 v52, v41, v40
	v_cvt_pk_bf16_f32 v40, v44, v45
	v_cvt_pk_bf16_f32 v41, v46, v47
	v_lshlrev_b32_e32 v44, 16, v144
	v_and_b32_e32 v45, 0xffff0000, v144
	v_lshlrev_b32_e32 v46, 16, v145
	v_and_b32_e32 v47, 0xffff0000, v145
	v_cvt_pk_bf16_f32 v42, v42, v43
	v_cvt_pk_bf16_f32 v43, v48, v49
	v_lshlrev_b32_e32 v48, 16, v146
	v_and_b32_e32 v49, 0xffff0000, v146
	v_pk_add_f32 v[38:39], v[38:39], v[46:47]
	v_pk_add_f32 v[36:37], v[36:37], v[44:45]
	v_pk_add_f32 v[46:47], v[32:33], v[48:49]
	v_mul_f32_e32 v32, v37, v37
	v_mul_f32_e32 v33, v39, v39
	v_fmac_f32_e32 v32, v36, v36
	v_fmac_f32_e32 v33, v38, v38
	v_lshlrev_b32_e32 v50, 16, v147
	v_and_b32_e32 v51, 0xffff0000, v147
	v_add_f32_e32 v32, v32, v33
	v_mul_f32_e32 v33, v47, v47
	v_pk_add_f32 v[44:45], v[34:35], v[50:51]
	v_fmac_f32_e32 v33, v46, v46
	v_add_f32_e32 v32, v33, v32
	v_mul_f32_e32 v33, v45, v45
	v_fmac_f32_e32 v33, v44, v44
	v_add_f32_e32 v32, v33, v32
	v_add_f32_e32 v35, v52, v32
	ds_bpermute_b32 v50, v120, v35
	v_lshl_add_u64 v[32:33], s[42:43], 0, v[206:207]
	v_lshl_add_u64 v[48:49], v[200:201], 1, v[32:33]
	global_store_dwordx4 v[48:49], v[40:43], off nt
	v_cvt_pk_bf16_f32 v34, v36, v37
	s_waitcnt lgkmcnt(0)
	v_add_f32_e32 v32, v35, v50
	ds_bpermute_b32 v33, v121, v32
	v_cvt_pk_bf16_f32 v35, v38, v39
	v_cvt_pk_bf16_f32 v36, v46, v47
	v_cvt_pk_bf16_f32 v37, v44, v45
	global_store_dwordx4 v[48:49], v[34:37], off offset:256 nt
	s_and_saveexec_b64 s[50:51], s[8:9]
	s_cbranch_execz .LBB0_1387
	s_waitcnt lgkmcnt(0)
	v_add_f32_e32 v32, v32, v33
	ds_write_b32 v225, v32 offset:2304
; __device__ __forceinline__ unsigned cvt_pk_bf16(float lo, float hi) { unsigned r; asm("v_cvt_pk_bf16_f32 %0, %1, %2" : "=v"(r) : "v"(lo), "v"(hi)); return r; }
;     __device__ __forceinline__ void operator()(const f32x4 (&acc)[2][2][4][2], const Unit& u, int wr, int wc, int fr, int fq, LAS unsigned char* xs, int wid, int lane) const {
;     ...
; #pragma unroll
;             for (int m = 0; m < 4; ++m) {
;                 const size_t row = (size_t)(row0 + ai * 128 + m * 16 + fr);
;                 float ss = 0.f;
; #pragma unroll
;                 for (int bj = 0; bj < 2; ++bj) {
;                     const size_t o = row * D + col0 + bj * 128;
;                     f32x4 x0, x1;
;                     if (SRCF32) { x0 = xf[m][bj][0]; x1 = xf[m][bj][1]; }
;                     else { const u32x4 r = raw[ai][m][bj]; x0 = (f32x4){bf_lo(r.x), bf_hi(r.x), bf_lo(r.y), bf_hi(r.y)}; x1 = (f32x4){bf_lo(r.z), bf_hi(r.z), bf_lo(r.w), bf_hi(r.w)}; }
;                     const f32x4 v0 = x0 + acc[ai][bj][m][0], v1 = x1 + acc[ai][bj][m][1];
;                     if (LAST) { *(f32x4*)(out + o) = v0; *(f32x4*)(out + o + 4) = v1; }
;                     else {
;                         ss += (v0[0] * v0[0] + v0[1] * v0[1]) + (v0[2] * v0[2] + v0[3] * v0[3]) + (v1[0] * v1[0] + v1[1] * v1[1]) + (v1[2] * v1[2] + v1[3] * v1[3]);
;                         u32x4 w; w.x = cvt_pk_bf16(v0[0], v0[1]); w.y = cvt_pk_bf16(v0[2], v0[3]); w.z = cvt_pk_bf16(v1[0], v1[1]); w.w = cvt_pk_bf16(v1[2], v1[3]); *(u32x4*)(xb + o) = w;
;                     }
;                 }
;                 if (!LAST) { ss += __shfl_xor(ss, 16); ss += __shfl_xor(ss, 32);
;                     if (fq == 0) P[(ai * 128 + wr * 64 + m * 16 + fr) * 4 + wc] = ss; }
.LBB0_1387:
	s_or_b64 exec, exec, s[50:51]
	v_lshlrev_b32_e32 v32, 16, v140
	s_waitcnt lgkmcnt(0)
	v_and_b32_e32 v33, 0xffff0000, v140
	v_lshlrev_b32_e32 v34, 16, v141
	v_and_b32_e32 v35, 0xffff0000, v141
	v_lshlrev_b32_e32 v36, 16, v142
	v_and_b32_e32 v37, 0xffff0000, v142
	v_lshlrev_b32_e32 v38, 16, v143
	v_and_b32_e32 v39, 0xffff0000, v143
	v_pk_add_f32 v[30:31], v[30:31], v[34:35]
	v_pk_add_f32 v[28:29], v[28:29], v[32:33]
	v_pk_add_f32 v[32:33], v[26:27], v[38:39]
	v_pk_add_f32 v[26:27], v[24:25], v[36:37]
	v_mul_f32_e32 v24, v29, v29
	v_mul_f32_e32 v25, v31, v31
	v_fmac_f32_e32 v24, v28, v28
	v_fmac_f32_e32 v25, v30, v30
	v_add_f32_e32 v24, v24, v25
	v_mul_f32_e32 v25, v27, v27
	v_fmac_f32_e32 v25, v26, v26
	v_add_f32_e32 v24, v25, v24
	v_mul_f32_e32 v25, v33, v33
	v_fmac_f32_e32 v25, v32, v32
	v_add_f32_e32 v36, v25, v24
	v_cvt_pk_bf16_f32 v24, v28, v29
	v_cvt_pk_bf16_f32 v25, v30, v31
	v_lshlrev_b32_e32 v28, 16, v124
	v_and_b32_e32 v29, 0xffff0000, v124
	v_lshlrev_b32_e32 v30, 16, v125
	v_and_b32_e32 v31, 0xffff0000, v125
	v_cvt_pk_bf16_f32 v26, v26, v27
	v_cvt_pk_bf16_f32 v27, v32, v33
	v_lshlrev_b32_e32 v32, 16, v126
	v_and_b32_e32 v33, 0xffff0000, v126
	v_pk_add_f32 v[22:23], v[22:23], v[30:31]
	v_pk_add_f32 v[20:21], v[20:21], v[28:29]
	v_pk_add_f32 v[30:31], v[16:17], v[32:33]
	v_mul_f32_e32 v16, v21, v21
	v_mul_f32_e32 v17, v23, v23
	v_fmac_f32_e32 v16, v20, v20
	v_fmac_f32_e32 v17, v22, v22
	v_lshlrev_b32_e32 v34, 16, v127
	v_and_b32_e32 v35, 0xffff0000, v127
	v_add_f32_e32 v16, v16, v17
	v_mul_f32_e32 v17, v31, v31
	v_pk_add_f32 v[28:29], v[18:19], v[34:35]
	v_fmac_f32_e32 v17, v30, v30
	v_add_f32_e32 v16, v17, v16
	v_mul_f32_e32 v17, v29, v29
	v_fmac_f32_e32 v17, v28, v28
	v_add_f32_e32 v16, v17, v16
	v_add_f32_e32 v19, v36, v16
	ds_bpermute_b32 v34, v120, v19
	v_lshl_add_u64 v[16:17], s[42:43], 0, v[204:205]
	v_lshl_add_u64 v[32:33], v[200:201], 1, v[16:17]
	global_store_dwordx4 v[32:33], v[24:27], off nt
	v_cvt_pk_bf16_f32 v18, v20, v21
	s_waitcnt lgkmcnt(0)
	v_add_f32_e32 v16, v19, v34
	ds_bpermute_b32 v17, v121, v16
	v_cvt_pk_bf16_f32 v19, v22, v23
	v_cvt_pk_bf16_f32 v20, v30, v31
	v_cvt_pk_bf16_f32 v21, v28, v29
	global_store_dwordx4 v[32:33], v[18:21], off offset:256 nt
	s_and_saveexec_b64 s[50:51], s[8:9]
	s_cbranch_execz .LBB0_1389
	s_waitcnt lgkmcnt(0)
	v_add_f32_e32 v16, v16, v17
	ds_write_b32 v225, v16 offset:2560
.LBB0_1389:
	s_or_b64 exec, exec, s[50:51]
	v_lshlrev_b32_e32 v16, 16, v112
	s_waitcnt lgkmcnt(0)
	v_and_b32_e32 v17, 0xffff0000, v112
	v_lshlrev_b32_e32 v18, 16, v113
	v_and_b32_e32 v19, 0xffff0000, v113
	v_lshlrev_b32_e32 v20, 16, v114
	v_and_b32_e32 v21, 0xffff0000, v114
	v_lshlrev_b32_e32 v22, 16, v115
	v_and_b32_e32 v23, 0xffff0000, v115
	v_pk_add_f32 v[14:15], v[14:15], v[18:19]
	v_pk_add_f32 v[12:13], v[12:13], v[16:17]
	v_pk_add_f32 v[16:17], v[10:11], v[22:23]
	v_pk_add_f32 v[10:11], v[8:9], v[20:21]
	v_mul_f32_e32 v8, v13, v13
	v_mul_f32_e32 v9, v15, v15
	v_fmac_f32_e32 v8, v12, v12
	v_fmac_f32_e32 v9, v14, v14
	v_add_f32_e32 v8, v8, v9
	v_mul_f32_e32 v9, v11, v11
	v_fmac_f32_e32 v9, v10, v10
	v_add_f32_e32 v8, v9, v8
	v_mul_f32_e32 v9, v17, v17
	v_fmac_f32_e32 v9, v16, v16
	v_add_f32_e32 v20, v9, v8
	v_cvt_pk_bf16_f32 v8, v12, v13
	v_cvt_pk_bf16_f32 v9, v14, v15
	v_lshlrev_b32_e32 v12, 16, v104
	v_and_b32_e32 v13, 0xffff0000, v104
	v_lshlrev_b32_e32 v14, 16, v105
	v_and_b32_e32 v15, 0xffff0000, v105
	v_cvt_pk_bf16_f32 v10, v10, v11
	v_cvt_pk_bf16_f32 v11, v16, v17
	v_lshlrev_b32_e32 v16, 16, v106
	v_and_b32_e32 v17, 0xffff0000, v106
	v_pk_add_f32 v[6:7], v[6:7], v[14:15]
	v_pk_add_f32 v[4:5], v[4:5], v[12:13]
	v_pk_add_f32 v[14:15], v[0:1], v[16:17]
	v_mul_f32_e32 v0, v5, v5
	v_mul_f32_e32 v1, v7, v7
	v_fmac_f32_e32 v0, v4, v4
	v_fmac_f32_e32 v1, v6, v6
	v_lshlrev_b32_e32 v18, 16, v107
	v_and_b32_e32 v19, 0xffff0000, v107
	v_add_f32_e32 v0, v0, v1
	v_mul_f32_e32 v1, v15, v15
	v_pk_add_f32 v[12:13], v[2:3], v[18:19]
	v_fmac_f32_e32 v1, v14, v14
	v_add_f32_e32 v0, v1, v0
	v_mul_f32_e32 v1, v13, v13
	v_fmac_f32_e32 v1, v12, v12
	v_add_f32_e32 v0, v1, v0
	v_add_f32_e32 v3, v20, v0
	ds_bpermute_b32 v18, v120, v3
	v_lshl_add_u64 v[0:1], s[42:43], 0, v[202:203]
	v_lshl_add_u64 v[16:17], v[200:201], 1, v[0:1]
	global_store_dwordx4 v[16:17], v[8:11], off nt
	v_cvt_pk_bf16_f32 v2, v4, v5
	s_waitcnt lgkmcnt(0)
	v_add_f32_e32 v0, v3, v18
	ds_bpermute_b32 v1, v121, v0
	v_cvt_pk_bf16_f32 v3, v6, v7
	v_cvt_pk_bf16_f32 v4, v14, v15
	v_cvt_pk_bf16_f32 v5, v12, v13
	global_store_dwordx4 v[16:17], v[2:5], off offset:256 nt
	s_and_saveexec_b64 s[50:51], s[8:9]
	s_cbranch_execz .LBB0_1391
	s_waitcnt lgkmcnt(0)
	v_add_f32_e32 v0, v0, v1
	ds_write_b32 v225, v0 offset:2816

; #define LAS __attribute__((address_space(3)))
; __device__ __forceinline__ unsigned cvt_pk_bf16(float lo, float hi) { unsigned r; asm("v_cvt_pk_bf16_f32 %0, %1, %2" : "=v"(r) : "v"(lo), "v"(hi)); return r; }
; #define LDS_WAIT() asm volatile("s_waitcnt lgkmcnt(0)" ::: "memory")
; __device__ __forceinline__ void tstore_sub(const f32x4 (&v)[4][2], bf16_t* dst  , LAS unsigned char* x, int fr, int fq, int lane) {
; #pragma unroll
;     for (int m = 0; m < 4; ++m)
; #pragma unroll
;         for (int n = 0; n < 2; ++n)
; #pragma unroll
;             for (int j = 0; j < 4; ++j) {
;                 const int ch = 8 * fq + 4 * n + j, tok = 16 * m + fr;
;                 const unsigned b = cvt_pk_bf16(v[m][n][j], 0.f);
;                 *(LAS unsigned short*)(x + ch * 128 + ((((tok >> 3) ^ fq) << 4) | ((tok & 7) << 1))) = (unsigned short)b;
;             }
;     LDS_WAIT();
; #pragma unroll
;     for (int i = 0; i < 4; ++i) {
;         const int q = lane + 64 * i, ch = q >> 3, tc = q & 7;
;         const u32x4 o = *(const LAS u32x4*)(x + ch * 128 + ((tc ^ ((ch >> 3) & 3)) << 4));
;         *(u32x4*)(dst + (size_t)ch * T + tc * 8) = o;
;     }
;     LDS_WAIT();
; }
;     __device__ __forceinline__ void operator()(const f32x4 (&acc)[2][2][4][2], const Unit& u, int wr, int wc, int fr, int fq, LAS unsigned char* xs, int wid, int lane) const {
;     ...
;                     if (ODD) {
;                         float* vss = (float*)(ws + OFF_VSS);
; #pragma unroll
;                         for (int m = 0; m < 4; ++m) {
;                             float s = 0.f;
; #pragma unroll
;                             for (int n = 0; n < 2; ++n) s += (v[m][n][0] * v[m][n][0] + v[m][n][1] * v[m][n][1]) + (v[m][n][2] * v[m][n][2] + v[m][n][3] * v[m][n][3]);
;                             s += __shfl_xor(s, 16); s += __shfl_xor(s, 32);
;                             if (fq == 0) vss[(size_t)(row0 + ai * 128 + m * 16 + fr) * 32 + (2 * (pn - 24) + bj) * 4 + wc] = s;
;                         }
;                     }
;                     tstore_sub(v, base + (size_t)(bj * 128 + wc * 32) * T + row0 + ai * 128, x, fr, fq, lane);
.LBB0_1469:
	s_or_b64 exec, exec, s[60:61]
	v_cvt_pk_bf16_f32 v159, v184, v137
	ds_write_b16 v237, v159
	v_cvt_pk_bf16_f32 v159, v185, v137
	ds_write_b16 v237, v159 offset:128
	v_cvt_pk_bf16_f32 v159, v182, v137
	ds_write_b16 v237, v159 offset:256
	v_cvt_pk_bf16_f32 v159, v183, v137
	ds_write_b16 v237, v159 offset:384
	v_cvt_pk_bf16_f32 v159, v180, v137
	ds_write_b16 v237, v159 offset:512
	v_cvt_pk_bf16_f32 v159, v181, v137
	ds_write_b16 v237, v159 offset:640
	v_cvt_pk_bf16_f32 v159, v178, v137
	ds_write_b16 v237, v159 offset:768
	v_cvt_pk_bf16_f32 v159, v179, v137
	ds_write_b16 v237, v159 offset:896
	v_cvt_pk_bf16_f32 v159, v192, v137
	ds_write_b16 v238, v159
	v_cvt_pk_bf16_f32 v159, v193, v137
	ds_write_b16 v238, v159 offset:128
	v_cvt_pk_bf16_f32 v159, v190, v137
	ds_write_b16 v238, v159 offset:256
	v_cvt_pk_bf16_f32 v159, v191, v137
	ds_write_b16 v238, v159 offset:384
	v_cvt_pk_bf16_f32 v159, v188, v137
	ds_write_b16 v238, v159 offset:512
	v_cvt_pk_bf16_f32 v159, v189, v137
	ds_write_b16 v238, v159 offset:640
	v_cvt_pk_bf16_f32 v159, v186, v137
	ds_write_b16 v238, v159 offset:768
	v_cvt_pk_bf16_f32 v159, v187, v137
	ds_write_b16 v238, v159 offset:896
	v_cvt_pk_bf16_f32 v159, v206, v137
	ds_write_b16 v239, v159
	v_cvt_pk_bf16_f32 v159, v207, v137
	ds_write_b16 v239, v159 offset:128
	v_cvt_pk_bf16_f32 v159, v204, v137
	ds_write_b16 v239, v159 offset:256
	v_cvt_pk_bf16_f32 v159, v205, v137
	ds_write_b16 v239, v159 offset:384
	v_cvt_pk_bf16_f32 v159, v202, v137
	ds_write_b16 v239, v159 offset:512
	v_cvt_pk_bf16_f32 v159, v203, v137
	ds_write_b16 v239, v159 offset:640
	v_cvt_pk_bf16_f32 v159, v200, v137
	ds_write_b16 v239, v159 offset:768
	v_cvt_pk_bf16_f32 v159, v201, v137
	ds_write_b16 v239, v159 offset:896
	v_cvt_pk_bf16_f32 v159, v214, v137
	ds_write_b16 v240, v159
	v_cvt_pk_bf16_f32 v159, v215, v137
	ds_write_b16 v240, v159 offset:128
	v_cvt_pk_bf16_f32 v159, v212, v137
	ds_write_b16 v240, v159 offset:256
	v_cvt_pk_bf16_f32 v159, v213, v137
	ds_write_b16 v240, v159 offset:384
	v_cvt_pk_bf16_f32 v159, v210, v137
	ds_write_b16 v240, v159 offset:512
	v_cvt_pk_bf16_f32 v159, v211, v137
	ds_write_b16 v240, v159 offset:640
	v_cvt_pk_bf16_f32 v159, v208, v137
	s_ashr_i32 s57, s56, 31
	ds_write_b16 v240, v159 offset:768
	v_cvt_pk_bf16_f32 v159, v209, v137
	ds_write_b16 v240, v159 offset:896
	s_lshl_b64 s[0:1], s[56:57], 1
	s_waitcnt lgkmcnt(0)
	s_add_u32 s0, s58, s0
	ds_read_b128 v[182:185], v241
	ds_read_b128 v[190:193], v242
	s_addc_u32 s1, s59, s1
	v_lshl_add_u64 v[176:177], s[0:1], 0, v[136:137]
	v_lshl_add_u64 v[212:213], v[176:177], 0, s[20:21]
	v_lshlrev_b32_e32 v180, 1, v138
	v_mov_b32_e32 v181, v137
	ds_read_b128 v[200:203], v243
	ds_read_b128 v[208:211], v244
	v_lshl_add_u64 v[186:187], v[212:213], 0, v[180:181]
	v_mov_b32_e32 v175, v174
	s_waitcnt lgkmcnt(3)
	global_store_dwordx4 v[186:187], v[182:185], off nt
	v_lshlrev_b32_e32 v178, 1, v142
	v_mov_b32_e32 v179, v137
	v_lshlrev_b32_e32 v182, 1, v140
	v_mov_b32_e32 v183, v137
	v_mov_b32_e32 v184, v174
	v_mov_b32_e32 v185, v174
	v_lshl_add_u64 v[188:189], v[212:213], 0, v[182:183]
	v_pk_mul_f32 v[204:205], v[122:123], v[184:185]
	v_pk_mul_f32 v[206:207], v[120:121], v[174:175]
	s_waitcnt lgkmcnt(2)
	global_store_dwordx4 v[188:189], v[190:193], off nt
	v_mul_f32_e32 v159, v207, v207
	v_mul_f32_e32 v161, v205, v205
	v_lshl_add_u64 v[190:191], v[212:213], 0, v[178:179]
	s_waitcnt lgkmcnt(1)
	global_store_dwordx4 v[190:191], v[200:203], off nt
	v_fmac_f32_e32 v159, v206, v206
	v_fmac_f32_e32 v161, v204, v204
	v_pk_mul_f32 v[200:201], v[114:115], v[184:185]
	v_pk_mul_f32 v[202:203], v[112:113], v[174:175]
	v_add_f32_e32 v159, v159, v161
	v_mul_f32_e32 v161, v203, v203
	v_mul_f32_e32 v165, v201, v201
	v_fmac_f32_e32 v161, v202, v202
	v_fmac_f32_e32 v165, v200, v200
	v_add_f32_e32 v161, v161, v165
	v_add_f32_e32 v159, v159, v161
	ds_bpermute_b32 v161, v151, v159
	v_lshlrev_b32_e32 v184, 1, v144
	v_mov_b32_e32 v185, v137
	v_lshl_add_u64 v[192:193], v[212:213], 0, v[184:185]
	s_waitcnt lgkmcnt(1)
	global_store_dwordx4 v[192:193], v[208:211], off nt
	s_waitcnt lgkmcnt(0)
	v_add_f32_e32 v159, v159, v161
	ds_bpermute_b32 v161, v245, v159
	s_waitcnt lgkmcnt(0)
	s_and_saveexec_b64 s[60:61], s[6:7]
	s_cbranch_execz .LBB0_1471
	v_lshlrev_b64 v[208:209], 7, v[162:163]
	v_lshl_add_u64 v[208:209], s[54:55], 0, v[208:209]
	s_waitcnt lgkmcnt(0)
	v_add_f32_e32 v159, v159, v161
	global_store_dword v[208:209], v159, off offset:-752

; #define LAS __attribute__((address_space(3)))
; __device__ __forceinline__ unsigned cvt_pk_bf16(float lo, float hi) { unsigned r; asm("v_cvt_pk_bf16_f32 %0, %1, %2" : "=v"(r) : "v"(lo), "v"(hi)); return r; }
; #define LDS_WAIT() asm volatile("s_waitcnt lgkmcnt(0)" ::: "memory")
; __device__ __forceinline__ void tstore_sub(const f32x4 (&v)[4][2], bf16_t* dst  , LAS unsigned char* x, int fr, int fq, int lane) {
; #pragma unroll
;     for (int m = 0; m < 4; ++m)
; #pragma unroll
;         for (int n = 0; n < 2; ++n)
; #pragma unroll
;             for (int j = 0; j < 4; ++j) {
;                 const int ch = 8 * fq + 4 * n + j, tok = 16 * m + fr;
;                 const unsigned b = cvt_pk_bf16(v[m][n][j], 0.f);
;                 *(LAS unsigned short*)(x + ch * 128 + ((((tok >> 3) ^ fq) << 4) | ((tok & 7) << 1))) = (unsigned short)b;
;             }
;     LDS_WAIT();
; #pragma unroll
;     for (int i = 0; i < 4; ++i) {
;         const int q = lane + 64 * i, ch = q >> 3, tc = q & 7;
;         const u32x4 o = *(const LAS u32x4*)(x + ch * 128 + ((tc ^ ((ch >> 3) & 3)) << 4));
;         *(u32x4*)(dst + (size_t)ch * T + tc * 8) = o;
;     }
;     LDS_WAIT();
; }
;     __device__ __forceinline__ void operator()(const f32x4 (&acc)[2][2][4][2], const Unit& u, int wr, int wc, int fr, int fq, LAS unsigned char* xs, int wid, int lane) const {
;     ...
;                     if (ODD) {
;                         float* vss = (float*)(ws + OFF_VSS);
; #pragma unroll
;                         for (int m = 0; m < 4; ++m) {
;                             float s = 0.f;
; #pragma unroll
;                             for (int n = 0; n < 2; ++n) s += (v[m][n][0] * v[m][n][0] + v[m][n][1] * v[m][n][1]) + (v[m][n][2] * v[m][n][2] + v[m][n][3] * v[m][n][3]);
;                             s += __shfl_xor(s, 16); s += __shfl_xor(s, 32);
;                             if (fq == 0) vss[(size_t)(row0 + ai * 128 + m * 16 + fr) * 32 + (2 * (pn - 24) + bj) * 4 + wc] = s;
;                         }
;                     }
;                     tstore_sub(v, base + (size_t)(bj * 128 + wc * 32) * T + row0 + ai * 128, x, fr, fq, lane);
.LBB0_1477:
	s_or_b64 exec, exec, s[60:61]
	v_cvt_pk_bf16_f32 v159, v206, v137
	ds_write_b16 v237, v159
	v_cvt_pk_bf16_f32 v159, v207, v137
	ds_write_b16 v237, v159 offset:128
	v_cvt_pk_bf16_f32 v159, v204, v137
	ds_write_b16 v237, v159 offset:256
	v_cvt_pk_bf16_f32 v159, v205, v137
	ds_write_b16 v237, v159 offset:384
	v_cvt_pk_bf16_f32 v159, v202, v137
	ds_write_b16 v237, v159 offset:512
	v_cvt_pk_bf16_f32 v159, v203, v137
	ds_write_b16 v237, v159 offset:640
	v_cvt_pk_bf16_f32 v159, v200, v137
	ds_write_b16 v237, v159 offset:768
	v_cvt_pk_bf16_f32 v159, v201, v137
	ds_write_b16 v237, v159 offset:896
	v_cvt_pk_bf16_f32 v159, v214, v137
	ds_write_b16 v238, v159
	v_cvt_pk_bf16_f32 v159, v215, v137
	ds_write_b16 v238, v159 offset:128
	v_cvt_pk_bf16_f32 v159, v212, v137
	ds_write_b16 v238, v159 offset:256
	v_cvt_pk_bf16_f32 v159, v213, v137
	ds_write_b16 v238, v159 offset:384
	v_cvt_pk_bf16_f32 v159, v210, v137
	ds_write_b16 v238, v159 offset:512
	v_cvt_pk_bf16_f32 v159, v211, v137
	ds_write_b16 v238, v159 offset:640
	v_cvt_pk_bf16_f32 v159, v208, v137
	ds_write_b16 v238, v159 offset:768
	v_cvt_pk_bf16_f32 v159, v209, v137
	ds_write_b16 v238, v159 offset:896
	v_cvt_pk_bf16_f32 v159, v220, v137
	ds_write_b16 v239, v159
	v_cvt_pk_bf16_f32 v159, v221, v137
	ds_write_b16 v239, v159 offset:128
	v_cvt_pk_bf16_f32 v159, v218, v137
	ds_write_b16 v239, v159 offset:256
	v_cvt_pk_bf16_f32 v159, v219, v137
	ds_write_b16 v239, v159 offset:384
	v_cvt_pk_bf16_f32 v159, v216, v137
	ds_write_b16 v239, v159 offset:512
	v_cvt_pk_bf16_f32 v159, v217, v137
	ds_write_b16 v239, v159 offset:640
	v_cvt_pk_bf16_f32 v159, v198, v137
	ds_write_b16 v239, v159 offset:768
	v_cvt_pk_bf16_f32 v159, v199, v137
	ds_write_b16 v239, v159 offset:896
	v_cvt_pk_bf16_f32 v159, v226, v137
	ds_write_b16 v240, v159
	v_cvt_pk_bf16_f32 v159, v227, v137
	ds_write_b16 v240, v159 offset:128
	v_cvt_pk_bf16_f32 v159, v224, v137
	ds_write_b16 v240, v159 offset:256
	v_cvt_pk_bf16_f32 v159, v225, v137
	ds_write_b16 v240, v159 offset:384
	v_cvt_pk_bf16_f32 v159, v222, v137
	ds_write_b16 v240, v159 offset:512
	v_cvt_pk_bf16_f32 v159, v223, v137
	ds_write_b16 v240, v159 offset:640
	v_cvt_pk_bf16_f32 v159, v196, v137
	ds_write_b16 v240, v159 offset:768
	v_cvt_pk_bf16_f32 v159, v197, v137
	ds_write_b16 v240, v159 offset:896
	s_waitcnt lgkmcnt(0)
	ds_read_b128 v[194:197], v241
	ds_read_b128 v[198:201], v242
	s_lshl_b32 s60, s68, 1
	s_mov_b32 s61, s21
	v_lshl_add_u64 v[210:211], v[176:177], 0, s[60:61]
	v_mov_b32_e32 v181, v137
	v_pk_mul_f32 v[206:207], v[62:63], v[166:167] op_sel_hi:[1,0]
	v_pk_mul_f32 v[208:209], v[60:61], v[166:167] op_sel_hi:[1,0]
	v_lshl_add_u64 v[202:203], v[210:211], 0, v[180:181]
	v_mul_f32_e32 v159, v209, v209
	s_waitcnt lgkmcnt(14)
	v_mul_f32_e32 v161, v207, v207
	s_waitcnt lgkmcnt(1)
	global_store_dwordx4 v[202:203], v[194:197], off nt
	v_pk_mul_f32 v[202:203], v[54:55], v[166:167] op_sel_hi:[1,0]
	v_pk_mul_f32 v[204:205], v[52:53], v[166:167] op_sel_hi:[1,0]
	v_fmac_f32_e32 v159, v208, v208
	v_fmac_f32_e32 v161, v206, v206
	v_add_f32_e32 v159, v159, v161
	v_mul_f32_e32 v161, v205, v205
	v_mul_f32_e32 v163, v203, v203
	v_fmac_f32_e32 v161, v204, v204
	v_fmac_f32_e32 v163, v202, v202
	v_add_f32_e32 v161, v161, v163
	v_mov_b32_e32 v183, v137
	v_add_f32_e32 v159, v159, v161
	v_lshl_add_u64 v[194:195], v[210:211], 0, v[182:183]
	ds_bpermute_b32 v161, v151, v159
	s_waitcnt lgkmcnt(1)
	global_store_dwordx4 v[194:195], v[198:201], off nt
	ds_read_b128 v[194:197], v243
	ds_read_b128 v[198:201], v244
	v_mov_b32_e32 v179, v137
	v_lshl_add_u64 v[212:213], v[210:211], 0, v[178:179]
	v_mov_b32_e32 v185, v137
	s_waitcnt lgkmcnt(2)
	v_add_f32_e32 v159, v159, v161
	s_waitcnt lgkmcnt(1)
	global_store_dwordx4 v[212:213], v[194:197], off nt
	ds_bpermute_b32 v161, v245, v159
	s_nop 0
	v_lshl_add_u64 v[194:195], v[210:211], 0, v[184:185]
	s_waitcnt lgkmcnt(1)
	global_store_dwordx4 v[194:195], v[198:201], off nt
	s_waitcnt lgkmcnt(0)
	s_nop 1
	v_add_u32_e32 v200, 0x80, v162
	v_ashrrev_i32_e32 v201, 31, v200
	s_and_saveexec_b64 s[62:63], s[6:7]
	s_cbranch_execz .LBB0_1479
	v_lshlrev_b64 v[194:195], 7, v[200:201]
	v_lshl_add_u64 v[194:195], s[54:55], 0, v[194:195]
	s_waitcnt lgkmcnt(0)
	v_add_f32_e32 v159, v159, v161
	global_store_dword v[194:195], v159, off offset:-768

; #define LAS __attribute__((address_space(3)))
; __device__ __forceinline__ unsigned cvt_pk_bf16(float lo, float hi) { unsigned r; asm("v_cvt_pk_bf16_f32 %0, %1, %2" : "=v"(r) : "v"(lo), "v"(hi)); return r; }
; #define LDS_WAIT() asm volatile("s_waitcnt lgkmcnt(0)" ::: "memory")
; __device__ __forceinline__ void tstore_sub(const f32x4 (&v)[4][2], bf16_t* dst  , LAS unsigned char* x, int fr, int fq, int lane) {
; #pragma unroll
;     for (int m = 0; m < 4; ++m)
; #pragma unroll
;         for (int n = 0; n < 2; ++n)
; #pragma unroll
;             for (int j = 0; j < 4; ++j) {
;                 const int ch = 8 * fq + 4 * n + j, tok = 16 * m + fr;
;                 const unsigned b = cvt_pk_bf16(v[m][n][j], 0.f);
;                 *(LAS unsigned short*)(x + ch * 128 + ((((tok >> 3) ^ fq) << 4) | ((tok & 7) << 1))) = (unsigned short)b;
;             }
;     LDS_WAIT();
; #pragma unroll
;     for (int i = 0; i < 4; ++i) {
;         const int q = lane + 64 * i, ch = q >> 3, tc = q & 7;
;         const u32x4 o = *(const LAS u32x4*)(x + ch * 128 + ((tc ^ ((ch >> 3) & 3)) << 4));
;         *(u32x4*)(dst + (size_t)ch * T + tc * 8) = o;
;     }
;     LDS_WAIT();
; }
;     __device__ __forceinline__ void operator()(const f32x4 (&acc)[2][2][4][2], const Unit& u, int wr, int wc, int fr, int fq, LAS unsigned char* xs, int wid, int lane) const {
;     ...
;                     if (ODD) {
;                         float* vss = (float*)(ws + OFF_VSS);
; #pragma unroll
;                         for (int m = 0; m < 4; ++m) {
;                             float s = 0.f;
; #pragma unroll
;                             for (int n = 0; n < 2; ++n) s += (v[m][n][0] * v[m][n][0] + v[m][n][1] * v[m][n][1]) + (v[m][n][2] * v[m][n][2] + v[m][n][3] * v[m][n][3]);
;                             s += __shfl_xor(s, 16); s += __shfl_xor(s, 32);
;                             if (fq == 0) vss[(size_t)(row0 + ai * 128 + m * 16 + fr) * 32 + (2 * (pn - 24) + bj) * 4 + wc] = s;
;                         }
;                     }
;                     tstore_sub(v, base + (size_t)(bj * 128 + wc * 32) * T + row0 + ai * 128, x, fr, fq, lane);
.LBB0_1485:
	s_or_b64 exec, exec, s[62:63]
	v_cvt_pk_bf16_f32 v159, v208, v137
	ds_write_b16 v237, v159
	v_cvt_pk_bf16_f32 v159, v209, v137
	ds_write_b16 v237, v159 offset:128
	v_cvt_pk_bf16_f32 v159, v206, v137
	ds_write_b16 v237, v159 offset:256
	v_cvt_pk_bf16_f32 v159, v207, v137
	ds_write_b16 v237, v159 offset:384
	v_cvt_pk_bf16_f32 v159, v204, v137
	ds_write_b16 v237, v159 offset:512
	v_cvt_pk_bf16_f32 v159, v205, v137
	ds_write_b16 v237, v159 offset:640
	v_cvt_pk_bf16_f32 v159, v202, v137
	ds_write_b16 v237, v159 offset:768
	v_cvt_pk_bf16_f32 v159, v203, v137
	ds_write_b16 v237, v159 offset:896
	v_cvt_pk_bf16_f32 v159, v216, v137
	ds_write_b16 v238, v159
	v_cvt_pk_bf16_f32 v159, v217, v137
	ds_write_b16 v238, v159 offset:128
	v_cvt_pk_bf16_f32 v159, v214, v137
	ds_write_b16 v238, v159 offset:256
	v_cvt_pk_bf16_f32 v159, v215, v137
	ds_write_b16 v238, v159 offset:384
	v_cvt_pk_bf16_f32 v159, v212, v137
	ds_write_b16 v238, v159 offset:512
	v_cvt_pk_bf16_f32 v159, v213, v137
	ds_write_b16 v238, v159 offset:640
	v_cvt_pk_bf16_f32 v159, v210, v137
	ds_write_b16 v238, v159 offset:768
	v_cvt_pk_bf16_f32 v159, v211, v137
	ds_write_b16 v238, v159 offset:896
	v_cvt_pk_bf16_f32 v159, v224, v137
	ds_write_b16 v239, v159
	v_cvt_pk_bf16_f32 v159, v225, v137
	ds_write_b16 v239, v159 offset:128
	v_cvt_pk_bf16_f32 v159, v222, v137
	ds_write_b16 v239, v159 offset:256
	v_cvt_pk_bf16_f32 v159, v223, v137
	ds_write_b16 v239, v159 offset:384
	v_cvt_pk_bf16_f32 v159, v220, v137
	ds_write_b16 v239, v159 offset:512
	v_cvt_pk_bf16_f32 v159, v221, v137
	ds_write_b16 v239, v159 offset:640
	v_cvt_pk_bf16_f32 v159, v218, v137
	ds_write_b16 v239, v159 offset:768
	v_cvt_pk_bf16_f32 v159, v219, v137
	ds_write_b16 v239, v159 offset:896
	v_cvt_pk_bf16_f32 v159, v232, v137
	ds_write_b16 v240, v159
	v_cvt_pk_bf16_f32 v159, v233, v137
	ds_write_b16 v240, v159 offset:128
	v_cvt_pk_bf16_f32 v159, v230, v137
	ds_write_b16 v240, v159 offset:256
	v_cvt_pk_bf16_f32 v159, v231, v137
	ds_write_b16 v240, v159 offset:384
	v_cvt_pk_bf16_f32 v159, v228, v137
	ds_write_b16 v240, v159 offset:512
	v_cvt_pk_bf16_f32 v159, v229, v137
	v_mov_b32_e32 v167, v166
	ds_write_b16 v240, v159 offset:640
	v_cvt_pk_bf16_f32 v159, v226, v137
	v_mov_b32_e32 v202, v166
	v_mov_b32_e32 v203, v166
	ds_write_b16 v240, v159 offset:768
	v_cvt_pk_bf16_f32 v159, v227, v137
	v_pk_mul_f32 v[206:207], v[58:59], v[202:203]
	v_pk_mul_f32 v[208:209], v[56:57], v[166:167]
	ds_write_b16 v240, v159 offset:896
	v_mul_f32_e32 v159, v209, v209
	s_waitcnt lgkmcnt(14)
	v_mul_f32_e32 v161, v207, v207
	v_pk_mul_f32 v[202:203], v[50:51], v[202:203]
	v_pk_mul_f32 v[204:205], v[48:49], v[166:167]
	v_fmac_f32_e32 v159, v208, v208
	v_fmac_f32_e32 v161, v206, v206
	v_add_f32_e32 v159, v159, v161
	v_mul_f32_e32 v161, v205, v205
	v_mul_f32_e32 v163, v203, v203
	v_fmac_f32_e32 v161, v204, v204
	v_fmac_f32_e32 v163, v202, v202
	v_add_f32_e32 v161, v161, v163
	v_add_f32_e32 v159, v159, v161
	ds_bpermute_b32 v161, v151, v159
	s_waitcnt lgkmcnt(0)
	ds_read_b128 v[210:213], v241
	ds_read_b128 v[214:217], v242
	ds_read_b128 v[218:221], v243
	ds_read_b128 v[222:225], v244
	s_waitcnt lgkmcnt(3)
	global_store_dwordx4 v[186:187], v[210:213], off offset:256 nt
	s_waitcnt lgkmcnt(2)
	global_store_dwordx4 v[188:189], v[214:217], off offset:256 nt
	s_waitcnt lgkmcnt(1)
	global_store_dwordx4 v[190:191], v[218:221], off offset:256 nt
	s_waitcnt lgkmcnt(0)
	global_store_dwordx4 v[192:193], v[222:225], off offset:256 nt
	v_add_f32_e32 v159, v159, v161
	ds_bpermute_b32 v161, v245, v159
	s_waitcnt lgkmcnt(0)
	s_and_saveexec_b64 s[62:63], s[6:7]
	s_cbranch_execz .LBB0_1487
	v_lshlrev_b64 v[186:187], 7, v[200:201]
	v_lshl_add_u64 v[186:187], s[54:55], 0, v[186:187]
	s_waitcnt lgkmcnt(0)
	v_add_f32_e32 v159, v159, v161
	global_store_dword v[186:187], v159, off offset:-752

; #define LAS __attribute__((address_space(3)))
; __device__ __forceinline__ unsigned cvt_pk_bf16(float lo, float hi) { unsigned r; asm("v_cvt_pk_bf16_f32 %0, %1, %2" : "=v"(r) : "v"(lo), "v"(hi)); return r; }
; __device__ __forceinline__ float silu_f(float x) { return x * __builtin_amdgcn_rcpf(1.f + __builtin_amdgcn_exp2f(-LOG2E * x)); }
; #define LDS_WAIT() asm volatile("s_waitcnt lgkmcnt(0)" ::: "memory")
; __device__ __forceinline__ void tstore_sub(const f32x4 (&v)[4][2], bf16_t* dst  , LAS unsigned char* x, int fr, int fq, int lane) {
; #pragma unroll
;     for (int m = 0; m < 4; ++m)
; #pragma unroll
;         for (int n = 0; n < 2; ++n)
; #pragma unroll
;             for (int j = 0; j < 4; ++j) {
;                 const int ch = 8 * fq + 4 * n + j, tok = 16 * m + fr;
;                 const unsigned b = cvt_pk_bf16(v[m][n][j], 0.f);
;                 *(LAS unsigned short*)(x + ch * 128 + ((((tok >> 3) ^ fq) << 4) | ((tok & 7) << 1))) = (unsigned short)b;
;             }
;     LDS_WAIT();
; #pragma unroll
;     for (int i = 0; i < 4; ++i) {
;         const int q = lane + 64 * i, ch = q >> 3, tc = q & 7;
;         const u32x4 o = *(const LAS u32x4*)(x + ch * 128 + ((tc ^ ((ch >> 3) & 3)) << 4));
;         *(u32x4*)(dst + (size_t)ch * T + tc * 8) = o;
;     }
;     LDS_WAIT();
; }
;     __device__ __forceinline__ void operator()(const f32x4 (&acc)[2][2][4][2], const Unit& u, int wr, int wc, int fr, int fq, LAS unsigned char* xs, int wid, int lane) const {
;     ...
;         } else if (mode == 1 || mode == 2) {
; #pragma unroll
;             for (int ai = 0; ai < 2; ++ai)
; #pragma unroll
;                 for (int m = 0; m < 4; ++m) {
;                     const float r = rs[ai][m];
;                     bf16_t* rowp = base + (size_t)(row0 + ai * 128 + m * 16 + fr) * ldc + wc * 32 + 8 * fq;
;                     float o[8];
; #pragma unroll
;                     for (int n = 0; n < 2; ++n)
; #pragma unroll
;                         for (int j = 0; j < 4; ++j) { const float a = acc[ai][0][m][n][j] * r, b = acc[ai][1][m][n][j] * r; o[4 * n + j] = (mode == 1) ? a * b : a * silu_f(b); }
;                     u32x4 w; w.x = cvt_pk_bf16(o[0], o[1]); w.y = cvt_pk_bf16(o[2], o[3]); w.z = cvt_pk_bf16(o[4], o[5]); w.w = cvt_pk_bf16(o[6], o[7]);
;                     *(u32x4*)rowp = w;
;                     __builtin_amdgcn_sched_barrier(0);
;                 }
.LBB0_1493:
	s_or_b64 exec, exec, s[62:63]
	v_cvt_pk_bf16_f32 v151, v208, v137
	ds_write_b16 v237, v151
	v_cvt_pk_bf16_f32 v151, v209, v137
	ds_write_b16 v237, v151 offset:128
	v_cvt_pk_bf16_f32 v151, v206, v137
	ds_write_b16 v237, v151 offset:256
	v_cvt_pk_bf16_f32 v151, v207, v137
	ds_write_b16 v237, v151 offset:384
	v_cvt_pk_bf16_f32 v151, v204, v137
	ds_write_b16 v237, v151 offset:512
	v_cvt_pk_bf16_f32 v151, v205, v137
	ds_write_b16 v237, v151 offset:640
	v_cvt_pk_bf16_f32 v151, v202, v137
	ds_write_b16 v237, v151 offset:768
	v_cvt_pk_bf16_f32 v151, v203, v137
	ds_write_b16 v237, v151 offset:896
	v_cvt_pk_bf16_f32 v151, v192, v137
	ds_write_b16 v238, v151
	v_cvt_pk_bf16_f32 v151, v193, v137
	ds_write_b16 v238, v151 offset:128
	v_cvt_pk_bf16_f32 v151, v190, v137
	ds_write_b16 v238, v151 offset:256
	v_cvt_pk_bf16_f32 v151, v191, v137
	ds_write_b16 v238, v151 offset:384
	v_cvt_pk_bf16_f32 v151, v188, v137
	ds_write_b16 v238, v151 offset:512
	v_cvt_pk_bf16_f32 v151, v189, v137
	ds_write_b16 v238, v151 offset:640
	v_cvt_pk_bf16_f32 v151, v186, v137
	ds_write_b16 v238, v151 offset:768
	v_cvt_pk_bf16_f32 v151, v187, v137
	ds_write_b16 v238, v151 offset:896
	v_cvt_pk_bf16_f32 v151, v212, v137
	ds_write_b16 v239, v151
	v_cvt_pk_bf16_f32 v151, v213, v137
	ds_write_b16 v239, v151 offset:128
	v_cvt_pk_bf16_f32 v151, v210, v137
	ds_write_b16 v239, v151 offset:256
	v_cvt_pk_bf16_f32 v151, v211, v137
	ds_write_b16 v239, v151 offset:384
	v_cvt_pk_bf16_f32 v151, v200, v137
	ds_write_b16 v239, v151 offset:512
	v_cvt_pk_bf16_f32 v151, v201, v137
	ds_write_b16 v239, v151 offset:640
	v_cvt_pk_bf16_f32 v151, v198, v137
	ds_write_b16 v239, v151 offset:768
	v_cvt_pk_bf16_f32 v151, v199, v137
	ds_write_b16 v239, v151 offset:896
	v_cvt_pk_bf16_f32 v151, v218, v137
	ds_write_b16 v240, v151
	v_cvt_pk_bf16_f32 v151, v219, v137
	ds_write_b16 v240, v151 offset:128
	v_cvt_pk_bf16_f32 v151, v216, v137
	ds_write_b16 v240, v151 offset:256
	v_cvt_pk_bf16_f32 v151, v217, v137
	ds_write_b16 v240, v151 offset:384
	v_cvt_pk_bf16_f32 v151, v214, v137
	ds_write_b16 v240, v151 offset:512
	v_cvt_pk_bf16_f32 v151, v215, v137
	ds_write_b16 v240, v151 offset:640
	v_cvt_pk_bf16_f32 v151, v196, v137
	ds_write_b16 v240, v151 offset:768
	v_cvt_pk_bf16_f32 v151, v197, v137
	ds_write_b16 v240, v151 offset:896
	s_waitcnt lgkmcnt(0)
	ds_read_b128 v[186:189], v241
	ds_read_b128 v[190:193], v242
	s_mov_b32 s61, s21
	v_lshl_add_u64 v[176:177], v[176:177], 0, s[60:61]
	v_lshl_add_u64 v[176:177], v[176:177], 0, s[36:37]
	v_mov_b32_e32 v181, v137
	v_lshl_add_u64 v[180:181], v[176:177], 0, v[180:181]
	v_mov_b32_e32 v183, v137
	s_waitcnt lgkmcnt(1)
	global_store_dwordx4 v[180:181], v[186:189], off nt
	v_mov_b32_e32 v179, v137
	v_mov_b32_e32 v185, v137
	v_lshl_add_u64 v[186:187], v[176:177], 0, v[182:183]
	ds_read_b128 v[180:183], v243
	s_waitcnt lgkmcnt(1)
	global_store_dwordx4 v[186:187], v[190:193], off nt
	ds_read_b128 v[186:189], v244
	v_lshl_add_u64 v[178:179], v[176:177], 0, v[178:179]
	v_lshl_add_u64 v[176:177], v[176:177], 0, v[184:185]
	s_waitcnt lgkmcnt(1)
	global_store_dwordx4 v[178:179], v[180:183], off nt
	s_waitcnt lgkmcnt(0)
	global_store_dwordx4 v[176:177], v[186:189], off nt
	s_waitcnt lgkmcnt(0)
	s_branch .LBB0_1460
.LBB0_1494:
	s_waitcnt lgkmcnt(7)
	v_mul_f32_e32 v120, v120, v174
	v_mul_f32_e32 v159, 0xbfb8aa3b, v120
	s_add_u32 s0, s58, s75
	v_exp_f32_e32 v159, v159
	s_addc_u32 s1, s59, 0
	v_mov_b32_e32 v151, v137
	v_lshl_add_u64 v[176:177], s[0:1], 0, v[150:151]
	s_ashr_i32 s0, s56, 31
	v_mul_lo_u32 v151, s53, v162
	s_mul_i32 s0, s52, s0
	v_mad_u64_u32 v[178:179], s[54:55], s52, v162, 0
	v_add3_u32 v179, v179, s0, v151
	v_add_f32_e32 v151, 1.0, v159
	v_rcp_f32_e32 v151, v151
	v_mul_f32_e32 v121, v121, v174
	v_mul_f32_e32 v159, 0xbfb8aa3b, v121
	v_exp_f32_e32 v159, v159
	v_mul_f32_e32 v151, v120, v151
	v_mul_f32_e32 v124, v124, v174
	v_cndmask_b32_e64 v120, v151, v120, s[10:11]
	v_mul_f32_e32 v120, v124, v120
	v_add_f32_e32 v124, 1.0, v159
	v_mul_f32_e32 v122, v122, v174
	v_rcp_f32_e32 v124, v124
	v_mul_f32_e32 v151, 0xbfb8aa3b, v122
	v_exp_f32_e32 v151, v151
	v_mul_f32_e32 v123, v123, v174
	v_mul_f32_e32 v124, v121, v124
	v_cndmask_b32_e64 v121, v124, v121, s[10:11]
	v_add_f32_e32 v124, 1.0, v151
	v_mul_f32_e32 v151, 0xbfb8aa3b, v123
	v_exp_f32_e32 v151, v151
	v_mul_f32_e32 v125, v125, v174
	v_rcp_f32_e32 v124, v124
	v_mul_f32_e32 v121, v125, v121
	v_mul_f32_e32 v125, v126, v174
	v_add_f32_e32 v126, 1.0, v151
	v_rcp_f32_e32 v126, v126
	v_mul_f32_e32 v124, v122, v124
	v_cndmask_b32_e64 v122, v124, v122, s[10:11]
	v_mul_f32_e32 v112, v112, v174
	v_mul_f32_e32 v122, v125, v122
	v_mul_f32_e32 v125, v123, v126
	v_mul_f32_e32 v126, 0xbfb8aa3b, v112
	v_exp_f32_e32 v126, v126
	v_mul_f32_e32 v124, v127, v174
	v_cndmask_b32_e64 v123, v125, v123, s[10:11]
	v_mul_f32_e32 v123, v124, v123
	v_add_f32_e32 v124, 1.0, v126
	v_rcp_f32_e32 v124, v124
	v_mul_f32_e32 v113, v113, v174
	v_mul_f32_e32 v125, 0xbfb8aa3b, v113
	v_exp_f32_e32 v125, v125
	v_mul_f32_e32 v124, v112, v124
	v_mul_f32_e32 v116, v116, v174
	v_cndmask_b32_e64 v112, v124, v112, s[10:11]
	v_mul_f32_e32 v124, v116, v112
	v_add_f32_e32 v112, 1.0, v125
	v_mul_f32_e32 v114, v114, v174
	v_rcp_f32_e32 v112, v112
	v_mul_f32_e32 v116, 0xbfb8aa3b, v114
	v_exp_f32_e32 v116, v116
	v_mul_f32_e32 v115, v115, v174
	v_mul_f32_e32 v112, v113, v112
	v_cndmask_b32_e64 v112, v112, v113, s[10:11]
	v_add_f32_e32 v113, 1.0, v116
	v_mul_f32_e32 v116, 0xbfb8aa3b, v115
	v_exp_f32_e32 v116, v116
	v_rcp_f32_e32 v113, v113
	v_mul_f32_e32 v117, v117, v174
	v_mul_f32_e32 v125, v117, v112
	v_add_f32_e32 v116, 1.0, v116
	v_rcp_f32_e32 v116, v116
	v_mul_f32_e32 v113, v114, v113
	v_mul_f32_e32 v112, v118, v174
	v_cndmask_b32_e64 v113, v113, v114, s[10:11]
	v_mul_f32_e32 v118, v112, v113
	v_mul_f32_e32 v113, v115, v116
	v_mul_f32_e32 v112, v119, v174
	v_cndmask_b32_e64 v113, v113, v115, s[10:11]
	v_mul_f32_e32 v115, v112, v113
	v_lshl_add_u64 v[116:117], v[178:179], 1, v[176:177]
	v_cvt_pk_bf16_f32 v112, v120, v121
	v_cvt_pk_bf16_f32 v113, v122, v123
	v_cvt_pk_bf16_f32 v114, v124, v125
	v_cvt_pk_bf16_f32 v115, v118, v115
	global_store_dwordx4 v[116:117], v[112:115], off nt
	s_waitcnt lgkmcnt(6)
; __device__ __forceinline__ unsigned cvt_pk_bf16(float lo, float hi) { unsigned r; asm("v_cvt_pk_bf16_f32 %0, %1, %2" : "=v"(r) : "v"(lo), "v"(hi)); return r; }
; __device__ __forceinline__ float silu_f(float x) { return x * __builtin_amdgcn_rcpf(1.f + __builtin_amdgcn_exp2f(-LOG2E * x)); }
;     __device__ __forceinline__ void operator()(const f32x4 (&acc)[2][2][4][2], const Unit& u, int wr, int wc, int fr, int fq, LAS unsigned char* xs, int wid, int lane) const {
;     ...
;         } else if (mode == 1 || mode == 2) {
; #pragma unroll
;             for (int ai = 0; ai < 2; ++ai)
; #pragma unroll
;                 for (int m = 0; m < 4; ++m) {
;                     const float r = rs[ai][m];
;                     bf16_t* rowp = base + (size_t)(row0 + ai * 128 + m * 16 + fr) * ldc + wc * 32 + 8 * fq;
;                     float o[8];
; #pragma unroll
;                     for (int n = 0; n < 2; ++n)
; #pragma unroll
;                         for (int j = 0; j < 4; ++j) { const float a = acc[ai][0][m][n][j] * r, b = acc[ai][1][m][n][j] * r; o[4 * n + j] = (mode == 1) ? a * b : a * silu_f(b); }
;                     u32x4 w; w.x = cvt_pk_bf16(o[0], o[1]); w.y = cvt_pk_bf16(o[2], o[3]); w.z = cvt_pk_bf16(o[4], o[5]); w.w = cvt_pk_bf16(o[6], o[7]);
;                     *(u32x4*)rowp = w;
;                     __builtin_amdgcn_sched_barrier(0);
;                 }
	v_mul_f32_e32 v104, v104, v172
	v_mul_f32_e32 v113, 0xbfb8aa3b, v104
	v_exp_f32_e32 v115, v113
	v_or_b32_e32 v112, 16, v162
	v_mul_lo_u32 v114, s53, v112
	v_mad_u64_u32 v[112:113], s[54:55], s52, v112, 0
	v_add3_u32 v113, v113, s0, v114
	v_add_f32_e32 v114, 1.0, v115
	v_rcp_f32_e32 v114, v114
	v_mul_f32_e32 v105, v105, v172
	v_mul_f32_e32 v115, 0xbfb8aa3b, v105
	v_exp_f32_e32 v115, v115
	v_mul_f32_e32 v114, v104, v114
	v_mul_f32_e32 v108, v108, v172
	v_cndmask_b32_e64 v104, v114, v104, s[10:11]
	v_mul_f32_e32 v104, v108, v104
	v_add_f32_e32 v108, 1.0, v115
	v_mul_f32_e32 v106, v106, v172
	v_rcp_f32_e32 v108, v108
	v_mul_f32_e32 v114, 0xbfb8aa3b, v106
	v_exp_f32_e32 v114, v114
	v_mul_f32_e32 v107, v107, v172
	v_mul_f32_e32 v108, v105, v108
	v_cndmask_b32_e64 v105, v108, v105, s[10:11]
	v_add_f32_e32 v108, 1.0, v114
	v_mul_f32_e32 v114, 0xbfb8aa3b, v107
	v_exp_f32_e32 v114, v114
	v_mul_f32_e32 v109, v109, v172
	v_rcp_f32_e32 v108, v108
	v_mul_f32_e32 v105, v109, v105
	v_mul_f32_e32 v109, v110, v172
	v_add_f32_e32 v110, 1.0, v114
	v_rcp_f32_e32 v110, v110
	v_mul_f32_e32 v108, v106, v108
	v_cndmask_b32_e64 v106, v108, v106, s[10:11]
	v_mul_f32_e32 v96, v96, v172
	v_mul_f32_e32 v106, v109, v106
	v_mul_f32_e32 v109, v107, v110
	v_mul_f32_e32 v110, 0xbfb8aa3b, v96
	v_exp_f32_e32 v110, v110
	v_mul_f32_e32 v108, v111, v172
	v_cndmask_b32_e64 v107, v109, v107, s[10:11]
	v_mul_f32_e32 v107, v108, v107
	v_add_f32_e32 v108, 1.0, v110
	v_rcp_f32_e32 v108, v108
	v_mul_f32_e32 v97, v97, v172
	v_mul_f32_e32 v109, 0xbfb8aa3b, v97
	v_exp_f32_e32 v109, v109
	v_mul_f32_e32 v108, v96, v108
	v_mul_f32_e32 v100, v100, v172
	v_cndmask_b32_e64 v96, v108, v96, s[10:11]
	v_mul_f32_e32 v108, v100, v96
	v_add_f32_e32 v96, 1.0, v109
	v_mul_f32_e32 v98, v98, v172
	v_rcp_f32_e32 v96, v96
	v_mul_f32_e32 v100, 0xbfb8aa3b, v98
	v_exp_f32_e32 v100, v100
	v_mul_f32_e32 v99, v99, v172
	v_mul_f32_e32 v96, v97, v96
	v_cndmask_b32_e64 v96, v96, v97, s[10:11]
	v_add_f32_e32 v97, 1.0, v100
	v_mul_f32_e32 v100, 0xbfb8aa3b, v99
	v_exp_f32_e32 v100, v100
	v_rcp_f32_e32 v97, v97
	v_mul_f32_e32 v101, v101, v172
	v_mul_f32_e32 v109, v101, v96
	v_add_f32_e32 v100, 1.0, v100
	v_rcp_f32_e32 v100, v100
	v_mul_f32_e32 v97, v98, v97
	v_mul_f32_e32 v96, v102, v172
	v_cndmask_b32_e64 v97, v97, v98, s[10:11]
	v_mul_f32_e32 v102, v96, v97
	v_mul_f32_e32 v97, v99, v100
	v_mul_f32_e32 v96, v103, v172
	v_cndmask_b32_e64 v97, v97, v99, s[10:11]
	v_mul_f32_e32 v99, v96, v97
	v_lshl_add_u64 v[100:101], v[112:113], 1, v[176:177]
	v_cvt_pk_bf16_f32 v96, v104, v105
	v_cvt_pk_bf16_f32 v97, v106, v107
	v_cvt_pk_bf16_f32 v98, v108, v109
	v_cvt_pk_bf16_f32 v99, v102, v99
	global_store_dwordx4 v[100:101], v[96:99], off nt
	s_waitcnt lgkmcnt(5)
	v_mul_f32_e32 v88, v88, v170
	v_mul_f32_e32 v97, 0xbfb8aa3b, v88
	v_exp_f32_e32 v99, v97
	v_or_b32_e32 v96, 32, v162
	v_mul_lo_u32 v98, s53, v96
	v_mad_u64_u32 v[96:97], s[54:55], s52, v96, 0
	v_add3_u32 v97, v97, s0, v98
	v_add_f32_e32 v98, 1.0, v99
	v_rcp_f32_e32 v98, v98
	v_mul_f32_e32 v89, v89, v170
	v_mul_f32_e32 v99, 0xbfb8aa3b, v89
	v_exp_f32_e32 v99, v99
	v_mul_f32_e32 v98, v88, v98
	v_mul_f32_e32 v92, v92, v170
	v_cndmask_b32_e64 v88, v98, v88, s[10:11]
	v_mul_f32_e32 v88, v92, v88
	v_add_f32_e32 v92, 1.0, v99
	v_mul_f32_e32 v90, v90, v170
	v_rcp_f32_e32 v92, v92
	v_mul_f32_e32 v98, 0xbfb8aa3b, v90
	v_exp_f32_e32 v98, v98
	v_mul_f32_e32 v91, v91, v170
	v_mul_f32_e32 v92, v89, v92
	v_cndmask_b32_e64 v89, v92, v89, s[10:11]
	v_add_f32_e32 v92, 1.0, v98
	v_mul_f32_e32 v98, 0xbfb8aa3b, v91
	v_exp_f32_e32 v98, v98
	v_mul_f32_e32 v93, v93, v170
	v_rcp_f32_e32 v92, v92
	v_mul_f32_e32 v89, v93, v89
	v_mul_f32_e32 v93, v94, v170
	v_add_f32_e32 v94, 1.0, v98
	v_rcp_f32_e32 v94, v94
	v_mul_f32_e32 v92, v90, v92
	v_cndmask_b32_e64 v90, v92, v90, s[10:11]
	v_mul_f32_e32 v80, v80, v170
	v_mul_f32_e32 v90, v93, v90
	v_mul_f32_e32 v93, v91, v94
	v_mul_f32_e32 v94, 0xbfb8aa3b, v80
	v_exp_f32_e32 v94, v94
	v_mul_f32_e32 v92, v95, v170
	v_cndmask_b32_e64 v91, v93, v91, s[10:11]
	v_mul_f32_e32 v91, v92, v91
	v_add_f32_e32 v92, 1.0, v94
	v_rcp_f32_e32 v92, v92
	v_mul_f32_e32 v81, v81, v170
	v_mul_f32_e32 v93, 0xbfb8aa3b, v81
	v_exp_f32_e32 v93, v93
	v_mul_f32_e32 v92, v80, v92
	v_mul_f32_e32 v84, v84, v170
	v_cndmask_b32_e64 v80, v92, v80, s[10:11]
	v_mul_f32_e32 v92, v84, v80
	v_add_f32_e32 v80, 1.0, v93
	v_mul_f32_e32 v82, v82, v170
	v_rcp_f32_e32 v80, v80
	v_mul_f32_e32 v84, 0xbfb8aa3b, v82
	v_exp_f32_e32 v84, v84
	v_mul_f32_e32 v83, v83, v170
	v_mul_f32_e32 v80, v81, v80
	v_cndmask_b32_e64 v80, v80, v81, s[10:11]
	v_add_f32_e32 v81, 1.0, v84
	v_mul_f32_e32 v84, 0xbfb8aa3b, v83
	v_exp_f32_e32 v84, v84
	v_rcp_f32_e32 v81, v81
	v_mul_f32_e32 v85, v85, v170
	v_mul_f32_e32 v93, v85, v80
	v_add_f32_e32 v84, 1.0, v84
	v_rcp_f32_e32 v84, v84
	v_mul_f32_e32 v81, v82, v81
	v_mul_f32_e32 v80, v86, v170
	v_cndmask_b32_e64 v81, v81, v82, s[10:11]
	v_mul_f32_e32 v86, v80, v81
	v_mul_f32_e32 v81, v83, v84
	v_mul_f32_e32 v80, v87, v170
	v_cndmask_b32_e64 v81, v81, v83, s[10:11]
	v_mul_f32_e32 v83, v80, v81
	v_lshl_add_u64 v[84:85], v[96:97], 1, v[176:177]
	v_cvt_pk_bf16_f32 v80, v88, v89
	v_cvt_pk_bf16_f32 v81, v90, v91
	v_cvt_pk_bf16_f32 v82, v92, v93
	v_cvt_pk_bf16_f32 v83, v86, v83
	global_store_dwordx4 v[84:85], v[80:83], off nt
	s_waitcnt lgkmcnt(4)
; __device__ __forceinline__ unsigned cvt_pk_bf16(float lo, float hi) { unsigned r; asm("v_cvt_pk_bf16_f32 %0, %1, %2" : "=v"(r) : "v"(lo), "v"(hi)); return r; }
; __device__ __forceinline__ float silu_f(float x) { return x * __builtin_amdgcn_rcpf(1.f + __builtin_amdgcn_exp2f(-LOG2E * x)); }
;     __device__ __forceinline__ void operator()(const f32x4 (&acc)[2][2][4][2], const Unit& u, int wr, int wc, int fr, int fq, LAS unsigned char* xs, int wid, int lane) const {
;     ...
;         } else if (mode == 1 || mode == 2) {
; #pragma unroll
;             for (int ai = 0; ai < 2; ++ai)
; #pragma unroll
;                 for (int m = 0; m < 4; ++m) {
;                     const float r = rs[ai][m];
;                     bf16_t* rowp = base + (size_t)(row0 + ai * 128 + m * 16 + fr) * ldc + wc * 32 + 8 * fq;
;                     float o[8];
; #pragma unroll
;                     for (int n = 0; n < 2; ++n)
; #pragma unroll
;                         for (int j = 0; j < 4; ++j) { const float a = acc[ai][0][m][n][j] * r, b = acc[ai][1][m][n][j] * r; o[4 * n + j] = (mode == 1) ? a * b : a * silu_f(b); }
;                     u32x4 w; w.x = cvt_pk_bf16(o[0], o[1]); w.y = cvt_pk_bf16(o[2], o[3]); w.z = cvt_pk_bf16(o[4], o[5]); w.w = cvt_pk_bf16(o[6], o[7]);
;                     *(u32x4*)rowp = w;
;                     __builtin_amdgcn_sched_barrier(0);
;                 }
	v_mul_f32_e32 v72, v72, v168
	v_mul_f32_e32 v81, 0xbfb8aa3b, v72
	v_exp_f32_e32 v83, v81
	v_or_b32_e32 v80, 48, v162
	v_mul_lo_u32 v82, s53, v80
	v_mad_u64_u32 v[80:81], s[54:55], s52, v80, 0
	v_add3_u32 v81, v81, s0, v82
	v_add_f32_e32 v82, 1.0, v83
	v_rcp_f32_e32 v82, v82
	v_mul_f32_e32 v73, v73, v168
	v_mul_f32_e32 v83, 0xbfb8aa3b, v73
	v_exp_f32_e32 v83, v83
	v_mul_f32_e32 v82, v72, v82
	v_mul_f32_e32 v76, v76, v168
	v_cndmask_b32_e64 v72, v82, v72, s[10:11]
	v_mul_f32_e32 v72, v76, v72
	v_add_f32_e32 v76, 1.0, v83
	v_mul_f32_e32 v74, v74, v168
	v_rcp_f32_e32 v76, v76
	v_mul_f32_e32 v82, 0xbfb8aa3b, v74
	v_exp_f32_e32 v82, v82
	v_mul_f32_e32 v75, v75, v168
	v_mul_f32_e32 v76, v73, v76
	v_cndmask_b32_e64 v73, v76, v73, s[10:11]
	v_add_f32_e32 v76, 1.0, v82
	v_mul_f32_e32 v82, 0xbfb8aa3b, v75
	v_exp_f32_e32 v82, v82
	v_mul_f32_e32 v77, v77, v168
	v_rcp_f32_e32 v76, v76
	v_mul_f32_e32 v73, v77, v73
	v_mul_f32_e32 v77, v78, v168
	v_add_f32_e32 v78, 1.0, v82
	v_rcp_f32_e32 v78, v78
	v_mul_f32_e32 v76, v74, v76
	v_cndmask_b32_e64 v74, v76, v74, s[10:11]
	v_mul_f32_e32 v64, v64, v168
	v_mul_f32_e32 v74, v77, v74
	v_mul_f32_e32 v77, v75, v78
	v_mul_f32_e32 v78, 0xbfb8aa3b, v64
	v_exp_f32_e32 v78, v78
	v_mul_f32_e32 v76, v79, v168
	v_cndmask_b32_e64 v75, v77, v75, s[10:11]
	v_mul_f32_e32 v75, v76, v75
	v_add_f32_e32 v76, 1.0, v78
	v_rcp_f32_e32 v76, v76
	v_mul_f32_e32 v65, v65, v168
	v_mul_f32_e32 v77, 0xbfb8aa3b, v65
	v_exp_f32_e32 v77, v77
	v_mul_f32_e32 v76, v64, v76
	v_mul_f32_e32 v68, v68, v168
	v_cndmask_b32_e64 v64, v76, v64, s[10:11]
	v_mul_f32_e32 v76, v68, v64
	v_add_f32_e32 v64, 1.0, v77
	v_mul_f32_e32 v66, v66, v168
	v_rcp_f32_e32 v64, v64
	v_mul_f32_e32 v68, 0xbfb8aa3b, v66
	v_exp_f32_e32 v68, v68
	v_mul_f32_e32 v67, v67, v168
	v_mul_f32_e32 v64, v65, v64
	v_cndmask_b32_e64 v64, v64, v65, s[10:11]
	v_add_f32_e32 v65, 1.0, v68
	v_mul_f32_e32 v68, 0xbfb8aa3b, v67
	v_exp_f32_e32 v68, v68
	v_rcp_f32_e32 v65, v65
	v_mul_f32_e32 v69, v69, v168
	v_mul_f32_e32 v77, v69, v64
	v_add_f32_e32 v68, 1.0, v68
	v_rcp_f32_e32 v68, v68
	v_mul_f32_e32 v65, v66, v65
	v_mul_f32_e32 v64, v70, v168
	v_cndmask_b32_e64 v65, v65, v66, s[10:11]
	v_mul_f32_e32 v70, v64, v65
	v_mul_f32_e32 v65, v67, v68
	v_mul_f32_e32 v64, v71, v168
	v_cndmask_b32_e64 v65, v65, v67, s[10:11]
	v_mul_f32_e32 v67, v64, v65
	v_lshl_add_u64 v[68:69], v[80:81], 1, v[176:177]
	v_cvt_pk_bf16_f32 v64, v72, v73
	v_cvt_pk_bf16_f32 v65, v74, v75
	v_cvt_pk_bf16_f32 v66, v76, v77
	v_cvt_pk_bf16_f32 v67, v70, v67
	global_store_dwordx4 v[68:69], v[64:67], off nt
	s_nop 1
	v_add_u32_e32 v64, 0x80, v162
	v_ashrrev_i32_e32 v65, 31, v64
	s_waitcnt lgkmcnt(3)
	v_mul_f32_e32 v56, v56, v166
	v_mul_lo_u32 v66, s52, v65
	v_mul_f32_e32 v65, 0xbfb8aa3b, v56
	v_exp_f32_e32 v68, v65
	v_mul_lo_u32 v67, s53, v64
	v_mad_u64_u32 v[64:65], s[0:1], s52, v64, 0
	v_add3_u32 v65, v65, v66, v67
	v_add_f32_e32 v66, 1.0, v68
	v_rcp_f32_e32 v66, v66
	v_mul_f32_e32 v57, v57, v166
	v_mul_f32_e32 v67, 0xbfb8aa3b, v57
	v_exp_f32_e32 v67, v67
	v_mul_f32_e32 v66, v56, v66
	v_mul_f32_e32 v60, v60, v166
	v_cndmask_b32_e64 v56, v66, v56, s[10:11]
	v_mul_f32_e32 v56, v60, v56
	v_add_f32_e32 v60, 1.0, v67
	v_mul_f32_e32 v58, v58, v166
	v_rcp_f32_e32 v60, v60
	v_mul_f32_e32 v66, 0xbfb8aa3b, v58
	v_exp_f32_e32 v66, v66
	v_mul_f32_e32 v59, v59, v166
	v_mul_f32_e32 v60, v57, v60
	v_cndmask_b32_e64 v57, v60, v57, s[10:11]
	v_add_f32_e32 v60, 1.0, v66
	v_mul_f32_e32 v66, 0xbfb8aa3b, v59
	v_exp_f32_e32 v66, v66
	v_mul_f32_e32 v61, v61, v166
	v_rcp_f32_e32 v60, v60
	v_mul_f32_e32 v57, v61, v57
	v_mul_f32_e32 v61, v62, v166
	v_add_f32_e32 v62, 1.0, v66
	v_rcp_f32_e32 v62, v62
	v_mul_f32_e32 v60, v58, v60
	v_cndmask_b32_e64 v58, v60, v58, s[10:11]
	v_mul_f32_e32 v48, v48, v166
	v_mul_f32_e32 v58, v61, v58
	v_mul_f32_e32 v61, v59, v62
	v_mul_f32_e32 v62, 0xbfb8aa3b, v48
	v_exp_f32_e32 v62, v62
	v_mul_f32_e32 v60, v63, v166
	v_cndmask_b32_e64 v59, v61, v59, s[10:11]
	v_mul_f32_e32 v59, v60, v59
	v_add_f32_e32 v60, 1.0, v62
	v_rcp_f32_e32 v60, v60
	v_mul_f32_e32 v49, v49, v166
	v_mul_f32_e32 v61, 0xbfb8aa3b, v49
	v_exp_f32_e32 v61, v61
	v_mul_f32_e32 v60, v48, v60
	v_mul_f32_e32 v52, v52, v166
	v_cndmask_b32_e64 v48, v60, v48, s[10:11]
	v_mul_f32_e32 v60, v52, v48
	v_add_f32_e32 v48, 1.0, v61
	v_mul_f32_e32 v50, v50, v166
	v_rcp_f32_e32 v48, v48
	v_mul_f32_e32 v52, 0xbfb8aa3b, v50
	v_exp_f32_e32 v52, v52
	v_mul_f32_e32 v51, v51, v166
	v_mul_f32_e32 v48, v49, v48
	v_cndmask_b32_e64 v48, v48, v49, s[10:11]
	v_add_f32_e32 v49, 1.0, v52
	v_mul_f32_e32 v52, 0xbfb8aa3b, v51
	v_exp_f32_e32 v52, v52
	v_rcp_f32_e32 v49, v49
	v_mul_f32_e32 v53, v53, v166
	v_mul_f32_e32 v61, v53, v48
	v_add_f32_e32 v52, 1.0, v52
	v_rcp_f32_e32 v52, v52
	v_mul_f32_e32 v49, v50, v49
	v_mul_f32_e32 v48, v54, v166
	v_cndmask_b32_e64 v49, v49, v50, s[10:11]
	v_mul_f32_e32 v54, v48, v49
	v_mul_f32_e32 v49, v51, v52
	v_mul_f32_e32 v48, v55, v166
	v_cndmask_b32_e64 v49, v49, v51, s[10:11]
	v_mul_f32_e32 v51, v48, v49
	v_lshl_add_u64 v[52:53], v[64:65], 1, v[176:177]
	v_cvt_pk_bf16_f32 v48, v56, v57
	v_cvt_pk_bf16_f32 v49, v58, v59
	v_cvt_pk_bf16_f32 v50, v60, v61
	v_cvt_pk_bf16_f32 v51, v54, v51
	global_store_dwordx4 v[52:53], v[48:51], off nt
	s_nop 1
	v_add_u32_e32 v48, 0x90, v162
	v_ashrrev_i32_e32 v49, 31, v48
	s_waitcnt lgkmcnt(2)
; __device__ __forceinline__ unsigned cvt_pk_bf16(float lo, float hi) { unsigned r; asm("v_cvt_pk_bf16_f32 %0, %1, %2" : "=v"(r) : "v"(lo), "v"(hi)); return r; }
; __device__ __forceinline__ float silu_f(float x) { return x * __builtin_amdgcn_rcpf(1.f + __builtin_amdgcn_exp2f(-LOG2E * x)); }
;     __device__ __forceinline__ void operator()(const f32x4 (&acc)[2][2][4][2], const Unit& u, int wr, int wc, int fr, int fq, LAS unsigned char* xs, int wid, int lane) const {
;     ...
;         } else if (mode == 1 || mode == 2) {
; #pragma unroll
;             for (int ai = 0; ai < 2; ++ai)
; #pragma unroll
;                 for (int m = 0; m < 4; ++m) {
;                     const float r = rs[ai][m];
;                     bf16_t* rowp = base + (size_t)(row0 + ai * 128 + m * 16 + fr) * ldc + wc * 32 + 8 * fq;
;                     float o[8];
; #pragma unroll
;                     for (int n = 0; n < 2; ++n)
; #pragma unroll
;                         for (int j = 0; j < 4; ++j) { const float a = acc[ai][0][m][n][j] * r, b = acc[ai][1][m][n][j] * r; o[4 * n + j] = (mode == 1) ? a * b : a * silu_f(b); }
;                     u32x4 w; w.x = cvt_pk_bf16(o[0], o[1]); w.y = cvt_pk_bf16(o[2], o[3]); w.z = cvt_pk_bf16(o[4], o[5]); w.w = cvt_pk_bf16(o[6], o[7]);
;                     *(u32x4*)rowp = w;
;                     __builtin_amdgcn_sched_barrier(0);
;                 }
	v_mul_f32_e32 v40, v40, v164
	v_mul_lo_u32 v50, s52, v49
	v_mul_f32_e32 v49, 0xbfb8aa3b, v40
	v_exp_f32_e32 v52, v49
	v_mul_lo_u32 v51, s53, v48
	v_mad_u64_u32 v[48:49], s[0:1], s52, v48, 0
	v_add3_u32 v49, v49, v50, v51
	v_add_f32_e32 v50, 1.0, v52
	v_rcp_f32_e32 v50, v50
	v_mul_f32_e32 v41, v41, v164
	v_mul_f32_e32 v51, 0xbfb8aa3b, v41
	v_exp_f32_e32 v51, v51
	v_mul_f32_e32 v50, v40, v50
	v_mul_f32_e32 v44, v44, v164
	v_cndmask_b32_e64 v40, v50, v40, s[10:11]
	v_mul_f32_e32 v40, v44, v40
	v_add_f32_e32 v44, 1.0, v51
	v_mul_f32_e32 v42, v42, v164
	v_rcp_f32_e32 v44, v44
	v_mul_f32_e32 v50, 0xbfb8aa3b, v42
	v_exp_f32_e32 v50, v50
	v_mul_f32_e32 v43, v43, v164
	v_mul_f32_e32 v44, v41, v44
	v_cndmask_b32_e64 v41, v44, v41, s[10:11]
	v_add_f32_e32 v44, 1.0, v50
	v_mul_f32_e32 v50, 0xbfb8aa3b, v43
	v_exp_f32_e32 v50, v50
	v_mul_f32_e32 v45, v45, v164
	v_rcp_f32_e32 v44, v44
	v_mul_f32_e32 v41, v45, v41
	v_mul_f32_e32 v45, v46, v164
	v_add_f32_e32 v46, 1.0, v50
	v_rcp_f32_e32 v46, v46
	v_mul_f32_e32 v44, v42, v44
	v_cndmask_b32_e64 v42, v44, v42, s[10:11]
	v_mul_f32_e32 v32, v32, v164
	v_mul_f32_e32 v42, v45, v42
	v_mul_f32_e32 v45, v43, v46
	v_mul_f32_e32 v46, 0xbfb8aa3b, v32
	v_exp_f32_e32 v46, v46
	v_mul_f32_e32 v44, v47, v164
	v_cndmask_b32_e64 v43, v45, v43, s[10:11]
	v_mul_f32_e32 v43, v44, v43
	v_add_f32_e32 v44, 1.0, v46
	v_rcp_f32_e32 v44, v44
	v_mul_f32_e32 v33, v33, v164
	v_mul_f32_e32 v45, 0xbfb8aa3b, v33
	v_exp_f32_e32 v45, v45
	v_mul_f32_e32 v44, v32, v44
	v_mul_f32_e32 v36, v36, v164
	v_cndmask_b32_e64 v32, v44, v32, s[10:11]
	v_mul_f32_e32 v44, v36, v32
	v_add_f32_e32 v32, 1.0, v45
	v_mul_f32_e32 v34, v34, v164
	v_rcp_f32_e32 v32, v32
	v_mul_f32_e32 v36, 0xbfb8aa3b, v34
	v_exp_f32_e32 v36, v36
	v_mul_f32_e32 v35, v35, v164
	v_mul_f32_e32 v32, v33, v32
	v_cndmask_b32_e64 v32, v32, v33, s[10:11]
	v_add_f32_e32 v33, 1.0, v36
	v_mul_f32_e32 v36, 0xbfb8aa3b, v35
	v_exp_f32_e32 v36, v36
	v_rcp_f32_e32 v33, v33
	v_mul_f32_e32 v37, v37, v164
	v_mul_f32_e32 v45, v37, v32
	v_add_f32_e32 v36, 1.0, v36
	v_rcp_f32_e32 v36, v36
	v_mul_f32_e32 v33, v34, v33
	v_mul_f32_e32 v32, v38, v164
	v_cndmask_b32_e64 v33, v33, v34, s[10:11]
	v_mul_f32_e32 v38, v32, v33
	v_mul_f32_e32 v33, v35, v36
	v_mul_f32_e32 v32, v39, v164
	v_cndmask_b32_e64 v33, v33, v35, s[10:11]
	v_mul_f32_e32 v35, v32, v33
	v_lshl_add_u64 v[36:37], v[48:49], 1, v[176:177]
	v_cvt_pk_bf16_f32 v32, v40, v41
	v_cvt_pk_bf16_f32 v33, v42, v43
	v_cvt_pk_bf16_f32 v34, v44, v45
	v_cvt_pk_bf16_f32 v35, v38, v35
	global_store_dwordx4 v[36:37], v[32:35], off nt
	s_nop 1
	v_add_u32_e32 v32, 0xa0, v162
	v_ashrrev_i32_e32 v33, 31, v32
	s_waitcnt lgkmcnt(1)
; __device__ __forceinline__ unsigned cvt_pk_bf16(float lo, float hi) { unsigned r; asm("v_cvt_pk_bf16_f32 %0, %1, %2" : "=v"(r) : "v"(lo), "v"(hi)); return r; }
; __device__ __forceinline__ float silu_f(float x) { return x * __builtin_amdgcn_rcpf(1.f + __builtin_amdgcn_exp2f(-LOG2E * x)); }
;     __device__ __forceinline__ void operator()(const f32x4 (&acc)[2][2][4][2], const Unit& u, int wr, int wc, int fr, int fq, LAS unsigned char* xs, int wid, int lane) const {
;     ...
;         } else if (mode == 1 || mode == 2) {
; #pragma unroll
;             for (int ai = 0; ai < 2; ++ai)
; #pragma unroll
;                 for (int m = 0; m < 4; ++m) {
;                     const float r = rs[ai][m];
;                     bf16_t* rowp = base + (size_t)(row0 + ai * 128 + m * 16 + fr) * ldc + wc * 32 + 8 * fq;
;                     float o[8];
; #pragma unroll
;                     for (int n = 0; n < 2; ++n)
; #pragma unroll
;                         for (int j = 0; j < 4; ++j) { const float a = acc[ai][0][m][n][j] * r, b = acc[ai][1][m][n][j] * r; o[4 * n + j] = (mode == 1) ? a * b : a * silu_f(b); }
;                     u32x4 w; w.x = cvt_pk_bf16(o[0], o[1]); w.y = cvt_pk_bf16(o[2], o[3]); w.z = cvt_pk_bf16(o[4], o[5]); w.w = cvt_pk_bf16(o[6], o[7]);
;                     *(u32x4*)rowp = w;
;                     __builtin_amdgcn_sched_barrier(0);
;                 }
	v_mul_f32_e32 v24, v24, v160
	v_mul_lo_u32 v34, s52, v33
	v_mul_f32_e32 v33, 0xbfb8aa3b, v24
	v_exp_f32_e32 v36, v33
	v_mul_lo_u32 v35, s53, v32
	v_mad_u64_u32 v[32:33], s[0:1], s52, v32, 0
	v_add3_u32 v33, v33, v34, v35
	v_add_f32_e32 v34, 1.0, v36
	v_rcp_f32_e32 v34, v34
	v_mul_f32_e32 v25, v25, v160
	v_mul_f32_e32 v35, 0xbfb8aa3b, v25
	v_exp_f32_e32 v35, v35
	v_mul_f32_e32 v34, v24, v34
	v_mul_f32_e32 v28, v28, v160
	v_cndmask_b32_e64 v24, v34, v24, s[10:11]
	v_mul_f32_e32 v24, v28, v24
	v_add_f32_e32 v28, 1.0, v35
	v_mul_f32_e32 v26, v26, v160
	v_rcp_f32_e32 v28, v28
	v_mul_f32_e32 v34, 0xbfb8aa3b, v26
	v_exp_f32_e32 v34, v34
	v_mul_f32_e32 v27, v27, v160
	v_mul_f32_e32 v28, v25, v28
	v_cndmask_b32_e64 v25, v28, v25, s[10:11]
	v_add_f32_e32 v28, 1.0, v34
	v_mul_f32_e32 v34, 0xbfb8aa3b, v27
	v_exp_f32_e32 v34, v34
	v_mul_f32_e32 v29, v29, v160
	v_rcp_f32_e32 v28, v28
	v_mul_f32_e32 v25, v29, v25
	v_mul_f32_e32 v29, v30, v160
	v_add_f32_e32 v30, 1.0, v34
	v_rcp_f32_e32 v30, v30
	v_mul_f32_e32 v28, v26, v28
	v_cndmask_b32_e64 v26, v28, v26, s[10:11]
	v_mul_f32_e32 v16, v16, v160
	v_mul_f32_e32 v26, v29, v26
	v_mul_f32_e32 v29, v27, v30
	v_mul_f32_e32 v30, 0xbfb8aa3b, v16
	v_exp_f32_e32 v30, v30
	v_mul_f32_e32 v28, v31, v160
	v_cndmask_b32_e64 v27, v29, v27, s[10:11]
	v_mul_f32_e32 v27, v28, v27
	v_add_f32_e32 v28, 1.0, v30
	v_rcp_f32_e32 v28, v28
	v_mul_f32_e32 v17, v17, v160
	v_mul_f32_e32 v29, 0xbfb8aa3b, v17
	v_exp_f32_e32 v29, v29
	v_mul_f32_e32 v28, v16, v28
	v_mul_f32_e32 v20, v20, v160
	v_cndmask_b32_e64 v16, v28, v16, s[10:11]
	v_mul_f32_e32 v28, v20, v16
	v_add_f32_e32 v16, 1.0, v29
	v_mul_f32_e32 v18, v18, v160
	v_rcp_f32_e32 v16, v16
	v_mul_f32_e32 v20, 0xbfb8aa3b, v18
	v_exp_f32_e32 v20, v20
	v_mul_f32_e32 v19, v19, v160
	v_mul_f32_e32 v16, v17, v16
	v_cndmask_b32_e64 v16, v16, v17, s[10:11]
	v_add_f32_e32 v17, 1.0, v20
	v_mul_f32_e32 v20, 0xbfb8aa3b, v19
	v_exp_f32_e32 v20, v20
	v_rcp_f32_e32 v17, v17
	v_mul_f32_e32 v21, v21, v160
	v_mul_f32_e32 v29, v21, v16
	v_add_f32_e32 v20, 1.0, v20
	v_rcp_f32_e32 v20, v20
	v_mul_f32_e32 v17, v18, v17
	v_mul_f32_e32 v16, v22, v160
	v_cndmask_b32_e64 v17, v17, v18, s[10:11]
	v_mul_f32_e32 v22, v16, v17
	v_mul_f32_e32 v17, v19, v20
	v_mul_f32_e32 v16, v23, v160
	v_cndmask_b32_e64 v17, v17, v19, s[10:11]
	v_mul_f32_e32 v19, v16, v17
	v_lshl_add_u64 v[20:21], v[32:33], 1, v[176:177]
	v_cvt_pk_bf16_f32 v16, v24, v25
	v_cvt_pk_bf16_f32 v17, v26, v27
	v_cvt_pk_bf16_f32 v18, v28, v29
	v_cvt_pk_bf16_f32 v19, v22, v19
	global_store_dwordx4 v[20:21], v[16:19], off nt
	s_nop 1
	v_add_u32_e32 v16, 0xb0, v162
	v_ashrrev_i32_e32 v17, 31, v16
	s_waitcnt lgkmcnt(0)
	v_mul_f32_e32 v8, v8, v158
	v_mul_lo_u32 v18, s52, v17
	v_mul_f32_e32 v17, 0xbfb8aa3b, v8
	v_exp_f32_e32 v20, v17
	v_mul_lo_u32 v19, s53, v16
	v_mad_u64_u32 v[16:17], s[0:1], s52, v16, 0
	v_add3_u32 v17, v17, v18, v19
	v_add_f32_e32 v18, 1.0, v20
	v_rcp_f32_e32 v18, v18
	v_mul_f32_e32 v9, v9, v158
	v_mul_f32_e32 v19, 0xbfb8aa3b, v9
	v_exp_f32_e32 v19, v19
	v_mul_f32_e32 v18, v8, v18
	v_mul_f32_e32 v12, v12, v158
	v_cndmask_b32_e64 v8, v18, v8, s[10:11]
	v_mul_f32_e32 v8, v12, v8
	v_add_f32_e32 v12, 1.0, v19
	v_mul_f32_e32 v10, v10, v158
	v_rcp_f32_e32 v12, v12
	v_mul_f32_e32 v18, 0xbfb8aa3b, v10
	v_exp_f32_e32 v18, v18
	v_mul_f32_e32 v11, v11, v158
	v_mul_f32_e32 v12, v9, v12
	v_cndmask_b32_e64 v9, v12, v9, s[10:11]
	v_add_f32_e32 v12, 1.0, v18
	v_mul_f32_e32 v18, 0xbfb8aa3b, v11
	v_exp_f32_e32 v18, v18
	v_mul_f32_e32 v13, v13, v158
	v_rcp_f32_e32 v12, v12
	v_mul_f32_e32 v9, v13, v9
	v_mul_f32_e32 v13, v14, v158
	v_add_f32_e32 v14, 1.0, v18
	v_rcp_f32_e32 v14, v14
	v_mul_f32_e32 v12, v10, v12
	v_cndmask_b32_e64 v10, v12, v10, s[10:11]
	v_mul_f32_e32 v0, v0, v158
	v_mul_f32_e32 v10, v13, v10
	v_mul_f32_e32 v13, v11, v14
	v_mul_f32_e32 v14, 0xbfb8aa3b, v0
	v_exp_f32_e32 v14, v14
	v_mul_f32_e32 v12, v15, v158
	v_cndmask_b32_e64 v11, v13, v11, s[10:11]
	v_mul_f32_e32 v11, v12, v11
	v_add_f32_e32 v12, 1.0, v14
	v_rcp_f32_e32 v12, v12
	v_mul_f32_e32 v1, v1, v158
	v_mul_f32_e32 v13, 0xbfb8aa3b, v1
	v_exp_f32_e32 v13, v13
	v_mul_f32_e32 v12, v0, v12
	v_mul_f32_e32 v4, v4, v158
	v_cndmask_b32_e64 v0, v12, v0, s[10:11]
	v_mul_f32_e32 v12, v4, v0
	v_add_f32_e32 v0, 1.0, v13
	v_mul_f32_e32 v2, v2, v158
	v_rcp_f32_e32 v0, v0
	v_mul_f32_e32 v4, 0xbfb8aa3b, v2
	v_exp_f32_e32 v4, v4
	v_mul_f32_e32 v3, v3, v158
	v_mul_f32_e32 v0, v1, v0
	v_cndmask_b32_e64 v0, v0, v1, s[10:11]
	v_add_f32_e32 v1, 1.0, v4
	v_mul_f32_e32 v4, 0xbfb8aa3b, v3
	v_exp_f32_e32 v4, v4
	v_rcp_f32_e32 v1, v1
	v_mul_f32_e32 v5, v5, v158
	v_mul_f32_e32 v13, v5, v0
	v_add_f32_e32 v4, 1.0, v4
	v_rcp_f32_e32 v4, v4
	v_mul_f32_e32 v1, v2, v1
	v_mul_f32_e32 v0, v6, v158
	v_cndmask_b32_e64 v1, v1, v2, s[10:11]
	v_mul_f32_e32 v6, v0, v1
	v_mul_f32_e32 v1, v3, v4
	v_mul_f32_e32 v0, v7, v158
	v_cndmask_b32_e64 v1, v1, v3, s[10:11]
	v_mul_f32_e32 v3, v0, v1
	v_lshl_add_u64 v[4:5], v[16:17], 1, v[176:177]
	v_cvt_pk_bf16_f32 v0, v8, v9
	v_cvt_pk_bf16_f32 v1, v10, v11
	v_cvt_pk_bf16_f32 v2, v12, v13
	v_cvt_pk_bf16_f32 v3, v6, v3
	global_store_dwordx4 v[4:5], v[0:3], off nt
	s_andn2_b64 vcc, exec, s[8:9]
	s_mov_b64 s[8:9], -1
	s_cbranch_vccnz .LBB0_1444

;     __device__ __forceinline__ void operator()(const f32x4 (&acc)[2][2][4][2], const Unit& u, int wr, int wc, int fr, int fq, LAS unsigned char* xs, int wid, int lane) const {
;     ...
;         if (!SRCF32) {
; #pragma unroll
;             for (int ai = 0; ai < 2; ++ai)
; #pragma unroll
;                 for (int m = 0; m < 4; ++m)
; #pragma unroll
;                     for (int bj = 0; bj < 2; ++bj) raw[ai][m][bj] = *(const u32x4*)(xb + (size_t)(row0 + ai * 128 + m * 16 + fr) * D + col0 + bj * 128);
;         }
; #pragma unroll
;         for (int ai = 0; ai < 2; ++ai) {
;             f32x4 xf[4][2][2];
;             if (SRCF32) {
; #pragma unroll
;                 for (int m = 0; m < 4; ++m)
; #pragma unroll
;                     for (int bj = 0; bj < 2; ++bj) { const size_t o = (size_t)(row0 + ai * 128 + m * 16 + fr) * D + col0 + bj * 128; xf[m][bj][0] = *(const f32x4*)(xo + o); xf[m][bj][1] = *(const f32x4*)(xo + o + 4); }
;             }
; #pragma unroll
;             for (int m = 0; m < 4; ++m) {
;                 const size_t row = (size_t)(row0 + ai * 128 + m * 16 + fr);
;                 float ss = 0.f;
; #pragma unroll
;                 for (int bj = 0; bj < 2; ++bj) {
;                     const size_t o = row * D + col0 + bj * 128;
;                     f32x4 x0, x1;
;                     if (SRCF32) { x0 = xf[m][bj][0]; x1 = xf[m][bj][1]; }
;                     else { const u32x4 r = raw[ai][m][bj]; x0 = (f32x4){bf_lo(r.x), bf_hi(r.x), bf_lo(r.y), bf_hi(r.y)}; x1 = (f32x4){bf_lo(r.z), bf_hi(r.z), bf_lo(r.w), bf_hi(r.w)}; }
;                     const f32x4 v0 = x0 + acc[ai][bj][m][0], v1 = x1 + acc[ai][bj][m][1];
;                     if (LAST) { *(f32x4*)(out + o) = v0; *(f32x4*)(out + o + 4) = v1; }
.LBB0_1628:
	v_lshl_or_b32 v128, s46, 8, v196
	v_lshl_add_u32 v130, s26, 8, v194
	v_ashrrev_i32_e32 v129, 31, v128
	v_ashrrev_i32_e32 v131, 31, v130
	v_lshl_add_u64 v[132:133], v[128:129], 1, s[16:17]
	v_lshlrev_b64 v[134:135], 12, v[130:131]
	v_or_b32_e32 v228, 16, v130
	v_lshl_add_u64 v[134:135], v[132:133], 0, v[134:135]
	v_ashrrev_i32_e32 v229, 31, v228
	global_load_dwordx4 v[200:203], v[134:135], off
	global_load_dwordx4 v[204:207], v[134:135], off offset:256
	v_lshlrev_b64 v[134:135], 12, v[228:229]
	v_lshl_add_u64 v[134:135], v[132:133], 0, v[134:135]
	global_load_dwordx4 v[208:211], v[134:135], off
	v_or_b32_e32 v192, 32, v130
	v_ashrrev_i32_e32 v193, 31, v192
	global_load_dwordx4 v[212:215], v[134:135], off offset:256
	v_lshlrev_b64 v[182:183], 2, v[128:129]
	v_lshlrev_b64 v[128:129], 12, v[192:193]
	v_lshl_add_u64 v[128:129], v[132:133], 0, v[128:129]
	global_load_dwordx4 v[216:219], v[128:129], off
	v_or_b32_e32 v190, 48, v130
	v_add_u32_e32 v188, 0x80, v130
	v_add_u32_e32 v186, 0x90, v130
	v_add_u32_e32 v184, 0xa0, v130
	v_add_u32_e32 v180, 0xb0, v130
	v_ashrrev_i32_e32 v191, 31, v190
	v_ashrrev_i32_e32 v189, 31, v188
	v_ashrrev_i32_e32 v187, 31, v186
	v_ashrrev_i32_e32 v185, 31, v184
	v_ashrrev_i32_e32 v181, 31, v180
	v_lshlrev_b64 v[130:131], 13, v[130:131]
	v_lshlrev_b64 v[134:135], 12, v[190:191]
	v_lshlrev_b64 v[136:137], 12, v[188:189]
	v_lshlrev_b64 v[138:139], 12, v[186:187]
	v_lshlrev_b64 v[140:141], 12, v[184:185]
	v_lshlrev_b64 v[142:143], 12, v[180:181]
	v_lshl_add_u64 v[130:131], s[4:5], 0, v[130:131]
	v_lshl_add_u64 v[134:135], v[132:133], 0, v[134:135]
	v_lshl_add_u64 v[136:137], v[132:133], 0, v[136:137]
	v_lshl_add_u64 v[138:139], v[132:133], 0, v[138:139]
	v_lshl_add_u64 v[230:231], v[132:133], 0, v[140:141]
	v_lshl_add_u64 v[232:233], v[132:133], 0, v[142:143]
	v_lshl_add_u64 v[234:235], v[130:131], 0, v[182:183]
	global_load_dwordx4 v[220:223], v[128:129], off offset:256
	global_load_dwordx4 v[224:227], v[134:135], off
	global_load_dwordx4 v[160:163], v[134:135], off offset:256
	global_load_dwordx4 v[156:159], v[136:137], off
	global_load_dwordx4 v[152:155], v[136:137], off offset:256
	global_load_dwordx4 v[148:151], v[138:139], off
	global_load_dwordx4 v[144:147], v[138:139], off offset:256
	global_load_dwordx4 v[140:143], v[230:231], off
	s_nop 0
	global_load_dwordx4 v[136:139], v[230:231], off offset:256
	global_load_dwordx4 v[132:135], v[232:233], off
	global_load_dwordx4 v[128:131], v[232:233], off offset:256
	s_andn2_b64 vcc, exec, s[0:1]
	s_mov_b64 s[0:1], -1
	s_waitcnt vmcnt(0)
	v_lshlrev_b32_e32 v230, 16, v200
	v_and_b32_e32 v231, 0xffff0000, v200
	v_lshlrev_b32_e32 v200, 16, v201
	v_and_b32_e32 v201, 0xffff0000, v201
	v_lshlrev_b32_e32 v238, 16, v206
	v_and_b32_e32 v239, 0xffff0000, v206
	v_lshlrev_b32_e32 v232, 16, v202
	v_and_b32_e32 v233, 0xffff0000, v202
	v_lshlrev_b32_e32 v202, 16, v203
	v_and_b32_e32 v203, 0xffff0000, v203
	v_lshlrev_b32_e32 v236, 16, v204
	v_and_b32_e32 v237, 0xffff0000, v204
	v_lshlrev_b32_e32 v204, 16, v205
	v_and_b32_e32 v205, 0xffff0000, v205
	v_lshlrev_b32_e32 v206, 16, v207
	v_and_b32_e32 v207, 0xffff0000, v207
	v_pk_add_f32 v[126:127], v[126:127], v[200:201]
	v_pk_add_f32 v[124:125], v[124:125], v[230:231]
	v_pk_add_f32 v[112:113], v[112:113], v[238:239]
	v_pk_add_f32 v[122:123], v[122:123], v[202:203]
	v_pk_add_f32 v[120:121], v[120:121], v[232:233]
	v_pk_add_f32 v[118:119], v[118:119], v[204:205]
	v_pk_add_f32 v[116:117], v[116:117], v[236:237]
	v_pk_add_f32 v[114:115], v[114:115], v[206:207]
	global_store_dwordx4 v[234:235], v[124:127], off nt
	global_store_dwordx4 v[234:235], v[120:123], off offset:16 nt
	global_store_dwordx4 v[234:235], v[116:119], off offset:512 nt
	global_store_dwordx4 v[234:235], v[112:115], off offset:528 nt
	v_lshlrev_b32_e32 v200, 16, v208
	v_and_b32_e32 v201, 0xffff0000, v208
	v_lshlrev_b32_e32 v112, 16, v210
	v_and_b32_e32 v113, 0xffff0000, v210
	v_pk_add_f32 v[104:105], v[104:105], v[112:113]
	v_lshlrev_b64 v[112:113], 13, v[228:229]
	v_lshlrev_b32_e32 v202, 16, v209
	v_and_b32_e32 v203, 0xffff0000, v209
	v_lshlrev_b32_e32 v114, 16, v211
	v_and_b32_e32 v115, 0xffff0000, v211
	v_lshl_add_u64 v[112:113], s[4:5], 0, v[112:113]
	v_pk_add_f32 v[110:111], v[110:111], v[202:203]
	v_pk_add_f32 v[108:109], v[108:109], v[200:201]
	v_pk_add_f32 v[106:107], v[106:107], v[114:115]
	v_lshl_add_u64 v[112:113], v[112:113], 0, v[182:183]
	global_store_dwordx4 v[112:113], v[108:111], off nt
	global_store_dwordx4 v[112:113], v[104:107], off offset:16 nt
	s_nop 0
	v_lshlrev_b32_e32 v108, 16, v214
	v_lshlrev_b32_e32 v104, 16, v212
	v_and_b32_e32 v105, 0xffff0000, v212
	v_lshlrev_b32_e32 v106, 16, v213
	v_and_b32_e32 v107, 0xffff0000, v213
	v_and_b32_e32 v109, 0xffff0000, v214
	v_lshlrev_b32_e32 v110, 16, v215
	v_and_b32_e32 v111, 0xffff0000, v215
	v_pk_add_f32 v[102:103], v[102:103], v[106:107]
	v_pk_add_f32 v[100:101], v[100:101], v[104:105]
	v_pk_add_f32 v[92:93], v[92:93], v[108:109]
	v_pk_add_f32 v[94:95], v[94:95], v[110:111]
	global_store_dwordx4 v[112:113], v[100:103], off offset:512 nt
	global_store_dwordx4 v[112:113], v[92:95], off offset:528 nt
	s_nop 0
	v_lshlrev_b32_e32 v100, 16, v218
	v_lshlrev_b32_e32 v92, 16, v216
	v_and_b32_e32 v93, 0xffff0000, v216
	v_pk_add_f32 v[92:93], v[96:97], v[92:93]
	v_lshlrev_b64 v[96:97], 13, v[192:193]
	v_lshlrev_b32_e32 v94, 16, v217
	v_and_b32_e32 v95, 0xffff0000, v217
	v_and_b32_e32 v101, 0xffff0000, v218
	v_lshlrev_b32_e32 v102, 16, v219
	v_and_b32_e32 v103, 0xffff0000, v219
	v_lshl_add_u64 v[96:97], s[4:5], 0, v[96:97]
	v_pk_add_f32 v[94:95], v[98:99], v[94:95]
	v_pk_add_f32 v[90:91], v[90:91], v[102:103]
;     __device__ __forceinline__ void operator()(const f32x4 (&acc)[2][2][4][2], const Unit& u, int wr, int wc, int fr, int fq, LAS unsigned char* xs, int wid, int lane) const {
;     ...
; #pragma unroll
;             for (int m = 0; m < 4; ++m) {
;                 const size_t row = (size_t)(row0 + ai * 128 + m * 16 + fr);
;                 float ss = 0.f;
; #pragma unroll
;                 for (int bj = 0; bj < 2; ++bj) {
;                     const size_t o = row * D + col0 + bj * 128;
;                     f32x4 x0, x1;
;                     if (SRCF32) { x0 = xf[m][bj][0]; x1 = xf[m][bj][1]; }
;                     else { const u32x4 r = raw[ai][m][bj]; x0 = (f32x4){bf_lo(r.x), bf_hi(r.x), bf_lo(r.y), bf_hi(r.y)}; x1 = (f32x4){bf_lo(r.z), bf_hi(r.z), bf_lo(r.w), bf_hi(r.w)}; }
;                     const f32x4 v0 = x0 + acc[ai][bj][m][0], v1 = x1 + acc[ai][bj][m][1];
;                     if (LAST) { *(f32x4*)(out + o) = v0; *(f32x4*)(out + o + 4) = v1; }
	v_pk_add_f32 v[88:89], v[88:89], v[100:101]
	v_lshl_add_u64 v[96:97], v[96:97], 0, v[182:183]
	global_store_dwordx4 v[96:97], v[92:95], off nt
	global_store_dwordx4 v[96:97], v[88:91], off offset:16 nt
	s_nop 0
	v_lshlrev_b32_e32 v92, 16, v222
	v_lshlrev_b32_e32 v88, 16, v220
	v_and_b32_e32 v89, 0xffff0000, v220
	v_lshlrev_b32_e32 v90, 16, v221
	v_and_b32_e32 v91, 0xffff0000, v221
	v_and_b32_e32 v93, 0xffff0000, v222
	v_lshlrev_b32_e32 v94, 16, v223
	v_and_b32_e32 v95, 0xffff0000, v223
	v_pk_add_f32 v[86:87], v[86:87], v[90:91]
	v_pk_add_f32 v[84:85], v[84:85], v[88:89]
	v_pk_add_f32 v[76:77], v[76:77], v[92:93]
	v_pk_add_f32 v[78:79], v[78:79], v[94:95]
	global_store_dwordx4 v[96:97], v[84:87], off offset:512 nt
	global_store_dwordx4 v[96:97], v[76:79], off offset:528 nt
	s_nop 0
	v_lshlrev_b32_e32 v84, 16, v226
	v_lshlrev_b32_e32 v76, 16, v224
	v_and_b32_e32 v77, 0xffff0000, v224
	v_pk_add_f32 v[76:77], v[80:81], v[76:77]
	v_lshlrev_b64 v[80:81], 13, v[190:191]
	v_lshlrev_b32_e32 v78, 16, v225
	v_and_b32_e32 v79, 0xffff0000, v225
	v_and_b32_e32 v85, 0xffff0000, v226
	v_lshlrev_b32_e32 v86, 16, v227
	v_and_b32_e32 v87, 0xffff0000, v227
	v_lshl_add_u64 v[80:81], s[4:5], 0, v[80:81]
	v_pk_add_f32 v[78:79], v[82:83], v[78:79]
	v_pk_add_f32 v[74:75], v[74:75], v[86:87]
	v_pk_add_f32 v[72:73], v[72:73], v[84:85]
	v_lshl_add_u64 v[80:81], v[80:81], 0, v[182:183]
	global_store_dwordx4 v[80:81], v[76:79], off nt
	global_store_dwordx4 v[80:81], v[72:75], off offset:16 nt
	s_nop 0
	v_lshlrev_b32_e32 v76, 16, v162
	v_lshlrev_b32_e32 v72, 16, v160
	v_and_b32_e32 v73, 0xffff0000, v160
	v_lshlrev_b32_e32 v74, 16, v161
	v_and_b32_e32 v75, 0xffff0000, v161
	v_and_b32_e32 v77, 0xffff0000, v162
	v_lshlrev_b32_e32 v78, 16, v163
	v_and_b32_e32 v79, 0xffff0000, v163
	v_pk_add_f32 v[70:71], v[70:71], v[74:75]
	v_pk_add_f32 v[68:69], v[68:69], v[72:73]
	v_pk_add_f32 v[64:65], v[64:65], v[76:77]
	v_pk_add_f32 v[66:67], v[66:67], v[78:79]
	global_store_dwordx4 v[80:81], v[68:71], off offset:512 nt
	global_store_dwordx4 v[80:81], v[64:67], off offset:528 nt
	s_nop 0
	v_lshlrev_b32_e32 v68, 16, v158
	v_lshlrev_b32_e32 v64, 16, v156
	v_and_b32_e32 v65, 0xffff0000, v156
	v_pk_add_f32 v[60:61], v[60:61], v[64:65]
	v_lshlrev_b64 v[64:65], 13, v[188:189]
	v_lshlrev_b32_e32 v66, 16, v157
	v_and_b32_e32 v67, 0xffff0000, v157
	v_and_b32_e32 v69, 0xffff0000, v158
	v_lshlrev_b32_e32 v70, 16, v159
	v_and_b32_e32 v71, 0xffff0000, v159
	v_lshl_add_u64 v[64:65], s[4:5], 0, v[64:65]
	v_pk_add_f32 v[62:63], v[62:63], v[66:67]
	v_pk_add_f32 v[58:59], v[58:59], v[70:71]
	v_pk_add_f32 v[56:57], v[56:57], v[68:69]
	v_lshl_add_u64 v[64:65], v[64:65], 0, v[182:183]
	global_store_dwordx4 v[64:65], v[60:63], off nt
	global_store_dwordx4 v[64:65], v[56:59], off offset:16 nt
	s_nop 0
	v_lshlrev_b32_e32 v60, 16, v154
	v_lshlrev_b32_e32 v56, 16, v152
	v_and_b32_e32 v57, 0xffff0000, v152
	v_lshlrev_b32_e32 v58, 16, v153
	v_and_b32_e32 v59, 0xffff0000, v153
	v_and_b32_e32 v61, 0xffff0000, v154
	v_lshlrev_b32_e32 v62, 16, v155
	v_and_b32_e32 v63, 0xffff0000, v155
	v_pk_add_f32 v[54:55], v[54:55], v[58:59]
	v_pk_add_f32 v[52:53], v[52:53], v[56:57]
	v_pk_add_f32 v[44:45], v[44:45], v[60:61]
	v_pk_add_f32 v[46:47], v[46:47], v[62:63]
	global_store_dwordx4 v[64:65], v[52:55], off offset:512 nt
	global_store_dwordx4 v[64:65], v[44:47], off offset:528 nt
	s_nop 0
	v_lshlrev_b32_e32 v52, 16, v150
	v_lshlrev_b32_e32 v44, 16, v148
	v_and_b32_e32 v45, 0xffff0000, v148
	v_pk_add_f32 v[44:45], v[48:49], v[44:45]
	v_lshlrev_b64 v[48:49], 13, v[186:187]
	v_lshlrev_b32_e32 v46, 16, v149
	v_and_b32_e32 v47, 0xffff0000, v149
	v_and_b32_e32 v53, 0xffff0000, v150
; #define PG8_BAR __builtin_amdgcn_s_barrier()
; template <class Epi, class Sched>
; __device__ __forceinline__ void gemm_phase(LAS unsigned char* lds, const int K, const int lda, const int ldb, const Sched& S, const Epi& E) {
;     ...
;         cur = nxt; cA = nA; cB = nB; ++ui;
;         if (wr == 1) PG8_BAR;
;     }
;     __device__ __forceinline__ void operator()(const f32x4 (&acc)[2][2][4][2], const Unit& u, int wr, int wc, int fr, int fq, LAS unsigned char* xs, int wid, int lane) const {
;     ...
; #pragma unroll
;             for (int m = 0; m < 4; ++m) {
;                 const size_t row = (size_t)(row0 + ai * 128 + m * 16 + fr);
;                 float ss = 0.f;
; #pragma unroll
;                 for (int bj = 0; bj < 2; ++bj) {
;                     const size_t o = row * D + col0 + bj * 128;
;                     f32x4 x0, x1;
;                     if (SRCF32) { x0 = xf[m][bj][0]; x1 = xf[m][bj][1]; }
;                     else { const u32x4 r = raw[ai][m][bj]; x0 = (f32x4){bf_lo(r.x), bf_hi(r.x), bf_lo(r.y), bf_hi(r.y)}; x1 = (f32x4){bf_lo(r.z), bf_hi(r.z), bf_lo(r.w), bf_hi(r.w)}; }
;                     const f32x4 v0 = x0 + acc[ai][bj][m][0], v1 = x1 + acc[ai][bj][m][1];
;                     if (LAST) { *(f32x4*)(out + o) = v0; *(f32x4*)(out + o + 4) = v1; }
	v_lshlrev_b32_e32 v54, 16, v151
	v_and_b32_e32 v55, 0xffff0000, v151
	v_lshl_add_u64 v[48:49], s[4:5], 0, v[48:49]
	v_pk_add_f32 v[46:47], v[50:51], v[46:47]
	v_pk_add_f32 v[42:43], v[42:43], v[54:55]
	v_pk_add_f32 v[40:41], v[40:41], v[52:53]
	v_lshl_add_u64 v[48:49], v[48:49], 0, v[182:183]
	global_store_dwordx4 v[48:49], v[44:47], off nt
	global_store_dwordx4 v[48:49], v[40:43], off offset:16 nt
	s_nop 0
	v_lshlrev_b32_e32 v44, 16, v146
	v_lshlrev_b32_e32 v40, 16, v144
	v_and_b32_e32 v41, 0xffff0000, v144
	v_lshlrev_b32_e32 v42, 16, v145
	v_and_b32_e32 v43, 0xffff0000, v145
	v_and_b32_e32 v45, 0xffff0000, v146
	v_lshlrev_b32_e32 v46, 16, v147
	v_and_b32_e32 v47, 0xffff0000, v147
	v_pk_add_f32 v[38:39], v[38:39], v[42:43]
	v_pk_add_f32 v[36:37], v[36:37], v[40:41]
	v_pk_add_f32 v[28:29], v[28:29], v[44:45]
	v_pk_add_f32 v[30:31], v[30:31], v[46:47]
	global_store_dwordx4 v[48:49], v[36:39], off offset:512 nt
	global_store_dwordx4 v[48:49], v[28:31], off offset:528 nt
	s_nop 0
	v_lshlrev_b32_e32 v36, 16, v142
	v_lshlrev_b32_e32 v28, 16, v140
	v_and_b32_e32 v29, 0xffff0000, v140
	v_pk_add_f32 v[28:29], v[32:33], v[28:29]
	v_lshlrev_b64 v[32:33], 13, v[184:185]
	v_lshlrev_b32_e32 v30, 16, v141
	v_and_b32_e32 v31, 0xffff0000, v141
	v_and_b32_e32 v37, 0xffff0000, v142
	v_lshlrev_b32_e32 v38, 16, v143
	v_and_b32_e32 v39, 0xffff0000, v143
	v_lshl_add_u64 v[32:33], s[4:5], 0, v[32:33]
	v_pk_add_f32 v[30:31], v[34:35], v[30:31]
	v_pk_add_f32 v[26:27], v[26:27], v[38:39]
	v_pk_add_f32 v[24:25], v[24:25], v[36:37]
	v_lshl_add_u64 v[32:33], v[32:33], 0, v[182:183]
	global_store_dwordx4 v[32:33], v[28:31], off nt
	global_store_dwordx4 v[32:33], v[24:27], off offset:16 nt
	s_nop 0
	v_lshlrev_b32_e32 v28, 16, v138
	v_lshlrev_b32_e32 v24, 16, v136
	v_and_b32_e32 v25, 0xffff0000, v136
	v_lshlrev_b32_e32 v26, 16, v137
	v_and_b32_e32 v27, 0xffff0000, v137
	v_and_b32_e32 v29, 0xffff0000, v138
	v_lshlrev_b32_e32 v30, 16, v139
	v_and_b32_e32 v31, 0xffff0000, v139
	v_pk_add_f32 v[22:23], v[22:23], v[26:27]
	v_pk_add_f32 v[20:21], v[20:21], v[24:25]
	v_pk_add_f32 v[12:13], v[12:13], v[28:29]
	v_pk_add_f32 v[14:15], v[14:15], v[30:31]
	global_store_dwordx4 v[32:33], v[20:23], off offset:512 nt
	global_store_dwordx4 v[32:33], v[12:15], off offset:528 nt
	s_nop 0
	v_lshlrev_b32_e32 v20, 16, v134
	v_lshlrev_b32_e32 v12, 16, v132
	v_and_b32_e32 v13, 0xffff0000, v132
	v_pk_add_f32 v[12:13], v[16:17], v[12:13]
	v_lshlrev_b64 v[16:17], 13, v[180:181]
	v_lshlrev_b32_e32 v14, 16, v133
	v_and_b32_e32 v15, 0xffff0000, v133
	v_and_b32_e32 v21, 0xffff0000, v134
	v_lshlrev_b32_e32 v22, 16, v135
	v_and_b32_e32 v23, 0xffff0000, v135
	v_lshl_add_u64 v[16:17], s[4:5], 0, v[16:17]
	v_pk_add_f32 v[14:15], v[18:19], v[14:15]
	v_pk_add_f32 v[10:11], v[10:11], v[22:23]
	v_pk_add_f32 v[8:9], v[8:9], v[20:21]
	v_lshl_add_u64 v[16:17], v[16:17], 0, v[182:183]
	global_store_dwordx4 v[16:17], v[12:15], off nt
	global_store_dwordx4 v[16:17], v[8:11], off offset:16 nt
	s_nop 0
	v_lshlrev_b32_e32 v12, 16, v130
	v_lshlrev_b32_e32 v8, 16, v128
	v_and_b32_e32 v9, 0xffff0000, v128
	v_lshlrev_b32_e32 v10, 16, v129
	v_and_b32_e32 v11, 0xffff0000, v129
	v_and_b32_e32 v13, 0xffff0000, v130
	v_lshlrev_b32_e32 v14, 16, v131
	v_and_b32_e32 v15, 0xffff0000, v131
	v_pk_add_f32 v[6:7], v[6:7], v[10:11]
	v_pk_add_f32 v[4:5], v[4:5], v[8:9]
	v_pk_add_f32 v[2:3], v[2:3], v[14:15]
	v_pk_add_f32 v[0:1], v[0:1], v[12:13]
	global_store_dwordx4 v[16:17], v[4:7], off offset:512 nt
	global_store_dwordx4 v[16:17], v[0:3], off offset:528 nt
	s_cbranch_vccnz .LBB0_1617
	s_andn2_b64 vcc, exec, s[6:7]
	s_cbranch_vccnz .LBB0_1616
	s_barrier
	s_branch .LBB0_1616
